# X16 residual stream stored as contiguous 1KiB 16x32 fragments so EpiRes epilogue loads and stores are contiguous
# speedup vs baseline: 1.0021x; 1.0021x over previous
; __device__ __forceinline__ int opaque_tid(int wave_s) { int l; asm volatile("v_mbcnt_lo_u32_b32 %0, -1, 0\n\tv_mbcnt_hi_u32_b32 %0, -1, %0" : "=v"(l)); return (wave_s << 6) | l; }
; __device__ __forceinline__ unsigned cvtpk(float lo, float hi) { unsigned r; asm volatile("v_cvt_pk_bf16_f32 %0, %1, %2" : "=v"(r) : "v"(lo), "v"(hi)); return r; }
; __device__ __forceinline__ void xg_pass(const float* x, const float* nw, const float* sc, bf16_t* XGp, bf16_t* X16p, unsigned long long* ssq, int vcu, int ngw, const int wave_s) {
;     const int tid_ = opaque_tid(wave_s), lane = tid_ & 63, gw = vcu * NWAVES + (tid_ >> 6);
;     f32x4 wv[4];
; #pragma unroll
;     for (int j = 0; j < 4; ++j) wv[j] = *(const f32x4*)(nw + 4 * lane + 256 * j);
;     for (int m0 = 2 * gw; m0 < MTOK; m0 += 2 * ngw) {
;         const int b = m0 >> 12;
;         f32x4 v[2][4], scv[4];
; #pragma unroll
;         for (int i = 0; i < 2; ++i)
; #pragma unroll
;             for (int j = 0; j < 4; ++j) v[i][j] = ((const f32x4*)(x + (size_t)(m0 + i) * DM) + lane)[64 * j];
; #pragma unroll
;         for (int j = 0; j < 4; ++j) scv[j] = *(const f32x4*)(sc + (size_t)b * NMOD + 4 * lane + 256 * j);
; #pragma unroll
;         for (int i = 0; i < 2; ++i) {
;             const int m = m0 + i; float s = 0.f;
; #pragma unroll
;             for (int j = 0; j < 4; ++j) s += (v[i][j].x * v[i][j].x + v[i][j].y * v[i][j].y) + (v[i][j].z * v[i][j].z + v[i][j].w * v[i][j].w);
;             s = wave_sum(s, lane);
;             if (lane == 0) ssq[m] = (unsigned long long)(s * 16777216.0f);
;             unsigned long long* o8 = (unsigned long long*)(XGp + (size_t)m * DM) + lane;
;             unsigned long long* x8 = (unsigned long long*)(X16p + (size_t)m * DM) + lane;
; #pragma unroll
;             for (int j = 0; j < 4; ++j) {
;                 const f32x4 h = v[i][j] * wv[j] * (scv[j] + 1.0f);
;                 o8[64 * j] = (unsigned long long)cvtpk(h.x, h.y) | ((unsigned long long)cvtpk(h.z, h.w) << 32);
;                 x8[64 * j] = (unsigned long long)cvtpk(v[i][j].x, v[i][j].y) | ((unsigned long long)cvtpk(v[i][j].z, v[i][j].w) << 32);
;             }
.LBB0_348:
	v_mbcnt_lo_u32_b32 v0, -1, 0
	v_mbcnt_hi_u32_b32 v0, -1, v0
	s_nop 0
	v_or_b32_e32 v1, s40, v0
	v_ashrrev_i32_e32 v1, 5, v1
	v_and_b32_e32 v1, -2, v1
	v_lshl_add_u32 v64, s8, 4, v1
	s_mov_b32 s8, 0x10000
	v_cmp_gt_i32_e32 vcc, s8, v64
	s_and_saveexec_b64 s[8:9], vcc
	s_cbranch_execz .LBB0_355
	v_and_b32_e32 v20, 63, v0
	v_lshlrev_b32_e32 v16, 4, v20
	s_waitcnt lgkmcnt(0)
	global_load_dwordx4 v[0:3], v16, s[10:11]
	global_load_dwordx4 v[4:7], v16, s[10:11] offset:1024
	global_load_dwordx4 v[8:11], v16, s[10:11] offset:2048
	global_load_dwordx4 v[12:15], v16, s[10:11] offset:3072
	v_mov_b32_e32 v17, 0
	v_lshl_add_u64 v[18:19], s[2:3], 0, v[16:17]
	s_mov_b64 s[2:3], 0x6001000
	v_ashrrev_i32_e32 v65, 31, v64
	v_lshl_add_u64 v[66:67], v[18:19], 0, s[2:3]
	v_lshl_add_u64 v[18:19], v[64:65], 3, s[12:13]
	s_mov_b64 s[2:3], 0x3d000008
	v_lshl_add_u64 v[68:69], v[18:19], 0, s[2:3]
	v_lshlrev_b64 v[18:19], 11, v[64:65]
	v_lshl_add_u64 v[72:73], s[14:15], 0, v[18:19]
	v_lshl_add_u64 v[74:75], s[6:7], 0, v[18:19]
	v_lshlrev_b64 v[18:19], 12, v[64:65]
	s_lshl_b32 s10, s38, 4
	v_or_b32_e32 v18, v18, v16
	v_lshlrev_b32_e32 v21, 2, v20
	s_ashr_i32 s11, s10, 31
	v_mov_b32_e32 v71, v17
	v_lshl_add_u64 v[16:17], s[4:5], 0, v[18:19]
	s_mov_b64 s[2:3], 0x1000
	v_xor_b32_e32 v80, 4, v21
	v_xor_b32_e32 v81, 8, v21
	v_xor_b32_e32 v82, 16, v21
	v_xor_b32_e32 v83, 32, v21
	v_xor_b32_e32 v84, 64, v21
	v_xor_b32_e32 v85, 0x80, v21
	v_cmp_eq_u32_e32 vcc, 0, v20
	s_lshl_b64 s[12:13], s[10:11], 3
	v_lshlrev_b32_e32 v70, 3, v20
	s_lshl_b64 s[14:15], s[10:11], 11
	v_lshl_add_u64 v[76:77], v[16:17], 0, s[2:3]
	s_lshl_b64 s[16:17], s[10:11], 12
	s_mov_b64 s[18:19], 0
	s_mov_b32 s4, 0x35000000
	s_brev_b32 s5, 16
	s_mov_b32 s11, 0xffff
	v_and_b32_e32 v94, 15, v64
	v_mul_u32_u24_e32 v94, 0x7c0, v94
	v_bfe_u32 v95, v20, 3, 2
	v_lshlrev_b32_e32 v95, 1, v95
	v_lshrrev_b32_e32 v96, 5, v20
	v_add_u32_e32 v95, v95, v96
	v_lshlrev_b32_e32 v95, 10, v95
	v_and_b32_e32 v96, 7, v20
	v_lshl_or_b32 v95, v96, 3, v95
	v_sub_u32_e32 v94, v95, v94
	v_ashrrev_i32_e32 v95, 31, v94
	v_mov_b32_e32 v104, 0x2000
	v_mov_b32_e32 v105, 0x4000
	v_mov_b32_e32 v106, 0x6000
	s_branch .LBB0_351
.LBB0_350:
	s_or_b64 exec, exec, s[2:3]
	v_pk_mul_f32 v[34:35], v[0:1], v[28:29]
	v_pk_mul_f32 v[32:33], v[2:3], v[30:31]
	v_pk_mul_f32 v[34:35], v[34:35], v[78:79]
	v_pk_mul_f32 v[32:33], v[32:33], v[62:63]
	v_cvt_pk_bf16_f32 v34, v34, v35
	v_add_u32_e32 v64, s10, v64
	v_cvt_pk_bf16_f32 v35, v32, v33
	flat_store_dwordx2 v[60:61], v[34:35] offset:2048
	v_cvt_pk_bf16_f32 v28, v28, v29
	v_cvt_pk_bf16_f32 v29, v30, v31
	v_pk_mul_f32 v[30:31], v[4:5], v[24:25]
	flat_store_dwordx2 v[56:57], v[28:29] offset:64
	v_pk_mul_f32 v[28:29], v[6:7], v[26:27]
	v_pk_mul_f32 v[30:31], v[30:31], v[52:53]
	v_pk_mul_f32 v[28:29], v[28:29], v[54:55]
	v_cvt_pk_bf16_f32 v30, v30, v31
	v_cmp_lt_i32_e64 s[6:7], s11, v64
	v_cvt_pk_bf16_f32 v31, v28, v29
	flat_store_dwordx2 v[60:61], v[30:31] offset:2560
	v_cvt_pk_bf16_f32 v24, v24, v25
	v_cvt_pk_bf16_f32 v25, v26, v27
	v_pk_mul_f32 v[26:27], v[8:9], v[20:21]
	flat_store_dwordx2 v[98:99], v[24:25] offset:64
	v_pk_mul_f32 v[24:25], v[10:11], v[22:23]
	v_pk_mul_f32 v[26:27], v[26:27], v[44:45]
	v_pk_mul_f32 v[24:25], v[24:25], v[46:47]
	v_cvt_pk_bf16_f32 v26, v26, v27
	v_lshl_add_u64 v[68:69], v[68:69], 0, s[12:13]
	v_cvt_pk_bf16_f32 v27, v24, v25
	flat_store_dwordx2 v[60:61], v[26:27] offset:3072
	v_cvt_pk_bf16_f32 v20, v20, v21
	v_cvt_pk_bf16_f32 v21, v22, v23
	v_pk_mul_f32 v[22:23], v[12:13], v[16:17]
	flat_store_dwordx2 v[100:101], v[20:21] offset:64
	v_pk_mul_f32 v[20:21], v[14:15], v[18:19]
	v_pk_mul_f32 v[22:23], v[22:23], v[38:39]
	v_lshl_add_u64 v[72:73], v[72:73], 0, s[14:15]
	v_lshl_add_u64 v[74:75], v[74:75], 0, s[14:15]
	s_or_b64 s[18:19], s[6:7], s[18:19]
	v_lshl_add_u64 v[76:77], v[76:77], 0, s[16:17]
	v_pk_mul_f32 v[20:21], v[20:21], v[36:37]
	v_cvt_pk_bf16_f32 v22, v22, v23
	s_nop 0
	v_cvt_pk_bf16_f32 v23, v20, v21
	flat_store_dwordx2 v[60:61], v[22:23] offset:3584
	v_cvt_pk_bf16_f32 v16, v16, v17
	v_cvt_pk_bf16_f32 v17, v18, v19
	flat_store_dwordx2 v[102:103], v[16:17] offset:64
	s_andn2_b64 exec, exec, s[18:19]
	s_cbranch_execz .LBB0_355

; __device__ __forceinline__ unsigned cvtpk(float lo, float hi) { unsigned r; asm volatile("v_cvt_pk_bf16_f32 %0, %1, %2" : "=v"(r) : "v"(lo), "v"(hi)); return r; }
; __device__ __forceinline__ void xg_pass(const float* x, const float* nw, const float* sc, bf16_t* XGp, bf16_t* X16p, unsigned long long* ssq, int vcu, int ngw, const int wave_s) {
;     ...
;         for (int i = 0; i < 2; ++i) {
;             const int m = m0 + i; float s = 0.f;
; #pragma unroll
;             for (int j = 0; j < 4; ++j) s += (v[i][j].x * v[i][j].x + v[i][j].y * v[i][j].y) + (v[i][j].z * v[i][j].z + v[i][j].w * v[i][j].w);
;             s = wave_sum(s, lane);
;             if (lane == 0) ssq[m] = (unsigned long long)(s * 16777216.0f);
;             unsigned long long* o8 = (unsigned long long*)(XGp + (size_t)m * DM) + lane;
;             unsigned long long* x8 = (unsigned long long*)(X16p + (size_t)m * DM) + lane;
; #pragma unroll
;             for (int j = 0; j < 4; ++j) {
;                 const f32x4 h = v[i][j] * wv[j] * (scv[j] + 1.0f);
;                 o8[64 * j] = (unsigned long long)cvtpk(h.x, h.y) | ((unsigned long long)cvtpk(h.z, h.w) << 32);
;                 x8[64 * j] = (unsigned long long)cvtpk(v[i][j].x, v[i][j].y) | ((unsigned long long)cvtpk(v[i][j].z, v[i][j].w) << 32);
;             }
.LBB0_353:
	s_or_b64 exec, exec, s[2:3]
	v_pk_mul_f32 v[90:91], v[2:3], v[58:59]
	v_pk_mul_f32 v[92:93], v[0:1], v[56:57]
	v_pk_add_f32 v[62:63], v[62:63], 1.0 op_sel_hi:[1,0]
	s_waitcnt lgkmcnt(0)
	v_pk_add_f32 v[78:79], v[60:61], 1.0 op_sel_hi:[1,0]
	v_lshl_add_u64 v[86:87], v[74:75], 0, v[70:71]
	v_pk_mul_f32 v[60:61], v[90:91], v[62:63]
	v_pk_mul_f32 v[90:91], v[92:93], v[78:79]
	v_lshl_add_u64 v[88:89], v[72:73], 0, v[70:71]
	v_lshl_add_u64 v[96:97], v[72:73], 0, v[94:95]
	v_cvt_pk_bf16_f32 v90, v90, v91
	v_cvt_pk_bf16_f32 v91, v60, v61
	v_add_co_u32_e64 v60, s[6:7], s4, v86
	v_pk_add_f32 v[52:53], v[52:53], 1.0 op_sel_hi:[1,0]
	s_nop 0
	v_addc_co_u32_e64 v61, s[6:7], 0, v87, s[6:7]
	flat_store_dwordx2 v[60:61], v[90:91]
	v_cvt_pk_bf16_f32 v86, v56, v57
	v_add_co_u32_e64 v56, s[6:7], s5, v96
	v_cvt_pk_bf16_f32 v87, v58, v59
	v_pk_mul_f32 v[58:59], v[6:7], v[50:51]
	s_nop 0
	v_addc_co_u32_e64 v57, s[6:7], 0, v97, s[6:7]
	v_add_co_u32_e64 v98, s[6:7], v104, v56
	s_nop 1
	v_addc_co_u32_e64 v99, s[6:7], 0, v57, s[6:7]
	v_add_co_u32_e64 v100, s[6:7], v105, v56
	s_nop 1
	v_addc_co_u32_e64 v101, s[6:7], 0, v57, s[6:7]
	v_add_co_u32_e64 v102, s[6:7], v106, v56
	s_nop 1
	v_addc_co_u32_e64 v103, s[6:7], 0, v57, s[6:7]
	flat_store_dwordx2 v[56:57], v[86:87]
	v_pk_mul_f32 v[86:87], v[4:5], v[48:49]
	v_pk_add_f32 v[54:55], v[54:55], 1.0 op_sel_hi:[1,0]
	v_pk_mul_f32 v[86:87], v[86:87], v[52:53]
	v_pk_mul_f32 v[58:59], v[58:59], v[54:55]
	v_cvt_pk_bf16_f32 v86, v86, v87
	v_pk_add_f32 v[46:47], v[46:47], 1.0 op_sel_hi:[1,0]
	v_cvt_pk_bf16_f32 v87, v58, v59
	flat_store_dwordx2 v[60:61], v[86:87] offset:512
	v_cvt_pk_bf16_f32 v48, v48, v49
	v_cvt_pk_bf16_f32 v49, v50, v51
	flat_store_dwordx2 v[98:99], v[48:49]
	v_mul_f32_e32 v48, v29, v29
	v_mul_f32_e32 v49, v31, v31
	v_fmac_f32_e32 v48, v28, v28
	v_fmac_f32_e32 v49, v30, v30
	v_add_f32_e32 v48, v48, v49
	v_mul_f32_e32 v49, v25, v25
	v_mul_f32_e32 v50, v27, v27
	v_fmac_f32_e32 v49, v24, v24
	v_fmac_f32_e32 v50, v26, v26
	v_add_f32_e32 v49, v49, v50
	v_add_f32_e32 v48, v48, v49
	v_mul_f32_e32 v49, v21, v21
	v_mul_f32_e32 v50, v23, v23
	v_fmac_f32_e32 v49, v20, v20
	v_fmac_f32_e32 v50, v22, v22
	v_add_f32_e32 v49, v49, v50
	v_add_f32_e32 v48, v48, v49
	v_mul_f32_e32 v49, v17, v17
	v_mul_f32_e32 v50, v19, v19
	v_fmac_f32_e32 v49, v16, v16
	v_fmac_f32_e32 v50, v18, v18
	v_add_f32_e32 v49, v49, v50
	v_add_f32_e32 v58, v48, v49
	ds_bpermute_b32 v59, v80, v58
	v_pk_mul_f32 v[48:49], v[10:11], v[38:39]
	v_pk_mul_f32 v[50:51], v[8:9], v[36:37]
	v_pk_add_f32 v[44:45], v[44:45], 1.0 op_sel_hi:[1,0]
	v_pk_mul_f32 v[48:49], v[48:49], v[46:47]
	s_waitcnt lgkmcnt(0)
	v_add_f32_e32 v58, v58, v59
	ds_bpermute_b32 v59, v81, v58
	v_pk_mul_f32 v[50:51], v[50:51], v[44:45]
	s_nop 0
	v_cvt_pk_bf16_f32 v50, v50, v51
	v_cvt_pk_bf16_f32 v51, v48, v49
	s_waitcnt lgkmcnt(0)
	v_add_f32_e32 v48, v58, v59
	ds_bpermute_b32 v49, v82, v48
	flat_store_dwordx2 v[60:61], v[50:51] offset:1024
	v_cvt_pk_bf16_f32 v36, v36, v37
	v_cvt_pk_bf16_f32 v37, v38, v39
	flat_store_dwordx2 v[100:101], v[36:37]
	s_waitcnt lgkmcnt(0)
	v_add_f32_e32 v58, v48, v49
	ds_bpermute_b32 v59, v83, v58
	v_pk_mul_f32 v[48:49], v[14:15], v[34:35]
	v_pk_mul_f32 v[50:51], v[12:13], v[32:33]
	v_pk_add_f32 v[36:37], v[42:43], 1.0 op_sel_hi:[1,0]
	v_pk_add_f32 v[38:39], v[40:41], 1.0 op_sel_hi:[1,0]
	s_waitcnt lgkmcnt(0)
	v_add_f32_e32 v58, v58, v59
	ds_bpermute_b32 v59, v84, v58
	v_pk_mul_f32 v[40:41], v[48:49], v[36:37]
	v_pk_mul_f32 v[42:43], v[50:51], v[38:39]
	s_nop 0
	v_cvt_pk_bf16_f32 v42, v42, v43
	v_cvt_pk_bf16_f32 v43, v40, v41
	s_waitcnt lgkmcnt(0)
	v_add_f32_e32 v40, v58, v59
	ds_bpermute_b32 v41, v85, v40
	flat_store_dwordx2 v[60:61], v[42:43] offset:1536
	v_cvt_pk_bf16_f32 v32, v32, v33
	v_cvt_pk_bf16_f32 v33, v34, v35
	flat_store_dwordx2 v[102:103], v[32:33]
	s_and_saveexec_b64 s[2:3], vcc
	s_cbranch_execz .LBB0_350
	s_waitcnt lgkmcnt(0)
	v_add_f32_e32 v32, v40, v41
	v_mul_f32_e32 v32, 0x4b800000, v32
	v_trunc_f32_e32 v32, v32
	v_mul_f32_e32 v33, 0x2f800000, v32
	v_floor_f32_e32 v33, v33
	v_fmac_f32_e32 v32, 0xcf800000, v33
	v_cvt_u32_f32_e32 v32, v32
	v_cvt_u32_f32_e32 v33, v33
	flat_store_dwordx2 v[68:69], v[32:33]
	s_branch .LBB0_350

; __device__ __forceinline__ float ssq_val(ssq_t v) { return (float)v * SSQ_IFX; }
;     __device__ __forceinline__ void operator()(const f32x4 (&acc)[2][2][4][2], const Unit& u, int wr, int wc, int fr, int fq) const {
;         const int row0 = u.pm * BM + wr * 64 + fr; const int b = (u.pm * BM) >> 12;
;         ssq_t sv[8]; float rsv[8];
; #pragma unroll
;         for (int i = 0; i < 8; ++i) sv[i] = ssqx[row0 + (i >> 2) * HALF + (i & 3) * 16];
; #pragma unroll
;         for (int i = 0; i < 8; ++i) rsv[i] = 1.0f / sqrtf(ssq_val(sv[i]) * (1.0f / DM) + EPS);
; #pragma unroll
;         for (int bj = 0; bj < 2; ++bj) {
;             const int colw = u.pn * BM + bj * HALF + wc * 32, col0 = colw + 8 * fq;
;             const int mode = colw < 512 ? 1 : (colw < 640 ? 0 : (colw < 672 ? 2 : (colw < 1536 ? 0 : 3)));
;             const int stat = (colw >= PC_CQ && colw < PC_CKV) ? 1 : ((colw >= PC_CKV && colw < PC_CKV + 256) ? 2 : 0);
;             const float sc = colw < 384 ? QS_A : 1.f;
;             const f32x4 s0 = *(const f32x4*)(shw + (size_t)b * 7680 + col0), s1 = *(const f32x4*)(shw + (size_t)b * 7680 + col0 + 4);
; #pragma unroll
;             for (int ai = 0; ai < 2; ++ai)
; #pragma unroll
;                 for (int m = 0; m < 4; ++m) {
;                     const int row = row0 + ai * HALF + m * 16;
;                     const float rs = rsv[ai * 4 + m];
;                     f32x4 v0 = acc[ai][bj][m][0] * rs + s0, v1 = acc[ai][bj][m][1] * rs + s1;
.LBB0_425:
	s_lshl_b32 s2, s12, 8
	v_mbcnt_lo_u32_b32 v0, -1, 0
	v_mbcnt_hi_u32_b32 v0, -1, v0
	s_add_i32 s2, s2, s83
	v_and_b32_e32 v203, 15, v0
	v_or_b32_e32 v152, s2, v203
	v_ashrrev_i32_e32 v153, 31, v152
	v_lshl_add_u64 v[86:87], v[152:153], 3, s[28:29]
	flat_load_dwordx2 v[88:89], v[86:87]
	flat_load_dwordx2 v[170:171], v[86:87] offset:128
	flat_load_dwordx2 v[168:169], v[86:87] offset:256
	flat_load_dwordx2 v[166:167], v[86:87] offset:384
	flat_load_dwordx2 v[164:165], v[86:87] offset:1024
	flat_load_dwordx2 v[162:163], v[86:87] offset:1152
	flat_load_dwordx2 v[160:161], v[86:87] offset:1280
	flat_load_dwordx2 v[158:159], v[86:87] offset:1408
	v_bfe_u32 v202, v0, 4, 2
	s_lshl_b32 s35, s10, 8
	s_waitcnt vmcnt(0) lgkmcnt(0)
	v_ffbh_u32_e32 v0, v89
	v_min_u32_e32 v0, 32, v0
	v_lshlrev_b64 v[86:87], v0, v[88:89]
	v_min_u32_e32 v86, 1, v86
	v_or_b32_e32 v86, v87, v86
	v_cvt_f32_u32_e32 v86, v86
	v_sub_u32_e32 v0, 32, v0
	v_ldexp_f32 v0, v86, v0
	v_mul_f32_e32 v0, 0x33800000, v0
	v_fmamk_f32 v0, v0, 0x3a800000, v226
	v_cmp_gt_f32_e32 vcc, s71, v0
	v_mul_f32_e32 v86, 0x4f800000, v0
	s_nop 0
	v_cndmask_b32_e32 v0, v0, v86, vcc
	v_sqrt_f32_e32 v86, v0
	s_nop 0
	v_add_u32_e32 v87, -1, v86
	v_fma_f32 v88, -v87, v86, v0
	v_cmp_ge_f32_e64 s[8:9], 0, v88
	v_add_u32_e32 v88, 1, v86
	s_nop 0
	v_cndmask_b32_e64 v87, v86, v87, s[8:9]
	v_fma_f32 v86, -v88, v86, v0
	v_cmp_lt_f32_e64 s[8:9], 0, v86
	s_nop 1
	v_cndmask_b32_e64 v86, v87, v88, s[8:9]
	v_mul_f32_e32 v87, 0x37800000, v86
	v_cndmask_b32_e32 v86, v86, v87, vcc
	v_cmp_class_f32_e32 vcc, v0, v223
	s_nop 1
	v_cndmask_b32_e32 v0, v86, v0, vcc
	v_div_scale_f32 v86, s[2:3], v0, v0, 1.0
	v_rcp_f32_e32 v87, v86
	s_ashr_i32 s2, s12, 4
	s_mul_hi_i32 s3, s2, 0x7800
	s_mul_i32 s11, s2, 0x7800
	v_fma_f32 v88, -v86, v87, 1.0
	s_or_b32 s2, s35, s66
	v_fmac_f32_e32 v87, v88, v87
	v_div_scale_f32 v88, vcc, 1.0, v0, 1.0
	s_cmpk_lt_u32 s35, 0x600
	v_mul_f32_e32 v89, v88, v87
	s_cselect_b32 s37, 0, 3
	s_cmpk_gt_u32 s2, 0x29f
	v_fma_f32 v90, -v86, v89, v88
	s_cselect_b32 s4, s37, 2
	s_cmpk_gt_u32 s35, 0x27f
	v_fmac_f32_e32 v89, v90, v87
	s_cselect_b32 s8, s4, 0
	s_cmpk_gt_i32 s2, 0x1ff
	v_fma_f32 v86, -v86, v89, v88
	s_cselect_b64 s[16:17], -1, 0
	v_div_fmas_f32 v86, v86, v87, v89
	s_and_b64 s[4:5], s[16:17], exec
	v_div_fixup_f32 v154, v86, v0, 1.0
	v_lshlrev_b32_e32 v0, 3, v202
	s_cselect_b32 s4, s8, 1
	s_cmpk_lt_i32 s2, 0x180
	v_or_b32_e32 v156, s2, v0
	s_cselect_b64 s[8:9], -1, 0
	s_add_u32 s86, s96, s11
	s_addc_u32 s87, s97, s3
	v_ashrrev_i32_e32 v157, 31, v156
	v_lshl_add_u64 v[90:91], v[156:157], 2, s[86:87]
	flat_load_dwordx4 v[86:89], v[90:91]
	s_nop 0
	flat_load_dwordx4 v[90:93], v[90:91] offset:16
	s_add_i32 s3, s4, -1
	s_cmp_gt_u32 s3, 1
	s_cselect_b64 s[18:19], -1, 0
	s_cmp_eq_u32 s4, 3
	s_cselect_b64 s[10:11], -1, 0
	s_mov_b64 s[4:5], -1
	s_and_b64 vcc, exec, s[18:19]
	s_waitcnt vmcnt(0) lgkmcnt(0)
	v_pk_fma_f32 v[176:177], v[140:141], v[154:155], v[88:89] op_sel_hi:[1,0,1]
	v_pk_fma_f32 v[174:175], v[136:137], v[154:155], v[92:93] op_sel_hi:[1,0,1]
	v_cndmask_b32_e64 v136, 0, 1, s[10:11]
	v_pk_fma_f32 v[194:195], v[138:139], v[154:155], v[86:87] op_sel_hi:[1,0,1]
	v_pk_fma_f32 v[134:135], v[134:135], v[154:155], v[90:91] op_sel_hi:[1,0,1]
	v_cmp_ne_u32_e64 s[10:11], 1, v136
	s_cbranch_vccz .LBB0_429
	s_and_b64 vcc, exec, s[10:11]
	v_mov_b32_e32 v173, v177
	v_mov_b32_e32 v172, v176
	v_mov_b32_e32 v141, v195
	v_mov_b32_e32 v140, v194
	v_mov_b32_e32 v199, v175
	v_mov_b32_e32 v198, v174
	v_mov_b32_e32 v197, v135
	v_mov_b32_e32 v196, v134
	s_cbranch_vccnz .LBB0_428
; __device__ __forceinline__ f32x2 gelu_pk(f32x2 v) {
;     const f32x2 av = __builtin_elementwise_abs(v), d = av * 0.2316418882f + 1.0f;
;     f32x2 t; t.x = __builtin_amdgcn_rcpf(d.x); t.y = __builtin_amdgcn_rcpf(d.y);
;     f32x2 q = t * 0.5307027145f + (-0.7265760135f); q = q * t + 0.7107068705f; q = q * t + (-0.142248368f); q = q * t + 0.127414796f; q = q * t;
;     const f32x2 s = (v * v) * (-0.72134752044f);
;     f32x2 e; e.x = __builtin_amdgcn_exp2f(s.x); e.y = __builtin_amdgcn_exp2f(s.y);
;     const f32x2 m = v * (q * e), r = v - m;
;     f32x2 o; o.x = v.x < 0.f ? m.x : r.x; o.y = v.y < 0.f ? m.y : r.y; return o;
; }
	v_and_b32_e32 v137, 0x7fffffff, v195
	v_and_b32_e32 v136, 0x7fffffff, v194
	v_pk_fma_f32 v[136:137], v[136:137], s[62:63], 1.0 op_sel_hi:[1,0,0]
	s_mov_b32 s4, 0xbf3a00e3
	v_rcp_f32_e32 v136, v136
	v_rcp_f32_e32 v137, v137
	v_mov_b64_e32 v[138:139], s[4:5]
	v_cmp_gt_f32_e32 vcc, 0, v194
	v_pk_mul_f32 v[172:173], v[176:177], v[176:177]
	v_pk_fma_f32 v[140:141], v[136:137], s[64:65], v[138:139] op_sel_hi:[1,0,0]
	v_pk_mul_f32 v[172:173], v[172:173], s[74:75] op_sel_hi:[1,0]
	v_pk_fma_f32 v[140:141], v[136:137], v[140:141], s[68:69] op_sel_hi:[1,1,0]
	v_exp_f32_e32 v172, v172
	v_pk_fma_f32 v[140:141], v[136:137], v[140:141], s[70:71] op_sel_hi:[1,1,0]
	v_exp_f32_e32 v173, v173
	v_pk_fma_f32 v[140:141], v[136:137], v[140:141], s[72:73] op_sel_hi:[1,1,0]
	v_pk_mul_f32 v[180:181], v[134:135], v[134:135]
	v_pk_mul_f32 v[136:137], v[136:137], v[140:141]
	v_pk_mul_f32 v[140:141], v[194:195], v[194:195]
	v_pk_mul_f32 v[180:181], v[180:181], s[74:75] op_sel_hi:[1,0]
	v_pk_mul_f32 v[140:141], v[140:141], s[74:75] op_sel_hi:[1,0]
	v_exp_f32_e32 v180, v180
	v_exp_f32_e32 v140, v140
	v_exp_f32_e32 v141, v141
	v_exp_f32_e32 v181, v181
	v_pk_mul_f32 v[136:137], v[140:141], v[136:137]
	s_nop 0
	v_pk_mul_f32 v[140:141], v[194:195], v[136:137]
	v_pk_fma_f32 v[136:137], v[194:195], v[136:137], v[194:195] neg_lo:[1,0,0] neg_hi:[1,0,0]
	s_nop 0
	v_cndmask_b32_e32 v140, v136, v140, vcc
	v_cmp_gt_f32_e32 vcc, 0, v195
	v_and_b32_e32 v136, 0x7fffffff, v176
	s_nop 0
	v_cndmask_b32_e32 v141, v137, v141, vcc
	v_and_b32_e32 v137, 0x7fffffff, v177
	v_pk_fma_f32 v[136:137], v[136:137], s[62:63], 1.0 op_sel_hi:[1,0,0]
	v_cmp_gt_f32_e32 vcc, 0, v176
	v_rcp_f32_e32 v136, v136
	v_rcp_f32_e32 v137, v137
	s_nop 0
	v_pk_fma_f32 v[178:179], v[136:137], s[64:65], v[138:139] op_sel_hi:[1,0,0]
	s_nop 0
	v_pk_fma_f32 v[178:179], v[136:137], v[178:179], s[68:69] op_sel_hi:[1,1,0]
	s_nop 0
	v_pk_fma_f32 v[178:179], v[136:137], v[178:179], s[70:71] op_sel_hi:[1,1,0]
	s_nop 0
	v_pk_fma_f32 v[178:179], v[136:137], v[178:179], s[72:73] op_sel_hi:[1,1,0]
	s_nop 0
	v_pk_mul_f32 v[136:137], v[136:137], v[178:179]
	s_nop 0
	v_pk_mul_f32 v[136:137], v[172:173], v[136:137]
	s_nop 0
	v_pk_mul_f32 v[172:173], v[176:177], v[136:137]
	v_pk_fma_f32 v[136:137], v[176:177], v[136:137], v[176:177] neg_lo:[1,0,0] neg_hi:[1,0,0]
	s_nop 0
	v_cndmask_b32_e32 v172, v136, v172, vcc
	v_cmp_gt_f32_e32 vcc, 0, v177
	v_and_b32_e32 v136, 0x7fffffff, v134
	s_nop 0
	v_cndmask_b32_e32 v173, v137, v173, vcc
	v_and_b32_e32 v137, 0x7fffffff, v135
	v_pk_fma_f32 v[136:137], v[136:137], s[62:63], 1.0 op_sel_hi:[1,0,0]
	v_cmp_gt_f32_e32 vcc, 0, v134
	v_rcp_f32_e32 v136, v136
	v_rcp_f32_e32 v137, v137
	s_nop 0
	v_pk_fma_f32 v[178:179], v[136:137], s[64:65], v[138:139] op_sel_hi:[1,0,0]
	s_nop 0
	v_pk_fma_f32 v[178:179], v[136:137], v[178:179], s[68:69] op_sel_hi:[1,1,0]
	s_nop 0
	v_pk_fma_f32 v[178:179], v[136:137], v[178:179], s[70:71] op_sel_hi:[1,1,0]
	s_nop 0
	v_pk_fma_f32 v[178:179], v[136:137], v[178:179], s[72:73] op_sel_hi:[1,1,0]
	s_nop 0
	v_pk_mul_f32 v[136:137], v[136:137], v[178:179]
	v_pk_mul_f32 v[178:179], v[174:175], v[174:175]
	v_pk_mul_f32 v[136:137], v[180:181], v[136:137]
	s_nop 0
	v_pk_mul_f32 v[180:181], v[134:135], v[136:137]
	v_pk_fma_f32 v[136:137], v[134:135], v[136:137], v[134:135] neg_lo:[1,0,0] neg_hi:[1,0,0]
	s_nop 0
	v_cndmask_b32_e32 v196, v136, v180, vcc
	v_cmp_gt_f32_e32 vcc, 0, v135
	v_and_b32_e32 v136, 0x7fffffff, v174
	s_nop 0
	v_cndmask_b32_e32 v197, v137, v181, vcc
	v_and_b32_e32 v137, 0x7fffffff, v175
	v_pk_fma_f32 v[136:137], v[136:137], s[62:63], 1.0 op_sel_hi:[1,0,0]
	v_cmp_gt_f32_e32 vcc, 0, v174
	v_rcp_f32_e32 v136, v136
	v_rcp_f32_e32 v137, v137
	s_nop 0
	v_pk_fma_f32 v[138:139], v[136:137], s[64:65], v[138:139] op_sel_hi:[1,0,0]
	s_nop 0
	v_pk_fma_f32 v[138:139], v[136:137], v[138:139], s[68:69] op_sel_hi:[1,1,0]
	s_nop 0
	v_pk_fma_f32 v[138:139], v[136:137], v[138:139], s[70:71] op_sel_hi:[1,1,0]
	s_nop 0
	v_pk_fma_f32 v[138:139], v[136:137], v[138:139], s[72:73] op_sel_hi:[1,1,0]
	s_nop 0
	v_pk_mul_f32 v[136:137], v[136:137], v[138:139]
	v_pk_mul_f32 v[138:139], v[178:179], s[74:75] op_sel_hi:[1,0]
	s_nop 0
	v_exp_f32_e32 v138, v138
	v_exp_f32_e32 v139, v139
	s_nop 0
	v_pk_mul_f32 v[136:137], v[138:139], v[136:137]
	s_nop 0
	v_pk_mul_f32 v[138:139], v[174:175], v[136:137]
	v_pk_fma_f32 v[136:137], v[174:175], v[136:137], v[174:175] neg_lo:[1,0,0] neg_hi:[1,0,0]
	s_nop 0
	v_cndmask_b32_e32 v198, v136, v138, vcc
	v_cmp_gt_f32_e32 vcc, 0, v175
	s_nop 1
	v_cndmask_b32_e32 v199, v137, v139, vcc

; __device__ __forceinline__ unsigned cvt_pk_bf16(float lo, float hi) { unsigned r; asm volatile("v_cvt_pk_bf16_f32 %0, %1, %2" : "=v"(r) : "v"(lo), "v"(hi)); return r; }
; #define PG8_GPTR(p) ((__attribute__((address_space(1))) char*)(p))
;     __device__ __forceinline__ void operator()(const f32x4 (&acc)[2][2][4][2], const Unit& u, int wr, int wc, int fr, int fq) const {
;     ...
;                 for (int m = 0; m < 4; ++m) {
;                     const int row = row0 + ai * HALF + m * 16;
;                     const float rs = rsv[ai * 4 + m];
;                     f32x4 v0 = acc[ai][bj][m][0] * rs + s0, v1 = acc[ai][bj][m][1] * rs + s1;
;                     if (mode == 1 || mode == 2) {
;                         const float* tp = (mode == 1) ? (ropA + ((size_t)row * 32 + ((col0 & 63) >> 1)) * 2) : (ropB + ((size_t)row * 16 + ((col0 - PC_KR) >> 1)) * 2);
;                         const f32x4 c0 = *(const f32x4*)tp, c1 = *(const f32x4*)(tp + 4);
;                         f32x4 w0, w1;
;                         w0[0] = v0[0] * c0[0] - v0[1] * c0[1]; w0[1] = v0[1] * c0[0] + v0[0] * c0[1];
;                         w0[2] = v0[2] * c0[2] - v0[3] * c0[3]; w0[3] = v0[3] * c0[2] + v0[2] * c0[3];
;                         w1[0] = v1[0] * c1[0] - v1[1] * c1[1]; w1[1] = v1[1] * c1[0] + v1[0] * c1[1];
;                         w1[2] = v1[2] * c1[2] - v1[3] * c1[3]; w1[3] = v1[3] * c1[2] + v1[2] * c1[3];
;                         v0 = w0 * sc; v1 = w1 * sc;
;                     } else if (mode == 3) {
;                         const f32x2 a = gelu_pk((f32x2){v0[0], v0[1]}), bb = gelu_pk((f32x2){v0[2], v0[3]}), c = gelu_pk((f32x2){v1[0], v1[1]}), d = gelu_pk((f32x2){v1[2], v1[3]});
;                         v0 = (f32x4){a.x, a.y, bb.x, bb.y}; v1 = (f32x4){c.x, c.y, d.x, d.y};
;                     }
;                     if (stat) {
;                         const float q = (v0[0] * v0[0] + v0[1] * v0[1]) + (v0[2] * v0[2] + v0[3] * v0[3]) + (v1[0] * v1[0] + v1[1] * v1[1]) + (v1[2] * v1[2] + v1[3] * v1[3]);
;                         ssq_put(stat == 1 ? ssq_cq : ssq_ckv, row, q, fr, fq);
;                     }
;                     u32x4 w; w.x = cvt_pk_bf16(v0[0], v0[1]); w.y = cvt_pk_bf16(v0[2], v0[3]); w.z = cvt_pk_bf16(v1[0], v1[1]); w.w = cvt_pk_bf16(v1[2], v1[3]);
;                     *(gs_u32x4*)(PG8_GPTR(O) + (unsigned)(row * PJP + col0) * 2u) = w;
.LBB0_439:
	v_ffbh_u32_e32 v134, v171
	v_min_u32_e32 v174, 32, v134
	s_waitcnt lgkmcnt(0)
	v_lshlrev_b64 v[134:135], v174, v[170:171]
	v_min_u32_e32 v134, 1, v134
	v_or_b32_e32 v134, v135, v134
	v_cvt_f32_u32_e32 v134, v134
	v_sub_u32_e32 v135, 32, v174
	v_ldexp_f32 v134, v134, v135
	v_mul_f32_e32 v134, 0x33800000, v134
	v_fmamk_f32 v134, v134, 0x3a800000, v226
	v_mul_f32_e32 v135, 0x4f800000, v134
	v_cmp_gt_f32_e32 vcc, s71, v134
	s_nop 1
	v_cndmask_b32_e32 v134, v134, v135, vcc
	v_sqrt_f32_e32 v135, v134
	s_nop 0
	v_add_u32_e32 v170, -1, v135
	v_add_u32_e32 v171, 1, v135
	v_fma_f32 v174, -v170, v135, v134
	v_fma_f32 v175, -v171, v135, v134
	v_cmp_ge_f32_e64 s[12:13], 0, v174
	s_nop 1
	v_cndmask_b32_e64 v135, v135, v170, s[12:13]
	v_cmp_lt_f32_e64 s[12:13], 0, v175
	s_nop 1
	v_cndmask_b32_e64 v135, v135, v171, s[12:13]
	v_mul_f32_e32 v170, 0x37800000, v135
	v_cndmask_b32_e32 v135, v135, v170, vcc
	v_cmp_class_f32_e32 vcc, v134, v223
	s_nop 1
	v_cndmask_b32_e32 v134, v135, v134, vcc
	v_div_scale_f32 v135, s[2:3], v134, v134, 1.0
	v_rcp_f32_e32 v170, v135
	s_movk_i32 s2, 0x840
	v_mul_lo_u32 v195, v152, s2
	s_mov_b64 s[2:3], -1
	v_fma_f32 v171, -v135, v170, 1.0
	v_fmac_f32_e32 v170, v171, v170
	v_div_scale_f32 v171, vcc, 1.0, v134, 1.0
	v_mul_f32_e32 v174, v171, v170
	v_fma_f32 v175, -v135, v174, v171
	v_fmac_f32_e32 v174, v175, v170
	v_fma_f32 v135, -v135, v174, v171
	v_div_fmas_f32 v135, v135, v170, v174
	v_div_fixup_f32 v134, v135, v134, 1.0
	v_cvt_pk_bf16_f32 v170, v140, v141
	v_cvt_pk_bf16_f32 v171, v172, v173
	v_cvt_pk_bf16_f32 v172, v196, v197
	v_cvt_pk_bf16_f32 v173, v198, v199
	v_add_lshl_u32 v135, v156, v195, 1
	global_store_dwordx4 v135, v[170:173], s[22:23]
	v_pk_fma_f32 v[140:141], v[132:133], v[134:135], v[88:89] op_sel_hi:[1,0,1]
	v_pk_fma_f32 v[128:129], v[128:129], v[134:135], v[92:93] op_sel_hi:[1,0,1]
	v_pk_fma_f32 v[172:173], v[126:127], v[134:135], v[90:91] op_sel_hi:[1,0,1]
	v_cndmask_b32_e64 v126, 0, 1, s[18:19]
	v_pk_fma_f32 v[170:171], v[130:131], v[134:135], v[86:87] op_sel_hi:[1,0,1]
	v_cmp_ne_u32_e64 s[14:15], 1, v126
	s_andn2_b64 vcc, exec, s[18:19]
	s_cbranch_vccnz .LBB0_443
	s_and_b64 vcc, exec, s[10:11]
	v_mov_b32_e32 v133, v141
	v_mov_b32_e32 v132, v140
	v_mov_b32_e32 v131, v171
	v_mov_b32_e32 v130, v170
	v_mov_b32_e32 v177, v129
	v_mov_b32_e32 v176, v128
	v_mov_b32_e32 v175, v173
	v_mov_b32_e32 v174, v172
	s_cbranch_vccnz .LBB0_442
	v_and_b32_e32 v127, 0x7fffffff, v171
	v_and_b32_e32 v126, 0x7fffffff, v170
	v_pk_fma_f32 v[126:127], v[126:127], s[62:63], 1.0 op_sel_hi:[1,0,0]
	s_mov_b32 s2, 0xbf3a00e3
	v_rcp_f32_e32 v126, v126
	v_rcp_f32_e32 v127, v127
	v_mov_b64_e32 v[176:177], s[2:3]
	v_cmp_gt_f32_e32 vcc, 0, v170
	v_pk_mul_f32 v[132:133], v[140:141], v[140:141]
	v_pk_fma_f32 v[130:131], v[126:127], s[64:65], v[176:177] op_sel_hi:[1,0,0]
	v_pk_mul_f32 v[132:133], v[132:133], s[74:75] op_sel_hi:[1,0]
	v_pk_fma_f32 v[130:131], v[126:127], v[130:131], s[68:69] op_sel_hi:[1,1,0]
	v_exp_f32_e32 v132, v132
	v_pk_fma_f32 v[130:131], v[126:127], v[130:131], s[70:71] op_sel_hi:[1,1,0]
	v_exp_f32_e32 v133, v133
	v_pk_fma_f32 v[130:131], v[126:127], v[130:131], s[72:73] op_sel_hi:[1,1,0]
	v_pk_mul_f32 v[178:179], v[128:129], v[128:129]
	v_pk_mul_f32 v[126:127], v[126:127], v[130:131]
	v_pk_mul_f32 v[130:131], v[170:171], v[170:171]
	s_nop 0
	v_pk_mul_f32 v[130:131], v[130:131], s[74:75] op_sel_hi:[1,0]
	s_nop 0
	v_exp_f32_e32 v130, v130
	v_exp_f32_e32 v131, v131
	s_nop 0
	v_pk_mul_f32 v[126:127], v[130:131], v[126:127]
	s_nop 0
	v_pk_mul_f32 v[130:131], v[170:171], v[126:127]
	v_pk_fma_f32 v[126:127], v[170:171], v[126:127], v[170:171] neg_lo:[1,0,0] neg_hi:[1,0,0]
	s_nop 0
	v_cndmask_b32_e32 v130, v126, v130, vcc
	v_cmp_gt_f32_e32 vcc, 0, v171
	v_and_b32_e32 v126, 0x7fffffff, v140
	s_nop 0
	v_cndmask_b32_e32 v131, v127, v131, vcc
	v_and_b32_e32 v127, 0x7fffffff, v141
	v_pk_fma_f32 v[126:127], v[126:127], s[62:63], 1.0 op_sel_hi:[1,0,0]
	v_cmp_gt_f32_e32 vcc, 0, v140
	v_rcp_f32_e32 v126, v126
	v_rcp_f32_e32 v127, v127
	s_nop 0
	v_pk_fma_f32 v[174:175], v[126:127], s[64:65], v[176:177] op_sel_hi:[1,0,0]
	s_nop 0
	v_pk_fma_f32 v[174:175], v[126:127], v[174:175], s[68:69] op_sel_hi:[1,1,0]
	s_nop 0
	v_pk_fma_f32 v[174:175], v[126:127], v[174:175], s[70:71] op_sel_hi:[1,1,0]
	s_nop 0
	v_pk_fma_f32 v[174:175], v[126:127], v[174:175], s[72:73] op_sel_hi:[1,1,0]
	s_nop 0
	v_pk_mul_f32 v[126:127], v[126:127], v[174:175]
	s_nop 0
	v_pk_mul_f32 v[126:127], v[132:133], v[126:127]
	s_nop 0
	v_pk_mul_f32 v[132:133], v[140:141], v[126:127]
	v_pk_fma_f32 v[126:127], v[140:141], v[126:127], v[140:141] neg_lo:[1,0,0] neg_hi:[1,0,0]
	s_nop 0
	v_cndmask_b32_e32 v132, v126, v132, vcc
	v_cmp_gt_f32_e32 vcc, 0, v141
	v_and_b32_e32 v126, 0x7fffffff, v172
	s_nop 0
	v_cndmask_b32_e32 v133, v127, v133, vcc
	v_and_b32_e32 v127, 0x7fffffff, v173
	v_pk_fma_f32 v[126:127], v[126:127], s[62:63], 1.0 op_sel_hi:[1,0,0]
	v_cmp_gt_f32_e32 vcc, 0, v172
	v_rcp_f32_e32 v126, v126
	v_rcp_f32_e32 v127, v127
	s_nop 0
	v_pk_fma_f32 v[174:175], v[126:127], s[64:65], v[176:177] op_sel_hi:[1,0,0]
	s_nop 0
	v_pk_fma_f32 v[174:175], v[126:127], v[174:175], s[68:69] op_sel_hi:[1,1,0]
	s_nop 0
	v_pk_fma_f32 v[174:175], v[126:127], v[174:175], s[70:71] op_sel_hi:[1,1,0]
	s_nop 0
	v_pk_fma_f32 v[174:175], v[126:127], v[174:175], s[72:73] op_sel_hi:[1,1,0]
	s_nop 0
	v_pk_mul_f32 v[126:127], v[126:127], v[174:175]
	v_pk_mul_f32 v[174:175], v[172:173], v[172:173]
	s_nop 0
	v_pk_mul_f32 v[174:175], v[174:175], s[74:75] op_sel_hi:[1,0]
	s_nop 0
	v_exp_f32_e32 v174, v174
	v_exp_f32_e32 v175, v175
	s_nop 0
	v_pk_mul_f32 v[126:127], v[174:175], v[126:127]
	s_nop 0
	v_pk_mul_f32 v[174:175], v[172:173], v[126:127]
	v_pk_fma_f32 v[126:127], v[172:173], v[126:127], v[172:173] neg_lo:[1,0,0] neg_hi:[1,0,0]
	s_nop 0
	v_cndmask_b32_e32 v174, v126, v174, vcc
	v_cmp_gt_f32_e32 vcc, 0, v173
	v_and_b32_e32 v126, 0x7fffffff, v128
	s_nop 0
	v_cndmask_b32_e32 v175, v127, v175, vcc
	v_and_b32_e32 v127, 0x7fffffff, v129
	v_pk_fma_f32 v[126:127], v[126:127], s[62:63], 1.0 op_sel_hi:[1,0,0]
	v_cmp_gt_f32_e32 vcc, 0, v128
	v_rcp_f32_e32 v126, v126
	v_rcp_f32_e32 v127, v127
	s_nop 0
	v_pk_fma_f32 v[176:177], v[126:127], s[64:65], v[176:177] op_sel_hi:[1,0,0]
	s_nop 0
	v_pk_fma_f32 v[176:177], v[126:127], v[176:177], s[68:69] op_sel_hi:[1,1,0]
	s_nop 0
	v_pk_fma_f32 v[176:177], v[126:127], v[176:177], s[70:71] op_sel_hi:[1,1,0]
	s_nop 0
	v_pk_fma_f32 v[176:177], v[126:127], v[176:177], s[72:73] op_sel_hi:[1,1,0]
	s_nop 0
	v_pk_mul_f32 v[126:127], v[126:127], v[176:177]
	v_pk_mul_f32 v[176:177], v[178:179], s[74:75] op_sel_hi:[1,0]
	s_nop 0
	v_exp_f32_e32 v176, v176
	v_exp_f32_e32 v177, v177
	s_nop 0
	v_pk_mul_f32 v[126:127], v[176:177], v[126:127]
	s_nop 0
	v_pk_mul_f32 v[176:177], v[128:129], v[126:127]
	v_pk_fma_f32 v[126:127], v[128:129], v[126:127], v[128:129] neg_lo:[1,0,0] neg_hi:[1,0,0]
	s_nop 0
	v_cndmask_b32_e32 v176, v126, v176, vcc
	v_cmp_gt_f32_e32 vcc, 0, v129
	s_nop 1
	v_cndmask_b32_e32 v177, v127, v177, vcc

; __device__ __forceinline__ unsigned cvt_pk_bf16(float lo, float hi) { unsigned r; asm volatile("v_cvt_pk_bf16_f32 %0, %1, %2" : "=v"(r) : "v"(lo), "v"(hi)); return r; }
; #define PG8_GPTR(p) ((__attribute__((address_space(1))) char*)(p))
;     __device__ __forceinline__ void operator()(const f32x4 (&acc)[2][2][4][2], const Unit& u, int wr, int wc, int fr, int fq) const {
;     ...
;                 for (int m = 0; m < 4; ++m) {
;                     const int row = row0 + ai * HALF + m * 16;
;                     const float rs = rsv[ai * 4 + m];
;                     f32x4 v0 = acc[ai][bj][m][0] * rs + s0, v1 = acc[ai][bj][m][1] * rs + s1;
;                     if (mode == 1 || mode == 2) {
;                         const float* tp = (mode == 1) ? (ropA + ((size_t)row * 32 + ((col0 & 63) >> 1)) * 2) : (ropB + ((size_t)row * 16 + ((col0 - PC_KR) >> 1)) * 2);
;                         const f32x4 c0 = *(const f32x4*)tp, c1 = *(const f32x4*)(tp + 4);
;                         f32x4 w0, w1;
;                         w0[0] = v0[0] * c0[0] - v0[1] * c0[1]; w0[1] = v0[1] * c0[0] + v0[0] * c0[1];
;                         w0[2] = v0[2] * c0[2] - v0[3] * c0[3]; w0[3] = v0[3] * c0[2] + v0[2] * c0[3];
;                         w1[0] = v1[0] * c1[0] - v1[1] * c1[1]; w1[1] = v1[1] * c1[0] + v1[0] * c1[1];
;                         w1[2] = v1[2] * c1[2] - v1[3] * c1[3]; w1[3] = v1[3] * c1[2] + v1[2] * c1[3];
;                         v0 = w0 * sc; v1 = w1 * sc;
;                     } else if (mode == 3) {
;                         const f32x2 a = gelu_pk((f32x2){v0[0], v0[1]}), bb = gelu_pk((f32x2){v0[2], v0[3]}), c = gelu_pk((f32x2){v1[0], v1[1]}), d = gelu_pk((f32x2){v1[2], v1[3]});
;                         v0 = (f32x4){a.x, a.y, bb.x, bb.y}; v1 = (f32x4){c.x, c.y, d.x, d.y};
;                     }
;                     if (stat) {
;                         const float q = (v0[0] * v0[0] + v0[1] * v0[1]) + (v0[2] * v0[2] + v0[3] * v0[3]) + (v1[0] * v1[0] + v1[1] * v1[1]) + (v1[2] * v1[2] + v1[3] * v1[3]);
;                         ssq_put(stat == 1 ? ssq_cq : ssq_ckv, row, q, fr, fq);
;                     }
;                     u32x4 w; w.x = cvt_pk_bf16(v0[0], v0[1]); w.y = cvt_pk_bf16(v0[2], v0[3]); w.z = cvt_pk_bf16(v1[0], v1[1]); w.w = cvt_pk_bf16(v1[2], v1[3]);
;                     *(gs_u32x4*)(PG8_GPTR(O) + (unsigned)(row * PJP + col0) * 2u) = w;
.LBB0_453:
	v_ffbh_u32_e32 v128, v169
	v_min_u32_e32 v140, 32, v128
	s_waitcnt lgkmcnt(0)
	v_lshlrev_b64 v[128:129], v140, v[168:169]
	v_min_u32_e32 v128, 1, v128
	v_or_b32_e32 v128, v129, v128
	v_cvt_f32_u32_e32 v128, v128
	v_sub_u32_e32 v129, 32, v140
	v_add_u32_e32 v172, 0x8400, v195
	v_cvt_pk_bf16_f32 v130, v130, v131
	v_ldexp_f32 v128, v128, v129
	v_mul_f32_e32 v128, 0x33800000, v128
	v_fmamk_f32 v128, v128, 0x3a800000, v226
	v_mul_f32_e32 v129, 0x4f800000, v128
	v_cmp_gt_f32_e32 vcc, s71, v128
	v_cvt_pk_bf16_f32 v131, v132, v133
	v_cvt_pk_bf16_f32 v132, v174, v175
	v_cvt_pk_bf16_f32 v133, v176, v177
	s_nop 1
	v_cndmask_b32_e32 v128, v128, v129, vcc
	v_sqrt_f32_e32 v129, v128
	s_nop 0
	v_add_u32_e32 v140, -1, v129
	v_add_u32_e32 v141, 1, v129
	v_fma_f32 v168, -v140, v129, v128
	v_fma_f32 v169, -v141, v129, v128
	v_cmp_ge_f32_e64 s[18:19], 0, v168
	s_nop 1
	v_cndmask_b32_e64 v129, v129, v140, s[18:19]
	v_cmp_lt_f32_e64 s[18:19], 0, v169
	s_nop 1
	v_cndmask_b32_e64 v129, v129, v141, s[18:19]
	v_mul_f32_e32 v140, 0x37800000, v129
	v_cndmask_b32_e32 v129, v129, v140, vcc
	v_cmp_class_f32_e32 vcc, v128, v223
	s_nop 1
	v_cndmask_b32_e32 v128, v129, v128, vcc
	v_div_scale_f32 v129, s[2:3], v128, v128, 1.0
	v_rcp_f32_e32 v140, v129
	s_mov_b64 s[2:3], -1
	v_fma_f32 v141, -v129, v140, 1.0
	v_fmac_f32_e32 v140, v141, v140
	v_div_scale_f32 v141, vcc, 1.0, v128, 1.0
	v_mul_f32_e32 v168, v141, v140
	v_fma_f32 v169, -v129, v168, v141
	v_fmac_f32_e32 v168, v169, v140
	v_fma_f32 v129, -v129, v168, v141
	v_div_fmas_f32 v129, v129, v140, v168
	v_div_fixup_f32 v128, v129, v128, 1.0
	v_add_lshl_u32 v129, v172, v156, 1
	global_store_dwordx4 v129, v[130:133], s[22:23]
	v_pk_fma_f32 v[120:121], v[120:121], v[128:129], v[92:93] op_sel_hi:[1,0,1]
	v_pk_fma_f32 v[140:141], v[118:119], v[128:129], v[90:91] op_sel_hi:[1,0,1]
	v_pk_fma_f32 v[130:131], v[124:125], v[128:129], v[88:89] op_sel_hi:[1,0,1]
	v_pk_fma_f32 v[132:133], v[122:123], v[128:129], v[86:87] op_sel_hi:[1,0,1]
	s_and_b64 vcc, exec, s[14:15]
	s_cbranch_vccnz .LBB0_458
	s_and_b64 vcc, exec, s[10:11]
	v_mov_b32_e32 v125, v131
	v_mov_b32_e32 v124, v130
	v_mov_b32_e32 v123, v133
	v_mov_b32_e32 v122, v132
	v_mov_b32_e32 v171, v121
	v_mov_b32_e32 v170, v120
	v_mov_b32_e32 v169, v141
	v_mov_b32_e32 v168, v140
	s_cbranch_vccnz .LBB0_456
	v_and_b32_e32 v119, 0x7fffffff, v133
	v_and_b32_e32 v118, 0x7fffffff, v132
	v_pk_fma_f32 v[118:119], v[118:119], s[62:63], 1.0 op_sel_hi:[1,0,0]
	s_mov_b32 s2, 0xbf3a00e3
	v_rcp_f32_e32 v118, v118
	v_rcp_f32_e32 v119, v119
	v_mov_b64_e32 v[170:171], s[2:3]
	v_cmp_gt_f32_e32 vcc, 0, v132
	v_pk_mul_f32 v[124:125], v[130:131], v[130:131]
	v_pk_fma_f32 v[122:123], v[118:119], s[64:65], v[170:171] op_sel_hi:[1,0,0]
	v_pk_mul_f32 v[124:125], v[124:125], s[74:75] op_sel_hi:[1,0]
	v_pk_fma_f32 v[122:123], v[118:119], v[122:123], s[68:69] op_sel_hi:[1,1,0]
	v_exp_f32_e32 v124, v124
	v_pk_fma_f32 v[122:123], v[118:119], v[122:123], s[70:71] op_sel_hi:[1,1,0]
	v_exp_f32_e32 v125, v125
	v_pk_fma_f32 v[122:123], v[118:119], v[122:123], s[72:73] op_sel_hi:[1,1,0]
	v_pk_mul_f32 v[174:175], v[120:121], v[120:121]
	v_pk_mul_f32 v[118:119], v[118:119], v[122:123]
	v_pk_mul_f32 v[122:123], v[132:133], v[132:133]
	s_nop 0
	v_pk_mul_f32 v[122:123], v[122:123], s[74:75] op_sel_hi:[1,0]
	s_nop 0
	v_exp_f32_e32 v122, v122
	v_exp_f32_e32 v123, v123
	s_nop 0
	v_pk_mul_f32 v[118:119], v[122:123], v[118:119]
	s_nop 0
	v_pk_mul_f32 v[122:123], v[132:133], v[118:119]
	v_pk_fma_f32 v[118:119], v[132:133], v[118:119], v[132:133] neg_lo:[1,0,0] neg_hi:[1,0,0]
	s_nop 0
	v_cndmask_b32_e32 v122, v118, v122, vcc
	v_cmp_gt_f32_e32 vcc, 0, v133
	v_and_b32_e32 v118, 0x7fffffff, v130
	s_nop 0
	v_cndmask_b32_e32 v123, v119, v123, vcc
	v_and_b32_e32 v119, 0x7fffffff, v131
	v_pk_fma_f32 v[118:119], v[118:119], s[62:63], 1.0 op_sel_hi:[1,0,0]
	v_cmp_gt_f32_e32 vcc, 0, v130
	v_rcp_f32_e32 v118, v118
	v_rcp_f32_e32 v119, v119
	s_nop 0
	v_pk_fma_f32 v[168:169], v[118:119], s[64:65], v[170:171] op_sel_hi:[1,0,0]
	s_nop 0
	v_pk_fma_f32 v[168:169], v[118:119], v[168:169], s[68:69] op_sel_hi:[1,1,0]
	s_nop 0
	v_pk_fma_f32 v[168:169], v[118:119], v[168:169], s[70:71] op_sel_hi:[1,1,0]
	s_nop 0
	v_pk_fma_f32 v[168:169], v[118:119], v[168:169], s[72:73] op_sel_hi:[1,1,0]
	s_nop 0
	v_pk_mul_f32 v[118:119], v[118:119], v[168:169]
	s_nop 0
	v_pk_mul_f32 v[118:119], v[124:125], v[118:119]
	s_nop 0
	v_pk_mul_f32 v[124:125], v[130:131], v[118:119]
	v_pk_fma_f32 v[118:119], v[130:131], v[118:119], v[130:131] neg_lo:[1,0,0] neg_hi:[1,0,0]
	s_nop 0
	v_cndmask_b32_e32 v124, v118, v124, vcc
	v_cmp_gt_f32_e32 vcc, 0, v131
	v_and_b32_e32 v118, 0x7fffffff, v140
	s_nop 0
	v_cndmask_b32_e32 v125, v119, v125, vcc
	v_and_b32_e32 v119, 0x7fffffff, v141
	v_pk_fma_f32 v[118:119], v[118:119], s[62:63], 1.0 op_sel_hi:[1,0,0]
	v_cmp_gt_f32_e32 vcc, 0, v140
	v_rcp_f32_e32 v118, v118
	v_rcp_f32_e32 v119, v119
	s_nop 0
	v_pk_fma_f32 v[168:169], v[118:119], s[64:65], v[170:171] op_sel_hi:[1,0,0]
	s_nop 0
	v_pk_fma_f32 v[168:169], v[118:119], v[168:169], s[68:69] op_sel_hi:[1,1,0]
	s_nop 0
	v_pk_fma_f32 v[168:169], v[118:119], v[168:169], s[70:71] op_sel_hi:[1,1,0]
	s_nop 0
	v_pk_fma_f32 v[168:169], v[118:119], v[168:169], s[72:73] op_sel_hi:[1,1,0]
	s_nop 0
	v_pk_mul_f32 v[118:119], v[118:119], v[168:169]
	v_pk_mul_f32 v[168:169], v[140:141], v[140:141]
	s_nop 0
	v_pk_mul_f32 v[168:169], v[168:169], s[74:75] op_sel_hi:[1,0]
	s_nop 0
	v_exp_f32_e32 v168, v168
	v_exp_f32_e32 v169, v169
	s_nop 0
	v_pk_mul_f32 v[118:119], v[168:169], v[118:119]
	s_nop 0
	v_pk_mul_f32 v[168:169], v[140:141], v[118:119]
	v_pk_fma_f32 v[118:119], v[140:141], v[118:119], v[140:141] neg_lo:[1,0,0] neg_hi:[1,0,0]
	s_nop 0
	v_cndmask_b32_e32 v168, v118, v168, vcc
	v_cmp_gt_f32_e32 vcc, 0, v141
	v_and_b32_e32 v118, 0x7fffffff, v120
	s_nop 0
	v_cndmask_b32_e32 v169, v119, v169, vcc
	v_and_b32_e32 v119, 0x7fffffff, v121
	v_pk_fma_f32 v[118:119], v[118:119], s[62:63], 1.0 op_sel_hi:[1,0,0]
	v_cmp_gt_f32_e32 vcc, 0, v120
	v_rcp_f32_e32 v118, v118
	v_rcp_f32_e32 v119, v119
	s_nop 0
	v_pk_fma_f32 v[170:171], v[118:119], s[64:65], v[170:171] op_sel_hi:[1,0,0]
	s_nop 0
	v_pk_fma_f32 v[170:171], v[118:119], v[170:171], s[68:69] op_sel_hi:[1,1,0]
	s_nop 0
	v_pk_fma_f32 v[170:171], v[118:119], v[170:171], s[70:71] op_sel_hi:[1,1,0]
	s_nop 0
	v_pk_fma_f32 v[170:171], v[118:119], v[170:171], s[72:73] op_sel_hi:[1,1,0]
	s_nop 0
	v_pk_mul_f32 v[118:119], v[118:119], v[170:171]
	v_pk_mul_f32 v[170:171], v[174:175], s[74:75] op_sel_hi:[1,0]
	s_nop 0
	v_exp_f32_e32 v170, v170
	v_exp_f32_e32 v171, v171
	s_nop 0
	v_pk_mul_f32 v[118:119], v[170:171], v[118:119]
	s_nop 0
	v_pk_mul_f32 v[170:171], v[120:121], v[118:119]
	v_pk_fma_f32 v[118:119], v[120:121], v[118:119], v[120:121] neg_lo:[1,0,0] neg_hi:[1,0,0]
	s_nop 0
	v_cndmask_b32_e32 v170, v118, v170, vcc
	v_cmp_gt_f32_e32 vcc, 0, v121
	s_nop 1
	v_cndmask_b32_e32 v171, v119, v171, vcc

; __device__ __forceinline__ unsigned cvt_pk_bf16(float lo, float hi) { unsigned r; asm volatile("v_cvt_pk_bf16_f32 %0, %1, %2" : "=v"(r) : "v"(lo), "v"(hi)); return r; }
; #define PG8_GPTR(p) ((__attribute__((address_space(1))) char*)(p))
;     __device__ __forceinline__ void operator()(const f32x4 (&acc)[2][2][4][2], const Unit& u, int wr, int wc, int fr, int fq) const {
;     ...
;                 for (int m = 0; m < 4; ++m) {
;                     const int row = row0 + ai * HALF + m * 16;
;                     const float rs = rsv[ai * 4 + m];
;                     f32x4 v0 = acc[ai][bj][m][0] * rs + s0, v1 = acc[ai][bj][m][1] * rs + s1;
;                     if (mode == 1 || mode == 2) {
;                         const float* tp = (mode == 1) ? (ropA + ((size_t)row * 32 + ((col0 & 63) >> 1)) * 2) : (ropB + ((size_t)row * 16 + ((col0 - PC_KR) >> 1)) * 2);
;                         const f32x4 c0 = *(const f32x4*)tp, c1 = *(const f32x4*)(tp + 4);
;                         f32x4 w0, w1;
;                         w0[0] = v0[0] * c0[0] - v0[1] * c0[1]; w0[1] = v0[1] * c0[0] + v0[0] * c0[1];
;                         w0[2] = v0[2] * c0[2] - v0[3] * c0[3]; w0[3] = v0[3] * c0[2] + v0[2] * c0[3];
;                         w1[0] = v1[0] * c1[0] - v1[1] * c1[1]; w1[1] = v1[1] * c1[0] + v1[0] * c1[1];
;                         w1[2] = v1[2] * c1[2] - v1[3] * c1[3]; w1[3] = v1[3] * c1[2] + v1[2] * c1[3];
;                         v0 = w0 * sc; v1 = w1 * sc;
;                     } else if (mode == 3) {
;                         const f32x2 a = gelu_pk((f32x2){v0[0], v0[1]}), bb = gelu_pk((f32x2){v0[2], v0[3]}), c = gelu_pk((f32x2){v1[0], v1[1]}), d = gelu_pk((f32x2){v1[2], v1[3]});
;                         v0 = (f32x4){a.x, a.y, bb.x, bb.y}; v1 = (f32x4){c.x, c.y, d.x, d.y};
;                     }
;                     if (stat) {
;                         const float q = (v0[0] * v0[0] + v0[1] * v0[1]) + (v0[2] * v0[2] + v0[3] * v0[3]) + (v1[0] * v1[0] + v1[1] * v1[1]) + (v1[2] * v1[2] + v1[3] * v1[3]);
;                         ssq_put(stat == 1 ? ssq_cq : ssq_ckv, row, q, fr, fq);
;                     }
;                     u32x4 w; w.x = cvt_pk_bf16(v0[0], v0[1]); w.y = cvt_pk_bf16(v0[2], v0[3]); w.z = cvt_pk_bf16(v1[0], v1[1]); w.w = cvt_pk_bf16(v1[2], v1[3]);
;                     *(gs_u32x4*)(PG8_GPTR(O) + (unsigned)(row * PJP + col0) * 2u) = w;
.LBB0_467:
	v_ffbh_u32_e32 v120, v167
	v_min_u32_e32 v130, 32, v120
	s_waitcnt lgkmcnt(0)
	v_lshlrev_b64 v[120:121], v130, v[166:167]
	v_min_u32_e32 v120, 1, v120
	v_or_b32_e32 v120, v121, v120
	v_cvt_f32_u32_e32 v120, v120
	v_sub_u32_e32 v121, 32, v130
	v_add_u32_e32 v166, 0x8400, v172
	v_cvt_pk_bf16_f32 v122, v122, v123
	v_ldexp_f32 v120, v120, v121
	v_mul_f32_e32 v120, 0x33800000, v120
	v_fmamk_f32 v120, v120, 0x3a800000, v226
	v_mul_f32_e32 v121, 0x4f800000, v120
	v_cmp_gt_f32_e32 vcc, s71, v120
	v_cvt_pk_bf16_f32 v123, v124, v125
	v_cvt_pk_bf16_f32 v124, v168, v169
	v_cvt_pk_bf16_f32 v125, v170, v171
	s_nop 1
	v_cndmask_b32_e32 v120, v120, v121, vcc
	v_sqrt_f32_e32 v121, v120
	s_nop 0
	v_add_u32_e32 v130, -1, v121
	v_add_u32_e32 v131, 1, v121
	v_fma_f32 v132, -v130, v121, v120
	v_fma_f32 v133, -v131, v121, v120
	v_cmp_ge_f32_e64 s[18:19], 0, v132
	s_nop 1
	v_cndmask_b32_e64 v121, v121, v130, s[18:19]
	v_cmp_lt_f32_e64 s[18:19], 0, v133
	s_nop 1
	v_cndmask_b32_e64 v121, v121, v131, s[18:19]
	v_mul_f32_e32 v130, 0x37800000, v121
	v_cndmask_b32_e32 v121, v121, v130, vcc
	v_cmp_class_f32_e32 vcc, v120, v223
	s_nop 1
	v_cndmask_b32_e32 v120, v121, v120, vcc
	v_div_scale_f32 v121, s[2:3], v120, v120, 1.0
	v_rcp_f32_e32 v130, v121
	s_mov_b64 s[2:3], -1
	v_fma_f32 v131, -v121, v130, 1.0
	v_fmac_f32_e32 v130, v131, v130
	v_div_scale_f32 v131, vcc, 1.0, v120, 1.0
	v_mul_f32_e32 v132, v131, v130
	v_fma_f32 v133, -v121, v132, v131
	v_fmac_f32_e32 v132, v133, v130
	v_fma_f32 v121, -v121, v132, v131
	v_div_fmas_f32 v121, v121, v130, v132
	v_div_fixup_f32 v120, v121, v120, 1.0
	v_add_lshl_u32 v121, v166, v156, 1
	global_store_dwordx4 v121, v[122:125], s[22:23]
	v_pk_fma_f32 v[112:113], v[112:113], v[120:121], v[92:93] op_sel_hi:[1,0,1]
	v_pk_fma_f32 v[130:131], v[110:111], v[120:121], v[90:91] op_sel_hi:[1,0,1]
	v_pk_fma_f32 v[122:123], v[116:117], v[120:121], v[88:89] op_sel_hi:[1,0,1]
	v_pk_fma_f32 v[124:125], v[114:115], v[120:121], v[86:87] op_sel_hi:[1,0,1]
	s_and_b64 vcc, exec, s[14:15]
	s_cbranch_vccnz .LBB0_472
	s_and_b64 vcc, exec, s[10:11]
	v_mov_b32_e32 v117, v123
	v_mov_b32_e32 v116, v122
	v_mov_b32_e32 v115, v125
	v_mov_b32_e32 v114, v124
	v_mov_b32_e32 v141, v113
	v_mov_b32_e32 v140, v112
	v_mov_b32_e32 v133, v131
	v_mov_b32_e32 v132, v130
	s_cbranch_vccnz .LBB0_470
	v_and_b32_e32 v111, 0x7fffffff, v125
	v_and_b32_e32 v110, 0x7fffffff, v124
	v_pk_fma_f32 v[110:111], v[110:111], s[62:63], 1.0 op_sel_hi:[1,0,0]
	s_mov_b32 s2, 0xbf3a00e3
	v_rcp_f32_e32 v110, v110
	v_rcp_f32_e32 v111, v111
	v_mov_b64_e32 v[140:141], s[2:3]
	v_cmp_gt_f32_e32 vcc, 0, v124
	v_pk_mul_f32 v[116:117], v[122:123], v[122:123]
	v_pk_fma_f32 v[114:115], v[110:111], s[64:65], v[140:141] op_sel_hi:[1,0,0]
	v_pk_mul_f32 v[116:117], v[116:117], s[74:75] op_sel_hi:[1,0]
	v_pk_fma_f32 v[114:115], v[110:111], v[114:115], s[68:69] op_sel_hi:[1,1,0]
	v_exp_f32_e32 v116, v116
	v_pk_fma_f32 v[114:115], v[110:111], v[114:115], s[70:71] op_sel_hi:[1,1,0]
	v_exp_f32_e32 v117, v117
	v_pk_fma_f32 v[114:115], v[110:111], v[114:115], s[72:73] op_sel_hi:[1,1,0]
	v_pk_mul_f32 v[168:169], v[112:113], v[112:113]
	v_pk_mul_f32 v[110:111], v[110:111], v[114:115]
	v_pk_mul_f32 v[114:115], v[124:125], v[124:125]
	s_nop 0
	v_pk_mul_f32 v[114:115], v[114:115], s[74:75] op_sel_hi:[1,0]
	s_nop 0
	v_exp_f32_e32 v114, v114
	v_exp_f32_e32 v115, v115
	s_nop 0
	v_pk_mul_f32 v[110:111], v[114:115], v[110:111]
	s_nop 0
	v_pk_mul_f32 v[114:115], v[124:125], v[110:111]
	v_pk_fma_f32 v[110:111], v[124:125], v[110:111], v[124:125] neg_lo:[1,0,0] neg_hi:[1,0,0]
	s_nop 0
	v_cndmask_b32_e32 v114, v110, v114, vcc
	v_cmp_gt_f32_e32 vcc, 0, v125
	v_and_b32_e32 v110, 0x7fffffff, v122
	s_nop 0
	v_cndmask_b32_e32 v115, v111, v115, vcc
	v_and_b32_e32 v111, 0x7fffffff, v123
	v_pk_fma_f32 v[110:111], v[110:111], s[62:63], 1.0 op_sel_hi:[1,0,0]
	v_cmp_gt_f32_e32 vcc, 0, v122
	v_rcp_f32_e32 v110, v110
	v_rcp_f32_e32 v111, v111
	s_nop 0
	v_pk_fma_f32 v[132:133], v[110:111], s[64:65], v[140:141] op_sel_hi:[1,0,0]
	s_nop 0
	v_pk_fma_f32 v[132:133], v[110:111], v[132:133], s[68:69] op_sel_hi:[1,1,0]
	s_nop 0
	v_pk_fma_f32 v[132:133], v[110:111], v[132:133], s[70:71] op_sel_hi:[1,1,0]
	s_nop 0
	v_pk_fma_f32 v[132:133], v[110:111], v[132:133], s[72:73] op_sel_hi:[1,1,0]
	s_nop 0
	v_pk_mul_f32 v[110:111], v[110:111], v[132:133]
	s_nop 0
	v_pk_mul_f32 v[110:111], v[116:117], v[110:111]
	s_nop 0
	v_pk_mul_f32 v[116:117], v[122:123], v[110:111]
	v_pk_fma_f32 v[110:111], v[122:123], v[110:111], v[122:123] neg_lo:[1,0,0] neg_hi:[1,0,0]
	s_nop 0
	v_cndmask_b32_e32 v116, v110, v116, vcc
	v_cmp_gt_f32_e32 vcc, 0, v123
	v_and_b32_e32 v110, 0x7fffffff, v130
	s_nop 0
	v_cndmask_b32_e32 v117, v111, v117, vcc
	v_and_b32_e32 v111, 0x7fffffff, v131
	v_pk_fma_f32 v[110:111], v[110:111], s[62:63], 1.0 op_sel_hi:[1,0,0]
	v_cmp_gt_f32_e32 vcc, 0, v130
	v_rcp_f32_e32 v110, v110
	v_rcp_f32_e32 v111, v111
	s_nop 0
	v_pk_fma_f32 v[132:133], v[110:111], s[64:65], v[140:141] op_sel_hi:[1,0,0]
	s_nop 0
	v_pk_fma_f32 v[132:133], v[110:111], v[132:133], s[68:69] op_sel_hi:[1,1,0]
	s_nop 0
	v_pk_fma_f32 v[132:133], v[110:111], v[132:133], s[70:71] op_sel_hi:[1,1,0]
	s_nop 0
	v_pk_fma_f32 v[132:133], v[110:111], v[132:133], s[72:73] op_sel_hi:[1,1,0]
	s_nop 0
	v_pk_mul_f32 v[110:111], v[110:111], v[132:133]
	v_pk_mul_f32 v[132:133], v[130:131], v[130:131]
	s_nop 0
	v_pk_mul_f32 v[132:133], v[132:133], s[74:75] op_sel_hi:[1,0]
	s_nop 0
	v_exp_f32_e32 v132, v132
	v_exp_f32_e32 v133, v133
	s_nop 0
	v_pk_mul_f32 v[110:111], v[132:133], v[110:111]
	s_nop 0
	v_pk_mul_f32 v[132:133], v[130:131], v[110:111]
	v_pk_fma_f32 v[110:111], v[130:131], v[110:111], v[130:131] neg_lo:[1,0,0] neg_hi:[1,0,0]
	s_nop 0
	v_cndmask_b32_e32 v132, v110, v132, vcc
	v_cmp_gt_f32_e32 vcc, 0, v131
	v_and_b32_e32 v110, 0x7fffffff, v112
	s_nop 0
	v_cndmask_b32_e32 v133, v111, v133, vcc
	v_and_b32_e32 v111, 0x7fffffff, v113
	v_pk_fma_f32 v[110:111], v[110:111], s[62:63], 1.0 op_sel_hi:[1,0,0]
	v_cmp_gt_f32_e32 vcc, 0, v112
	v_rcp_f32_e32 v110, v110
	v_rcp_f32_e32 v111, v111
	s_nop 0
	v_pk_fma_f32 v[140:141], v[110:111], s[64:65], v[140:141] op_sel_hi:[1,0,0]
	s_nop 0
	v_pk_fma_f32 v[140:141], v[110:111], v[140:141], s[68:69] op_sel_hi:[1,1,0]
	s_nop 0
	v_pk_fma_f32 v[140:141], v[110:111], v[140:141], s[70:71] op_sel_hi:[1,1,0]
	s_nop 0
	v_pk_fma_f32 v[140:141], v[110:111], v[140:141], s[72:73] op_sel_hi:[1,1,0]
	s_nop 0
	v_pk_mul_f32 v[110:111], v[110:111], v[140:141]
	v_pk_mul_f32 v[140:141], v[168:169], s[74:75] op_sel_hi:[1,0]
	s_nop 0
	v_exp_f32_e32 v140, v140
	v_exp_f32_e32 v141, v141
	s_nop 0
	v_pk_mul_f32 v[110:111], v[140:141], v[110:111]
	s_nop 0
	v_pk_mul_f32 v[140:141], v[112:113], v[110:111]
	v_pk_fma_f32 v[110:111], v[112:113], v[110:111], v[112:113] neg_lo:[1,0,0] neg_hi:[1,0,0]
	s_nop 0
	v_cndmask_b32_e32 v140, v110, v140, vcc
	v_cmp_gt_f32_e32 vcc, 0, v113
	s_nop 1
	v_cndmask_b32_e32 v141, v111, v141, vcc

; __device__ __forceinline__ unsigned cvt_pk_bf16(float lo, float hi) { unsigned r; asm volatile("v_cvt_pk_bf16_f32 %0, %1, %2" : "=v"(r) : "v"(lo), "v"(hi)); return r; }
; #define PG8_GPTR(p) ((__attribute__((address_space(1))) char*)(p))
;     __device__ __forceinline__ void operator()(const f32x4 (&acc)[2][2][4][2], const Unit& u, int wr, int wc, int fr, int fq) const {
;     ...
;                 for (int m = 0; m < 4; ++m) {
;                     const int row = row0 + ai * HALF + m * 16;
;                     const float rs = rsv[ai * 4 + m];
;                     f32x4 v0 = acc[ai][bj][m][0] * rs + s0, v1 = acc[ai][bj][m][1] * rs + s1;
;                     if (mode == 1 || mode == 2) {
;                         const float* tp = (mode == 1) ? (ropA + ((size_t)row * 32 + ((col0 & 63) >> 1)) * 2) : (ropB + ((size_t)row * 16 + ((col0 - PC_KR) >> 1)) * 2);
;                         const f32x4 c0 = *(const f32x4*)tp, c1 = *(const f32x4*)(tp + 4);
;                         f32x4 w0, w1;
;                         w0[0] = v0[0] * c0[0] - v0[1] * c0[1]; w0[1] = v0[1] * c0[0] + v0[0] * c0[1];
;                         w0[2] = v0[2] * c0[2] - v0[3] * c0[3]; w0[3] = v0[3] * c0[2] + v0[2] * c0[3];
;                         w1[0] = v1[0] * c1[0] - v1[1] * c1[1]; w1[1] = v1[1] * c1[0] + v1[0] * c1[1];
;                         w1[2] = v1[2] * c1[2] - v1[3] * c1[3]; w1[3] = v1[3] * c1[2] + v1[2] * c1[3];
;                         v0 = w0 * sc; v1 = w1 * sc;
;                     } else if (mode == 3) {
;                         const f32x2 a = gelu_pk((f32x2){v0[0], v0[1]}), bb = gelu_pk((f32x2){v0[2], v0[3]}), c = gelu_pk((f32x2){v1[0], v1[1]}), d = gelu_pk((f32x2){v1[2], v1[3]});
;                         v0 = (f32x4){a.x, a.y, bb.x, bb.y}; v1 = (f32x4){c.x, c.y, d.x, d.y};
;                     }
;                     if (stat) {
;                         const float q = (v0[0] * v0[0] + v0[1] * v0[1]) + (v0[2] * v0[2] + v0[3] * v0[3]) + (v1[0] * v1[0] + v1[1] * v1[1]) + (v1[2] * v1[2] + v1[3] * v1[3]);
;                         ssq_put(stat == 1 ? ssq_cq : ssq_ckv, row, q, fr, fq);
;                     }
;                     u32x4 w; w.x = cvt_pk_bf16(v0[0], v0[1]); w.y = cvt_pk_bf16(v0[2], v0[3]); w.z = cvt_pk_bf16(v1[0], v1[1]); w.w = cvt_pk_bf16(v1[2], v1[3]);
;                     *(gs_u32x4*)(PG8_GPTR(O) + (unsigned)(row * PJP + col0) * 2u) = w;
.LBB0_481:
	v_ffbh_u32_e32 v112, v165
	v_min_u32_e32 v122, 32, v112
	s_waitcnt lgkmcnt(0)
	v_lshlrev_b64 v[112:113], v122, v[164:165]
	v_min_u32_e32 v112, 1, v112
	v_or_b32_e32 v112, v113, v112
	v_cvt_f32_u32_e32 v112, v112
	v_sub_u32_e32 v113, 32, v122
	v_cvt_pk_bf16_f32 v114, v114, v115
	v_cvt_pk_bf16_f32 v115, v116, v117
	v_ldexp_f32 v112, v112, v113
	v_mul_f32_e32 v112, 0x33800000, v112
	v_fmamk_f32 v112, v112, 0x3a800000, v226
	v_mul_f32_e32 v113, 0x4f800000, v112
	v_cmp_gt_f32_e32 vcc, s71, v112
	v_cvt_pk_bf16_f32 v116, v132, v133
	v_add_u32_e32 v132, 0x8400, v166
	v_cvt_pk_bf16_f32 v117, v140, v141
	s_nop 0
	v_cndmask_b32_e32 v112, v112, v113, vcc
	v_sqrt_f32_e32 v113, v112
	s_nop 0
	v_add_u32_e32 v122, -1, v113
	v_add_u32_e32 v123, 1, v113
	v_fma_f32 v124, -v122, v113, v112
	v_fma_f32 v125, -v123, v113, v112
	v_cmp_ge_f32_e64 s[18:19], 0, v124
	s_nop 1
	v_cndmask_b32_e64 v113, v113, v122, s[18:19]
	v_cmp_lt_f32_e64 s[18:19], 0, v125
	s_nop 1
	v_cndmask_b32_e64 v113, v113, v123, s[18:19]
	v_mul_f32_e32 v122, 0x37800000, v113
	v_cndmask_b32_e32 v113, v113, v122, vcc
	v_cmp_class_f32_e32 vcc, v112, v223
	s_nop 1
	v_cndmask_b32_e32 v112, v113, v112, vcc
	v_div_scale_f32 v113, s[2:3], v112, v112, 1.0
	v_rcp_f32_e32 v122, v113
	s_mov_b64 s[2:3], -1
	v_fma_f32 v123, -v113, v122, 1.0
	v_fmac_f32_e32 v122, v123, v122
	v_div_scale_f32 v123, vcc, 1.0, v112, 1.0
	v_mul_f32_e32 v124, v123, v122
	v_fma_f32 v125, -v113, v124, v123
	v_fmac_f32_e32 v124, v125, v122
	v_fma_f32 v113, -v113, v124, v123
	v_div_fmas_f32 v113, v113, v122, v124
	v_div_fixup_f32 v112, v113, v112, 1.0
	v_add_lshl_u32 v113, v132, v156, 1
	global_store_dwordx4 v113, v[114:117], s[22:23]
	v_pk_fma_f32 v[104:105], v[104:105], v[112:113], v[92:93] op_sel_hi:[1,0,1]
	v_pk_fma_f32 v[122:123], v[102:103], v[112:113], v[90:91] op_sel_hi:[1,0,1]
	v_pk_fma_f32 v[114:115], v[108:109], v[112:113], v[88:89] op_sel_hi:[1,0,1]
	v_pk_fma_f32 v[116:117], v[106:107], v[112:113], v[86:87] op_sel_hi:[1,0,1]
	s_and_b64 vcc, exec, s[14:15]
	s_cbranch_vccnz .LBB0_486
	s_and_b64 vcc, exec, s[10:11]
	v_mov_b32_e32 v109, v115
	v_mov_b32_e32 v108, v114
	v_mov_b32_e32 v107, v117
	v_mov_b32_e32 v106, v116
	v_mov_b32_e32 v131, v105
	v_mov_b32_e32 v130, v104
	v_mov_b32_e32 v125, v123
	v_mov_b32_e32 v124, v122
	s_cbranch_vccnz .LBB0_484
	v_and_b32_e32 v103, 0x7fffffff, v117
	v_and_b32_e32 v102, 0x7fffffff, v116
	v_pk_fma_f32 v[102:103], v[102:103], s[62:63], 1.0 op_sel_hi:[1,0,0]
	s_mov_b32 s2, 0xbf3a00e3
	v_rcp_f32_e32 v102, v102
	v_rcp_f32_e32 v103, v103
	v_mov_b64_e32 v[130:131], s[2:3]
	v_cmp_gt_f32_e32 vcc, 0, v116
	v_pk_mul_f32 v[108:109], v[114:115], v[114:115]
	v_pk_fma_f32 v[106:107], v[102:103], s[64:65], v[130:131] op_sel_hi:[1,0,0]
	v_pk_mul_f32 v[108:109], v[108:109], s[74:75] op_sel_hi:[1,0]
	v_pk_fma_f32 v[106:107], v[102:103], v[106:107], s[68:69] op_sel_hi:[1,1,0]
	v_exp_f32_e32 v108, v108
	v_pk_fma_f32 v[106:107], v[102:103], v[106:107], s[70:71] op_sel_hi:[1,1,0]
	v_exp_f32_e32 v109, v109
	v_pk_fma_f32 v[106:107], v[102:103], v[106:107], s[72:73] op_sel_hi:[1,1,0]
	v_pk_mul_f32 v[140:141], v[104:105], v[104:105]
	v_pk_mul_f32 v[102:103], v[102:103], v[106:107]
	v_pk_mul_f32 v[106:107], v[116:117], v[116:117]
	s_nop 0
	v_pk_mul_f32 v[106:107], v[106:107], s[74:75] op_sel_hi:[1,0]
	s_nop 0
	v_exp_f32_e32 v106, v106
	v_exp_f32_e32 v107, v107
	s_nop 0
	v_pk_mul_f32 v[102:103], v[106:107], v[102:103]
	s_nop 0
	v_pk_mul_f32 v[106:107], v[116:117], v[102:103]
	v_pk_fma_f32 v[102:103], v[116:117], v[102:103], v[116:117] neg_lo:[1,0,0] neg_hi:[1,0,0]
	s_nop 0
	v_cndmask_b32_e32 v106, v102, v106, vcc
	v_cmp_gt_f32_e32 vcc, 0, v117
	v_and_b32_e32 v102, 0x7fffffff, v114
	s_nop 0
	v_cndmask_b32_e32 v107, v103, v107, vcc
	v_and_b32_e32 v103, 0x7fffffff, v115
	v_pk_fma_f32 v[102:103], v[102:103], s[62:63], 1.0 op_sel_hi:[1,0,0]
	v_cmp_gt_f32_e32 vcc, 0, v114
	v_rcp_f32_e32 v102, v102
	v_rcp_f32_e32 v103, v103
	s_nop 0
	v_pk_fma_f32 v[124:125], v[102:103], s[64:65], v[130:131] op_sel_hi:[1,0,0]
	s_nop 0
	v_pk_fma_f32 v[124:125], v[102:103], v[124:125], s[68:69] op_sel_hi:[1,1,0]
	s_nop 0
	v_pk_fma_f32 v[124:125], v[102:103], v[124:125], s[70:71] op_sel_hi:[1,1,0]
	s_nop 0
	v_pk_fma_f32 v[124:125], v[102:103], v[124:125], s[72:73] op_sel_hi:[1,1,0]
	s_nop 0
	v_pk_mul_f32 v[102:103], v[102:103], v[124:125]
	s_nop 0
	v_pk_mul_f32 v[102:103], v[108:109], v[102:103]
	s_nop 0
	v_pk_mul_f32 v[108:109], v[114:115], v[102:103]
	v_pk_fma_f32 v[102:103], v[114:115], v[102:103], v[114:115] neg_lo:[1,0,0] neg_hi:[1,0,0]
	s_nop 0
	v_cndmask_b32_e32 v108, v102, v108, vcc
	v_cmp_gt_f32_e32 vcc, 0, v115
	v_and_b32_e32 v102, 0x7fffffff, v122
	s_nop 0
	v_cndmask_b32_e32 v109, v103, v109, vcc
	v_and_b32_e32 v103, 0x7fffffff, v123
	v_pk_fma_f32 v[102:103], v[102:103], s[62:63], 1.0 op_sel_hi:[1,0,0]
	v_cmp_gt_f32_e32 vcc, 0, v122
	v_rcp_f32_e32 v102, v102
	v_rcp_f32_e32 v103, v103
	s_nop 0
	v_pk_fma_f32 v[124:125], v[102:103], s[64:65], v[130:131] op_sel_hi:[1,0,0]
	s_nop 0
	v_pk_fma_f32 v[124:125], v[102:103], v[124:125], s[68:69] op_sel_hi:[1,1,0]
	s_nop 0
	v_pk_fma_f32 v[124:125], v[102:103], v[124:125], s[70:71] op_sel_hi:[1,1,0]
	s_nop 0
	v_pk_fma_f32 v[124:125], v[102:103], v[124:125], s[72:73] op_sel_hi:[1,1,0]
	s_nop 0
	v_pk_mul_f32 v[102:103], v[102:103], v[124:125]
	v_pk_mul_f32 v[124:125], v[122:123], v[122:123]
	s_nop 0
	v_pk_mul_f32 v[124:125], v[124:125], s[74:75] op_sel_hi:[1,0]
	s_nop 0
	v_exp_f32_e32 v124, v124
	v_exp_f32_e32 v125, v125
	s_nop 0
	v_pk_mul_f32 v[102:103], v[124:125], v[102:103]
	s_nop 0
	v_pk_mul_f32 v[124:125], v[122:123], v[102:103]
	v_pk_fma_f32 v[102:103], v[122:123], v[102:103], v[122:123] neg_lo:[1,0,0] neg_hi:[1,0,0]
	s_nop 0
	v_cndmask_b32_e32 v124, v102, v124, vcc
	v_cmp_gt_f32_e32 vcc, 0, v123
	v_and_b32_e32 v102, 0x7fffffff, v104
	s_nop 0
	v_cndmask_b32_e32 v125, v103, v125, vcc
	v_and_b32_e32 v103, 0x7fffffff, v105
	v_pk_fma_f32 v[102:103], v[102:103], s[62:63], 1.0 op_sel_hi:[1,0,0]
	v_cmp_gt_f32_e32 vcc, 0, v104
	v_rcp_f32_e32 v102, v102
	v_rcp_f32_e32 v103, v103
	s_nop 0
	v_pk_fma_f32 v[130:131], v[102:103], s[64:65], v[130:131] op_sel_hi:[1,0,0]
	s_nop 0
	v_pk_fma_f32 v[130:131], v[102:103], v[130:131], s[68:69] op_sel_hi:[1,1,0]
	s_nop 0
	v_pk_fma_f32 v[130:131], v[102:103], v[130:131], s[70:71] op_sel_hi:[1,1,0]
	s_nop 0
	v_pk_fma_f32 v[130:131], v[102:103], v[130:131], s[72:73] op_sel_hi:[1,1,0]
	s_nop 0
	v_pk_mul_f32 v[102:103], v[102:103], v[130:131]
	v_pk_mul_f32 v[130:131], v[140:141], s[74:75] op_sel_hi:[1,0]
	s_nop 0
	v_exp_f32_e32 v130, v130
	v_exp_f32_e32 v131, v131
	s_nop 0
	v_pk_mul_f32 v[102:103], v[130:131], v[102:103]
	s_nop 0
	v_pk_mul_f32 v[130:131], v[104:105], v[102:103]
	v_pk_fma_f32 v[102:103], v[104:105], v[102:103], v[104:105] neg_lo:[1,0,0] neg_hi:[1,0,0]
	s_nop 0
	v_cndmask_b32_e32 v130, v102, v130, vcc
	v_cmp_gt_f32_e32 vcc, 0, v105
	s_nop 1
	v_cndmask_b32_e32 v131, v103, v131, vcc

; __device__ __forceinline__ unsigned cvt_pk_bf16(float lo, float hi) { unsigned r; asm volatile("v_cvt_pk_bf16_f32 %0, %1, %2" : "=v"(r) : "v"(lo), "v"(hi)); return r; }
; #define PG8_GPTR(p) ((__attribute__((address_space(1))) char*)(p))
;     __device__ __forceinline__ void operator()(const f32x4 (&acc)[2][2][4][2], const Unit& u, int wr, int wc, int fr, int fq) const {
;     ...
;                 for (int m = 0; m < 4; ++m) {
;                     const int row = row0 + ai * HALF + m * 16;
;                     const float rs = rsv[ai * 4 + m];
;                     f32x4 v0 = acc[ai][bj][m][0] * rs + s0, v1 = acc[ai][bj][m][1] * rs + s1;
;                     if (mode == 1 || mode == 2) {
;                         const float* tp = (mode == 1) ? (ropA + ((size_t)row * 32 + ((col0 & 63) >> 1)) * 2) : (ropB + ((size_t)row * 16 + ((col0 - PC_KR) >> 1)) * 2);
;                         const f32x4 c0 = *(const f32x4*)tp, c1 = *(const f32x4*)(tp + 4);
;                         f32x4 w0, w1;
;                         w0[0] = v0[0] * c0[0] - v0[1] * c0[1]; w0[1] = v0[1] * c0[0] + v0[0] * c0[1];
;                         w0[2] = v0[2] * c0[2] - v0[3] * c0[3]; w0[3] = v0[3] * c0[2] + v0[2] * c0[3];
;                         w1[0] = v1[0] * c1[0] - v1[1] * c1[1]; w1[1] = v1[1] * c1[0] + v1[0] * c1[1];
;                         w1[2] = v1[2] * c1[2] - v1[3] * c1[3]; w1[3] = v1[3] * c1[2] + v1[2] * c1[3];
;                         v0 = w0 * sc; v1 = w1 * sc;
;                     } else if (mode == 3) {
;                         const f32x2 a = gelu_pk((f32x2){v0[0], v0[1]}), bb = gelu_pk((f32x2){v0[2], v0[3]}), c = gelu_pk((f32x2){v1[0], v1[1]}), d = gelu_pk((f32x2){v1[2], v1[3]});
;                         v0 = (f32x4){a.x, a.y, bb.x, bb.y}; v1 = (f32x4){c.x, c.y, d.x, d.y};
;                     }
;                     if (stat) {
;                         const float q = (v0[0] * v0[0] + v0[1] * v0[1]) + (v0[2] * v0[2] + v0[3] * v0[3]) + (v1[0] * v1[0] + v1[1] * v1[1]) + (v1[2] * v1[2] + v1[3] * v1[3]);
;                         ssq_put(stat == 1 ? ssq_cq : ssq_ckv, row, q, fr, fq);
;                     }
;                     u32x4 w; w.x = cvt_pk_bf16(v0[0], v0[1]); w.y = cvt_pk_bf16(v0[2], v0[3]); w.z = cvt_pk_bf16(v1[0], v1[1]); w.w = cvt_pk_bf16(v1[2], v1[3]);
;                     *(gs_u32x4*)(PG8_GPTR(O) + (unsigned)(row * PJP + col0) * 2u) = w;
.LBB0_495:
	v_ffbh_u32_e32 v104, v163
	v_min_u32_e32 v114, 32, v104
	s_waitcnt lgkmcnt(0)
	v_lshlrev_b64 v[104:105], v114, v[162:163]
	v_min_u32_e32 v104, 1, v104
	v_or_b32_e32 v104, v105, v104
	v_cvt_f32_u32_e32 v104, v104
	v_sub_u32_e32 v105, 32, v114
	v_cvt_pk_bf16_f32 v106, v106, v107
	v_cvt_pk_bf16_f32 v107, v108, v109
	v_ldexp_f32 v104, v104, v105
	v_mul_f32_e32 v104, 0x33800000, v104
	v_fmamk_f32 v104, v104, 0x3a800000, v226
	v_mul_f32_e32 v105, 0x4f800000, v104
	v_cmp_gt_f32_e32 vcc, s71, v104
	v_cvt_pk_bf16_f32 v108, v124, v125
	v_add_u32_e32 v124, 0x29400, v132
	v_cvt_pk_bf16_f32 v109, v130, v131
	s_nop 0
	v_cndmask_b32_e32 v104, v104, v105, vcc
	v_sqrt_f32_e32 v105, v104
	s_nop 0
	v_add_u32_e32 v114, -1, v105
	v_add_u32_e32 v115, 1, v105
	v_fma_f32 v116, -v114, v105, v104
	v_fma_f32 v117, -v115, v105, v104
	v_cmp_ge_f32_e64 s[18:19], 0, v116
	s_nop 1
	v_cndmask_b32_e64 v105, v105, v114, s[18:19]
	v_cmp_lt_f32_e64 s[18:19], 0, v117
	s_nop 1
	v_cndmask_b32_e64 v105, v105, v115, s[18:19]
	v_mul_f32_e32 v114, 0x37800000, v105
	v_cndmask_b32_e32 v105, v105, v114, vcc
	v_cmp_class_f32_e32 vcc, v104, v223
	s_nop 1
	v_cndmask_b32_e32 v104, v105, v104, vcc
	v_div_scale_f32 v105, s[2:3], v104, v104, 1.0
	v_rcp_f32_e32 v114, v105
	s_mov_b64 s[2:3], -1
	v_fma_f32 v115, -v105, v114, 1.0
	v_fmac_f32_e32 v114, v115, v114
	v_div_scale_f32 v115, vcc, 1.0, v104, 1.0
	v_mul_f32_e32 v116, v115, v114
	v_fma_f32 v117, -v105, v116, v115
	v_fmac_f32_e32 v116, v117, v114
	v_fma_f32 v105, -v105, v116, v115
	v_div_fmas_f32 v105, v105, v114, v116
	v_div_fixup_f32 v104, v105, v104, 1.0
	v_add_lshl_u32 v105, v124, v156, 1
	global_store_dwordx4 v105, v[106:109], s[22:23]
	v_pk_fma_f32 v[96:97], v[96:97], v[104:105], v[92:93] op_sel_hi:[1,0,1]
	v_pk_fma_f32 v[114:115], v[94:95], v[104:105], v[90:91] op_sel_hi:[1,0,1]
	v_pk_fma_f32 v[106:107], v[100:101], v[104:105], v[88:89] op_sel_hi:[1,0,1]
	v_pk_fma_f32 v[108:109], v[98:99], v[104:105], v[86:87] op_sel_hi:[1,0,1]
	s_and_b64 vcc, exec, s[14:15]
	s_cbranch_vccnz .LBB0_500
	s_and_b64 vcc, exec, s[10:11]
	v_mov_b32_e32 v101, v107
	v_mov_b32_e32 v100, v106
	v_mov_b32_e32 v99, v109
	v_mov_b32_e32 v98, v108
	v_mov_b32_e32 v123, v97
	v_mov_b32_e32 v122, v96
	v_mov_b32_e32 v117, v115
	v_mov_b32_e32 v116, v114
	s_cbranch_vccnz .LBB0_498
	v_and_b32_e32 v95, 0x7fffffff, v109
	v_and_b32_e32 v94, 0x7fffffff, v108
	v_pk_fma_f32 v[94:95], v[94:95], s[62:63], 1.0 op_sel_hi:[1,0,0]
	s_mov_b32 s2, 0xbf3a00e3
	v_rcp_f32_e32 v94, v94
	v_rcp_f32_e32 v95, v95
	v_mov_b64_e32 v[122:123], s[2:3]
	v_cmp_gt_f32_e32 vcc, 0, v108
	v_pk_mul_f32 v[100:101], v[106:107], v[106:107]
	v_pk_fma_f32 v[98:99], v[94:95], s[64:65], v[122:123] op_sel_hi:[1,0,0]
	v_pk_mul_f32 v[100:101], v[100:101], s[74:75] op_sel_hi:[1,0]
	v_pk_fma_f32 v[98:99], v[94:95], v[98:99], s[68:69] op_sel_hi:[1,1,0]
	v_exp_f32_e32 v100, v100
	v_pk_fma_f32 v[98:99], v[94:95], v[98:99], s[70:71] op_sel_hi:[1,1,0]
	v_exp_f32_e32 v101, v101
	v_pk_fma_f32 v[98:99], v[94:95], v[98:99], s[72:73] op_sel_hi:[1,1,0]
	v_pk_mul_f32 v[130:131], v[96:97], v[96:97]
	v_pk_mul_f32 v[94:95], v[94:95], v[98:99]
	v_pk_mul_f32 v[98:99], v[108:109], v[108:109]
	s_nop 0
	v_pk_mul_f32 v[98:99], v[98:99], s[74:75] op_sel_hi:[1,0]
	s_nop 0
	v_exp_f32_e32 v98, v98
	v_exp_f32_e32 v99, v99
	s_nop 0
	v_pk_mul_f32 v[94:95], v[98:99], v[94:95]
	s_nop 0
	v_pk_mul_f32 v[98:99], v[108:109], v[94:95]
	v_pk_fma_f32 v[94:95], v[108:109], v[94:95], v[108:109] neg_lo:[1,0,0] neg_hi:[1,0,0]
	s_nop 0
	v_cndmask_b32_e32 v98, v94, v98, vcc
	v_cmp_gt_f32_e32 vcc, 0, v109
	v_and_b32_e32 v94, 0x7fffffff, v106
	s_nop 0
	v_cndmask_b32_e32 v99, v95, v99, vcc
	v_and_b32_e32 v95, 0x7fffffff, v107
	v_pk_fma_f32 v[94:95], v[94:95], s[62:63], 1.0 op_sel_hi:[1,0,0]
	v_cmp_gt_f32_e32 vcc, 0, v106
	v_rcp_f32_e32 v94, v94
	v_rcp_f32_e32 v95, v95
	s_nop 0
	v_pk_fma_f32 v[116:117], v[94:95], s[64:65], v[122:123] op_sel_hi:[1,0,0]
	s_nop 0
	v_pk_fma_f32 v[116:117], v[94:95], v[116:117], s[68:69] op_sel_hi:[1,1,0]
	s_nop 0
	v_pk_fma_f32 v[116:117], v[94:95], v[116:117], s[70:71] op_sel_hi:[1,1,0]
	s_nop 0
	v_pk_fma_f32 v[116:117], v[94:95], v[116:117], s[72:73] op_sel_hi:[1,1,0]
	s_nop 0
	v_pk_mul_f32 v[94:95], v[94:95], v[116:117]
	s_nop 0
	v_pk_mul_f32 v[94:95], v[100:101], v[94:95]
	s_nop 0
	v_pk_mul_f32 v[100:101], v[106:107], v[94:95]
	v_pk_fma_f32 v[94:95], v[106:107], v[94:95], v[106:107] neg_lo:[1,0,0] neg_hi:[1,0,0]
	s_nop 0
	v_cndmask_b32_e32 v100, v94, v100, vcc
	v_cmp_gt_f32_e32 vcc, 0, v107
	v_and_b32_e32 v94, 0x7fffffff, v114
	s_nop 0
	v_cndmask_b32_e32 v101, v95, v101, vcc
	v_and_b32_e32 v95, 0x7fffffff, v115
	v_pk_fma_f32 v[94:95], v[94:95], s[62:63], 1.0 op_sel_hi:[1,0,0]
	v_cmp_gt_f32_e32 vcc, 0, v114
	v_rcp_f32_e32 v94, v94
	v_rcp_f32_e32 v95, v95
	s_nop 0
	v_pk_fma_f32 v[116:117], v[94:95], s[64:65], v[122:123] op_sel_hi:[1,0,0]
	s_nop 0
	v_pk_fma_f32 v[116:117], v[94:95], v[116:117], s[68:69] op_sel_hi:[1,1,0]
	s_nop 0
	v_pk_fma_f32 v[116:117], v[94:95], v[116:117], s[70:71] op_sel_hi:[1,1,0]
	s_nop 0
	v_pk_fma_f32 v[116:117], v[94:95], v[116:117], s[72:73] op_sel_hi:[1,1,0]
	s_nop 0
	v_pk_mul_f32 v[94:95], v[94:95], v[116:117]
	v_pk_mul_f32 v[116:117], v[114:115], v[114:115]
	s_nop 0
	v_pk_mul_f32 v[116:117], v[116:117], s[74:75] op_sel_hi:[1,0]
	s_nop 0
	v_exp_f32_e32 v116, v116
	v_exp_f32_e32 v117, v117
	s_nop 0
	v_pk_mul_f32 v[94:95], v[116:117], v[94:95]
	s_nop 0
	v_pk_mul_f32 v[116:117], v[114:115], v[94:95]
	v_pk_fma_f32 v[94:95], v[114:115], v[94:95], v[114:115] neg_lo:[1,0,0] neg_hi:[1,0,0]
	s_nop 0
	v_cndmask_b32_e32 v116, v94, v116, vcc
	v_cmp_gt_f32_e32 vcc, 0, v115
	v_and_b32_e32 v94, 0x7fffffff, v96
	s_nop 0
	v_cndmask_b32_e32 v117, v95, v117, vcc
	v_and_b32_e32 v95, 0x7fffffff, v97
	v_pk_fma_f32 v[94:95], v[94:95], s[62:63], 1.0 op_sel_hi:[1,0,0]
	v_cmp_gt_f32_e32 vcc, 0, v96
	v_rcp_f32_e32 v94, v94
	v_rcp_f32_e32 v95, v95
	s_nop 0
	v_pk_fma_f32 v[122:123], v[94:95], s[64:65], v[122:123] op_sel_hi:[1,0,0]
	s_nop 0
	v_pk_fma_f32 v[122:123], v[94:95], v[122:123], s[68:69] op_sel_hi:[1,1,0]
	s_nop 0
	v_pk_fma_f32 v[122:123], v[94:95], v[122:123], s[70:71] op_sel_hi:[1,1,0]
	s_nop 0
	v_pk_fma_f32 v[122:123], v[94:95], v[122:123], s[72:73] op_sel_hi:[1,1,0]
	s_nop 0
	v_pk_mul_f32 v[94:95], v[94:95], v[122:123]
	v_pk_mul_f32 v[122:123], v[130:131], s[74:75] op_sel_hi:[1,0]
	s_nop 0
	v_exp_f32_e32 v122, v122
	v_exp_f32_e32 v123, v123
	s_nop 0
	v_pk_mul_f32 v[94:95], v[122:123], v[94:95]
	s_nop 0
	v_pk_mul_f32 v[122:123], v[96:97], v[94:95]
	v_pk_fma_f32 v[94:95], v[96:97], v[94:95], v[96:97] neg_lo:[1,0,0] neg_hi:[1,0,0]
	s_nop 0
	v_cndmask_b32_e32 v122, v94, v122, vcc
	v_cmp_gt_f32_e32 vcc, 0, v97
	s_nop 1
	v_cndmask_b32_e32 v123, v95, v123, vcc

; __device__ __forceinline__ unsigned cvt_pk_bf16(float lo, float hi) { unsigned r; asm volatile("v_cvt_pk_bf16_f32 %0, %1, %2" : "=v"(r) : "v"(lo), "v"(hi)); return r; }
; #define PG8_GPTR(p) ((__attribute__((address_space(1))) char*)(p))
;     __device__ __forceinline__ void operator()(const f32x4 (&acc)[2][2][4][2], const Unit& u, int wr, int wc, int fr, int fq) const {
;     ...
;                 for (int m = 0; m < 4; ++m) {
;                     const int row = row0 + ai * HALF + m * 16;
;                     const float rs = rsv[ai * 4 + m];
;                     f32x4 v0 = acc[ai][bj][m][0] * rs + s0, v1 = acc[ai][bj][m][1] * rs + s1;
;                     if (mode == 1 || mode == 2) {
;                         const float* tp = (mode == 1) ? (ropA + ((size_t)row * 32 + ((col0 & 63) >> 1)) * 2) : (ropB + ((size_t)row * 16 + ((col0 - PC_KR) >> 1)) * 2);
;                         const f32x4 c0 = *(const f32x4*)tp, c1 = *(const f32x4*)(tp + 4);
;                         f32x4 w0, w1;
;                         w0[0] = v0[0] * c0[0] - v0[1] * c0[1]; w0[1] = v0[1] * c0[0] + v0[0] * c0[1];
;                         w0[2] = v0[2] * c0[2] - v0[3] * c0[3]; w0[3] = v0[3] * c0[2] + v0[2] * c0[3];
;                         w1[0] = v1[0] * c1[0] - v1[1] * c1[1]; w1[1] = v1[1] * c1[0] + v1[0] * c1[1];
;                         w1[2] = v1[2] * c1[2] - v1[3] * c1[3]; w1[3] = v1[3] * c1[2] + v1[2] * c1[3];
;                         v0 = w0 * sc; v1 = w1 * sc;
;                     } else if (mode == 3) {
;                         const f32x2 a = gelu_pk((f32x2){v0[0], v0[1]}), bb = gelu_pk((f32x2){v0[2], v0[3]}), c = gelu_pk((f32x2){v1[0], v1[1]}), d = gelu_pk((f32x2){v1[2], v1[3]});
;                         v0 = (f32x4){a.x, a.y, bb.x, bb.y}; v1 = (f32x4){c.x, c.y, d.x, d.y};
;                     }
;                     if (stat) {
;                         const float q = (v0[0] * v0[0] + v0[1] * v0[1]) + (v0[2] * v0[2] + v0[3] * v0[3]) + (v1[0] * v1[0] + v1[1] * v1[1]) + (v1[2] * v1[2] + v1[3] * v1[3]);
;                         ssq_put(stat == 1 ? ssq_cq : ssq_ckv, row, q, fr, fq);
;                     }
;                     u32x4 w; w.x = cvt_pk_bf16(v0[0], v0[1]); w.y = cvt_pk_bf16(v0[2], v0[3]); w.z = cvt_pk_bf16(v1[0], v1[1]); w.w = cvt_pk_bf16(v1[2], v1[3]);
;                     *(gs_u32x4*)(PG8_GPTR(O) + (unsigned)(row * PJP + col0) * 2u) = w;
.LBB0_509:
	v_ffbh_u32_e32 v96, v161
	v_min_u32_e32 v106, 32, v96
	s_waitcnt lgkmcnt(0)
	v_lshlrev_b64 v[96:97], v106, v[160:161]
	v_min_u32_e32 v96, 1, v96
	v_or_b32_e32 v96, v97, v96
	v_cvt_f32_u32_e32 v96, v96
	v_sub_u32_e32 v97, 32, v106
	v_cvt_pk_bf16_f32 v98, v98, v99
	v_cvt_pk_bf16_f32 v99, v100, v101
	v_ldexp_f32 v96, v96, v97
	v_mul_f32_e32 v96, 0x33800000, v96
	v_fmamk_f32 v96, v96, 0x3a800000, v226
	v_mul_f32_e32 v97, 0x4f800000, v96
	v_cmp_gt_f32_e32 vcc, s71, v96
	v_cvt_pk_bf16_f32 v100, v116, v117
	v_add_u32_e32 v116, 0x8400, v124
	v_cvt_pk_bf16_f32 v101, v122, v123
	s_nop 0
	v_cndmask_b32_e32 v96, v96, v97, vcc
	v_sqrt_f32_e32 v97, v96
	s_nop 0
	v_add_u32_e32 v106, -1, v97
	v_add_u32_e32 v107, 1, v97
	v_fma_f32 v108, -v106, v97, v96
	v_fma_f32 v109, -v107, v97, v96
	v_cmp_ge_f32_e64 s[18:19], 0, v108
	s_nop 1
	v_cndmask_b32_e64 v97, v97, v106, s[18:19]
	v_cmp_lt_f32_e64 s[18:19], 0, v109
	s_nop 1
	v_cndmask_b32_e64 v97, v97, v107, s[18:19]
	v_mul_f32_e32 v106, 0x37800000, v97
	v_cndmask_b32_e32 v97, v97, v106, vcc
	v_cmp_class_f32_e32 vcc, v96, v223
	s_nop 1
	v_cndmask_b32_e32 v96, v97, v96, vcc
	v_div_scale_f32 v97, s[2:3], v96, v96, 1.0
	v_rcp_f32_e32 v106, v97
	s_mov_b64 s[2:3], -1
	v_fma_f32 v107, -v97, v106, 1.0
	v_fmac_f32_e32 v106, v107, v106
	v_div_scale_f32 v107, vcc, 1.0, v96, 1.0
	v_mul_f32_e32 v108, v107, v106
	v_fma_f32 v109, -v97, v108, v107
	v_fmac_f32_e32 v108, v109, v106
	v_fma_f32 v97, -v97, v108, v107
	v_div_fmas_f32 v97, v97, v106, v108
	v_div_fixup_f32 v96, v97, v96, 1.0
	v_add_lshl_u32 v97, v116, v156, 1
	global_store_dwordx4 v97, v[98:101], s[22:23]
	v_pk_fma_f32 v[106:107], v[78:79], v[96:97], v[90:91] op_sel_hi:[1,0,1]
	s_and_b64 vcc, exec, s[14:15]
	v_pk_fma_f32 v[98:99], v[84:85], v[96:97], v[88:89] op_sel_hi:[1,0,1]
	v_pk_fma_f32 v[100:101], v[82:83], v[96:97], v[86:87] op_sel_hi:[1,0,1]
	v_pk_fma_f32 v[82:83], v[80:81], v[96:97], v[92:93] op_sel_hi:[1,0,1]
	s_cbranch_vccnz .LBB0_514
	s_and_b64 vcc, exec, s[10:11]
	v_mov_b32_e32 v85, v99
	v_mov_b32_e32 v84, v98
	v_mov_b32_e32 v81, v101
	v_mov_b32_e32 v80, v100
	v_mov_b32_e32 v115, v83
	v_mov_b32_e32 v114, v82
	v_mov_b32_e32 v109, v107
	v_mov_b32_e32 v108, v106
	s_cbranch_vccnz .LBB0_512
	v_and_b32_e32 v79, 0x7fffffff, v101
	v_and_b32_e32 v78, 0x7fffffff, v100
	v_pk_fma_f32 v[78:79], v[78:79], s[62:63], 1.0 op_sel_hi:[1,0,0]
	s_mov_b32 s2, 0xbf3a00e3
	v_rcp_f32_e32 v78, v78
	v_rcp_f32_e32 v79, v79
	v_mov_b64_e32 v[114:115], s[2:3]
	v_cmp_gt_f32_e32 vcc, 0, v100
	v_pk_mul_f32 v[84:85], v[98:99], v[98:99]
	v_pk_fma_f32 v[80:81], v[78:79], s[64:65], v[114:115] op_sel_hi:[1,0,0]
	v_pk_mul_f32 v[84:85], v[84:85], s[74:75] op_sel_hi:[1,0]
	v_pk_fma_f32 v[80:81], v[78:79], v[80:81], s[68:69] op_sel_hi:[1,1,0]
	v_exp_f32_e32 v84, v84
	v_pk_fma_f32 v[80:81], v[78:79], v[80:81], s[70:71] op_sel_hi:[1,1,0]
	v_exp_f32_e32 v85, v85
	v_pk_fma_f32 v[80:81], v[78:79], v[80:81], s[72:73] op_sel_hi:[1,1,0]
	v_pk_mul_f32 v[122:123], v[82:83], v[82:83]
	v_pk_mul_f32 v[78:79], v[78:79], v[80:81]
	v_pk_mul_f32 v[80:81], v[100:101], v[100:101]
	s_nop 0
	v_pk_mul_f32 v[80:81], v[80:81], s[74:75] op_sel_hi:[1,0]
	s_nop 0
	v_exp_f32_e32 v80, v80
	v_exp_f32_e32 v81, v81
	s_nop 0
	v_pk_mul_f32 v[78:79], v[80:81], v[78:79]
	s_nop 0
	v_pk_mul_f32 v[80:81], v[100:101], v[78:79]
	v_pk_fma_f32 v[78:79], v[100:101], v[78:79], v[100:101] neg_lo:[1,0,0] neg_hi:[1,0,0]
	s_nop 0
	v_cndmask_b32_e32 v80, v78, v80, vcc
	v_cmp_gt_f32_e32 vcc, 0, v101
	v_and_b32_e32 v78, 0x7fffffff, v98
	s_nop 0
	v_cndmask_b32_e32 v81, v79, v81, vcc
	v_and_b32_e32 v79, 0x7fffffff, v99
	v_pk_fma_f32 v[78:79], v[78:79], s[62:63], 1.0 op_sel_hi:[1,0,0]
	v_cmp_gt_f32_e32 vcc, 0, v98
	v_rcp_f32_e32 v78, v78
	v_rcp_f32_e32 v79, v79
	s_nop 0
	v_pk_fma_f32 v[108:109], v[78:79], s[64:65], v[114:115] op_sel_hi:[1,0,0]
	s_nop 0
	v_pk_fma_f32 v[108:109], v[78:79], v[108:109], s[68:69] op_sel_hi:[1,1,0]
	s_nop 0
	v_pk_fma_f32 v[108:109], v[78:79], v[108:109], s[70:71] op_sel_hi:[1,1,0]
	s_nop 0
	v_pk_fma_f32 v[108:109], v[78:79], v[108:109], s[72:73] op_sel_hi:[1,1,0]
	s_nop 0
	v_pk_mul_f32 v[78:79], v[78:79], v[108:109]
	s_nop 0
	v_pk_mul_f32 v[78:79], v[84:85], v[78:79]
	s_nop 0
	v_pk_mul_f32 v[84:85], v[98:99], v[78:79]
	v_pk_fma_f32 v[78:79], v[98:99], v[78:79], v[98:99] neg_lo:[1,0,0] neg_hi:[1,0,0]
	s_nop 0
	v_cndmask_b32_e32 v84, v78, v84, vcc
	v_cmp_gt_f32_e32 vcc, 0, v99
	v_and_b32_e32 v78, 0x7fffffff, v106
	s_nop 0
	v_cndmask_b32_e32 v85, v79, v85, vcc
	v_and_b32_e32 v79, 0x7fffffff, v107
	v_pk_fma_f32 v[78:79], v[78:79], s[62:63], 1.0 op_sel_hi:[1,0,0]
	v_cmp_gt_f32_e32 vcc, 0, v106
	v_rcp_f32_e32 v78, v78
	v_rcp_f32_e32 v79, v79
	s_nop 0
	v_pk_fma_f32 v[108:109], v[78:79], s[64:65], v[114:115] op_sel_hi:[1,0,0]
	s_nop 0
	v_pk_fma_f32 v[108:109], v[78:79], v[108:109], s[68:69] op_sel_hi:[1,1,0]
	s_nop 0
	v_pk_fma_f32 v[108:109], v[78:79], v[108:109], s[70:71] op_sel_hi:[1,1,0]
	s_nop 0
	v_pk_fma_f32 v[108:109], v[78:79], v[108:109], s[72:73] op_sel_hi:[1,1,0]
	s_nop 0
	v_pk_mul_f32 v[78:79], v[78:79], v[108:109]
	v_pk_mul_f32 v[108:109], v[106:107], v[106:107]
	s_nop 0
	v_pk_mul_f32 v[108:109], v[108:109], s[74:75] op_sel_hi:[1,0]
	s_nop 0
	v_exp_f32_e32 v108, v108
	v_exp_f32_e32 v109, v109
	s_nop 0
	v_pk_mul_f32 v[78:79], v[108:109], v[78:79]
	s_nop 0
	v_pk_mul_f32 v[108:109], v[106:107], v[78:79]
	v_pk_fma_f32 v[78:79], v[106:107], v[78:79], v[106:107] neg_lo:[1,0,0] neg_hi:[1,0,0]
	s_nop 0
	v_cndmask_b32_e32 v108, v78, v108, vcc
	v_cmp_gt_f32_e32 vcc, 0, v107
	v_and_b32_e32 v78, 0x7fffffff, v82
	s_nop 0
	v_cndmask_b32_e32 v109, v79, v109, vcc
	v_and_b32_e32 v79, 0x7fffffff, v83
	v_pk_fma_f32 v[78:79], v[78:79], s[62:63], 1.0 op_sel_hi:[1,0,0]
	v_cmp_gt_f32_e32 vcc, 0, v82
	v_rcp_f32_e32 v78, v78
	v_rcp_f32_e32 v79, v79
	s_nop 0
	v_pk_fma_f32 v[114:115], v[78:79], s[64:65], v[114:115] op_sel_hi:[1,0,0]
	s_nop 0
	v_pk_fma_f32 v[114:115], v[78:79], v[114:115], s[68:69] op_sel_hi:[1,1,0]
	s_nop 0
	v_pk_fma_f32 v[114:115], v[78:79], v[114:115], s[70:71] op_sel_hi:[1,1,0]
	s_nop 0
	v_pk_fma_f32 v[114:115], v[78:79], v[114:115], s[72:73] op_sel_hi:[1,1,0]
	s_nop 0
	v_pk_mul_f32 v[78:79], v[78:79], v[114:115]
	v_pk_mul_f32 v[114:115], v[122:123], s[74:75] op_sel_hi:[1,0]
	s_nop 0
	v_exp_f32_e32 v114, v114
	v_exp_f32_e32 v115, v115
	s_nop 0
	v_pk_mul_f32 v[78:79], v[114:115], v[78:79]
	s_nop 0
	v_pk_mul_f32 v[114:115], v[82:83], v[78:79]
	v_pk_fma_f32 v[78:79], v[82:83], v[78:79], v[82:83] neg_lo:[1,0,0] neg_hi:[1,0,0]
	s_nop 0
	v_cndmask_b32_e32 v114, v78, v114, vcc
	v_cmp_gt_f32_e32 vcc, 0, v83
	s_nop 1
	v_cndmask_b32_e32 v115, v79, v115, vcc

; __device__ __forceinline__ unsigned cvt_pk_bf16(float lo, float hi) { unsigned r; asm volatile("v_cvt_pk_bf16_f32 %0, %1, %2" : "=v"(r) : "v"(lo), "v"(hi)); return r; }
; #define PG8_GPTR(p) ((__attribute__((address_space(1))) char*)(p))
;     __device__ __forceinline__ void operator()(const f32x4 (&acc)[2][2][4][2], const Unit& u, int wr, int wc, int fr, int fq) const {
;     ...
;                 for (int m = 0; m < 4; ++m) {
;                     const int row = row0 + ai * HALF + m * 16;
;                     const float rs = rsv[ai * 4 + m];
;                     f32x4 v0 = acc[ai][bj][m][0] * rs + s0, v1 = acc[ai][bj][m][1] * rs + s1;
;                     if (mode == 1 || mode == 2) {
;                         const float* tp = (mode == 1) ? (ropA + ((size_t)row * 32 + ((col0 & 63) >> 1)) * 2) : (ropB + ((size_t)row * 16 + ((col0 - PC_KR) >> 1)) * 2);
;                         const f32x4 c0 = *(const f32x4*)tp, c1 = *(const f32x4*)(tp + 4);
;                         f32x4 w0, w1;
;                         w0[0] = v0[0] * c0[0] - v0[1] * c0[1]; w0[1] = v0[1] * c0[0] + v0[0] * c0[1];
;                         w0[2] = v0[2] * c0[2] - v0[3] * c0[3]; w0[3] = v0[3] * c0[2] + v0[2] * c0[3];
;                         w1[0] = v1[0] * c1[0] - v1[1] * c1[1]; w1[1] = v1[1] * c1[0] + v1[0] * c1[1];
;                         w1[2] = v1[2] * c1[2] - v1[3] * c1[3]; w1[3] = v1[3] * c1[2] + v1[2] * c1[3];
;                         v0 = w0 * sc; v1 = w1 * sc;
;                     } else if (mode == 3) {
;                         const f32x2 a = gelu_pk((f32x2){v0[0], v0[1]}), bb = gelu_pk((f32x2){v0[2], v0[3]}), c = gelu_pk((f32x2){v1[0], v1[1]}), d = gelu_pk((f32x2){v1[2], v1[3]});
;                         v0 = (f32x4){a.x, a.y, bb.x, bb.y}; v1 = (f32x4){c.x, c.y, d.x, d.y};
;                     }
;                     if (stat) {
;                         const float q = (v0[0] * v0[0] + v0[1] * v0[1]) + (v0[2] * v0[2] + v0[3] * v0[3]) + (v1[0] * v1[0] + v1[1] * v1[1]) + (v1[2] * v1[2] + v1[3] * v1[3]);
;                         ssq_put(stat == 1 ? ssq_cq : ssq_ckv, row, q, fr, fq);
;                     }
;                     u32x4 w; w.x = cvt_pk_bf16(v0[0], v0[1]); w.y = cvt_pk_bf16(v0[2], v0[3]); w.z = cvt_pk_bf16(v1[0], v1[1]); w.w = cvt_pk_bf16(v1[2], v1[3]);
;                     *(gs_u32x4*)(PG8_GPTR(O) + (unsigned)(row * PJP + col0) * 2u) = w;
.LBB0_523:
	v_ffbh_u32_e32 v82, v159
	v_min_u32_e32 v98, 32, v82
	s_waitcnt lgkmcnt(0)
	v_lshlrev_b64 v[82:83], v98, v[158:159]
	v_min_u32_e32 v82, 1, v82
	v_or_b32_e32 v82, v83, v82
	v_cvt_f32_u32_e32 v82, v82
	v_sub_u32_e32 v83, 32, v98
	v_cvt_pk_bf16_f32 v106, v80, v81
	v_cvt_pk_bf16_f32 v107, v84, v85
	v_ldexp_f32 v82, v82, v83
	v_mul_f32_e32 v82, 0x33800000, v82
	v_fmamk_f32 v82, v82, 0x3a800000, v226
	v_mul_f32_e32 v83, 0x4f800000, v82
	v_cmp_gt_f32_e32 vcc, s71, v82
	v_cvt_pk_bf16_f32 v108, v108, v109
	v_cvt_pk_bf16_f32 v109, v114, v115
	s_nop 1
	v_cndmask_b32_e32 v82, v82, v83, vcc
	v_sqrt_f32_e32 v83, v82
	s_nop 0
	v_add_u32_e32 v98, -1, v83
	v_add_u32_e32 v99, 1, v83
	v_fma_f32 v100, -v98, v83, v82
	v_fma_f32 v101, -v99, v83, v82
	v_cmp_ge_f32_e64 s[18:19], 0, v100
	s_nop 1
	v_cndmask_b32_e64 v83, v83, v98, s[18:19]
	v_cmp_lt_f32_e64 s[18:19], 0, v101
	s_nop 1
	v_cndmask_b32_e64 v83, v83, v99, s[18:19]
	v_mul_f32_e32 v98, 0x37800000, v83
	v_cndmask_b32_e32 v83, v83, v98, vcc
	v_cmp_class_f32_e32 vcc, v82, v223
	s_nop 1
	v_cndmask_b32_e32 v82, v83, v82, vcc
	v_div_scale_f32 v83, s[2:3], v82, v82, 1.0
	v_rcp_f32_e32 v98, v83
	s_mov_b64 s[2:3], -1
	v_fma_f32 v99, -v83, v98, 1.0
	v_fmac_f32_e32 v98, v99, v98
	v_div_scale_f32 v99, vcc, 1.0, v82, 1.0
	v_mul_f32_e32 v100, v99, v98
	v_fma_f32 v101, -v83, v100, v99
	v_fmac_f32_e32 v100, v101, v98
	v_fma_f32 v83, -v83, v100, v99
	v_div_fmas_f32 v83, v83, v98, v100
	v_div_fixup_f32 v82, v83, v82, 1.0
	v_add_u32_e32 v100, 0x8400, v116
	v_add_lshl_u32 v80, v100, v156, 1
	v_pk_fma_f32 v[76:77], v[76:77], v[82:83], v[88:89] op_sel_hi:[1,0,1]
	v_pk_fma_f32 v[84:85], v[74:75], v[82:83], v[86:87] op_sel_hi:[1,0,1]
	v_pk_fma_f32 v[74:75], v[72:73], v[82:83], v[92:93] op_sel_hi:[1,0,1]
	v_pk_fma_f32 v[86:87], v[70:71], v[82:83], v[90:91] op_sel_hi:[1,0,1]
	s_and_b64 vcc, exec, s[14:15]
	global_store_dwordx4 v80, v[106:109], s[22:23]
	s_cbranch_vccnz .LBB0_528
	s_and_b64 vcc, exec, s[10:11]
	v_mov_b32_e32 v73, v77
	v_mov_b32_e32 v72, v76
	v_mov_b32_e32 v71, v85
	v_mov_b32_e32 v70, v84
	v_mov_b32_e32 v91, v75
	v_mov_b32_e32 v90, v74
	v_mov_b32_e32 v89, v87
	v_mov_b32_e32 v88, v86
	s_cbranch_vccnz .LBB0_526
	v_and_b32_e32 v71, 0x7fffffff, v85
	v_and_b32_e32 v70, 0x7fffffff, v84
	v_pk_fma_f32 v[70:71], v[70:71], s[62:63], 1.0 op_sel_hi:[1,0,0]
	s_mov_b32 s2, 0xbf3a00e3
	v_rcp_f32_e32 v70, v70
	v_rcp_f32_e32 v71, v71
	v_mov_b64_e32 v[80:81], s[2:3]
	v_pk_mul_f32 v[88:89], v[84:85], v[84:85]
	v_cmp_gt_f32_e32 vcc, 0, v84
	v_pk_fma_f32 v[72:73], v[70:71], s[64:65], v[80:81] op_sel_hi:[1,0,0]
	v_pk_mul_f32 v[88:89], v[88:89], s[74:75] op_sel_hi:[1,0]
	v_pk_fma_f32 v[72:73], v[70:71], v[72:73], s[68:69] op_sel_hi:[1,1,0]
	v_exp_f32_e32 v88, v88
	v_exp_f32_e32 v89, v89
	v_pk_fma_f32 v[72:73], v[70:71], v[72:73], s[70:71] op_sel_hi:[1,1,0]
	v_pk_mul_f32 v[92:93], v[86:87], v[86:87]
	v_pk_fma_f32 v[72:73], v[70:71], v[72:73], s[72:73] op_sel_hi:[1,1,0]
	v_pk_mul_f32 v[92:93], v[92:93], s[74:75] op_sel_hi:[1,0]
	v_pk_mul_f32 v[70:71], v[70:71], v[72:73]
	v_pk_mul_f32 v[72:73], v[76:77], v[76:77]
	v_pk_mul_f32 v[70:71], v[88:89], v[70:71]
	v_pk_mul_f32 v[72:73], v[72:73], s[74:75] op_sel_hi:[1,0]
	v_pk_mul_f32 v[88:89], v[84:85], v[70:71]
	v_pk_fma_f32 v[70:71], v[84:85], v[70:71], v[84:85] neg_lo:[1,0,0] neg_hi:[1,0,0]
	v_exp_f32_e32 v72, v72
	v_cndmask_b32_e32 v70, v70, v88, vcc
	v_cmp_gt_f32_e32 vcc, 0, v85
	v_and_b32_e32 v88, 0x7fffffff, v76
	v_exp_f32_e32 v73, v73
	v_cndmask_b32_e32 v71, v71, v89, vcc
	v_and_b32_e32 v89, 0x7fffffff, v77
	v_pk_fma_f32 v[88:89], v[88:89], s[62:63], 1.0 op_sel_hi:[1,0,0]
	v_cmp_gt_f32_e32 vcc, 0, v76
	v_rcp_f32_e32 v88, v88
	v_rcp_f32_e32 v89, v89
	v_exp_f32_e32 v92, v92
	v_exp_f32_e32 v93, v93
	v_pk_fma_f32 v[90:91], v[88:89], s[64:65], v[80:81] op_sel_hi:[1,0,0]
	s_nop 0
	v_pk_fma_f32 v[90:91], v[88:89], v[90:91], s[68:69] op_sel_hi:[1,1,0]
	s_nop 0
	v_pk_fma_f32 v[90:91], v[88:89], v[90:91], s[70:71] op_sel_hi:[1,1,0]
	s_nop 0
	v_pk_fma_f32 v[90:91], v[88:89], v[90:91], s[72:73] op_sel_hi:[1,1,0]
	s_nop 0
	v_pk_mul_f32 v[88:89], v[88:89], v[90:91]
	s_nop 0
	v_pk_mul_f32 v[72:73], v[72:73], v[88:89]
	s_nop 0
	v_pk_mul_f32 v[88:89], v[76:77], v[72:73]
	v_pk_fma_f32 v[72:73], v[76:77], v[72:73], v[76:77] neg_lo:[1,0,0] neg_hi:[1,0,0]
	s_nop 0
	v_cndmask_b32_e32 v72, v72, v88, vcc
	v_cmp_gt_f32_e32 vcc, 0, v77
	v_and_b32_e32 v88, 0x7fffffff, v86
	s_nop 0
	v_cndmask_b32_e32 v73, v73, v89, vcc
	v_and_b32_e32 v89, 0x7fffffff, v87
	v_pk_fma_f32 v[88:89], v[88:89], s[62:63], 1.0 op_sel_hi:[1,0,0]
	v_cmp_gt_f32_e32 vcc, 0, v86
	v_rcp_f32_e32 v88, v88
	v_rcp_f32_e32 v89, v89
	s_nop 0
	v_pk_fma_f32 v[90:91], v[88:89], s[64:65], v[80:81] op_sel_hi:[1,0,0]
	s_nop 0
	v_pk_fma_f32 v[90:91], v[88:89], v[90:91], s[68:69] op_sel_hi:[1,1,0]
	s_nop 0
	v_pk_fma_f32 v[90:91], v[88:89], v[90:91], s[70:71] op_sel_hi:[1,1,0]
	s_nop 0
	v_pk_fma_f32 v[90:91], v[88:89], v[90:91], s[72:73] op_sel_hi:[1,1,0]
	s_nop 0
	v_pk_mul_f32 v[88:89], v[88:89], v[90:91]
	v_pk_mul_f32 v[90:91], v[74:75], v[74:75]
	v_pk_mul_f32 v[88:89], v[92:93], v[88:89]
	v_pk_mul_f32 v[90:91], v[90:91], s[74:75] op_sel_hi:[1,0]
	v_pk_mul_f32 v[92:93], v[86:87], v[88:89]
	v_pk_fma_f32 v[88:89], v[86:87], v[88:89], v[86:87] neg_lo:[1,0,0] neg_hi:[1,0,0]
	v_exp_f32_e32 v90, v90
	v_cndmask_b32_e32 v88, v88, v92, vcc
	v_cmp_gt_f32_e32 vcc, 0, v87
	v_and_b32_e32 v92, 0x7fffffff, v74
	v_exp_f32_e32 v91, v91
	v_cndmask_b32_e32 v89, v89, v93, vcc
	v_and_b32_e32 v93, 0x7fffffff, v75
	v_pk_fma_f32 v[92:93], v[92:93], s[62:63], 1.0 op_sel_hi:[1,0,0]
	v_cmp_gt_f32_e32 vcc, 0, v74
	v_rcp_f32_e32 v92, v92
	v_rcp_f32_e32 v93, v93
	s_nop 0
	v_pk_fma_f32 v[80:81], v[92:93], s[64:65], v[80:81] op_sel_hi:[1,0,0]
	s_nop 0
	v_pk_fma_f32 v[80:81], v[92:93], v[80:81], s[68:69] op_sel_hi:[1,1,0]
	s_nop 0
	v_pk_fma_f32 v[80:81], v[92:93], v[80:81], s[70:71] op_sel_hi:[1,1,0]
	s_nop 0
	v_pk_fma_f32 v[80:81], v[92:93], v[80:81], s[72:73] op_sel_hi:[1,1,0]
	s_nop 0
	v_pk_mul_f32 v[80:81], v[92:93], v[80:81]
	s_nop 0
	v_pk_mul_f32 v[80:81], v[90:91], v[80:81]
	s_nop 0
	v_pk_mul_f32 v[90:91], v[74:75], v[80:81]
	v_pk_fma_f32 v[80:81], v[74:75], v[80:81], v[74:75] neg_lo:[1,0,0] neg_hi:[1,0,0]
	s_nop 0
	v_cndmask_b32_e32 v90, v80, v90, vcc
	v_cmp_gt_f32_e32 vcc, 0, v75
	s_nop 1
	v_cndmask_b32_e32 v91, v81, v91, vcc

; __device__ __forceinline__ float ssq_val(ssq_t v) { return (float)v * SSQ_IFX; }
;     __device__ __forceinline__ void operator()(const f32x4 (&acc)[2][2][4][2], const Unit& u, int wr, int wc, int fr, int fq) const {
;         const int row0 = u.pm * BM + wr * 64 + fr;
;         ssq_t sv[8]; float rsv[8];
; #pragma unroll
;         for (int i = 0; i < 8; ++i) sv[i] = ssq[row0 + (i >> 2) * HALF + (i & 3) * 16];
; #pragma unroll
;         for (int i = 0; i < 8; ++i) rsv[i] = QS_B / sqrtf(ssq_val(sv[i]) * (1.0f / 384.0f) + EPS);
; #pragma unroll
;         for (int ai = 0; ai < 2; ++ai)
; #pragma unroll
;             for (int m = 0; m < 4; ++m) {
;                 const int row = row0 + ai * HALF + m * 16;
;                 const float rs = rsv[ai * 4 + m];
; #pragma unroll
;                 for (int bj = 0; bj < 2; ++bj) {
;                     const int colw = u.pn * BM + bj * HALF + wc * 32, col0 = colw + 8 * fq;
;                     const bool rope = (colw % 96) == 64 && colw < 576;
;                     f32x4 v0 = acc[ai][bj][m][0] * rs, v1 = acc[ai][bj][m][1] * rs;
;                     if (rope) {
;                         const float* tp = ropB + ((size_t)row * 16 + ((col0 - colw) >> 1)) * 2;
;                         const f32x4 c0 = *(const f32x4*)tp, c1 = *(const f32x4*)(tp + 4);
;                         f32x4 w0, w1;
;                         w0[0] = v0[0] * c0[0] - v0[1] * c0[1]; w0[1] = v0[1] * c0[0] + v0[0] * c0[1];
;                         w0[2] = v0[2] * c0[2] - v0[3] * c0[3]; w0[3] = v0[3] * c0[2] + v0[2] * c0[3];
;                         w1[0] = v1[0] * c1[0] - v1[1] * c1[1]; w1[1] = v1[1] * c1[0] + v1[0] * c1[1];
;                         w1[2] = v1[2] * c1[2] - v1[3] * c1[3]; w1[3] = v1[3] * c1[2] + v1[2] * c1[3];
;                         v0 = w0; v1 = w1;
;                     }
.LBB0_713:
	s_lshl_b32 s2, s31, 8
	s_add_i32 s2, s2, s4
	v_mbcnt_lo_u32_b32 v0, -1, 0
	v_mbcnt_hi_u32_b32 v0, -1, v0
	s_nop 0
	v_and_or_b32 v140, v0, 15, s2
	v_ashrrev_i32_e32 v141, 31, v140
	v_lshl_add_u64 v[142:143], v[140:141], 3, s[18:19]
	flat_load_dwordx2 v[156:157], v[142:143]
	flat_load_dwordx2 v[154:155], v[142:143] offset:128
	flat_load_dwordx2 v[152:153], v[142:143] offset:256
	flat_load_dwordx2 v[150:151], v[142:143] offset:384
	flat_load_dwordx2 v[148:149], v[142:143] offset:1024
	flat_load_dwordx2 v[146:147], v[142:143] offset:1152
	flat_load_dwordx2 v[144:145], v[142:143] offset:1280
	s_nop 0
	flat_load_dwordx2 v[142:143], v[142:143] offset:1408
	v_lshrrev_b32_e32 v0, 1, v0
	v_and_b32_e32 v0, 24, v0
	v_lshlrev_b64 v[166:167], 7, v[140:141]
	s_waitcnt vmcnt(0) lgkmcnt(0)
	v_ffbh_u32_e32 v158, v157
	v_min_u32_e32 v158, 32, v158
	v_lshlrev_b64 v[156:157], v158, v[156:157]
	v_min_u32_e32 v156, 1, v156
	v_or_b32_e32 v156, v157, v156
	v_cvt_f32_u32_e32 v156, v156
	v_sub_u32_e32 v157, 32, v158
	v_ldexp_f32 v156, v156, v157
	v_mul_f32_e32 v156, 0x33800000, v156
	v_fmamk_f32 v156, v156, 0x3b2aaaab, v226
	v_cmp_gt_f32_e32 vcc, s71, v156
	v_mul_f32_e32 v157, 0x4f800000, v156
	s_nop 0
	v_cndmask_b32_e32 v156, v156, v157, vcc
	v_sqrt_f32_e32 v157, v156
	s_nop 0
	v_add_u32_e32 v158, -1, v157
	v_fma_f32 v159, -v158, v157, v156
	v_cmp_ge_f32_e64 s[8:9], 0, v159
	v_add_u32_e32 v159, 1, v157
	s_nop 0
	v_cndmask_b32_e64 v158, v157, v158, s[8:9]
	v_fma_f32 v157, -v159, v157, v156
	v_cmp_lt_f32_e64 s[8:9], 0, v157
	s_nop 1
	v_cndmask_b32_e64 v157, v158, v159, s[8:9]
	v_mul_f32_e32 v158, 0x37800000, v157
	v_cndmask_b32_e32 v157, v157, v158, vcc
	v_cmp_class_f32_e32 vcc, v156, v223
	s_nop 1
	v_cndmask_b32_e32 v156, v157, v156, vcc
	v_div_scale_f32 v157, s[2:3], v156, v156, s69
	v_rcp_f32_e32 v158, v157
	s_lshl_b32 s2, s30, 8
	s_or_b32 s30, s2, s5
	s_mul_hi_i32 s2, s30, 0x2aaaaaab
	v_fma_f32 v159, -v157, v158, 1.0
	s_lshr_b32 s3, s2, 31
	s_lshr_b32 s2, s2, 4
	v_fmac_f32_e32 v158, v159, v158
	v_div_scale_f32 v159, vcc, s69, v156, s69
	s_add_i32 s2, s2, s3
	v_mul_f32_e32 v160, v159, v158
	s_mulk_i32 s2, 0x60
	v_fma_f32 v161, -v157, v160, v159
	s_sub_i32 s2, s30, s2
	v_fmac_f32_e32 v160, v161, v158
	s_cmp_eq_u32 s2, 64
	v_fma_f32 v157, -v157, v160, v159
	s_cselect_b64 s[2:3], -1, 0
	s_cmpk_lt_i32 s30, 0x240
	v_div_fmas_f32 v157, v157, v158, v160
	s_cselect_b64 s[8:9], -1, 0
	v_div_fixup_f32 v156, v157, v156, s69
	s_and_b64 s[2:3], s[8:9], s[2:3]
	v_pk_mul_f32 v[158:159], v[126:127], v[156:157] op_sel_hi:[1,0]
	v_cndmask_b32_e64 v126, 0, 1, s[2:3]
	v_pk_mul_f32 v[162:163], v[128:129], v[156:157] op_sel_hi:[1,0]
	v_pk_mul_f32 v[160:161], v[132:133], v[156:157] op_sel_hi:[1,0]
	v_pk_mul_f32 v[130:131], v[130:131], v[156:157] op_sel_hi:[1,0]
	v_cmp_ne_u32_e64 s[8:9], 1, v126
	s_andn2_b64 vcc, exec, s[2:3]
	v_lshl_add_u64 v[132:133], s[20:21], 0, v[166:167]
	v_lshlrev_b32_e32 v126, 2, v0
	s_cbranch_vccnz .LBB0_715
	v_mov_b32_e32 v127, v1
	v_lshl_add_u64 v[128:129], v[132:133], 0, v[126:127]
	flat_load_dwordx4 v[166:169], v[128:129]
	flat_load_dwordx4 v[170:173], v[128:129] offset:16
	s_waitcnt vmcnt(0) lgkmcnt(0)
	v_pk_mul_f32 v[174:175], v[158:159], v[166:167] op_sel:[1,1] op_sel_hi:[0,1]
	v_pk_mul_f32 v[128:129], v[158:159], v[166:167]
	v_pk_fma_f32 v[158:159], v[158:159], v[166:167], v[174:175] op_sel_hi:[1,0,1]
	v_pk_mul_f32 v[176:177], v[130:131], v[170:171] op_sel:[1,1] op_sel_hi:[0,1]
	v_mul_f32_e32 v158, v163, v169
	v_pk_fma_f32 v[166:167], v[162:163], v[168:169], v[158:159] op_sel_hi:[1,1,0] neg_lo:[0,0,1] neg_hi:[0,0,1]
	v_mul_f32_e32 v158, v162, v169
	v_pk_fma_f32 v[168:169], v[162:163], v[168:169], v[158:159] op_sel:[1,0,0] op_sel_hi:[0,1,0]
	v_pk_mul_f32 v[162:163], v[130:131], v[170:171]
	v_pk_fma_f32 v[130:131], v[130:131], v[170:171], v[176:177] op_sel_hi:[1,0,1]
	v_sub_f32_e32 v158, v128, v174
	v_mul_f32_e32 v130, v161, v173
	v_pk_fma_f32 v[170:171], v[160:161], v[172:173], v[130:131] op_sel_hi:[1,1,0] neg_lo:[0,0,1] neg_hi:[0,0,1]
	v_mul_f32_e32 v130, v160, v173
	v_pk_fma_f32 v[172:173], v[160:161], v[172:173], v[130:131] op_sel:[1,0,0] op_sel_hi:[0,1,0]
	v_sub_f32_e32 v130, v162, v176
	v_mov_b32_e32 v162, v166
	v_mov_b32_e32 v163, v168
	v_mov_b32_e32 v160, v170
	v_mov_b32_e32 v161, v172

; __device__ __forceinline__ unsigned cvt_pk_bf16(float lo, float hi) { unsigned r; asm volatile("v_cvt_pk_bf16_f32 %0, %1, %2" : "=v"(r) : "v"(lo), "v"(hi)); return r; }
;     __device__ __forceinline__ void operator()(const f32x4 (&acc)[2][2][4][2], const Unit& u, int wr, int wc, int fr, int fq) const {
;     ...
;             for (int m = 0; m < 4; ++m) {
;                 const int row = row0 + ai * HALF + m * 16;
;                 const float rs = rsv[ai * 4 + m];
; #pragma unroll
;                 for (int bj = 0; bj < 2; ++bj) {
;                     const int colw = u.pn * BM + bj * HALF + wc * 32, col0 = colw + 8 * fq;
;                     const bool rope = (colw % 96) == 64 && colw < 576;
;                     f32x4 v0 = acc[ai][bj][m][0] * rs, v1 = acc[ai][bj][m][1] * rs;
;                     if (rope) {
;                         const float* tp = ropB + ((size_t)row * 16 + ((col0 - colw) >> 1)) * 2;
;                         const f32x4 c0 = *(const f32x4*)tp, c1 = *(const f32x4*)(tp + 4);
;                         f32x4 w0, w1;
;                         w0[0] = v0[0] * c0[0] - v0[1] * c0[1]; w0[1] = v0[1] * c0[0] + v0[0] * c0[1];
;                         w0[2] = v0[2] * c0[2] - v0[3] * c0[3]; w0[3] = v0[3] * c0[2] + v0[2] * c0[3];
;                         w1[0] = v1[0] * c1[0] - v1[1] * c1[1]; w1[1] = v1[1] * c1[0] + v1[0] * c1[1];
;                         w1[2] = v1[2] * c1[2] - v1[3] * c1[3]; w1[3] = v1[3] * c1[2] + v1[2] * c1[3];
;                         v0 = w0; v1 = w1;
;                     }
;                     u32x4 w; w.x = cvt_pk_bf16(v0[0], v0[1]); w.y = cvt_pk_bf16(v0[2], v0[3]); w.z = cvt_pk_bf16(v1[0], v1[1]); w.w = cvt_pk_bf16(v1[2], v1[3]);
;                     *(u32x4*)(O + (size_t)row * QMP + col0) = w;
.LBB0_717:
	v_ffbh_u32_e32 v120, v155
	v_min_u32_e32 v127, 32, v120
	v_lshlrev_b64 v[120:121], v127, v[154:155]
	v_min_u32_e32 v120, 1, v120
	v_or_b32_e32 v120, v121, v120
	v_cvt_f32_u32_e32 v120, v120
	v_sub_u32_e32 v121, 32, v127
	s_ashr_i32 s31, s30, 31
	v_cvt_pk_bf16_f32 v154, v122, v123
	v_ldexp_f32 v120, v120, v121
	v_mul_f32_e32 v120, 0x33800000, v120
	v_fmamk_f32 v120, v120, 0x3b2aaaab, v226
	v_mul_f32_e32 v121, 0x4f800000, v120
	v_cmp_gt_f32_e32 vcc, s71, v120
	v_cvt_pk_bf16_f32 v155, v158, v159
	v_cvt_pk_bf16_f32 v156, v118, v119
	v_lshl_add_u64 v[118:119], v[0:1], 0, s[30:31]
	v_lshl_add_u64 v[122:123], v[118:119], 1, v[130:131]
	v_cndmask_b32_e32 v120, v120, v121, vcc
	v_sqrt_f32_e32 v121, v120
	v_cvt_pk_bf16_f32 v157, v124, v125
	flat_store_dwordx4 v[122:123], v[154:157] offset:256
	v_or_b32_e32 v122, 16, v140
	v_add_u32_e32 v127, -1, v121
	v_add_u32_e32 v132, 1, v121
	v_fma_f32 v133, -v127, v121, v120
	v_fma_f32 v141, -v132, v121, v120
	v_cmp_ge_f32_e64 s[12:13], 0, v133
	v_ashrrev_i32_e32 v123, 31, v122
	v_lshlrev_b64 v[130:131], 7, v[122:123]
	v_cndmask_b32_e64 v121, v121, v127, s[12:13]
	v_cmp_lt_f32_e64 s[12:13], 0, v141
	s_nop 1
	v_cndmask_b32_e64 v121, v121, v132, s[12:13]
	v_mul_f32_e32 v127, 0x37800000, v121
	v_cndmask_b32_e32 v121, v121, v127, vcc
	v_cmp_class_f32_e32 vcc, v120, v223
	s_nop 1
	v_cndmask_b32_e32 v120, v121, v120, vcc
	v_div_scale_f32 v121, s[2:3], v120, v120, s69
	v_rcp_f32_e32 v127, v121
	s_nop 0
	v_fma_f32 v132, -v121, v127, 1.0
	v_fmac_f32_e32 v127, v132, v127
	v_div_scale_f32 v132, vcc, s69, v120, s69
	v_mul_f32_e32 v133, v132, v127
	v_fma_f32 v141, -v121, v133, v132
	v_fmac_f32_e32 v133, v141, v127
	v_fma_f32 v121, -v121, v133, v132
	v_div_fmas_f32 v121, v121, v127, v133
	v_div_fixup_f32 v120, v121, v120, s69
	v_pk_mul_f32 v[124:125], v[116:117], v[120:121] op_sel_hi:[1,0]
	v_pk_mul_f32 v[114:115], v[114:115], v[120:121] op_sel_hi:[1,0]
	v_pk_mul_f32 v[116:117], v[112:113], v[120:121] op_sel_hi:[1,0]
	v_pk_mul_f32 v[110:111], v[110:111], v[120:121] op_sel_hi:[1,0]
	s_and_b64 vcc, exec, s[8:9]
	v_lshl_add_u64 v[112:113], s[20:21], 0, v[130:131]
	s_cbranch_vccnz .LBB0_719
	v_mov_b32_e32 v127, v1
	v_lshl_add_u64 v[154:155], v[112:113], 0, v[126:127]
	flat_load_dwordx4 v[130:133], v[154:155]
	s_nop 0
	flat_load_dwordx4 v[154:157], v[154:155] offset:16
	s_waitcnt vmcnt(0) lgkmcnt(0)
	v_pk_mul_f32 v[160:161], v[114:115], v[130:131] op_sel:[1,1] op_sel_hi:[0,1]
	v_mul_f32_e32 v0, v125, v133
	v_pk_mul_f32 v[158:159], v[114:115], v[130:131]
	v_pk_fma_f32 v[114:115], v[114:115], v[130:131], v[160:161] op_sel_hi:[1,0,1]
	v_pk_fma_f32 v[130:131], v[124:125], v[132:133], v[0:1] op_sel_hi:[1,1,0] neg_lo:[0,0,1] neg_hi:[0,0,1]
	v_mul_f32_e32 v0, v124, v133
	v_pk_fma_f32 v[132:133], v[124:125], v[132:133], v[0:1] op_sel:[1,0,0] op_sel_hi:[0,1,0]
	v_pk_mul_f32 v[162:163], v[110:111], v[154:155] op_sel:[1,1] op_sel_hi:[0,1]
	v_mul_f32_e32 v0, v117, v157
	v_pk_mul_f32 v[124:125], v[110:111], v[154:155]
	v_pk_fma_f32 v[110:111], v[110:111], v[154:155], v[162:163] op_sel_hi:[1,0,1]
	v_pk_fma_f32 v[154:155], v[116:117], v[156:157], v[0:1] op_sel_hi:[1,1,0] neg_lo:[0,0,1] neg_hi:[0,0,1]
	v_mul_f32_e32 v0, v116, v157
	v_pk_fma_f32 v[156:157], v[116:117], v[156:157], v[0:1] op_sel:[1,0,0] op_sel_hi:[0,1,0]
	v_sub_f32_e32 v114, v158, v160
	v_sub_f32_e32 v110, v124, v162
	v_mov_b32_e32 v124, v130
	v_mov_b32_e32 v125, v132
	v_mov_b32_e32 v116, v154
	v_mov_b32_e32 v117, v156

; __device__ __forceinline__ unsigned cvt_pk_bf16(float lo, float hi) { unsigned r; asm volatile("v_cvt_pk_bf16_f32 %0, %1, %2" : "=v"(r) : "v"(lo), "v"(hi)); return r; }
;     __device__ __forceinline__ void operator()(const f32x4 (&acc)[2][2][4][2], const Unit& u, int wr, int wc, int fr, int fq) const {
;     ...
;             for (int m = 0; m < 4; ++m) {
;                 const int row = row0 + ai * HALF + m * 16;
;                 const float rs = rsv[ai * 4 + m];
; #pragma unroll
;                 for (int bj = 0; bj < 2; ++bj) {
;                     const int colw = u.pn * BM + bj * HALF + wc * 32, col0 = colw + 8 * fq;
;                     const bool rope = (colw % 96) == 64 && colw < 576;
;                     f32x4 v0 = acc[ai][bj][m][0] * rs, v1 = acc[ai][bj][m][1] * rs;
;                     if (rope) {
;                         const float* tp = ropB + ((size_t)row * 16 + ((col0 - colw) >> 1)) * 2;
;                         const f32x4 c0 = *(const f32x4*)tp, c1 = *(const f32x4*)(tp + 4);
;                         f32x4 w0, w1;
;                         w0[0] = v0[0] * c0[0] - v0[1] * c0[1]; w0[1] = v0[1] * c0[0] + v0[0] * c0[1];
;                         w0[2] = v0[2] * c0[2] - v0[3] * c0[3]; w0[3] = v0[3] * c0[2] + v0[2] * c0[3];
;                         w1[0] = v1[0] * c1[0] - v1[1] * c1[1]; w1[1] = v1[1] * c1[0] + v1[0] * c1[1];
;                         w1[2] = v1[2] * c1[2] - v1[3] * c1[3]; w1[3] = v1[3] * c1[2] + v1[2] * c1[3];
;                         v0 = w0; v1 = w1;
;                     }
;                     u32x4 w; w.x = cvt_pk_bf16(v0[0], v0[1]); w.y = cvt_pk_bf16(v0[2], v0[3]); w.z = cvt_pk_bf16(v1[0], v1[1]); w.w = cvt_pk_bf16(v1[2], v1[3]);
;                     *(u32x4*)(O + (size_t)row * QMP + col0) = w;
.LBB0_721:
	v_ffbh_u32_e32 v0, v153
	v_min_u32_e32 v0, 32, v0
	v_lshlrev_b64 v[104:105], v0, v[152:153]
	v_min_u32_e32 v104, 1, v104
	v_or_b32_e32 v104, v105, v104
	v_cvt_f32_u32_e32 v104, v104
	v_sub_u32_e32 v0, 32, v0
	v_ldexp_f32 v0, v104, v0
	v_mul_f32_e32 v0, 0x33800000, v0
	v_fmamk_f32 v0, v0, 0x3b2aaaab, v226
	v_mul_f32_e32 v104, 0x4f800000, v0
	v_cmp_gt_f32_e32 vcc, s71, v0
	s_nop 1
	v_cndmask_b32_e32 v0, v0, v104, vcc
	v_sqrt_f32_e32 v104, v0
	s_nop 0
	v_add_u32_e32 v105, -1, v104
	v_add_u32_e32 v112, 1, v104
	v_fma_f32 v113, -v105, v104, v0
	v_fma_f32 v116, -v112, v104, v0
	v_cmp_ge_f32_e64 s[12:13], 0, v113
	s_nop 1
	v_cndmask_b32_e64 v104, v104, v105, s[12:13]
	v_cmp_lt_f32_e64 s[12:13], 0, v116
	s_nop 1
	v_cndmask_b32_e64 v104, v104, v112, s[12:13]
	v_mul_f32_e32 v105, 0x37800000, v104
	v_cndmask_b32_e32 v104, v104, v105, vcc
	v_cmp_class_f32_e32 vcc, v0, v223
	s_nop 1
	v_cndmask_b32_e32 v0, v104, v0, vcc
	v_div_scale_f32 v104, s[2:3], v0, v0, s69
	v_rcp_f32_e32 v105, v104
	s_nop 0
	v_fma_f32 v112, -v104, v105, 1.0
	v_fmac_f32_e32 v105, v112, v105
	v_div_scale_f32 v112, vcc, s69, v0, s69
	v_mul_f32_e32 v113, v112, v105
	v_fma_f32 v116, -v104, v113, v112
	v_fmac_f32_e32 v113, v116, v105
	v_fma_f32 v104, -v104, v113, v112
	v_div_fmas_f32 v104, v104, v105, v113
	v_cvt_pk_bf16_f32 v112, v106, v107
	v_cvt_pk_bf16_f32 v113, v114, v115
	v_cvt_pk_bf16_f32 v114, v102, v103
	v_lshl_add_u64 v[102:103], v[118:119], 1, v[110:111]
	v_cvt_pk_bf16_f32 v115, v108, v109
	flat_store_dwordx4 v[102:103], v[112:115] offset:256
	v_or_b32_e32 v102, 32, v140
	v_ashrrev_i32_e32 v103, 31, v102
	v_div_fixup_f32 v104, v104, v0, s69
	v_lshlrev_b64 v[108:109], 7, v[102:103]
	v_pk_mul_f32 v[106:107], v[100:101], v[104:105] op_sel_hi:[1,0]
	v_pk_mul_f32 v[98:99], v[98:99], v[104:105] op_sel_hi:[1,0]
	v_pk_mul_f32 v[100:101], v[96:97], v[104:105] op_sel_hi:[1,0]
	v_pk_mul_f32 v[94:95], v[94:95], v[104:105] op_sel_hi:[1,0]
	s_and_b64 vcc, exec, s[8:9]
	v_lshl_add_u64 v[96:97], s[20:21], 0, v[108:109]
	s_cbranch_vccnz .LBB0_723
	v_mov_b32_e32 v127, v1
	v_lshl_add_u64 v[112:113], v[96:97], 0, v[126:127]
	flat_load_dwordx4 v[108:111], v[112:113]
	s_nop 0
	flat_load_dwordx4 v[112:115], v[112:113] offset:16
	s_waitcnt vmcnt(0) lgkmcnt(0)
	v_pk_mul_f32 v[120:121], v[98:99], v[108:109] op_sel:[1,1] op_sel_hi:[0,1]
	v_mul_f32_e32 v0, v107, v111
	v_pk_mul_f32 v[116:117], v[98:99], v[108:109]
	v_pk_fma_f32 v[98:99], v[98:99], v[108:109], v[120:121] op_sel_hi:[1,0,1]
	v_pk_fma_f32 v[108:109], v[106:107], v[110:111], v[0:1] op_sel_hi:[1,1,0] neg_lo:[0,0,1] neg_hi:[0,0,1]
	v_mul_f32_e32 v0, v106, v111
	v_pk_fma_f32 v[110:111], v[106:107], v[110:111], v[0:1] op_sel:[1,0,0] op_sel_hi:[0,1,0]
	v_pk_mul_f32 v[122:123], v[94:95], v[112:113] op_sel:[1,1] op_sel_hi:[0,1]
	v_mul_f32_e32 v0, v101, v115
	v_pk_mul_f32 v[106:107], v[94:95], v[112:113]
	v_pk_fma_f32 v[94:95], v[94:95], v[112:113], v[122:123] op_sel_hi:[1,0,1]
	v_pk_fma_f32 v[112:113], v[100:101], v[114:115], v[0:1] op_sel_hi:[1,1,0] neg_lo:[0,0,1] neg_hi:[0,0,1]
	v_mul_f32_e32 v0, v100, v115
	v_pk_fma_f32 v[114:115], v[100:101], v[114:115], v[0:1] op_sel:[1,0,0] op_sel_hi:[0,1,0]
	v_sub_f32_e32 v98, v116, v120
	v_sub_f32_e32 v94, v106, v122
	v_mov_b32_e32 v106, v108
	v_mov_b32_e32 v107, v110
	v_mov_b32_e32 v100, v112
	v_mov_b32_e32 v101, v114

; __device__ __forceinline__ unsigned cvt_pk_bf16(float lo, float hi) { unsigned r; asm volatile("v_cvt_pk_bf16_f32 %0, %1, %2" : "=v"(r) : "v"(lo), "v"(hi)); return r; }
;     __device__ __forceinline__ void operator()(const f32x4 (&acc)[2][2][4][2], const Unit& u, int wr, int wc, int fr, int fq) const {
;     ...
;             for (int m = 0; m < 4; ++m) {
;                 const int row = row0 + ai * HALF + m * 16;
;                 const float rs = rsv[ai * 4 + m];
; #pragma unroll
;                 for (int bj = 0; bj < 2; ++bj) {
;                     const int colw = u.pn * BM + bj * HALF + wc * 32, col0 = colw + 8 * fq;
;                     const bool rope = (colw % 96) == 64 && colw < 576;
;                     f32x4 v0 = acc[ai][bj][m][0] * rs, v1 = acc[ai][bj][m][1] * rs;
;                     if (rope) {
;                         const float* tp = ropB + ((size_t)row * 16 + ((col0 - colw) >> 1)) * 2;
;                         const f32x4 c0 = *(const f32x4*)tp, c1 = *(const f32x4*)(tp + 4);
;                         f32x4 w0, w1;
;                         w0[0] = v0[0] * c0[0] - v0[1] * c0[1]; w0[1] = v0[1] * c0[0] + v0[0] * c0[1];
;                         w0[2] = v0[2] * c0[2] - v0[3] * c0[3]; w0[3] = v0[3] * c0[2] + v0[2] * c0[3];
;                         w1[0] = v1[0] * c1[0] - v1[1] * c1[1]; w1[1] = v1[1] * c1[0] + v1[0] * c1[1];
;                         w1[2] = v1[2] * c1[2] - v1[3] * c1[3]; w1[3] = v1[3] * c1[2] + v1[2] * c1[3];
;                         v0 = w0; v1 = w1;
;                     }
;                     u32x4 w; w.x = cvt_pk_bf16(v0[0], v0[1]); w.y = cvt_pk_bf16(v0[2], v0[3]); w.z = cvt_pk_bf16(v1[0], v1[1]); w.w = cvt_pk_bf16(v1[2], v1[3]);
;                     *(u32x4*)(O + (size_t)row * QMP + col0) = w;
.LBB0_725:
	v_ffbh_u32_e32 v0, v151
	v_min_u32_e32 v0, 32, v0
	v_lshlrev_b64 v[88:89], v0, v[150:151]
	v_min_u32_e32 v88, 1, v88
	v_or_b32_e32 v88, v89, v88
	v_cvt_f32_u32_e32 v88, v88
	v_sub_u32_e32 v0, 32, v0
	v_ldexp_f32 v0, v88, v0
	v_mul_f32_e32 v0, 0x33800000, v0
	v_fmamk_f32 v0, v0, 0x3b2aaaab, v226
	v_mul_f32_e32 v88, 0x4f800000, v0
	v_cmp_gt_f32_e32 vcc, s71, v0
	s_nop 1
	v_cndmask_b32_e32 v0, v0, v88, vcc
	v_sqrt_f32_e32 v88, v0
	s_nop 0
	v_add_u32_e32 v89, -1, v88
	v_add_u32_e32 v96, 1, v88
	v_fma_f32 v97, -v89, v88, v0
	v_fma_f32 v100, -v96, v88, v0
	v_cmp_ge_f32_e64 s[12:13], 0, v97
	s_nop 1
	v_cndmask_b32_e64 v88, v88, v89, s[12:13]
	v_cmp_lt_f32_e64 s[12:13], 0, v100
	s_nop 1
	v_cndmask_b32_e64 v88, v88, v96, s[12:13]
	v_mul_f32_e32 v89, 0x37800000, v88
	v_cndmask_b32_e32 v88, v88, v89, vcc
	v_cmp_class_f32_e32 vcc, v0, v223
	s_nop 1
	v_cndmask_b32_e32 v0, v88, v0, vcc
	v_div_scale_f32 v88, s[2:3], v0, v0, s69
	v_rcp_f32_e32 v89, v88
	s_nop 0
	v_fma_f32 v96, -v88, v89, 1.0
	v_fmac_f32_e32 v89, v96, v89
	v_div_scale_f32 v96, vcc, s69, v0, s69
	v_mul_f32_e32 v97, v96, v89
	v_fma_f32 v100, -v88, v97, v96
	v_fmac_f32_e32 v97, v100, v89
	v_fma_f32 v88, -v88, v97, v96
	v_div_fmas_f32 v88, v88, v89, v97
	v_cvt_pk_bf16_f32 v96, v90, v91
	v_cvt_pk_bf16_f32 v97, v98, v99
	v_cvt_pk_bf16_f32 v98, v86, v87
	v_lshl_add_u64 v[86:87], v[118:119], 1, v[94:95]
	v_cvt_pk_bf16_f32 v99, v92, v93
	flat_store_dwordx4 v[86:87], v[96:99] offset:256
	v_or_b32_e32 v86, 48, v140
	v_ashrrev_i32_e32 v87, 31, v86
	v_div_fixup_f32 v88, v88, v0, s69
	v_lshlrev_b64 v[92:93], 7, v[86:87]
	v_pk_mul_f32 v[90:91], v[84:85], v[88:89] op_sel_hi:[1,0]
	v_pk_mul_f32 v[82:83], v[82:83], v[88:89] op_sel_hi:[1,0]
	v_pk_mul_f32 v[84:85], v[80:81], v[88:89] op_sel_hi:[1,0]
	v_pk_mul_f32 v[78:79], v[78:79], v[88:89] op_sel_hi:[1,0]
	s_and_b64 vcc, exec, s[8:9]
	v_lshl_add_u64 v[80:81], s[20:21], 0, v[92:93]
	s_cbranch_vccnz .LBB0_727
	v_mov_b32_e32 v127, v1
	v_lshl_add_u64 v[96:97], v[80:81], 0, v[126:127]
	flat_load_dwordx4 v[92:95], v[96:97]
	s_nop 0
	flat_load_dwordx4 v[96:99], v[96:97] offset:16
	s_waitcnt vmcnt(0) lgkmcnt(0)
	v_pk_mul_f32 v[102:103], v[82:83], v[92:93] op_sel:[1,1] op_sel_hi:[0,1]
	v_mul_f32_e32 v0, v91, v95
	v_pk_mul_f32 v[100:101], v[82:83], v[92:93]
	v_pk_fma_f32 v[82:83], v[82:83], v[92:93], v[102:103] op_sel_hi:[1,0,1]
	v_pk_fma_f32 v[92:93], v[90:91], v[94:95], v[0:1] op_sel_hi:[1,1,0] neg_lo:[0,0,1] neg_hi:[0,0,1]
	v_mul_f32_e32 v0, v90, v95
	v_pk_fma_f32 v[94:95], v[90:91], v[94:95], v[0:1] op_sel:[1,0,0] op_sel_hi:[0,1,0]
	v_pk_mul_f32 v[104:105], v[78:79], v[96:97] op_sel:[1,1] op_sel_hi:[0,1]
	v_mul_f32_e32 v0, v85, v99
	v_pk_mul_f32 v[90:91], v[78:79], v[96:97]
	v_pk_fma_f32 v[78:79], v[78:79], v[96:97], v[104:105] op_sel_hi:[1,0,1]
	v_pk_fma_f32 v[96:97], v[84:85], v[98:99], v[0:1] op_sel_hi:[1,1,0] neg_lo:[0,0,1] neg_hi:[0,0,1]
	v_mul_f32_e32 v0, v84, v99
	v_pk_fma_f32 v[98:99], v[84:85], v[98:99], v[0:1] op_sel:[1,0,0] op_sel_hi:[0,1,0]
	v_sub_f32_e32 v82, v100, v102
	v_sub_f32_e32 v78, v90, v104
	v_mov_b32_e32 v90, v92
	v_mov_b32_e32 v91, v94
	v_mov_b32_e32 v84, v96
	v_mov_b32_e32 v85, v98

; __device__ __forceinline__ unsigned cvt_pk_bf16(float lo, float hi) { unsigned r; asm volatile("v_cvt_pk_bf16_f32 %0, %1, %2" : "=v"(r) : "v"(lo), "v"(hi)); return r; }
;     __device__ __forceinline__ void operator()(const f32x4 (&acc)[2][2][4][2], const Unit& u, int wr, int wc, int fr, int fq) const {
;     ...
;             for (int m = 0; m < 4; ++m) {
;                 const int row = row0 + ai * HALF + m * 16;
;                 const float rs = rsv[ai * 4 + m];
; #pragma unroll
;                 for (int bj = 0; bj < 2; ++bj) {
;                     const int colw = u.pn * BM + bj * HALF + wc * 32, col0 = colw + 8 * fq;
;                     const bool rope = (colw % 96) == 64 && colw < 576;
;                     f32x4 v0 = acc[ai][bj][m][0] * rs, v1 = acc[ai][bj][m][1] * rs;
;                     if (rope) {
;                         const float* tp = ropB + ((size_t)row * 16 + ((col0 - colw) >> 1)) * 2;
;                         const f32x4 c0 = *(const f32x4*)tp, c1 = *(const f32x4*)(tp + 4);
;                         f32x4 w0, w1;
;                         w0[0] = v0[0] * c0[0] - v0[1] * c0[1]; w0[1] = v0[1] * c0[0] + v0[0] * c0[1];
;                         w0[2] = v0[2] * c0[2] - v0[3] * c0[3]; w0[3] = v0[3] * c0[2] + v0[2] * c0[3];
;                         w1[0] = v1[0] * c1[0] - v1[1] * c1[1]; w1[1] = v1[1] * c1[0] + v1[0] * c1[1];
;                         w1[2] = v1[2] * c1[2] - v1[3] * c1[3]; w1[3] = v1[3] * c1[2] + v1[2] * c1[3];
;                         v0 = w0; v1 = w1;
;                     }
;                     u32x4 w; w.x = cvt_pk_bf16(v0[0], v0[1]); w.y = cvt_pk_bf16(v0[2], v0[3]); w.z = cvt_pk_bf16(v1[0], v1[1]); w.w = cvt_pk_bf16(v1[2], v1[3]);
;                     *(u32x4*)(O + (size_t)row * QMP + col0) = w;
.LBB0_729:
	v_ffbh_u32_e32 v0, v149
	v_min_u32_e32 v0, 32, v0
	v_lshlrev_b64 v[76:77], v0, v[148:149]
	v_min_u32_e32 v76, 1, v76
	v_or_b32_e32 v76, v77, v76
	v_cvt_f32_u32_e32 v76, v76
	v_sub_u32_e32 v0, 32, v0
	v_ldexp_f32 v0, v76, v0
	v_mul_f32_e32 v0, 0x33800000, v0
	v_fmamk_f32 v0, v0, 0x3b2aaaab, v226
	v_mul_f32_e32 v76, 0x4f800000, v0
	v_cmp_gt_f32_e32 vcc, s71, v0
	s_nop 1
	v_cndmask_b32_e32 v0, v0, v76, vcc
	v_sqrt_f32_e32 v76, v0
	s_nop 0
	v_add_u32_e32 v77, -1, v76
	v_add_u32_e32 v80, 1, v76
	v_fma_f32 v81, -v77, v76, v0
	v_fma_f32 v84, -v80, v76, v0
	v_cmp_ge_f32_e64 s[12:13], 0, v81
	s_nop 1
	v_cndmask_b32_e64 v76, v76, v77, s[12:13]
	v_cmp_lt_f32_e64 s[12:13], 0, v84
	s_nop 1
	v_cndmask_b32_e64 v76, v76, v80, s[12:13]
	v_mul_f32_e32 v77, 0x37800000, v76
	v_cndmask_b32_e32 v76, v76, v77, vcc
	v_cmp_class_f32_e32 vcc, v0, v223
	v_add_u32_e32 v80, 0x80, v140
	v_ashrrev_i32_e32 v81, 31, v80
	v_cndmask_b32_e32 v0, v76, v0, vcc
	v_div_scale_f32 v76, s[2:3], v0, v0, s69
	v_rcp_f32_e32 v77, v76
	s_nop 0
	v_fma_f32 v84, -v76, v77, 1.0
	v_fmac_f32_e32 v77, v84, v77
	v_div_scale_f32 v84, vcc, s69, v0, s69
	v_mul_f32_e32 v85, v84, v77
	v_fma_f32 v86, -v76, v85, v84
	v_fmac_f32_e32 v85, v86, v77
	v_fma_f32 v76, -v76, v85, v84
	v_div_fmas_f32 v76, v76, v77, v85
	v_div_fixup_f32 v76, v76, v0, s69
	v_cvt_pk_bf16_f32 v84, v74, v75
	v_cvt_pk_bf16_f32 v85, v82, v83
	v_cvt_pk_bf16_f32 v86, v70, v71
	v_cvt_pk_bf16_f32 v87, v72, v73
	v_lshl_add_u64 v[70:71], v[118:119], 1, v[78:79]
	v_lshlrev_b64 v[72:73], 7, v[80:81]
	flat_store_dwordx4 v[70:71], v[84:87] offset:256
	v_pk_mul_f32 v[70:71], v[68:69], v[76:77] op_sel_hi:[1,0]
	v_pk_mul_f32 v[66:67], v[66:67], v[76:77] op_sel_hi:[1,0]
	v_pk_mul_f32 v[68:69], v[64:65], v[76:77] op_sel_hi:[1,0]
	v_pk_mul_f32 v[62:63], v[62:63], v[76:77] op_sel_hi:[1,0]
	s_and_b64 vcc, exec, s[8:9]
	v_lshl_add_u64 v[64:65], s[20:21], 0, v[72:73]
	s_cbranch_vccnz .LBB0_731
	v_mov_b32_e32 v127, v1
	v_lshl_add_u64 v[78:79], v[64:65], 0, v[126:127]
	flat_load_dwordx4 v[72:75], v[78:79]
	flat_load_dwordx4 v[82:85], v[78:79] offset:16
	s_waitcnt vmcnt(0) lgkmcnt(0)
	v_pk_mul_f32 v[86:87], v[66:67], v[72:73] op_sel:[1,1] op_sel_hi:[0,1]
	v_mul_f32_e32 v0, v71, v75
	v_pk_mul_f32 v[78:79], v[66:67], v[72:73]
	v_pk_fma_f32 v[66:67], v[66:67], v[72:73], v[86:87] op_sel_hi:[1,0,1]
	v_pk_fma_f32 v[72:73], v[70:71], v[74:75], v[0:1] op_sel_hi:[1,1,0] neg_lo:[0,0,1] neg_hi:[0,0,1]
	v_mul_f32_e32 v0, v70, v75
	v_pk_fma_f32 v[74:75], v[70:71], v[74:75], v[0:1] op_sel:[1,0,0] op_sel_hi:[0,1,0]
	v_pk_mul_f32 v[88:89], v[62:63], v[82:83] op_sel:[1,1] op_sel_hi:[0,1]
	v_mul_f32_e32 v0, v69, v85
	v_pk_mul_f32 v[70:71], v[62:63], v[82:83]
	v_pk_fma_f32 v[62:63], v[62:63], v[82:83], v[88:89] op_sel_hi:[1,0,1]
	v_pk_fma_f32 v[82:83], v[68:69], v[84:85], v[0:1] op_sel_hi:[1,1,0] neg_lo:[0,0,1] neg_hi:[0,0,1]
	v_mul_f32_e32 v0, v68, v85
	v_pk_fma_f32 v[84:85], v[68:69], v[84:85], v[0:1] op_sel:[1,0,0] op_sel_hi:[0,1,0]
	v_sub_f32_e32 v66, v78, v86
	v_sub_f32_e32 v62, v70, v88
	v_mov_b32_e32 v70, v72
	v_mov_b32_e32 v71, v74
	v_mov_b32_e32 v68, v82
	v_mov_b32_e32 v69, v84

; __device__ __forceinline__ unsigned cvt_pk_bf16(float lo, float hi) { unsigned r; asm volatile("v_cvt_pk_bf16_f32 %0, %1, %2" : "=v"(r) : "v"(lo), "v"(hi)); return r; }
;     __device__ __forceinline__ void operator()(const f32x4 (&acc)[2][2][4][2], const Unit& u, int wr, int wc, int fr, int fq) const {
;     ...
;             for (int m = 0; m < 4; ++m) {
;                 const int row = row0 + ai * HALF + m * 16;
;                 const float rs = rsv[ai * 4 + m];
; #pragma unroll
;                 for (int bj = 0; bj < 2; ++bj) {
;                     const int colw = u.pn * BM + bj * HALF + wc * 32, col0 = colw + 8 * fq;
;                     const bool rope = (colw % 96) == 64 && colw < 576;
;                     f32x4 v0 = acc[ai][bj][m][0] * rs, v1 = acc[ai][bj][m][1] * rs;
;                     if (rope) {
;                         const float* tp = ropB + ((size_t)row * 16 + ((col0 - colw) >> 1)) * 2;
;                         const f32x4 c0 = *(const f32x4*)tp, c1 = *(const f32x4*)(tp + 4);
;                         f32x4 w0, w1;
;                         w0[0] = v0[0] * c0[0] - v0[1] * c0[1]; w0[1] = v0[1] * c0[0] + v0[0] * c0[1];
;                         w0[2] = v0[2] * c0[2] - v0[3] * c0[3]; w0[3] = v0[3] * c0[2] + v0[2] * c0[3];
;                         w1[0] = v1[0] * c1[0] - v1[1] * c1[1]; w1[1] = v1[1] * c1[0] + v1[0] * c1[1];
;                         w1[2] = v1[2] * c1[2] - v1[3] * c1[3]; w1[3] = v1[3] * c1[2] + v1[2] * c1[3];
;                         v0 = w0; v1 = w1;
;                     }
;                     u32x4 w; w.x = cvt_pk_bf16(v0[0], v0[1]); w.y = cvt_pk_bf16(v0[2], v0[3]); w.z = cvt_pk_bf16(v1[0], v1[1]); w.w = cvt_pk_bf16(v1[2], v1[3]);
;                     *(u32x4*)(O + (size_t)row * QMP + col0) = w;
.LBB0_733:
	v_ffbh_u32_e32 v0, v147
	v_min_u32_e32 v0, 32, v0
	v_lshlrev_b64 v[56:57], v0, v[146:147]
	v_min_u32_e32 v56, 1, v56
	v_or_b32_e32 v56, v57, v56
	v_cvt_f32_u32_e32 v56, v56
	v_sub_u32_e32 v0, 32, v0
	v_ldexp_f32 v0, v56, v0
	v_mul_f32_e32 v0, 0x33800000, v0
	v_fmamk_f32 v0, v0, 0x3b2aaaab, v226
	v_mul_f32_e32 v56, 0x4f800000, v0
	v_cmp_gt_f32_e32 vcc, s71, v0
	s_nop 1
	v_cndmask_b32_e32 v0, v0, v56, vcc
	v_sqrt_f32_e32 v56, v0
	s_nop 0
	v_add_u32_e32 v57, -1, v56
	v_add_u32_e32 v64, 1, v56
	v_fma_f32 v65, -v57, v56, v0
	v_fma_f32 v68, -v64, v56, v0
	v_cmp_ge_f32_e64 s[12:13], 0, v65
	s_nop 1
	v_cndmask_b32_e64 v56, v56, v57, s[12:13]
	v_cmp_lt_f32_e64 s[12:13], 0, v68
	s_nop 1
	v_cndmask_b32_e64 v56, v56, v64, s[12:13]
	v_mul_f32_e32 v57, 0x37800000, v56
	v_cndmask_b32_e32 v56, v56, v57, vcc
	v_cmp_class_f32_e32 vcc, v0, v223
	s_nop 1
	v_cndmask_b32_e32 v0, v56, v0, vcc
	v_div_scale_f32 v56, s[2:3], v0, v0, s69
	v_rcp_f32_e32 v57, v56
	s_nop 0
	v_fma_f32 v64, -v56, v57, 1.0
	v_fmac_f32_e32 v57, v64, v57
	v_div_scale_f32 v64, vcc, s69, v0, s69
	v_mul_f32_e32 v65, v64, v57
	v_fma_f32 v68, -v56, v65, v64
	v_fmac_f32_e32 v65, v68, v57
	v_fma_f32 v56, -v56, v65, v64
	v_div_fmas_f32 v56, v56, v57, v65
	v_cvt_pk_bf16_f32 v64, v58, v59
	v_cvt_pk_bf16_f32 v65, v66, v67
	v_cvt_pk_bf16_f32 v66, v54, v55
	v_lshl_add_u64 v[54:55], v[118:119], 1, v[62:63]
	v_cvt_pk_bf16_f32 v67, v60, v61
	flat_store_dwordx4 v[54:55], v[64:67] offset:256
	v_add_u32_e32 v54, 0x90, v140
	v_ashrrev_i32_e32 v55, 31, v54
	v_div_fixup_f32 v56, v56, v0, s69
	v_lshlrev_b64 v[60:61], 7, v[54:55]
	v_pk_mul_f32 v[58:59], v[52:53], v[56:57] op_sel_hi:[1,0]
	v_pk_mul_f32 v[50:51], v[50:51], v[56:57] op_sel_hi:[1,0]
	v_pk_mul_f32 v[52:53], v[48:49], v[56:57] op_sel_hi:[1,0]
	v_pk_mul_f32 v[46:47], v[46:47], v[56:57] op_sel_hi:[1,0]
	s_and_b64 vcc, exec, s[8:9]
	v_lshl_add_u64 v[48:49], s[20:21], 0, v[60:61]
	s_cbranch_vccnz .LBB0_735
	v_mov_b32_e32 v127, v1
	v_lshl_add_u64 v[64:65], v[48:49], 0, v[126:127]
	flat_load_dwordx4 v[60:63], v[64:65]
	s_nop 0
	flat_load_dwordx4 v[64:67], v[64:65] offset:16
	s_waitcnt vmcnt(0) lgkmcnt(0)
	v_pk_mul_f32 v[70:71], v[50:51], v[60:61] op_sel:[1,1] op_sel_hi:[0,1]
	v_mul_f32_e32 v0, v59, v63
	v_pk_mul_f32 v[68:69], v[50:51], v[60:61]
	v_pk_fma_f32 v[50:51], v[50:51], v[60:61], v[70:71] op_sel_hi:[1,0,1]
	v_pk_fma_f32 v[60:61], v[58:59], v[62:63], v[0:1] op_sel_hi:[1,1,0] neg_lo:[0,0,1] neg_hi:[0,0,1]
	v_mul_f32_e32 v0, v58, v63
	v_pk_fma_f32 v[62:63], v[58:59], v[62:63], v[0:1] op_sel:[1,0,0] op_sel_hi:[0,1,0]
	v_pk_mul_f32 v[72:73], v[46:47], v[64:65] op_sel:[1,1] op_sel_hi:[0,1]
	v_mul_f32_e32 v0, v53, v67
	v_pk_mul_f32 v[58:59], v[46:47], v[64:65]
	v_pk_fma_f32 v[46:47], v[46:47], v[64:65], v[72:73] op_sel_hi:[1,0,1]
	v_pk_fma_f32 v[64:65], v[52:53], v[66:67], v[0:1] op_sel_hi:[1,1,0] neg_lo:[0,0,1] neg_hi:[0,0,1]
	v_mul_f32_e32 v0, v52, v67
	v_pk_fma_f32 v[66:67], v[52:53], v[66:67], v[0:1] op_sel:[1,0,0] op_sel_hi:[0,1,0]
	v_sub_f32_e32 v50, v68, v70
	v_sub_f32_e32 v46, v58, v72
	v_mov_b32_e32 v58, v60
	v_mov_b32_e32 v59, v62
	v_mov_b32_e32 v52, v64
	v_mov_b32_e32 v53, v66

; __device__ __forceinline__ unsigned cvt_pk_bf16(float lo, float hi) { unsigned r; asm volatile("v_cvt_pk_bf16_f32 %0, %1, %2" : "=v"(r) : "v"(lo), "v"(hi)); return r; }
;     __device__ __forceinline__ void operator()(const f32x4 (&acc)[2][2][4][2], const Unit& u, int wr, int wc, int fr, int fq) const {
;     ...
;             for (int m = 0; m < 4; ++m) {
;                 const int row = row0 + ai * HALF + m * 16;
;                 const float rs = rsv[ai * 4 + m];
; #pragma unroll
;                 for (int bj = 0; bj < 2; ++bj) {
;                     const int colw = u.pn * BM + bj * HALF + wc * 32, col0 = colw + 8 * fq;
;                     const bool rope = (colw % 96) == 64 && colw < 576;
;                     f32x4 v0 = acc[ai][bj][m][0] * rs, v1 = acc[ai][bj][m][1] * rs;
;                     if (rope) {
;                         const float* tp = ropB + ((size_t)row * 16 + ((col0 - colw) >> 1)) * 2;
;                         const f32x4 c0 = *(const f32x4*)tp, c1 = *(const f32x4*)(tp + 4);
;                         f32x4 w0, w1;
;                         w0[0] = v0[0] * c0[0] - v0[1] * c0[1]; w0[1] = v0[1] * c0[0] + v0[0] * c0[1];
;                         w0[2] = v0[2] * c0[2] - v0[3] * c0[3]; w0[3] = v0[3] * c0[2] + v0[2] * c0[3];
;                         w1[0] = v1[0] * c1[0] - v1[1] * c1[1]; w1[1] = v1[1] * c1[0] + v1[0] * c1[1];
;                         w1[2] = v1[2] * c1[2] - v1[3] * c1[3]; w1[3] = v1[3] * c1[2] + v1[2] * c1[3];
;                         v0 = w0; v1 = w1;
;                     }
;                     u32x4 w; w.x = cvt_pk_bf16(v0[0], v0[1]); w.y = cvt_pk_bf16(v0[2], v0[3]); w.z = cvt_pk_bf16(v1[0], v1[1]); w.w = cvt_pk_bf16(v1[2], v1[3]);
;                     *(u32x4*)(O + (size_t)row * QMP + col0) = w;
.LBB0_737:
	v_ffbh_u32_e32 v0, v145
	v_min_u32_e32 v0, 32, v0
	v_lshlrev_b64 v[40:41], v0, v[144:145]
	v_min_u32_e32 v40, 1, v40
	v_or_b32_e32 v40, v41, v40
	v_cvt_f32_u32_e32 v40, v40
	v_sub_u32_e32 v0, 32, v0
	v_ldexp_f32 v0, v40, v0
	v_mul_f32_e32 v0, 0x33800000, v0
	v_fmamk_f32 v0, v0, 0x3b2aaaab, v226
	v_mul_f32_e32 v40, 0x4f800000, v0
	v_cmp_gt_f32_e32 vcc, s71, v0
	s_nop 1
	v_cndmask_b32_e32 v0, v0, v40, vcc
	v_sqrt_f32_e32 v40, v0
	s_nop 0
	v_add_u32_e32 v41, -1, v40
	v_add_u32_e32 v48, 1, v40
	v_fma_f32 v49, -v41, v40, v0
	v_fma_f32 v52, -v48, v40, v0
	v_cmp_ge_f32_e64 s[12:13], 0, v49
	s_nop 1
	v_cndmask_b32_e64 v40, v40, v41, s[12:13]
	v_cmp_lt_f32_e64 s[12:13], 0, v52
	s_nop 1
	v_cndmask_b32_e64 v40, v40, v48, s[12:13]
	v_mul_f32_e32 v41, 0x37800000, v40
	v_cndmask_b32_e32 v40, v40, v41, vcc
	v_cmp_class_f32_e32 vcc, v0, v223
	s_nop 1
	v_cndmask_b32_e32 v0, v40, v0, vcc
	v_div_scale_f32 v40, s[2:3], v0, v0, s69
	v_rcp_f32_e32 v41, v40
	s_nop 0
	v_fma_f32 v48, -v40, v41, 1.0
	v_fmac_f32_e32 v41, v48, v41
	v_div_scale_f32 v48, vcc, s69, v0, s69
	v_mul_f32_e32 v49, v48, v41
	v_fma_f32 v52, -v40, v49, v48
	v_fmac_f32_e32 v49, v52, v41
	v_fma_f32 v40, -v40, v49, v48
	v_div_fmas_f32 v40, v40, v41, v49
	v_cvt_pk_bf16_f32 v48, v42, v43
	v_cvt_pk_bf16_f32 v49, v50, v51
	v_cvt_pk_bf16_f32 v50, v38, v39
	v_lshl_add_u64 v[38:39], v[118:119], 1, v[46:47]
	v_cvt_pk_bf16_f32 v51, v44, v45
	flat_store_dwordx4 v[38:39], v[48:51] offset:256
	v_add_u32_e32 v38, 0xa0, v140
	v_ashrrev_i32_e32 v39, 31, v38
	v_div_fixup_f32 v40, v40, v0, s69
	v_lshlrev_b64 v[44:45], 7, v[38:39]
	v_pk_mul_f32 v[42:43], v[36:37], v[40:41] op_sel_hi:[1,0]
	v_pk_mul_f32 v[34:35], v[34:35], v[40:41] op_sel_hi:[1,0]
	v_pk_mul_f32 v[36:37], v[32:33], v[40:41] op_sel_hi:[1,0]
	v_pk_mul_f32 v[30:31], v[30:31], v[40:41] op_sel_hi:[1,0]
	s_and_b64 vcc, exec, s[8:9]
	v_lshl_add_u64 v[32:33], s[20:21], 0, v[44:45]
	s_cbranch_vccnz .LBB0_739
	v_mov_b32_e32 v127, v1
	v_lshl_add_u64 v[48:49], v[32:33], 0, v[126:127]
	flat_load_dwordx4 v[44:47], v[48:49]
	s_nop 0
	flat_load_dwordx4 v[48:51], v[48:49] offset:16
	s_waitcnt vmcnt(0) lgkmcnt(0)
	v_pk_mul_f32 v[54:55], v[34:35], v[44:45] op_sel:[1,1] op_sel_hi:[0,1]
	v_mul_f32_e32 v0, v43, v47
	v_pk_mul_f32 v[52:53], v[34:35], v[44:45]
	v_pk_fma_f32 v[34:35], v[34:35], v[44:45], v[54:55] op_sel_hi:[1,0,1]
	v_pk_fma_f32 v[44:45], v[42:43], v[46:47], v[0:1] op_sel_hi:[1,1,0] neg_lo:[0,0,1] neg_hi:[0,0,1]
	v_mul_f32_e32 v0, v42, v47
	v_pk_fma_f32 v[46:47], v[42:43], v[46:47], v[0:1] op_sel:[1,0,0] op_sel_hi:[0,1,0]
	v_pk_mul_f32 v[56:57], v[30:31], v[48:49] op_sel:[1,1] op_sel_hi:[0,1]
	v_mul_f32_e32 v0, v37, v51
	v_pk_mul_f32 v[42:43], v[30:31], v[48:49]
	v_pk_fma_f32 v[30:31], v[30:31], v[48:49], v[56:57] op_sel_hi:[1,0,1]
	v_pk_fma_f32 v[48:49], v[36:37], v[50:51], v[0:1] op_sel_hi:[1,1,0] neg_lo:[0,0,1] neg_hi:[0,0,1]
	v_mul_f32_e32 v0, v36, v51
	v_pk_fma_f32 v[50:51], v[36:37], v[50:51], v[0:1] op_sel:[1,0,0] op_sel_hi:[0,1,0]
	v_sub_f32_e32 v34, v52, v54
	v_sub_f32_e32 v30, v42, v56
	v_mov_b32_e32 v42, v44
	v_mov_b32_e32 v43, v46
	v_mov_b32_e32 v36, v48
	v_mov_b32_e32 v37, v50

; __device__ __forceinline__ unsigned cvt_pk_bf16(float lo, float hi) { unsigned r; asm volatile("v_cvt_pk_bf16_f32 %0, %1, %2" : "=v"(r) : "v"(lo), "v"(hi)); return r; }
;     __device__ __forceinline__ void operator()(const f32x4 (&acc)[2][2][4][2], const Unit& u, int wr, int wc, int fr, int fq) const {
;     ...
;             for (int m = 0; m < 4; ++m) {
;                 const int row = row0 + ai * HALF + m * 16;
;                 const float rs = rsv[ai * 4 + m];
; #pragma unroll
;                 for (int bj = 0; bj < 2; ++bj) {
;                     const int colw = u.pn * BM + bj * HALF + wc * 32, col0 = colw + 8 * fq;
;                     const bool rope = (colw % 96) == 64 && colw < 576;
;                     f32x4 v0 = acc[ai][bj][m][0] * rs, v1 = acc[ai][bj][m][1] * rs;
;                     if (rope) {
;                         const float* tp = ropB + ((size_t)row * 16 + ((col0 - colw) >> 1)) * 2;
;                         const f32x4 c0 = *(const f32x4*)tp, c1 = *(const f32x4*)(tp + 4);
;                         f32x4 w0, w1;
;                         w0[0] = v0[0] * c0[0] - v0[1] * c0[1]; w0[1] = v0[1] * c0[0] + v0[0] * c0[1];
;                         w0[2] = v0[2] * c0[2] - v0[3] * c0[3]; w0[3] = v0[3] * c0[2] + v0[2] * c0[3];
;                         w1[0] = v1[0] * c1[0] - v1[1] * c1[1]; w1[1] = v1[1] * c1[0] + v1[0] * c1[1];
;                         w1[2] = v1[2] * c1[2] - v1[3] * c1[3]; w1[3] = v1[3] * c1[2] + v1[2] * c1[3];
;                         v0 = w0; v1 = w1;
;                     }
;                     u32x4 w; w.x = cvt_pk_bf16(v0[0], v0[1]); w.y = cvt_pk_bf16(v0[2], v0[3]); w.z = cvt_pk_bf16(v1[0], v1[1]); w.w = cvt_pk_bf16(v1[2], v1[3]);
;                     *(u32x4*)(O + (size_t)row * QMP + col0) = w;
.LBB0_741:
	v_ffbh_u32_e32 v0, v143
	v_min_u32_e32 v0, 32, v0
	v_lshlrev_b64 v[24:25], v0, v[142:143]
	v_min_u32_e32 v24, 1, v24
	v_or_b32_e32 v24, v25, v24
	v_cvt_f32_u32_e32 v24, v24
	v_sub_u32_e32 v0, 32, v0
	v_ldexp_f32 v0, v24, v0
	v_mul_f32_e32 v0, 0x33800000, v0
	v_fmamk_f32 v0, v0, 0x3b2aaaab, v226
	v_mul_f32_e32 v24, 0x4f800000, v0
	v_cmp_gt_f32_e32 vcc, s71, v0
	s_nop 1
	v_cndmask_b32_e32 v0, v0, v24, vcc
	v_sqrt_f32_e32 v24, v0
	s_nop 0
	v_add_u32_e32 v25, -1, v24
	v_add_u32_e32 v32, 1, v24
	v_fma_f32 v33, -v25, v24, v0
	v_fma_f32 v36, -v32, v24, v0
	v_cmp_ge_f32_e64 s[12:13], 0, v33
	s_nop 1
	v_cndmask_b32_e64 v24, v24, v25, s[12:13]
	v_cmp_lt_f32_e64 s[12:13], 0, v36
	s_nop 1
	v_cndmask_b32_e64 v24, v24, v32, s[12:13]
	v_mul_f32_e32 v25, 0x37800000, v24
	v_cndmask_b32_e32 v24, v24, v25, vcc
	v_cmp_class_f32_e32 vcc, v0, v223
	s_nop 1
	v_cndmask_b32_e32 v0, v24, v0, vcc
	v_div_scale_f32 v24, s[2:3], v0, v0, s69
	v_rcp_f32_e32 v25, v24
	s_nop 0
	v_fma_f32 v32, -v24, v25, 1.0
	v_fmac_f32_e32 v25, v32, v25
	v_div_scale_f32 v32, vcc, s69, v0, s69
	v_mul_f32_e32 v33, v32, v25
	v_fma_f32 v36, -v24, v33, v32
	v_fmac_f32_e32 v33, v36, v25
	v_fma_f32 v24, -v24, v33, v32
	v_div_fmas_f32 v24, v24, v25, v33
	v_cvt_pk_bf16_f32 v32, v26, v27
	v_cvt_pk_bf16_f32 v33, v34, v35
	v_cvt_pk_bf16_f32 v34, v22, v23
	v_lshl_add_u64 v[22:23], v[118:119], 1, v[30:31]
	v_cvt_pk_bf16_f32 v35, v28, v29
	flat_store_dwordx4 v[22:23], v[32:35] offset:256
	v_add_u32_e32 v22, 0xb0, v140
	v_ashrrev_i32_e32 v23, 31, v22
	v_div_fixup_f32 v24, v24, v0, s69
	v_lshlrev_b64 v[28:29], 7, v[22:23]
	v_pk_mul_f32 v[26:27], v[20:21], v[24:25] op_sel_hi:[1,0]
	v_pk_mul_f32 v[18:19], v[18:19], v[24:25] op_sel_hi:[1,0]
	v_pk_mul_f32 v[20:21], v[12:13], v[24:25] op_sel_hi:[1,0]
	v_pk_mul_f32 v[12:13], v[10:11], v[24:25] op_sel_hi:[1,0]
	s_and_b64 vcc, exec, s[8:9]
	v_lshl_add_u64 v[10:11], s[20:21], 0, v[28:29]
	s_cbranch_vccnz .LBB0_743
	v_mov_b32_e32 v127, v1
	v_lshl_add_u64 v[32:33], v[10:11], 0, v[126:127]
	flat_load_dwordx4 v[28:31], v[32:33]
	s_nop 0
	flat_load_dwordx4 v[32:35], v[32:33] offset:16
	s_waitcnt vmcnt(0) lgkmcnt(0)
	v_pk_mul_f32 v[38:39], v[18:19], v[28:29] op_sel:[1,1] op_sel_hi:[0,1]
	v_mul_f32_e32 v0, v27, v31
	v_pk_mul_f32 v[36:37], v[18:19], v[28:29]
	v_pk_fma_f32 v[18:19], v[18:19], v[28:29], v[38:39] op_sel_hi:[1,0,1]
	v_pk_fma_f32 v[28:29], v[26:27], v[30:31], v[0:1] op_sel_hi:[1,1,0] neg_lo:[0,0,1] neg_hi:[0,0,1]
	v_mul_f32_e32 v0, v26, v31
	v_pk_fma_f32 v[30:31], v[26:27], v[30:31], v[0:1] op_sel:[1,0,0] op_sel_hi:[0,1,0]
	v_pk_mul_f32 v[40:41], v[12:13], v[32:33] op_sel:[1,1] op_sel_hi:[0,1]
	v_mul_f32_e32 v0, v21, v35
	v_pk_mul_f32 v[26:27], v[12:13], v[32:33]
	v_pk_fma_f32 v[12:13], v[12:13], v[32:33], v[40:41] op_sel_hi:[1,0,1]
	v_pk_fma_f32 v[32:33], v[20:21], v[34:35], v[0:1] op_sel_hi:[1,1,0] neg_lo:[0,0,1] neg_hi:[0,0,1]
	v_mul_f32_e32 v0, v20, v35
	v_pk_fma_f32 v[34:35], v[20:21], v[34:35], v[0:1] op_sel:[1,0,0] op_sel_hi:[0,1,0]
	v_sub_f32_e32 v18, v36, v38
	v_sub_f32_e32 v12, v26, v40
	v_mov_b32_e32 v26, v28
	v_mov_b32_e32 v27, v30
	v_mov_b32_e32 v20, v32
	v_mov_b32_e32 v21, v34

; __device__ __forceinline__ unsigned cvt_pk_bf16(float lo, float hi) { unsigned r; asm volatile("v_cvt_pk_bf16_f32 %0, %1, %2" : "=v"(r) : "v"(lo), "v"(hi)); return r; }
; __device__ __forceinline__ float ssq_val(ssq_t v) { return (float)v * SSQ_IFX; }
;     __device__ __forceinline__ void operator()(const f32x4 (&acc)[2][2][4][2], const Unit& u, int wr, int wc, int fr, int fq) const {
;         const int row0 = u.pm * BM + wr * 64 + fr;
;         ssq_t sv[8]; float rsv[8];
; #pragma unroll
;         for (int i = 0; i < 8; ++i) sv[i] = ssq[row0 + (i >> 2) * HALF + (i & 3) * 16];
; #pragma unroll
;         for (int i = 0; i < 8; ++i) rsv[i] = 1.0f / sqrtf(ssq_val(sv[i]) * (1.0f / 256.0f) + EPS);
; #pragma unroll
;         for (int ai = 0; ai < 2; ++ai)
; #pragma unroll
;             for (int m = 0; m < 4; ++m) {
;                 const int row = row0 + ai * HALF + m * 16;
;                 const float rs = rsv[ai * 4 + m];
; #pragma unroll
;                 for (int bj = 0; bj < 2; ++bj) {
;                     const int col0 = u.pn * BM + bj * HALF + wc * 32 + 8 * fq;
;                     const f32x4 v0 = acc[ai][bj][m][0] * rs, v1 = acc[ai][bj][m][1] * rs;
;                     u32x4 w; w.x = cvt_pk_bf16(v0[0], v0[1]); w.y = cvt_pk_bf16(v0[2], v0[3]); w.z = cvt_pk_bf16(v1[0], v1[1]); w.w = cvt_pk_bf16(v1[2], v1[3]);
;                     *(u32x4*)(O + (size_t)row * KVP + col0) = w;
.LBB0_761:
	s_lshl_b32 s3, s3, 8
	s_add_i32 s3, s3, s4
	v_mbcnt_lo_u32_b32 v145, -1, 0
	v_mbcnt_hi_u32_b32 v145, -1, v145
	v_mov_b32_e32 v226, 0x358637bd
	v_and_or_b32 v138, v145, 15, s3
	v_ashrrev_i32_e32 v139, 31, v138
	v_lshl_add_u64 v[142:143], v[138:139], 3, s[14:15]
	flat_load_dwordx2 v[156:157], v[142:143]
	flat_load_dwordx2 v[158:159], v[142:143] offset:128
	flat_load_dwordx2 v[154:155], v[142:143] offset:256
	flat_load_dwordx2 v[152:153], v[142:143] offset:384
	v_mov_b32_e32 v223, 0x260
	flat_load_dwordx2 v[150:151], v[142:143] offset:1024
	flat_load_dwordx2 v[148:149], v[142:143] offset:1152
	flat_load_dwordx2 v[146:147], v[142:143] offset:1280
	s_nop 0
	flat_load_dwordx2 v[142:143], v[142:143] offset:1408
	s_lshl_b32 s2, s2, 8
	v_add_u32_e32 v139, 0x80, v138
	v_mov_b32_e32 v222, v224
	v_mov_b64_e32 v[252:253], 0x300
	s_waitcnt vmcnt(0) lgkmcnt(0)
	v_ffbh_u32_e32 v140, v157
	v_min_u32_e32 v140, 32, v140
	v_lshlrev_b64 v[156:157], v140, v[156:157]
	v_min_u32_e32 v144, 1, v156
	v_or_b32_e32 v144, v157, v144
	v_cvt_f32_u32_e32 v144, v144
	v_sub_u32_e32 v140, 32, v140
	v_ldexp_f32 v140, v144, v140
	v_mul_f32_e32 v140, 0x33800000, v140
	v_fmamk_f32 v140, v140, 0x3b800000, v226
	v_cmp_gt_f32_e32 vcc, s71, v140
	v_mul_f32_e32 v144, 0x4f800000, v140
	s_nop 0
	v_cndmask_b32_e32 v140, v140, v144, vcc
	v_sqrt_f32_e32 v144, v140
	s_nop 0
	v_add_u32_e32 v156, -1, v144
	v_fma_f32 v157, -v156, v144, v140
	v_cmp_ge_f32_e64 s[8:9], 0, v157
	v_add_u32_e32 v157, 1, v144
	s_nop 0
	v_cndmask_b32_e64 v156, v144, v156, s[8:9]
	v_fma_f32 v144, -v157, v144, v140
	v_cmp_lt_f32_e64 s[8:9], 0, v144
	s_nop 1
	v_cndmask_b32_e64 v144, v156, v157, s[8:9]
	v_mul_f32_e32 v156, 0x37800000, v144
	v_cndmask_b32_e32 v144, v144, v156, vcc
	v_cmp_class_f32_e32 vcc, v140, v223
	s_nop 1
	v_cndmask_b32_e32 v140, v144, v140, vcc
	v_div_scale_f32 v144, s[8:9], v140, v140, 1.0
	v_rcp_f32_e32 v156, v144
	s_nop 0
	v_fma_f32 v157, -v144, v156, 1.0
	v_fmac_f32_e32 v156, v157, v156
	v_div_scale_f32 v157, vcc, 1.0, v140, 1.0
	v_mul_f32_e32 v160, v157, v156
	v_fma_f32 v161, -v144, v160, v157
	v_fmac_f32_e32 v160, v161, v156
	v_fma_f32 v144, -v144, v160, v157
	v_div_fmas_f32 v144, v144, v156, v160
	v_div_fixup_f32 v140, v144, v140, 1.0
	v_ffbh_u32_e32 v144, v159
	v_min_u32_e32 v144, 32, v144
	v_lshlrev_b64 v[156:157], v144, v[158:159]
	v_min_u32_e32 v156, 1, v156
	v_or_b32_e32 v156, v157, v156
	v_cvt_f32_u32_e32 v156, v156
	v_sub_u32_e32 v144, 32, v144
	v_pk_mul_f32 v[132:133], v[132:133], v[140:141] op_sel_hi:[1,0]
	v_pk_mul_f32 v[130:131], v[130:131], v[140:141] op_sel_hi:[1,0]
	v_ldexp_f32 v144, v156, v144
	v_mul_f32_e32 v144, 0x33800000, v144
	v_fmamk_f32 v144, v144, 0x3b800000, v226
	v_cmp_gt_f32_e32 vcc, s71, v144
	v_mul_f32_e32 v156, 0x4f800000, v144
	v_pk_mul_f32 v[126:127], v[126:127], v[140:141] op_sel_hi:[1,0]
	v_cndmask_b32_e32 v144, v144, v156, vcc
	v_sqrt_f32_e32 v156, v144
	v_pk_mul_f32 v[128:129], v[128:129], v[140:141] op_sel_hi:[1,0]
	v_cvt_pk_bf16_f32 v130, v130, v131
	v_cvt_pk_bf16_f32 v131, v132, v133
	v_add_u32_e32 v157, -1, v156
	v_fma_f32 v158, -v157, v156, v144
	v_cmp_ge_f32_e64 s[8:9], 0, v158
	v_add_u32_e32 v158, 1, v156
	v_cvt_pk_bf16_f32 v132, v126, v127
	v_mov_b64_e32 v[126:127], s[12:13]
	v_cndmask_b32_e64 v157, v156, v157, s[8:9]
	v_fma_f32 v156, -v158, v156, v144
	v_cmp_lt_f32_e64 s[8:9], 0, v156
	v_cvt_pk_bf16_f32 v133, v128, v129
	v_pk_mul_f32 v[124:125], v[124:125], v[140:141] op_sel_hi:[1,0]
	v_pk_mul_f32 v[122:123], v[122:123], v[140:141] op_sel_hi:[1,0]
	v_cndmask_b32_e64 v156, v157, v158, s[8:9]
	v_mul_f32_e32 v157, 0x37800000, v156
	v_cndmask_b32_e32 v156, v156, v157, vcc
	v_cmp_class_f32_e32 vcc, v144, v223
	s_nop 1
	v_cndmask_b32_e32 v144, v156, v144, vcc
	v_div_scale_f32 v156, s[8:9], v144, v144, 1.0
	v_rcp_f32_e32 v157, v156
	s_nop 0
	v_fma_f32 v158, -v156, v157, 1.0
	v_fmac_f32_e32 v157, v158, v157
	v_div_scale_f32 v158, vcc, 1.0, v144, 1.0
	v_mul_f32_e32 v159, v158, v157
	v_fma_f32 v160, -v156, v159, v158
	v_fmac_f32_e32 v159, v160, v157
	v_fma_f32 v156, -v156, v159, v158
	v_div_fmas_f32 v156, v156, v157, v159
	v_div_fixup_f32 v144, v156, v144, 1.0
	v_ffbh_u32_e32 v156, v155
	v_min_u32_e32 v156, 32, v156
	v_lshlrev_b64 v[154:155], v156, v[154:155]
	v_min_u32_e32 v154, 1, v154
	v_or_b32_e32 v154, v155, v154
	v_cvt_f32_u32_e32 v154, v154
	v_sub_u32_e32 v155, 32, v156
	v_pk_mul_f32 v[114:115], v[114:115], v[144:145] op_sel_hi:[1,0]
	v_pk_mul_f32 v[116:117], v[116:117], v[144:145] op_sel_hi:[1,0]
	v_ldexp_f32 v154, v154, v155
	v_mul_f32_e32 v154, 0x33800000, v154
	v_fmamk_f32 v154, v154, 0x3b800000, v226
	v_cmp_gt_f32_e32 vcc, s71, v154
	v_mul_f32_e32 v155, 0x4f800000, v154
	v_pk_mul_f32 v[108:109], v[108:109], v[144:145] op_sel_hi:[1,0]
	v_cndmask_b32_e32 v154, v154, v155, vcc
	v_sqrt_f32_e32 v155, v154
	v_pk_mul_f32 v[106:107], v[106:107], v[144:145] op_sel_hi:[1,0]
	v_add_u32_e32 v156, -1, v155
	v_fma_f32 v157, -v156, v155, v154
	v_cmp_ge_f32_e64 s[8:9], 0, v157
	v_add_u32_e32 v157, 1, v155
	s_nop 0
	v_cndmask_b32_e64 v156, v155, v156, s[8:9]
	v_fma_f32 v155, -v157, v155, v154
	v_cmp_lt_f32_e64 s[8:9], 0, v155
	s_nop 1
	v_cndmask_b32_e64 v155, v156, v157, s[8:9]
	v_mul_f32_e32 v156, 0x37800000, v155
	v_cndmask_b32_e32 v155, v155, v156, vcc
	v_cmp_class_f32_e32 vcc, v154, v223
	s_nop 1
	v_cndmask_b32_e32 v154, v155, v154, vcc
	v_div_scale_f32 v155, s[8:9], v154, v154, 1.0
	v_rcp_f32_e32 v156, v155
	s_nop 0
	v_fma_f32 v157, -v155, v156, 1.0
	v_fmac_f32_e32 v156, v157, v156
	v_div_scale_f32 v157, vcc, 1.0, v154, 1.0
	v_mul_f32_e32 v158, v157, v156
	v_fma_f32 v159, -v155, v158, v157
	v_fmac_f32_e32 v158, v159, v156
	v_fma_f32 v155, -v155, v158, v157
; __device__ __forceinline__ unsigned cvt_pk_bf16(float lo, float hi) { unsigned r; asm volatile("v_cvt_pk_bf16_f32 %0, %1, %2" : "=v"(r) : "v"(lo), "v"(hi)); return r; }
; __device__ __forceinline__ float ssq_val(ssq_t v) { return (float)v * SSQ_IFX; }
;     __device__ __forceinline__ void operator()(const f32x4 (&acc)[2][2][4][2], const Unit& u, int wr, int wc, int fr, int fq) const {
;         const int row0 = u.pm * BM + wr * 64 + fr;
;         ssq_t sv[8]; float rsv[8];
; #pragma unroll
;         for (int i = 0; i < 8; ++i) sv[i] = ssq[row0 + (i >> 2) * HALF + (i & 3) * 16];
; #pragma unroll
;         for (int i = 0; i < 8; ++i) rsv[i] = 1.0f / sqrtf(ssq_val(sv[i]) * (1.0f / 256.0f) + EPS);
; #pragma unroll
;         for (int ai = 0; ai < 2; ++ai)
; #pragma unroll
;             for (int m = 0; m < 4; ++m) {
;                 const int row = row0 + ai * HALF + m * 16;
;                 const float rs = rsv[ai * 4 + m];
; #pragma unroll
;                 for (int bj = 0; bj < 2; ++bj) {
;                     const int col0 = u.pn * BM + bj * HALF + wc * 32 + 8 * fq;
;                     const f32x4 v0 = acc[ai][bj][m][0] * rs, v1 = acc[ai][bj][m][1] * rs;
;                     u32x4 w; w.x = cvt_pk_bf16(v0[0], v0[1]); w.y = cvt_pk_bf16(v0[2], v0[3]); w.z = cvt_pk_bf16(v1[0], v1[1]); w.w = cvt_pk_bf16(v1[2], v1[3]);
;                     *(u32x4*)(O + (size_t)row * KVP + col0) = w;
	v_div_fmas_f32 v155, v155, v156, v158
	v_div_fixup_f32 v154, v155, v154, 1.0
	v_ffbh_u32_e32 v155, v153
	v_min_u32_e32 v155, 32, v155
	v_lshlrev_b64 v[152:153], v155, v[152:153]
	v_min_u32_e32 v152, 1, v152
	v_or_b32_e32 v152, v153, v152
	v_cvt_f32_u32_e32 v152, v152
	v_sub_u32_e32 v153, 32, v155
	v_ldexp_f32 v152, v152, v153
	v_mul_f32_e32 v152, 0x33800000, v152
	v_fmamk_f32 v152, v152, 0x3b800000, v226
	v_cmp_gt_f32_e32 vcc, s71, v152
	v_mul_f32_e32 v153, 0x4f800000, v152
	s_nop 0
	v_cndmask_b32_e32 v152, v152, v153, vcc
	v_sqrt_f32_e32 v153, v152
	s_nop 0
	v_add_u32_e32 v155, -1, v153
	v_fma_f32 v156, -v155, v153, v152
	v_cmp_ge_f32_e64 s[8:9], 0, v156
	v_add_u32_e32 v156, 1, v153
	s_nop 0
	v_cndmask_b32_e64 v155, v153, v155, s[8:9]
	v_fma_f32 v153, -v156, v153, v152
	v_cmp_lt_f32_e64 s[8:9], 0, v153
	s_nop 1
	v_cndmask_b32_e64 v153, v155, v156, s[8:9]
	v_mul_f32_e32 v155, 0x37800000, v153
	v_cndmask_b32_e32 v153, v153, v155, vcc
	v_cmp_class_f32_e32 vcc, v152, v223
	s_nop 1
	v_cndmask_b32_e32 v152, v153, v152, vcc
	v_div_scale_f32 v153, s[8:9], v152, v152, 1.0
	v_rcp_f32_e32 v155, v153
	s_nop 0
	v_fma_f32 v156, -v153, v155, 1.0
	v_fmac_f32_e32 v155, v156, v155
	v_div_scale_f32 v156, vcc, 1.0, v152, 1.0
	v_mul_f32_e32 v157, v156, v155
	v_fma_f32 v158, -v153, v157, v156
	v_fmac_f32_e32 v157, v158, v155
	v_fma_f32 v153, -v153, v157, v156
	v_div_fmas_f32 v153, v153, v155, v157
	v_div_fixup_f32 v152, v153, v152, 1.0
	v_ffbh_u32_e32 v153, v151
	v_min_u32_e32 v153, 32, v153
	v_lshlrev_b64 v[150:151], v153, v[150:151]
	v_min_u32_e32 v150, 1, v150
	v_or_b32_e32 v150, v151, v150
	v_cvt_f32_u32_e32 v150, v150
	v_sub_u32_e32 v151, 32, v153
	v_ldexp_f32 v150, v150, v151
	v_mul_f32_e32 v150, 0x33800000, v150
	v_fmamk_f32 v150, v150, 0x3b800000, v226
	v_cmp_gt_f32_e32 vcc, s71, v150
	v_mul_f32_e32 v151, 0x4f800000, v150
	s_nop 0
	v_cndmask_b32_e32 v150, v150, v151, vcc
	v_sqrt_f32_e32 v151, v150
	s_nop 0
	v_add_u32_e32 v153, -1, v151
	v_fma_f32 v155, -v153, v151, v150
	v_cmp_ge_f32_e64 s[8:9], 0, v155
	v_add_u32_e32 v155, 1, v151
	s_nop 0
	v_cndmask_b32_e64 v153, v151, v153, s[8:9]
	v_fma_f32 v151, -v155, v151, v150
	v_cmp_lt_f32_e64 s[8:9], 0, v151
	s_nop 1
	v_cndmask_b32_e64 v151, v153, v155, s[8:9]
	v_mul_f32_e32 v153, 0x37800000, v151
	v_cndmask_b32_e32 v151, v151, v153, vcc
	v_cmp_class_f32_e32 vcc, v150, v223
	s_nop 1
	v_cndmask_b32_e32 v150, v151, v150, vcc
	v_div_scale_f32 v151, s[8:9], v150, v150, 1.0
	v_rcp_f32_e32 v153, v151
	s_nop 0
	v_fma_f32 v155, -v151, v153, 1.0
	v_fmac_f32_e32 v153, v155, v153
	v_div_scale_f32 v155, vcc, 1.0, v150, 1.0
	v_mul_f32_e32 v156, v155, v153
	v_fma_f32 v157, -v151, v156, v155
	v_fmac_f32_e32 v156, v157, v153
	v_fma_f32 v151, -v151, v156, v155
	v_div_fmas_f32 v151, v151, v153, v156
	v_div_fixup_f32 v150, v151, v150, 1.0
	v_ffbh_u32_e32 v151, v149
	v_min_u32_e32 v151, 32, v151
	v_lshlrev_b64 v[148:149], v151, v[148:149]
	v_min_u32_e32 v148, 1, v148
	v_or_b32_e32 v148, v149, v148
	v_cvt_f32_u32_e32 v148, v148
	v_sub_u32_e32 v149, 32, v151
	v_ldexp_f32 v148, v148, v149
	v_mul_f32_e32 v148, 0x33800000, v148
	v_fmamk_f32 v148, v148, 0x3b800000, v226
	v_cmp_gt_f32_e32 vcc, s71, v148
	v_mul_f32_e32 v149, 0x4f800000, v148
	s_nop 0
	v_cndmask_b32_e32 v148, v148, v149, vcc
	v_sqrt_f32_e32 v149, v148
	s_nop 0
	v_add_u32_e32 v151, -1, v149
	v_fma_f32 v153, -v151, v149, v148
	v_cmp_ge_f32_e64 s[8:9], 0, v153
	v_add_u32_e32 v153, 1, v149
	s_nop 0
	v_cndmask_b32_e64 v151, v149, v151, s[8:9]
	v_fma_f32 v149, -v153, v149, v148
	v_cmp_lt_f32_e64 s[8:9], 0, v149
	s_nop 1
	v_cndmask_b32_e64 v149, v151, v153, s[8:9]
	v_mul_f32_e32 v151, 0x37800000, v149
	v_cndmask_b32_e32 v149, v149, v151, vcc
	v_cmp_class_f32_e32 vcc, v148, v223
	s_nop 1
	v_cndmask_b32_e32 v148, v149, v148, vcc
	v_div_scale_f32 v149, s[8:9], v148, v148, 1.0
	v_rcp_f32_e32 v151, v149
	s_nop 0
	v_fma_f32 v153, -v149, v151, 1.0
	v_fmac_f32_e32 v151, v153, v151
	v_div_scale_f32 v153, vcc, 1.0, v148, 1.0
	v_mul_f32_e32 v155, v153, v151
	v_fma_f32 v156, -v149, v155, v153
	v_fmac_f32_e32 v155, v156, v151
	v_fma_f32 v149, -v149, v155, v153
	v_div_fmas_f32 v149, v149, v151, v155
	v_div_fixup_f32 v148, v149, v148, 1.0
	v_ffbh_u32_e32 v149, v147
	v_min_u32_e32 v149, 32, v149
	v_lshlrev_b64 v[146:147], v149, v[146:147]
	v_min_u32_e32 v146, 1, v146
	v_or_b32_e32 v146, v147, v146
	v_cvt_f32_u32_e32 v146, v146
	v_sub_u32_e32 v147, 32, v149
	v_ldexp_f32 v146, v146, v147
	v_mul_f32_e32 v146, 0x33800000, v146
	v_fmamk_f32 v146, v146, 0x3b800000, v226
	v_cmp_gt_f32_e32 vcc, s71, v146
	v_mul_f32_e32 v147, 0x4f800000, v146
	s_nop 0
	v_cndmask_b32_e32 v146, v146, v147, vcc
	v_sqrt_f32_e32 v147, v146
	s_nop 0
	v_add_u32_e32 v149, -1, v147
	v_fma_f32 v151, -v149, v147, v146
	v_cmp_ge_f32_e64 s[8:9], 0, v151
	v_add_u32_e32 v151, 1, v147
	s_nop 0
	v_cndmask_b32_e64 v149, v147, v149, s[8:9]
	v_fma_f32 v147, -v151, v147, v146
	v_cmp_lt_f32_e64 s[8:9], 0, v147
	s_nop 1
	v_cndmask_b32_e64 v147, v149, v151, s[8:9]
	v_mul_f32_e32 v149, 0x37800000, v147
	v_cndmask_b32_e32 v147, v147, v149, vcc
	v_cmp_class_f32_e32 vcc, v146, v223
	s_nop 1
	v_cndmask_b32_e32 v146, v147, v146, vcc
	v_div_scale_f32 v147, s[8:9], v146, v146, 1.0
	v_rcp_f32_e32 v149, v147
	s_nop 0
	v_fma_f32 v151, -v147, v149, 1.0
	v_fmac_f32_e32 v149, v151, v149
	v_div_scale_f32 v151, vcc, 1.0, v146, 1.0
	v_mul_f32_e32 v153, v151, v149
	v_fma_f32 v155, -v147, v153, v151
	v_fmac_f32_e32 v153, v155, v149
	v_fma_f32 v147, -v147, v153, v151
	v_div_fmas_f32 v147, v147, v149, v153
	v_div_fixup_f32 v146, v147, v146, 1.0
	v_ffbh_u32_e32 v147, v143
	v_min_u32_e32 v147, 32, v147
	v_lshlrev_b64 v[142:143], v147, v[142:143]
; __device__ __forceinline__ unsigned cvt_pk_bf16(float lo, float hi) { unsigned r; asm volatile("v_cvt_pk_bf16_f32 %0, %1, %2" : "=v"(r) : "v"(lo), "v"(hi)); return r; }
; __device__ __forceinline__ float ssq_val(ssq_t v) { return (float)v * SSQ_IFX; }
;     __device__ __forceinline__ void operator()(const f32x4 (&acc)[2][2][4][2], const Unit& u, int wr, int wc, int fr, int fq) const {
;         const int row0 = u.pm * BM + wr * 64 + fr;
;         ssq_t sv[8]; float rsv[8];
; #pragma unroll
;         for (int i = 0; i < 8; ++i) sv[i] = ssq[row0 + (i >> 2) * HALF + (i & 3) * 16];
; #pragma unroll
;         for (int i = 0; i < 8; ++i) rsv[i] = 1.0f / sqrtf(ssq_val(sv[i]) * (1.0f / 256.0f) + EPS);
; #pragma unroll
;         for (int ai = 0; ai < 2; ++ai)
; #pragma unroll
;             for (int m = 0; m < 4; ++m) {
;                 const int row = row0 + ai * HALF + m * 16;
;                 const float rs = rsv[ai * 4 + m];
; #pragma unroll
;                 for (int bj = 0; bj < 2; ++bj) {
;                     const int col0 = u.pn * BM + bj * HALF + wc * 32 + 8 * fq;
;                     const f32x4 v0 = acc[ai][bj][m][0] * rs, v1 = acc[ai][bj][m][1] * rs;
;                     u32x4 w; w.x = cvt_pk_bf16(v0[0], v0[1]); w.y = cvt_pk_bf16(v0[2], v0[3]); w.z = cvt_pk_bf16(v1[0], v1[1]); w.w = cvt_pk_bf16(v1[2], v1[3]);
;                     *(u32x4*)(O + (size_t)row * KVP + col0) = w;
	v_min_u32_e32 v142, 1, v142
	v_or_b32_e32 v142, v143, v142
	v_cvt_f32_u32_e32 v142, v142
	v_sub_u32_e32 v143, 32, v147
	v_pk_mul_f32 v[98:99], v[98:99], v[154:155] op_sel_hi:[1,0]
	v_pk_mul_f32 v[100:101], v[100:101], v[154:155] op_sel_hi:[1,0]
	v_ldexp_f32 v142, v142, v143
	v_mul_f32_e32 v142, 0x33800000, v142
	v_fmamk_f32 v142, v142, 0x3b800000, v226
	v_cmp_gt_f32_e32 vcc, s71, v142
	v_mul_f32_e32 v143, 0x4f800000, v142
	v_pk_mul_f32 v[92:93], v[92:93], v[154:155] op_sel_hi:[1,0]
	v_cndmask_b32_e32 v142, v142, v143, vcc
	v_sqrt_f32_e32 v143, v142
	v_pk_mul_f32 v[90:91], v[90:91], v[154:155] op_sel_hi:[1,0]
	v_add_u32_e32 v147, -1, v143
	v_fma_f32 v149, -v147, v143, v142
	v_cmp_ge_f32_e64 s[8:9], 0, v149
	v_add_u32_e32 v149, 1, v143
	s_nop 0
	v_cndmask_b32_e64 v147, v143, v147, s[8:9]
	v_fma_f32 v143, -v149, v143, v142
	v_cmp_lt_f32_e64 s[8:9], 0, v143
	s_nop 1
	v_cndmask_b32_e64 v143, v147, v149, s[8:9]
	v_mul_f32_e32 v147, 0x37800000, v143
	v_cndmask_b32_e32 v143, v143, v147, vcc
	v_cmp_class_f32_e32 vcc, v142, v223
	s_nop 1
	v_cndmask_b32_e32 v142, v143, v142, vcc
	v_div_scale_f32 v143, s[8:9], v142, v142, 1.0
	v_rcp_f32_e32 v147, v143
	s_nop 0
	v_fma_f32 v149, -v143, v147, 1.0
	v_fmac_f32_e32 v147, v149, v147
	v_div_scale_f32 v149, vcc, 1.0, v142, 1.0
	v_mul_f32_e32 v151, v149, v147
	v_fma_f32 v153, -v143, v151, v149
	v_fmac_f32_e32 v151, v153, v147
	v_fma_f32 v143, -v143, v151, v149
	v_div_fmas_f32 v143, v143, v147, v151
	v_div_fixup_f32 v142, v143, v142, 1.0
	v_lshrrev_b32_e32 v143, 1, v145
	v_and_or_b32 v143, v143, 24, s2
	v_or_b32_e32 v156, s5, v143
	v_ashrrev_i32_e32 v157, 31, v156
	v_mad_i64_i32 v[158:159], s[2:3], v138, s75, v[126:127]
	v_lshlrev_b64 v[128:129], 1, v[156:157]
	v_lshl_add_u64 v[156:157], v[158:159], 0, v[128:129]
	flat_store_dwordx4 v[156:157], v[130:133]
	v_pk_mul_f32 v[74:75], v[74:75], v[152:153] op_sel_hi:[1,0]
	v_pk_mul_f32 v[76:77], v[76:77], v[152:153] op_sel_hi:[1,0]
	v_pk_mul_f32 v[130:131], v[120:121], v[140:141] op_sel_hi:[1,0]
	v_pk_mul_f32 v[120:121], v[118:119], v[140:141] op_sel_hi:[1,0]
	v_cvt_pk_bf16_f32 v118, v122, v123
	v_cvt_pk_bf16_f32 v119, v124, v125
	v_pk_mul_f32 v[60:61], v[60:61], v[152:153] op_sel_hi:[1,0]
	v_cvt_pk_bf16_f32 v120, v120, v121
	v_cvt_pk_bf16_f32 v121, v130, v131
	flat_store_dwordx4 v[156:157], v[118:121] offset:256
	v_pk_mul_f32 v[58:59], v[58:59], v[152:153] op_sel_hi:[1,0]
	v_pk_mul_f32 v[62:63], v[62:63], v[150:151] op_sel_hi:[1,0]
	v_or_b32_e32 v120, 16, v138
	v_pk_mul_f32 v[118:119], v[112:113], v[144:145] op_sel_hi:[1,0]
	v_pk_mul_f32 v[112:113], v[110:111], v[144:145] op_sel_hi:[1,0]
	v_cvt_pk_bf16_f32 v110, v114, v115
	v_mad_i64_i32 v[114:115], s[2:3], v120, s75, v[126:127]
	v_cvt_pk_bf16_f32 v111, v116, v117
	v_lshl_add_u64 v[114:115], v[114:115], 0, v[128:129]
	v_cvt_pk_bf16_f32 v112, v112, v113
	v_cvt_pk_bf16_f32 v113, v118, v119
	flat_store_dwordx4 v[114:115], v[110:113]
	v_pk_mul_f32 v[50:51], v[50:51], v[148:149] op_sel_hi:[1,0]
	v_pk_mul_f32 v[52:53], v[52:53], v[148:149] op_sel_hi:[1,0]
	v_pk_mul_f32 v[110:111], v[104:105], v[144:145] op_sel_hi:[1,0]
	v_pk_mul_f32 v[104:105], v[102:103], v[144:145] op_sel_hi:[1,0]
	v_cvt_pk_bf16_f32 v102, v106, v107
	v_cvt_pk_bf16_f32 v103, v108, v109
	v_pk_mul_f32 v[44:45], v[44:45], v[148:149] op_sel_hi:[1,0]
	v_cvt_pk_bf16_f32 v104, v104, v105
	v_cvt_pk_bf16_f32 v105, v110, v111
	flat_store_dwordx4 v[114:115], v[102:105] offset:256
	v_pk_mul_f32 v[42:43], v[42:43], v[148:149] op_sel_hi:[1,0]
	v_pk_mul_f32 v[34:35], v[34:35], v[146:147] op_sel_hi:[1,0]
	v_or_b32_e32 v104, 32, v138
	v_pk_mul_f32 v[102:103], v[96:97], v[154:155] op_sel_hi:[1,0]
	v_pk_mul_f32 v[96:97], v[94:95], v[154:155] op_sel_hi:[1,0]
	v_cvt_pk_bf16_f32 v94, v98, v99
	v_mad_i64_i32 v[98:99], s[2:3], v104, s75, v[126:127]
	v_cvt_pk_bf16_f32 v95, v100, v101
	v_lshl_add_u64 v[98:99], v[98:99], 0, v[128:129]
	v_cvt_pk_bf16_f32 v96, v96, v97
	v_cvt_pk_bf16_f32 v97, v102, v103
	flat_store_dwordx4 v[98:99], v[94:97]
	v_pk_mul_f32 v[36:37], v[36:37], v[146:147] op_sel_hi:[1,0]
	v_pk_mul_f32 v[28:29], v[28:29], v[146:147] op_sel_hi:[1,0]
	v_pk_mul_f32 v[94:95], v[88:89], v[154:155] op_sel_hi:[1,0]
	v_pk_mul_f32 v[88:89], v[86:87], v[154:155] op_sel_hi:[1,0]
	v_cvt_pk_bf16_f32 v86, v90, v91
	v_cvt_pk_bf16_f32 v87, v92, v93
	v_pk_mul_f32 v[26:27], v[26:27], v[146:147] op_sel_hi:[1,0]
	v_cvt_pk_bf16_f32 v88, v88, v89
; __device__ __forceinline__ unsigned cvt_pk_bf16(float lo, float hi) { unsigned r; asm volatile("v_cvt_pk_bf16_f32 %0, %1, %2" : "=v"(r) : "v"(lo), "v"(hi)); return r; }
;     __device__ __forceinline__ void operator()(const f32x4 (&acc)[2][2][4][2], const Unit& u, int wr, int wc, int fr, int fq) const {
;     ...
;         for (int ai = 0; ai < 2; ++ai)
; #pragma unroll
;             for (int m = 0; m < 4; ++m) {
;                 const int row = row0 + ai * HALF + m * 16;
;                 const float rs = rsv[ai * 4 + m];
; #pragma unroll
;                 for (int bj = 0; bj < 2; ++bj) {
;                     const int col0 = u.pn * BM + bj * HALF + wc * 32 + 8 * fq;
;                     const f32x4 v0 = acc[ai][bj][m][0] * rs, v1 = acc[ai][bj][m][1] * rs;
;                     u32x4 w; w.x = cvt_pk_bf16(v0[0], v0[1]); w.y = cvt_pk_bf16(v0[2], v0[3]); w.z = cvt_pk_bf16(v1[0], v1[1]); w.w = cvt_pk_bf16(v1[2], v1[3]);
;                     *(u32x4*)(O + (size_t)row * KVP + col0) = w;
;                 }
;             }
	v_cvt_pk_bf16_f32 v89, v94, v95
	flat_store_dwordx4 v[98:99], v[86:89] offset:256
	v_pk_mul_f32 v[18:19], v[18:19], v[142:143] op_sel_hi:[1,0]
	v_pk_mul_f32 v[20:21], v[20:21], v[142:143] op_sel_hi:[1,0]
	v_or_b32_e32 v88, 48, v138
	v_pk_mul_f32 v[86:87], v[68:69], v[152:153] op_sel_hi:[1,0]
	v_pk_mul_f32 v[68:69], v[66:67], v[152:153] op_sel_hi:[1,0]
	v_cvt_pk_bf16_f32 v66, v74, v75
	v_mad_i64_i32 v[74:75], s[2:3], v88, s75, v[126:127]
	v_cvt_pk_bf16_f32 v67, v76, v77
	v_lshl_add_u64 v[74:75], v[74:75], 0, v[128:129]
	v_cvt_pk_bf16_f32 v68, v68, v69
	v_cvt_pk_bf16_f32 v69, v86, v87
	flat_store_dwordx4 v[74:75], v[66:69]
	s_and_b64 vcc, exec, s[6:7]
	v_pk_mul_f32 v[8:9], v[8:9], v[142:143] op_sel_hi:[1,0]
	v_pk_mul_f32 v[66:67], v[56:57], v[152:153] op_sel_hi:[1,0]
	v_pk_mul_f32 v[56:57], v[54:55], v[152:153] op_sel_hi:[1,0]
	v_cvt_pk_bf16_f32 v54, v58, v59
	v_cvt_pk_bf16_f32 v55, v60, v61
	v_pk_mul_f32 v[58:59], v[80:81], v[150:151] op_sel_hi:[1,0]
	v_cvt_pk_bf16_f32 v56, v56, v57
	v_cvt_pk_bf16_f32 v57, v66, v67
	flat_store_dwordx4 v[74:75], v[54:57] offset:256
	v_pk_mul_f32 v[60:61], v[78:79], v[150:151] op_sel_hi:[1,0]
	v_pk_mul_f32 v[6:7], v[6:7], v[142:143] op_sel_hi:[1,0]
	v_pk_mul_f32 v[56:57], v[84:85], v[150:151] op_sel_hi:[1,0]
	v_pk_mul_f32 v[54:55], v[82:83], v[150:151] op_sel_hi:[1,0]
	s_nop 0
	v_cvt_pk_bf16_f32 v54, v54, v55
	v_cvt_pk_bf16_f32 v55, v56, v57
	v_cvt_pk_bf16_f32 v56, v60, v61
	v_cvt_pk_bf16_f32 v57, v58, v59
	v_mad_i64_i32 v[58:59], s[2:3], v139, s75, v[126:127]
	v_lshl_add_u64 v[58:59], v[58:59], 0, v[128:129]
	flat_store_dwordx4 v[58:59], v[54:57]
	v_pk_mul_f32 v[60:61], v[64:65], v[150:151] op_sel_hi:[1,0]
	s_nop 0
	v_pk_mul_f32 v[56:57], v[72:73], v[150:151] op_sel_hi:[1,0]
	v_pk_mul_f32 v[54:55], v[70:71], v[150:151] op_sel_hi:[1,0]
	s_nop 0
	v_cvt_pk_bf16_f32 v54, v54, v55
	v_cvt_pk_bf16_f32 v55, v56, v57
	v_cvt_pk_bf16_f32 v56, v62, v63
	v_cvt_pk_bf16_f32 v57, v60, v61
	flat_store_dwordx4 v[58:59], v[54:57] offset:256
	s_nop 1
	v_add_u32_e32 v56, 0x90, v138
	v_pk_mul_f32 v[54:55], v[48:49], v[148:149] op_sel_hi:[1,0]
	v_pk_mul_f32 v[48:49], v[46:47], v[148:149] op_sel_hi:[1,0]
	v_cvt_pk_bf16_f32 v46, v50, v51
	v_mad_i64_i32 v[50:51], s[2:3], v56, s75, v[126:127]
	v_cvt_pk_bf16_f32 v47, v52, v53
	v_lshl_add_u64 v[50:51], v[50:51], 0, v[128:129]
	v_cvt_pk_bf16_f32 v48, v48, v49
	v_cvt_pk_bf16_f32 v49, v54, v55
	flat_store_dwordx4 v[50:51], v[46:49]
	s_nop 1
	v_pk_mul_f32 v[46:47], v[40:41], v[148:149] op_sel_hi:[1,0]
	v_pk_mul_f32 v[40:41], v[38:39], v[148:149] op_sel_hi:[1,0]
	v_cvt_pk_bf16_f32 v38, v42, v43
	v_cvt_pk_bf16_f32 v39, v44, v45
	s_nop 0
	v_cvt_pk_bf16_f32 v40, v40, v41
	v_cvt_pk_bf16_f32 v41, v46, v47
	flat_store_dwordx4 v[50:51], v[38:41] offset:256
	s_nop 1
	v_add_u32_e32 v40, 0xa0, v138
	v_pk_mul_f32 v[38:39], v[32:33], v[146:147] op_sel_hi:[1,0]
	v_pk_mul_f32 v[32:33], v[30:31], v[146:147] op_sel_hi:[1,0]
	v_cvt_pk_bf16_f32 v30, v34, v35
	v_mad_i64_i32 v[34:35], s[2:3], v40, s75, v[126:127]
	v_cvt_pk_bf16_f32 v31, v36, v37
	v_lshl_add_u64 v[34:35], v[34:35], 0, v[128:129]
	v_cvt_pk_bf16_f32 v32, v32, v33
	v_cvt_pk_bf16_f32 v33, v38, v39
	flat_store_dwordx4 v[34:35], v[30:33]
	s_nop 1
	v_pk_mul_f32 v[30:31], v[24:25], v[146:147] op_sel_hi:[1,0]
	v_pk_mul_f32 v[24:25], v[22:23], v[146:147] op_sel_hi:[1,0]
	v_cvt_pk_bf16_f32 v22, v26, v27
	v_cvt_pk_bf16_f32 v23, v28, v29
	s_nop 0
	v_cvt_pk_bf16_f32 v24, v24, v25
	v_cvt_pk_bf16_f32 v25, v30, v31
	flat_store_dwordx4 v[34:35], v[22:25] offset:256
	s_nop 1
	v_add_u32_e32 v24, 0xb0, v138
	v_pk_mul_f32 v[22:23], v[12:13], v[142:143] op_sel_hi:[1,0]
	v_pk_mul_f32 v[12:13], v[10:11], v[142:143] op_sel_hi:[1,0]
	v_cvt_pk_bf16_f32 v10, v18, v19
	v_mad_i64_i32 v[18:19], s[2:3], v24, s75, v[126:127]
	v_cvt_pk_bf16_f32 v11, v20, v21
	v_lshl_add_u64 v[18:19], v[18:19], 0, v[128:129]
	v_cvt_pk_bf16_f32 v12, v12, v13
	v_cvt_pk_bf16_f32 v13, v22, v23
	flat_store_dwordx4 v[18:19], v[10:13]
	s_mov_b64 s[2:3], -1
	s_nop 0
	v_pk_mul_f32 v[10:11], v[4:5], v[142:143] op_sel_hi:[1,0]
	v_pk_mul_f32 v[4:5], v[2:3], v[142:143] op_sel_hi:[1,0]
	v_cvt_pk_bf16_f32 v2, v6, v7
	v_cvt_pk_bf16_f32 v3, v8, v9
	s_nop 0
	v_cvt_pk_bf16_f32 v4, v4, v5
	v_cvt_pk_bf16_f32 v5, v10, v11
	flat_store_dwordx4 v[18:19], v[2:5] offset:256
	s_cbranch_vccnz .LBB0_754
	s_andn2_b64 vcc, exec, s[10:11]
	s_cbranch_vccnz .LBB0_753
	s_barrier
	s_branch .LBB0_753

; __device__ __forceinline__ float shfl_x(float v, int m, int lane) { return __builtin_bit_cast(float, __builtin_amdgcn_ds_bpermute((lane ^ m) << 2, __builtin_bit_cast(int, v))); }
; __device__ __forceinline__ float max3f(float a, float b, float c) { float r; asm("v_max3_f32 %0, %1, %2, %3" : "=v"(r) : "v"(a), "v"(b), "v"(c)); return r; }
; template <int NDS, int MODE> ...
;     ...
;             float mxa = max3f(p0[0], p0[1], p1[0]), mxb = max3f(p0[2], p0[3], p1[1]); mxa = max3f(mxa, p1[2], p1[3]);
; #pragma unroll
;             for (int r = 4; r < 16; r += 4) { mxa = max3f(mxa, p0[r], p0[r + 1]); mxb = max3f(mxb, p0[r + 2], p0[r + 3]); mxa = max3f(mxa, p1[r], p1[r + 1]); mxb = max3f(mxb, p1[r + 2], p1[r + 3]); }
;             float mx = max3f(mxa, mxb, mxb);
;             mx = max3f(mx, shfl_x(mx, 32, lane), mx);
;             if (first || __builtin_amdgcn_ballot_w64(mx > RESC_THR) != 0ull) {
;                 const float dl = first ? mx : fmaxf(mx, 0.f);
;                 const float f = first ? 1.0f : __builtin_amdgcn_exp2f(-dl);
;                 m_run += dl; l_run *= f;
; #pragma unroll
;                 for (int r = 0; r < 16; ++r) { p0[r] -= dl; p1[r] -= dl; o0[r] *= f; o1[r] *= f; negm[r] = -m_run; }
;                 first = false;
;             }
.LBB0_797:
	v_max3_f32 v14, v82, v83, v66
	v_max3_f32 v15, v84, v85, v67
	s_nop 0
	v_max3_f32 v14, v14, v68, v69
	v_max3_f32 v15, v15, v88, v89
	s_nop 0
	v_max3_f32 v14, v14, v86, v87
	v_max3_f32 v15, v15, v72, v73
	s_nop 0
	v_max3_f32 v14, v14, v70, v71
	v_max3_f32 v15, v15, v92, v93
	s_nop 0
	v_max3_f32 v14, v14, v90, v91
	v_max3_f32 v15, v15, v76, v77
	s_nop 0
	v_max3_f32 v14, v14, v74, v75
	v_max3_f32 v15, v15, v96, v97
	s_nop 0
	v_max3_f32 v14, v14, v94, v95
	v_max3_f32 v15, v15, v80, v81
	s_nop 0
	v_max3_f32 v14, v14, v78, v79
	s_nop 0
	v_max3_f32 v14, v14, v15, v15
	ds_bpermute_b32 v15, v17, v14
	s_waitcnt lgkmcnt(0)
	v_max3_f32 v14, v14, v15, v14
	s_nop 0
	v_cmp_lt_f32_e32 vcc, s39, v14
	s_cbranch_vccz .LBB0_792
	v_max_f32_e32 v14, v14, v14
	v_max_f32_e32 v14, 0, v14
	v_exp_f32_e64 v52, -v14
	v_add_f32_e32 v0, v0, v14
	v_xor_b32_e32 v50, 0x80000000, v0
	v_pk_add_f32 v[82:83], v[82:83], v[14:15] op_sel_hi:[1,0] neg_lo:[0,1] neg_hi:[0,1]
	v_pk_add_f32 v[66:67], v[66:67], v[14:15] op_sel_hi:[1,0] neg_lo:[0,1] neg_hi:[0,1]
	v_pk_add_f32 v[84:85], v[84:85], v[14:15] op_sel_hi:[1,0] neg_lo:[0,1] neg_hi:[0,1]
	v_pk_add_f32 v[68:69], v[68:69], v[14:15] op_sel_hi:[1,0] neg_lo:[0,1] neg_hi:[0,1]
	v_pk_add_f32 v[86:87], v[86:87], v[14:15] op_sel_hi:[1,0] neg_lo:[0,1] neg_hi:[0,1]
	v_pk_add_f32 v[70:71], v[70:71], v[14:15] op_sel_hi:[1,0] neg_lo:[0,1] neg_hi:[0,1]
	v_pk_add_f32 v[88:89], v[88:89], v[14:15] op_sel_hi:[1,0] neg_lo:[0,1] neg_hi:[0,1]
	v_pk_add_f32 v[72:73], v[72:73], v[14:15] op_sel_hi:[1,0] neg_lo:[0,1] neg_hi:[0,1]
	v_pk_add_f32 v[90:91], v[90:91], v[14:15] op_sel_hi:[1,0] neg_lo:[0,1] neg_hi:[0,1]
	v_pk_add_f32 v[74:75], v[74:75], v[14:15] op_sel_hi:[1,0] neg_lo:[0,1] neg_hi:[0,1]
	v_pk_add_f32 v[92:93], v[92:93], v[14:15] op_sel_hi:[1,0] neg_lo:[0,1] neg_hi:[0,1]
	v_pk_add_f32 v[76:77], v[76:77], v[14:15] op_sel_hi:[1,0] neg_lo:[0,1] neg_hi:[0,1]
	v_pk_add_f32 v[94:95], v[94:95], v[14:15] op_sel_hi:[1,0] neg_lo:[0,1] neg_hi:[0,1]
	v_pk_add_f32 v[78:79], v[78:79], v[14:15] op_sel_hi:[1,0] neg_lo:[0,1] neg_hi:[0,1]
	v_pk_add_f32 v[96:97], v[96:97], v[14:15] op_sel_hi:[1,0] neg_lo:[0,1] neg_hi:[0,1]
	v_pk_add_f32 v[80:81], v[80:81], v[14:15] op_sel_hi:[1,0] neg_lo:[0,1] neg_hi:[0,1]
	v_pk_mul_f32 v[48:49], v[48:49], v[52:53] op_sel_hi:[1,0]
	v_pk_mul_f32 v[46:47], v[46:47], v[52:53] op_sel_hi:[1,0]
	v_pk_mul_f32 v[44:45], v[44:45], v[52:53] op_sel_hi:[1,0]
	v_pk_mul_f32 v[42:43], v[42:43], v[52:53] op_sel_hi:[1,0]
	v_pk_mul_f32 v[40:41], v[40:41], v[52:53] op_sel_hi:[1,0]
	v_pk_mul_f32 v[38:39], v[38:39], v[52:53] op_sel_hi:[1,0]
	v_pk_mul_f32 v[36:37], v[36:37], v[52:53] op_sel_hi:[1,0]
	v_pk_mul_f32 v[34:35], v[34:35], v[52:53] op_sel_hi:[1,0]
	v_pk_mul_f32 v[32:33], v[32:33], v[52:53] op_sel_hi:[1,0]
	v_pk_mul_f32 v[30:31], v[30:31], v[52:53] op_sel_hi:[1,0]
	v_pk_mul_f32 v[28:29], v[28:29], v[52:53] op_sel_hi:[1,0]
	v_pk_mul_f32 v[26:27], v[26:27], v[52:53] op_sel_hi:[1,0]
	v_pk_mul_f32 v[24:25], v[24:25], v[52:53] op_sel_hi:[1,0]
	v_pk_mul_f32 v[22:23], v[22:23], v[52:53] op_sel_hi:[1,0]
	v_pk_mul_f32 v[20:21], v[20:21], v[52:53] op_sel_hi:[1,0]
	v_pk_mul_f32 v[18:19], v[18:19], v[52:53] op_sel_hi:[1,0]
	v_mul_f32_e32 v173, v173, v52
	v_mov_b32_e32 v51, v50
	v_mov_b32_e32 v52, v50
	v_mov_b32_e32 v53, v50
	v_mov_b32_e32 v54, v50
	v_mov_b32_e32 v55, v50
	v_mov_b32_e32 v56, v50
	v_mov_b32_e32 v57, v50
	v_mov_b32_e32 v58, v50
	v_mov_b32_e32 v59, v50
	v_mov_b32_e32 v60, v50
	v_mov_b32_e32 v61, v50
	v_mov_b32_e32 v62, v50
	v_mov_b32_e32 v63, v50
	v_mov_b32_e32 v64, v50
	v_mov_b32_e32 v65, v50
	s_branch .LBB0_792

; __device__ __forceinline__ float shfl_x(float v, int m, int lane) { return __builtin_bit_cast(float, __builtin_amdgcn_ds_bpermute((lane ^ m) << 2, __builtin_bit_cast(int, v))); }
; __device__ __forceinline__ float max3f(float a, float b, float c) { float r; asm("v_max3_f32 %0, %1, %2, %3" : "=v"(r) : "v"(a), "v"(b), "v"(c)); return r; }
; __device__ __forceinline__ void swa_unit3(LAS unsigned char* lds, const bf16_t* pb  , bf16_t* Yb  , int q0, int kvh,
;                                           const float* sinks  , unsigned long long* gss, const int wave_s) {
;     ...
;             float mxa = max3f(p0[0], p0[1], p1[0]), mxb = max3f(p0[2], p0[3], p1[1]); mxa = max3f(mxa, p1[2], p1[3]);
; #pragma unroll
;             for (int r = 4; r < 16; r += 4) { mxa = max3f(mxa, p0[r], p0[r + 1]); mxb = max3f(mxb, p0[r + 2], p0[r + 3]); mxa = max3f(mxa, p1[r], p1[r + 1]); mxb = max3f(mxb, p1[r + 2], p1[r + 3]); }
;             float mx = max3f(mxa, mxb, mxb);
;             mx = max3f(mx, shfl_x(mx, 32, lane), mx);
;             if (__builtin_amdgcn_ballot_w64(mx > RESC_THR) != 0ull) {
;                 const float dl = fmaxf(mx, 0.f), f = __builtin_amdgcn_exp2f(-dl);
;                 m_run += dl; l_run *= f;
; #pragma unroll
;                 for (int r = 0; r < 16; ++r) { p0[r] -= dl; p1[r] -= dl; o0[r] *= f; o1[r] *= f; negm[r] = -m_run; }
;             }
.LBB0_813:
	v_max3_f32 v14, v82, v83, v66
	v_max3_f32 v15, v84, v85, v67
	s_nop 0
	v_max3_f32 v14, v14, v68, v69
	v_max3_f32 v15, v15, v88, v89
	s_nop 0
	v_max3_f32 v14, v14, v86, v87
	v_max3_f32 v15, v15, v72, v73
	s_nop 0
	v_max3_f32 v14, v14, v70, v71
	v_max3_f32 v15, v15, v92, v93
	s_nop 0
	v_max3_f32 v14, v14, v90, v91
	v_max3_f32 v15, v15, v76, v77
	s_nop 0
	v_max3_f32 v14, v14, v74, v75
	v_max3_f32 v15, v15, v96, v97
	s_nop 0
	v_max3_f32 v14, v14, v94, v95
	v_max3_f32 v15, v15, v80, v81
	s_nop 0
	v_max3_f32 v14, v14, v78, v79
	s_nop 0
	v_max3_f32 v14, v14, v15, v15
	ds_bpermute_b32 v15, v17, v14
	s_waitcnt lgkmcnt(0)
	v_max3_f32 v14, v14, v15, v14
	s_nop 0
	v_cmp_lt_f32_e32 vcc, s39, v14
	s_cbranch_vccz .LBB0_808
	v_max_f32_e32 v14, v14, v14
	v_max_f32_e32 v14, 0, v14
	v_exp_f32_e64 v52, -v14
	v_add_f32_e32 v0, v0, v14
	v_xor_b32_e32 v50, 0x80000000, v0
	v_pk_add_f32 v[82:83], v[82:83], v[14:15] op_sel_hi:[1,0] neg_lo:[0,1] neg_hi:[0,1]
	v_pk_add_f32 v[66:67], v[66:67], v[14:15] op_sel_hi:[1,0] neg_lo:[0,1] neg_hi:[0,1]
	v_pk_add_f32 v[84:85], v[84:85], v[14:15] op_sel_hi:[1,0] neg_lo:[0,1] neg_hi:[0,1]
	v_pk_add_f32 v[68:69], v[68:69], v[14:15] op_sel_hi:[1,0] neg_lo:[0,1] neg_hi:[0,1]
	v_pk_add_f32 v[86:87], v[86:87], v[14:15] op_sel_hi:[1,0] neg_lo:[0,1] neg_hi:[0,1]
	v_pk_add_f32 v[70:71], v[70:71], v[14:15] op_sel_hi:[1,0] neg_lo:[0,1] neg_hi:[0,1]
	v_pk_add_f32 v[88:89], v[88:89], v[14:15] op_sel_hi:[1,0] neg_lo:[0,1] neg_hi:[0,1]
	v_pk_add_f32 v[72:73], v[72:73], v[14:15] op_sel_hi:[1,0] neg_lo:[0,1] neg_hi:[0,1]
	v_pk_add_f32 v[90:91], v[90:91], v[14:15] op_sel_hi:[1,0] neg_lo:[0,1] neg_hi:[0,1]
	v_pk_add_f32 v[74:75], v[74:75], v[14:15] op_sel_hi:[1,0] neg_lo:[0,1] neg_hi:[0,1]
	v_pk_add_f32 v[92:93], v[92:93], v[14:15] op_sel_hi:[1,0] neg_lo:[0,1] neg_hi:[0,1]
	v_pk_add_f32 v[76:77], v[76:77], v[14:15] op_sel_hi:[1,0] neg_lo:[0,1] neg_hi:[0,1]
	v_pk_add_f32 v[94:95], v[94:95], v[14:15] op_sel_hi:[1,0] neg_lo:[0,1] neg_hi:[0,1]
	v_pk_add_f32 v[78:79], v[78:79], v[14:15] op_sel_hi:[1,0] neg_lo:[0,1] neg_hi:[0,1]
	v_pk_add_f32 v[96:97], v[96:97], v[14:15] op_sel_hi:[1,0] neg_lo:[0,1] neg_hi:[0,1]
	v_pk_add_f32 v[80:81], v[80:81], v[14:15] op_sel_hi:[1,0] neg_lo:[0,1] neg_hi:[0,1]
	v_pk_mul_f32 v[48:49], v[48:49], v[52:53] op_sel_hi:[1,0]
	v_pk_mul_f32 v[46:47], v[46:47], v[52:53] op_sel_hi:[1,0]
	v_pk_mul_f32 v[44:45], v[44:45], v[52:53] op_sel_hi:[1,0]
	v_pk_mul_f32 v[42:43], v[42:43], v[52:53] op_sel_hi:[1,0]
	v_pk_mul_f32 v[40:41], v[40:41], v[52:53] op_sel_hi:[1,0]
	v_pk_mul_f32 v[38:39], v[38:39], v[52:53] op_sel_hi:[1,0]
	v_pk_mul_f32 v[36:37], v[36:37], v[52:53] op_sel_hi:[1,0]
	v_pk_mul_f32 v[34:35], v[34:35], v[52:53] op_sel_hi:[1,0]
	v_pk_mul_f32 v[32:33], v[32:33], v[52:53] op_sel_hi:[1,0]
	v_pk_mul_f32 v[30:31], v[30:31], v[52:53] op_sel_hi:[1,0]
	v_pk_mul_f32 v[28:29], v[28:29], v[52:53] op_sel_hi:[1,0]
	v_pk_mul_f32 v[26:27], v[26:27], v[52:53] op_sel_hi:[1,0]
	v_pk_mul_f32 v[24:25], v[24:25], v[52:53] op_sel_hi:[1,0]
	v_pk_mul_f32 v[22:23], v[22:23], v[52:53] op_sel_hi:[1,0]
	v_pk_mul_f32 v[20:21], v[20:21], v[52:53] op_sel_hi:[1,0]
	v_pk_mul_f32 v[18:19], v[18:19], v[52:53] op_sel_hi:[1,0]
	v_mul_f32_e32 v154, v154, v52
	v_mov_b32_e32 v51, v50
	v_mov_b32_e32 v52, v50
	v_mov_b32_e32 v53, v50
	v_mov_b32_e32 v54, v50
	v_mov_b32_e32 v55, v50
	v_mov_b32_e32 v56, v50
	v_mov_b32_e32 v57, v50
	v_mov_b32_e32 v58, v50
	v_mov_b32_e32 v59, v50
	v_mov_b32_e32 v60, v50
	v_mov_b32_e32 v61, v50
	v_mov_b32_e32 v62, v50
	v_mov_b32_e32 v63, v50
	v_mov_b32_e32 v64, v50
	v_mov_b32_e32 v65, v50
	s_branch .LBB0_808

; __device__ __forceinline__ float shfl_x(float v, int m, int lane) { return __builtin_bit_cast(float, __builtin_amdgcn_ds_bpermute((lane ^ m) << 2, __builtin_bit_cast(int, v))); }
; __device__ __forceinline__ float max3f(float a, float b, float c) { float r; asm("v_max3_f32 %0, %1, %2, %3" : "=v"(r) : "v"(a), "v"(b), "v"(c)); return r; }
; __device__ __forceinline__ void swa_unit3(LAS unsigned char* lds, const bf16_t* pb  , bf16_t* Yb  , int q0, int kvh,
;                                           const float* sinks  , unsigned long long* gss, const int wave_s) {
;     ...
;             float mxa = max3f(p0[0], p0[1], p1[0]), mxb = max3f(p0[2], p0[3], p1[1]); mxa = max3f(mxa, p1[2], p1[3]);
; #pragma unroll
;             for (int r = 4; r < 16; r += 4) { mxa = max3f(mxa, p0[r], p0[r + 1]); mxb = max3f(mxb, p0[r + 2], p0[r + 3]); mxa = max3f(mxa, p1[r], p1[r + 1]); mxb = max3f(mxb, p1[r + 2], p1[r + 3]); }
;             float mx = max3f(mxa, mxb, mxb);
;             mx = max3f(mx, shfl_x(mx, 32, lane), mx);
;             if (__builtin_amdgcn_ballot_w64(mx > RESC_THR) != 0ull) {
;                 const float dl = fmaxf(mx, 0.f), f = __builtin_amdgcn_exp2f(-dl);
;                 m_run += dl; l_run *= f;
; #pragma unroll
;                 for (int r = 0; r < 16; ++r) { p0[r] -= dl; p1[r] -= dl; o0[r] *= f; o1[r] *= f; negm[r] = -m_run; }
;             }
.LBB0_825:
	v_max3_f32 v14, v82, v83, v66
	v_max3_f32 v15, v84, v85, v67
	s_nop 0
	v_max3_f32 v14, v14, v68, v69
	v_max3_f32 v15, v15, v88, v89
	s_nop 0
	v_max3_f32 v14, v14, v86, v87
	v_max3_f32 v15, v15, v72, v73
	s_nop 0
	v_max3_f32 v14, v14, v70, v71
	v_max3_f32 v15, v15, v92, v93
	s_nop 0
	v_max3_f32 v14, v14, v90, v91
	v_max3_f32 v15, v15, v76, v77
	s_nop 0
	v_max3_f32 v14, v14, v74, v75
	v_max3_f32 v15, v15, v96, v97
	s_nop 0
	v_max3_f32 v14, v14, v94, v95
	v_max3_f32 v15, v15, v80, v81
	s_nop 0
	v_max3_f32 v14, v14, v78, v79
	s_nop 0
	v_max3_f32 v14, v14, v15, v15
	ds_bpermute_b32 v15, v17, v14
	s_waitcnt lgkmcnt(0)
	v_max3_f32 v14, v14, v15, v14
	s_nop 0
	v_cmp_lt_f32_e32 vcc, s39, v14
	s_cbranch_vccz .LBB0_820
	v_max_f32_e32 v14, v14, v14
	v_max_f32_e32 v14, 0, v14
	v_exp_f32_e64 v52, -v14
	v_add_f32_e32 v0, v0, v14
	v_xor_b32_e32 v50, 0x80000000, v0
	v_pk_add_f32 v[82:83], v[82:83], v[14:15] op_sel_hi:[1,0] neg_lo:[0,1] neg_hi:[0,1]
	v_pk_add_f32 v[66:67], v[66:67], v[14:15] op_sel_hi:[1,0] neg_lo:[0,1] neg_hi:[0,1]
	v_pk_add_f32 v[84:85], v[84:85], v[14:15] op_sel_hi:[1,0] neg_lo:[0,1] neg_hi:[0,1]
	v_pk_add_f32 v[68:69], v[68:69], v[14:15] op_sel_hi:[1,0] neg_lo:[0,1] neg_hi:[0,1]
	v_pk_add_f32 v[86:87], v[86:87], v[14:15] op_sel_hi:[1,0] neg_lo:[0,1] neg_hi:[0,1]
	v_pk_add_f32 v[70:71], v[70:71], v[14:15] op_sel_hi:[1,0] neg_lo:[0,1] neg_hi:[0,1]
	v_pk_add_f32 v[88:89], v[88:89], v[14:15] op_sel_hi:[1,0] neg_lo:[0,1] neg_hi:[0,1]
	v_pk_add_f32 v[72:73], v[72:73], v[14:15] op_sel_hi:[1,0] neg_lo:[0,1] neg_hi:[0,1]
	v_pk_add_f32 v[90:91], v[90:91], v[14:15] op_sel_hi:[1,0] neg_lo:[0,1] neg_hi:[0,1]
	v_pk_add_f32 v[74:75], v[74:75], v[14:15] op_sel_hi:[1,0] neg_lo:[0,1] neg_hi:[0,1]
	v_pk_add_f32 v[92:93], v[92:93], v[14:15] op_sel_hi:[1,0] neg_lo:[0,1] neg_hi:[0,1]
	v_pk_add_f32 v[76:77], v[76:77], v[14:15] op_sel_hi:[1,0] neg_lo:[0,1] neg_hi:[0,1]
	v_pk_add_f32 v[94:95], v[94:95], v[14:15] op_sel_hi:[1,0] neg_lo:[0,1] neg_hi:[0,1]
	v_pk_add_f32 v[78:79], v[78:79], v[14:15] op_sel_hi:[1,0] neg_lo:[0,1] neg_hi:[0,1]
	v_pk_add_f32 v[96:97], v[96:97], v[14:15] op_sel_hi:[1,0] neg_lo:[0,1] neg_hi:[0,1]
	v_pk_add_f32 v[80:81], v[80:81], v[14:15] op_sel_hi:[1,0] neg_lo:[0,1] neg_hi:[0,1]
	v_pk_mul_f32 v[48:49], v[48:49], v[52:53] op_sel_hi:[1,0]
	v_pk_mul_f32 v[46:47], v[46:47], v[52:53] op_sel_hi:[1,0]
	v_pk_mul_f32 v[44:45], v[44:45], v[52:53] op_sel_hi:[1,0]
	v_pk_mul_f32 v[42:43], v[42:43], v[52:53] op_sel_hi:[1,0]
	v_pk_mul_f32 v[40:41], v[40:41], v[52:53] op_sel_hi:[1,0]
	v_pk_mul_f32 v[38:39], v[38:39], v[52:53] op_sel_hi:[1,0]
	v_pk_mul_f32 v[36:37], v[36:37], v[52:53] op_sel_hi:[1,0]
	v_pk_mul_f32 v[34:35], v[34:35], v[52:53] op_sel_hi:[1,0]
	v_pk_mul_f32 v[32:33], v[32:33], v[52:53] op_sel_hi:[1,0]
	v_pk_mul_f32 v[30:31], v[30:31], v[52:53] op_sel_hi:[1,0]
	v_pk_mul_f32 v[28:29], v[28:29], v[52:53] op_sel_hi:[1,0]
	v_pk_mul_f32 v[26:27], v[26:27], v[52:53] op_sel_hi:[1,0]
	v_pk_mul_f32 v[24:25], v[24:25], v[52:53] op_sel_hi:[1,0]
	v_pk_mul_f32 v[22:23], v[22:23], v[52:53] op_sel_hi:[1,0]
	v_pk_mul_f32 v[20:21], v[20:21], v[52:53] op_sel_hi:[1,0]
	v_pk_mul_f32 v[18:19], v[18:19], v[52:53] op_sel_hi:[1,0]
	v_mul_f32_e32 v134, v134, v52
	v_mov_b32_e32 v51, v50
	v_mov_b32_e32 v52, v50
	v_mov_b32_e32 v53, v50
	v_mov_b32_e32 v54, v50
	v_mov_b32_e32 v55, v50
	v_mov_b32_e32 v56, v50
	v_mov_b32_e32 v57, v50
	v_mov_b32_e32 v58, v50
	v_mov_b32_e32 v59, v50
	v_mov_b32_e32 v60, v50
	v_mov_b32_e32 v61, v50
	v_mov_b32_e32 v62, v50
	v_mov_b32_e32 v63, v50
	v_mov_b32_e32 v64, v50
	v_mov_b32_e32 v65, v50
	s_branch .LBB0_820

; __device__ __forceinline__ float shfl_x(float v, int m, int lane) { return __builtin_bit_cast(float, __builtin_amdgcn_ds_bpermute((lane ^ m) << 2, __builtin_bit_cast(int, v))); }
; __device__ __forceinline__ float max3f(float a, float b, float c) { float r; asm("v_max3_f32 %0, %1, %2, %3" : "=v"(r) : "v"(a), "v"(b), "v"(c)); return r; }
; template <int NDS, int MODE> ...
;     ...
;             float mxa = max3f(p0[0], p0[1], p1[0]), mxb = max3f(p0[2], p0[3], p1[1]); mxa = max3f(mxa, p1[2], p1[3]);
; #pragma unroll
;             for (int r = 4; r < 16; r += 4) { mxa = max3f(mxa, p0[r], p0[r + 1]); mxb = max3f(mxb, p0[r + 2], p0[r + 3]); mxa = max3f(mxa, p1[r], p1[r + 1]); mxb = max3f(mxb, p1[r + 2], p1[r + 3]); }
;             float mx = max3f(mxa, mxb, mxb);
;             mx = max3f(mx, shfl_x(mx, 32, lane), mx);
;             if (first || __builtin_amdgcn_ballot_w64(mx > RESC_THR) != 0ull) {
;                 const float dl = first ? mx : fmaxf(mx, 0.f);
;                 const float f = first ? 1.0f : __builtin_amdgcn_exp2f(-dl);
.LBB0_933:
	v_max3_f32 v0, v96, v97, v80
	v_max3_f32 v30, v98, v99, v81
	s_xor_b64 s[2:3], s[36:37], -1
	v_max3_f32 v0, v0, v82, v83
	v_max3_f32 v30, v30, v102, v103
	s_and_b64 vcc, exec, s[2:3]
	v_max3_f32 v0, v0, v100, v101
	v_max3_f32 v30, v30, v86, v87
	s_nop 0
	v_max3_f32 v0, v0, v84, v85
	v_max3_f32 v30, v30, v106, v107
	s_nop 0
	v_max3_f32 v0, v0, v104, v105
	v_max3_f32 v30, v30, v90, v91
	s_nop 0
	v_max3_f32 v0, v0, v88, v89
	v_max3_f32 v30, v30, v110, v111
	s_nop 0
	v_max3_f32 v0, v0, v108, v109
	v_max3_f32 v30, v30, v94, v95
	s_nop 0
	v_max3_f32 v0, v0, v92, v93
	s_nop 0
	v_max3_f32 v0, v0, v30, v30
	ds_bpermute_b32 v30, v194, v0
	s_waitcnt lgkmcnt(0)
	v_max3_f32 v30, v0, v30, v0
	s_cbranch_vccz .LBB0_957
	v_cmp_lt_f32_e32 vcc, s39, v30
	s_mov_b64 s[4:5], 0
	s_mov_b64 s[40:41], 0
	s_cbranch_vccz .LBB0_936
	v_max_f32_e32 v0, v30, v30
	v_max_f32_e32 v0, 0, v0
	s_mov_b64 s[40:41], -1

; __device__ __forceinline__ float shfl_x(float v, int m, int lane) { return __builtin_bit_cast(float, __builtin_amdgcn_ds_bpermute((lane ^ m) << 2, __builtin_bit_cast(int, v))); }
; __device__ __forceinline__ float max3f(float a, float b, float c) { float r; asm("v_max3_f32 %0, %1, %2, %3" : "=v"(r) : "v"(a), "v"(b), "v"(c)); return r; }
; template <int NDS, int MODE> ...
;     ...
;             float mxa = max3f(p0[0], p0[1], p1[0]), mxb = max3f(p0[2], p0[3], p1[1]); mxa = max3f(mxa, p1[2], p1[3]);
; #pragma unroll
;             for (int r = 4; r < 16; r += 4) { mxa = max3f(mxa, p0[r], p0[r + 1]); mxb = max3f(mxb, p0[r + 2], p0[r + 3]); mxa = max3f(mxa, p1[r], p1[r + 1]); mxb = max3f(mxb, p1[r + 2], p1[r + 3]); }
;             float mx = max3f(mxa, mxb, mxb);
;             mx = max3f(mx, shfl_x(mx, 32, lane), mx);
;             if (first || __builtin_amdgcn_ballot_w64(mx > RESC_THR) != 0ull) {
;                 const float dl = first ? mx : fmaxf(mx, 0.f);
;                 const float f = first ? 1.0f : __builtin_amdgcn_exp2f(-dl);
.LBB0_945:
	v_max3_f32 v0, v96, v97, v80
	v_max3_f32 v15, v98, v99, v81
	s_xor_b64 s[2:3], s[36:37], -1
	v_max3_f32 v0, v0, v82, v83
	v_max3_f32 v15, v15, v102, v103
	s_and_b64 vcc, exec, s[2:3]
	v_max3_f32 v0, v0, v100, v101
	v_max3_f32 v15, v15, v86, v87
	s_nop 0
	v_max3_f32 v0, v0, v84, v85
	v_max3_f32 v15, v15, v106, v107
	s_nop 0
	v_max3_f32 v0, v0, v104, v105
	v_max3_f32 v15, v15, v90, v91
	s_nop 0
	v_max3_f32 v0, v0, v88, v89
	v_max3_f32 v15, v15, v110, v111
	s_nop 0
	v_max3_f32 v0, v0, v108, v109
	v_max3_f32 v15, v15, v94, v95
	s_nop 0
	v_max3_f32 v0, v0, v92, v93
	s_nop 0
	v_max3_f32 v0, v0, v15, v15
	ds_bpermute_b32 v15, v194, v0
	s_waitcnt lgkmcnt(0)
	v_max3_f32 v15, v0, v15, v0
	s_cbranch_vccz .LBB0_958
	v_cmp_lt_f32_e32 vcc, s39, v15
	s_mov_b64 s[4:5], 0
	s_mov_b64 s[40:41], 0
	s_cbranch_vccz .LBB0_948
	v_max_f32_e32 v0, v15, v15
	v_max_f32_e32 v0, 0, v0
	s_mov_b64 s[40:41], -1

; __device__ __forceinline__ float shfl_x(float v, int m, int lane) { return __builtin_bit_cast(float, __builtin_amdgcn_ds_bpermute((lane ^ m) << 2, __builtin_bit_cast(int, v))); }
; __device__ __forceinline__ float max3f(float a, float b, float c) { float r; asm("v_max3_f32 %0, %1, %2, %3" : "=v"(r) : "v"(a), "v"(b), "v"(c)); return r; }
; template <int NDS, int MODE> ...
;     ...
;             float mxa = max3f(p0[0], p0[1], p1[0]), mxb = max3f(p0[2], p0[3], p1[1]); mxa = max3f(mxa, p1[2], p1[3]);
; #pragma unroll
;             for (int r = 4; r < 16; r += 4) { mxa = max3f(mxa, p0[r], p0[r + 1]); mxb = max3f(mxb, p0[r + 2], p0[r + 3]); mxa = max3f(mxa, p1[r], p1[r + 1]); mxb = max3f(mxb, p1[r + 2], p1[r + 3]); }
;             float mx = max3f(mxa, mxb, mxb);
;             mx = max3f(mx, shfl_x(mx, 32, lane), mx);
;             if (first || __builtin_amdgcn_ballot_w64(mx > RESC_THR) != 0ull) {
;                 const float dl = first ? mx : fmaxf(mx, 0.f);
;                 const float f = first ? 1.0f : __builtin_amdgcn_exp2f(-dl);
.LBB0_983:
	v_max3_f32 v30, v96, v97, v80
	v_max3_f32 v178, v98, v99, v81
	s_xor_b64 s[2:3], s[14:15], -1
	v_max3_f32 v30, v30, v82, v83
	v_max3_f32 v178, v178, v102, v103
	s_and_b64 vcc, exec, s[2:3]
	v_max3_f32 v30, v30, v100, v101
	v_max3_f32 v178, v178, v86, v87
	s_nop 0
	v_max3_f32 v30, v30, v84, v85
	v_max3_f32 v178, v178, v106, v107
	s_nop 0
	v_max3_f32 v30, v30, v104, v105
	v_max3_f32 v178, v178, v90, v91
	s_nop 0
	v_max3_f32 v30, v30, v88, v89
	v_max3_f32 v178, v178, v110, v111
	s_nop 0
	v_max3_f32 v30, v30, v108, v109
	v_max3_f32 v178, v178, v94, v95
	s_nop 0
	v_max3_f32 v30, v30, v92, v93
	s_nop 0
	v_max3_f32 v30, v30, v178, v178
	ds_bpermute_b32 v178, v174, v30
	s_waitcnt lgkmcnt(0)
	v_max3_f32 v199, v30, v178, v30
	s_cbranch_vccz .LBB0_1007
	v_cmp_lt_f32_e32 vcc, s39, v199
	s_mov_b64 s[4:5], 0
	s_mov_b64 s[16:17], 0
	s_cbranch_vccz .LBB0_986
	v_max_f32_e32 v30, v199, v199
	v_max_f32_e32 v30, 0, v30
	s_mov_b64 s[16:17], -1

; __device__ __forceinline__ float shfl_x(float v, int m, int lane) { return __builtin_bit_cast(float, __builtin_amdgcn_ds_bpermute((lane ^ m) << 2, __builtin_bit_cast(int, v))); }
; __device__ __forceinline__ float max3f(float a, float b, float c) { float r; asm("v_max3_f32 %0, %1, %2, %3" : "=v"(r) : "v"(a), "v"(b), "v"(c)); return r; }
; template <int NDS, int MODE> ...
;     ...
;             float mxa = max3f(p0[0], p0[1], p1[0]), mxb = max3f(p0[2], p0[3], p1[1]); mxa = max3f(mxa, p1[2], p1[3]);
; #pragma unroll
;             for (int r = 4; r < 16; r += 4) { mxa = max3f(mxa, p0[r], p0[r + 1]); mxb = max3f(mxb, p0[r + 2], p0[r + 3]); mxa = max3f(mxa, p1[r], p1[r + 1]); mxb = max3f(mxb, p1[r + 2], p1[r + 3]); }
;             float mx = max3f(mxa, mxb, mxb);
;             mx = max3f(mx, shfl_x(mx, 32, lane), mx);
;             if (first || __builtin_amdgcn_ballot_w64(mx > RESC_THR) != 0ull) {
;                 const float dl = first ? mx : fmaxf(mx, 0.f);
;                 const float f = first ? 1.0f : __builtin_amdgcn_exp2f(-dl);
.LBB0_995:
	v_max3_f32 v17, v96, v97, v80
	v_max3_f32 v30, v98, v99, v81
	s_xor_b64 s[2:3], s[14:15], -1
	v_max3_f32 v17, v17, v82, v83
	v_max3_f32 v30, v30, v102, v103
	s_and_b64 vcc, exec, s[2:3]
	v_max3_f32 v17, v17, v100, v101
	v_max3_f32 v30, v30, v86, v87
	s_nop 0
	v_max3_f32 v17, v17, v84, v85
	v_max3_f32 v30, v30, v106, v107
	s_nop 0
	v_max3_f32 v17, v17, v104, v105
	v_max3_f32 v30, v30, v90, v91
	s_nop 0
	v_max3_f32 v17, v17, v88, v89
	v_max3_f32 v30, v30, v110, v111
	s_nop 0
	v_max3_f32 v17, v17, v108, v109
	v_max3_f32 v30, v30, v94, v95
	s_nop 0
	v_max3_f32 v17, v17, v92, v93
	s_nop 0
	v_max3_f32 v17, v17, v30, v30
	ds_bpermute_b32 v30, v174, v17
	s_waitcnt lgkmcnt(0)
	v_max3_f32 v17, v17, v30, v17
	s_cbranch_vccz .LBB0_1008
	v_cmp_lt_f32_e32 vcc, s39, v17
	s_mov_b64 s[4:5], 0
	s_mov_b64 s[16:17], 0
	s_cbranch_vccz .LBB0_998
	v_max_f32_e32 v30, v17, v17
	v_max_f32_e32 v30, 0, v30
	s_mov_b64 s[16:17], -1

; #define PG8_GCPTR(p) ((__attribute__((address_space(1))) const char*)(p))
; __device__ __forceinline__ float ssq_val(ssq_t v) { return (float)v * SSQ_IFX; }
;     __device__ __forceinline__ void operator()(const f32x4 (&acc)[2][2][4][2], const Unit& u, int wr, int wc, int fr, int fq) const {
;     ...
;         if constexpr (GN) { ssq_t sc_[8];
; #pragma unroll
;             for (int i = 0; i < 8; ++i) sc_[i] = gsc[u.pm * BM + wr * 64 + fr + (i >> 2) * HALF + (i & 3) * 16];
; #pragma unroll
;             for (int i = 0; i < 8; ++i) rc[i] = 1.0f / sqrtf(ssq_val(sc_[i]) * (1.0f / 256.0f) + EPS); }
;         const int col0 = u.pn * BM + wc * 32 + 8 * fq; const int b = (u.pm * BM) >> 12;
;         const float* gp = gate + (size_t)b * NMOD + col0; const float* sp = sc + (size_t)b * NMOD + col0;
;         f32x4 g[2][2], cf[2][2];
; #pragma unroll
;         for (int bj = 0; bj < 2; ++bj) {
;             g[bj][0] = *(const f32x4*)(gp + bj * HALF); g[bj][1] = *(const f32x4*)(gp + bj * HALF + 4);
;             const f32x4 n0 = *(const f32x4*)(nw + col0 + bj * HALF), n1 = *(const f32x4*)(nw + col0 + bj * HALF + 4);
;             const f32x4 c0 = *(const f32x4*)(sp + bj * HALF), c1 = *(const f32x4*)(sp + bj * HALF + 4);
;             cf[bj][0] = n0 * (c0 + 1.0f); cf[bj][1] = n1 * (c1 + 1.0f);
;         }
; #pragma unroll
;         for (int ai = 0; ai < 2; ++ai)
; #pragma unroll
;         for (int mp = 0; mp < 4; mp += 2) {
;             u32x4 bv[2][2];
; #pragma unroll
;             for (int mm = 0; mm < 2; ++mm)
; #pragma unroll
;                 for (int bj = 0; bj < 2; ++bj)
;                     bv[mm][bj] = *(gl_u32x4*)(PG8_GCPTR(base) + (unsigned)((u.pm * BM + ai * HALF + wr * 64 + (mp + mm) * 16 + fr) * DM + col0 + bj * HALF) * 2u);
.LBB0_1087:
	s_lshl_b32 s2, s10, 8
	v_mbcnt_lo_u32_b32 v0, -1, 0
	v_mbcnt_hi_u32_b32 v0, -1, v0
	s_add_i32 s2, s2, s90
	v_and_b32_e32 v182, 15, v0
	v_or_b32_e32 v216, s2, v182
	v_ashrrev_i32_e32 v217, 31, v216
	v_lshl_add_u64 v[2:3], v[216:217], 3, s[16:17]
	flat_load_dwordx2 v[70:71], v[2:3]
	flat_load_dwordx2 v[218:219], v[2:3] offset:128
	flat_load_dwordx2 v[214:215], v[2:3] offset:256
	flat_load_dwordx2 v[212:213], v[2:3] offset:384
	flat_load_dwordx2 v[210:211], v[2:3] offset:1024
	flat_load_dwordx2 v[208:209], v[2:3] offset:1152
	flat_load_dwordx2 v[206:207], v[2:3] offset:1280
	s_nop 0
	flat_load_dwordx2 v[2:3], v[2:3] offset:1408
	v_bfe_u32 v183, v0, 4, 2
	v_lshlrev_b32_e32 v232, 11, v216
	s_waitcnt vmcnt(0) lgkmcnt(0)
	v_ffbh_u32_e32 v0, v71
	v_min_u32_e32 v0, 32, v0
	v_lshlrev_b64 v[70:71], v0, v[70:71]
	v_min_u32_e32 v70, 1, v70
	v_or_b32_e32 v70, v71, v70
	v_cvt_f32_u32_e32 v70, v70
	v_sub_u32_e32 v0, 32, v0
	v_ldexp_f32 v0, v70, v0
	v_mul_f32_e32 v0, 0x33800000, v0
	v_fmamk_f32 v0, v0, 0x3b800000, v226
	v_cmp_gt_f32_e32 vcc, s71, v0
	v_mul_f32_e32 v70, 0x4f800000, v0
	s_nop 0
	v_cndmask_b32_e32 v0, v0, v70, vcc
	v_sqrt_f32_e32 v70, v0
	s_nop 0
	v_add_u32_e32 v71, -1, v70
	v_fma_f32 v72, -v71, v70, v0
	v_cmp_ge_f32_e64 s[8:9], 0, v72
	v_add_u32_e32 v72, 1, v70
	s_nop 0
	v_cndmask_b32_e64 v71, v70, v71, s[8:9]
	v_fma_f32 v70, -v72, v70, v0
	v_cmp_lt_f32_e64 s[8:9], 0, v70
	s_nop 1
	v_cndmask_b32_e64 v70, v71, v72, s[8:9]
	v_mul_f32_e32 v71, 0x37800000, v70
	v_cndmask_b32_e32 v70, v70, v71, vcc
	v_cmp_class_f32_e32 vcc, v0, v223
	v_cmp_eq_u32_e64 s[8:9], 0, v183
	s_nop 0
	v_cndmask_b32_e32 v0, v70, v0, vcc
	v_div_scale_f32 v70, s[2:3], v0, v0, 1.0
	v_rcp_f32_e32 v71, v70
	s_lshl_b32 s2, s50, 8
	v_fma_f32 v72, -v70, v71, 1.0
	v_fmac_f32_e32 v71, v72, v71
	v_div_scale_f32 v72, vcc, 1.0, v0, 1.0
	v_mul_f32_e32 v73, v72, v71
	v_fma_f32 v74, -v70, v73, v72
	v_fmac_f32_e32 v73, v74, v71
	v_fma_f32 v70, -v70, v73, v72
	v_div_fmas_f32 v70, v70, v71, v73
	v_div_fixup_f32 v0, v70, v0, 1.0
	v_lshl_or_b32 v70, v183, 3, s2
	s_ashr_i32 s2, s10, 4
	v_or_b32_e32 v180, s91, v70
	s_mul_i32 s5, s2, 0x6000
	s_mul_hi_i32 s4, s2, 0x6000
	s_add_u32 s2, s52, s5
	v_ashrrev_i32_e32 v181, 31, v180
	s_addc_u32 s3, s83, s4
	v_lshlrev_b64 v[70:71], 2, v[180:181]
	v_lshl_add_u64 v[158:159], s[2:3], 0, v[70:71]
	s_add_u32 s2, s88, s5
	s_addc_u32 s3, s89, s4
	v_lshl_add_u64 v[174:175], s[2:3], 0, v[70:71]
	v_lshl_add_u64 v[160:161], s[20:21], 0, v[70:71]
	flat_load_dwordx4 v[82:85], v[158:159]
	flat_load_dwordx4 v[78:81], v[158:159] offset:16
	global_load_dwordx4 v[70:73], v[160:161], off offset:16
	global_load_dwordx4 v[74:77], v[160:161], off
	flat_load_dwordx4 v[150:153], v[174:175]
	flat_load_dwordx4 v[154:157], v[174:175] offset:16
	v_lshlrev_b32_e32 v230, 1, v180
	v_add_u32_e32 v231, v230, v232
	v_and_b32_e32 v240, 0xffff8000, v231
	v_bfe_u32 v241, v231, 11, 4
	v_lshl_or_b32 v240, v241, 6, v240
	v_bfe_u32 v241, v231, 9, 2
	v_lshl_or_b32 v240, v241, 13, v240
	v_bfe_u32 v241, v231, 6, 2
	v_lshl_or_b32 v240, v241, 11, v240
	v_and_b32_e32 v241, 48, v231
	v_or_b32_e32 v240, v240, v241
	s_movk_i32 s2, 0x80
	v_pk_mul_f32 v[146:147], v[146:147], v[0:1] op_sel_hi:[1,0]
	v_pk_mul_f32 v[148:149], v[148:149], v[0:1] op_sel_hi:[1,0]
	v_pk_mul_f32 v[142:143], v[142:143], v[0:1] op_sel_hi:[1,0]
	v_pk_mul_f32 v[144:145], v[144:145], v[0:1] op_sel_hi:[1,0]
	v_pk_mul_f32 v[138:139], v[138:139], v[0:1] op_sel_hi:[1,0]
	v_pk_mul_f32 v[140:141], v[140:141], v[0:1] op_sel_hi:[1,0]
	v_pk_mul_f32 v[134:135], v[134:135], v[0:1] op_sel_hi:[1,0]
	v_pk_mul_f32 v[136:137], v[136:137], v[0:1] op_sel_hi:[1,0]
	s_waitcnt vmcnt(0) lgkmcnt(0)
	v_pk_add_f32 v[152:153], v[152:153], 1.0 op_sel_hi:[1,0]
	v_pk_add_f32 v[150:151], v[150:151], 1.0 op_sel_hi:[1,0]
	v_pk_mul_f32 v[200:201], v[76:77], v[152:153]
	v_pk_mul_f32 v[204:205], v[74:75], v[150:151]
	v_pk_add_f32 v[74:75], v[156:157], 1.0 op_sel_hi:[1,0]
	v_pk_add_f32 v[76:77], v[154:155], 1.0 op_sel_hi:[1,0]
	v_pk_mul_f32 v[198:199], v[72:73], v[74:75]
	v_pk_mul_f32 v[202:203], v[70:71], v[76:77]
	flat_load_dwordx4 v[74:77], v[158:159] offset:512
	flat_load_dwordx4 v[70:73], v[158:159] offset:528
	global_load_dwordx4 v[150:153], v[160:161], off offset:528
	global_load_dwordx4 v[154:157], v[160:161], off offset:512
	s_nop 0
	flat_load_dwordx4 v[158:161], v[174:175] offset:512
	flat_load_dwordx4 v[176:179], v[174:175] offset:528
	s_waitcnt vmcnt(0) lgkmcnt(0)
	v_pk_add_f32 v[160:161], v[160:161], 1.0 op_sel_hi:[1,0]
	v_pk_add_f32 v[158:159], v[158:159], 1.0 op_sel_hi:[1,0]
	v_pk_mul_f32 v[196:197], v[156:157], v[160:161]
	v_pk_mul_f32 v[174:175], v[154:155], v[158:159]
	v_pk_add_f32 v[154:155], v[178:179], 1.0 op_sel_hi:[1,0]
	global_load_dwordx4 v[178:181], v240, s[22:23]
	global_load_dwordx4 v[158:161], v240, s[22:23] offset:1024
	v_pk_add_f32 v[156:157], v[176:177], 1.0 op_sel_hi:[1,0]
	v_pk_mul_f32 v[176:177], v[152:153], v[154:155]
	v_pk_mul_f32 v[194:195], v[150:151], v[156:157]
	v_lshlrev_b32_e32 v150, 6, v183
	v_lshlrev_b32_e32 v151, 2, v182
	v_bitop3_b32 v229, v150, 64, v151 bitop3:0x36
	v_bitop3_b32 v228, v150, s2, v151 bitop3:0x36
	v_add_u32_e32 v150, 0x8000, v240
	global_load_dwordx4 v[154:157], v150, s[22:23]
	s_nop 0
	global_load_dwordx4 v[150:153], v150, s[22:23] offset:1024
	s_waitcnt vmcnt(3)
; __device__ __forceinline__ unsigned cvt_pk_bf16(float lo, float hi) { unsigned r; asm volatile("v_cvt_pk_bf16_f32 %0, %1, %2" : "=v"(r) : "v"(lo), "v"(hi)); return r; }
; #define PG8_GPTR(p) ((__attribute__((address_space(1))) char*)(p))
;     __device__ __forceinline__ void operator()(const f32x4 (&acc)[2][2][4][2], const Unit& u, int wr, int wc, int fr, int fq) const {
;     ...
; #pragma unroll
;             for (int mm = 0; mm < 2; ++mm) {
;                 const int m = mp + mm;
;                 const int row = u.pm * BM + ai * HALF + wr * 64 + m * 16 + fr; float q = 0.f;
; #pragma unroll
;                 for (int bj = 0; bj < 2; ++bj) {
;                     const unsigned offb = (unsigned)(row * DM + col0 + bj * HALF) * 2u;
;                     const u32x4 bw = bv[mm][bj];
;                     const f32x4 b0 = (f32x4){__uint_as_float(bw.x << 16), __uint_as_float(bw.x & 0xffff0000u), __uint_as_float(bw.y << 16), __uint_as_float(bw.y & 0xffff0000u)};
;                     const f32x4 b1 = (f32x4){__uint_as_float(bw.z << 16), __uint_as_float(bw.z & 0xffff0000u), __uint_as_float(bw.w << 16), __uint_as_float(bw.w & 0xffff0000u)};
;                     f32x4 a0 = acc[ai][bj][m][0], a1 = acc[ai][bj][m][1]; if constexpr (GN) { a0 *= rc[ai * 4 + m]; a1 *= rc[ai * 4 + m]; }
;                     const f32x4 o0 = b0 + g[bj][0] * a0, o1 = b1 + g[bj][1] * a1;
;                     u32x4 wo; wo.x = cvt_pk_bf16(o0[0], o0[1]); wo.y = cvt_pk_bf16(o0[2], o0[3]); wo.z = cvt_pk_bf16(o1[0], o1[1]); wo.w = cvt_pk_bf16(o1[2], o1[3]);
;                     *(gs_u32x4*)(PG8_GPTR(out) + offb) = wo;
;                     if (xg) {
;                         const f32x4 h0 = o0 * cf[bj][0], h1 = o1 * cf[bj][1];
;                         u32x4 w; w.x = cvt_pk_bf16(h0[0], h0[1]); w.y = cvt_pk_bf16(h0[2], h0[3]); w.z = cvt_pk_bf16(h1[0], h1[1]); w.w = cvt_pk_bf16(h1[2], h1[3]);
;                         *(gs_u32x4*)(PG8_GPTR(xg) + offb) = w;
;                         q += (o0[0] * o0[0] + o0[1] * o0[1]) + (o0[2] * o0[2] + o0[3] * o0[3]) + (o1[0] * o1[0] + o1[1] * o1[1]) + (o1[2] * o1[2] + o1[3] * o1[3]);
;                     }
;                 }
;                 if (xg) ssq_put(ssq, row, q, fr, fq);
	v_lshlrev_b32_e32 v182, 16, v178
	v_and_b32_e32 v183, 0xffff0000, v178
	v_lshlrev_b32_e32 v178, 16, v179
	v_and_b32_e32 v179, 0xffff0000, v179
	v_lshlrev_b32_e32 v184, 16, v180
	v_and_b32_e32 v185, 0xffff0000, v180
	v_lshlrev_b32_e32 v180, 16, v181
	v_and_b32_e32 v181, 0xffff0000, v181
	v_pk_fma_f32 v[148:149], v[84:85], v[148:149], v[178:179]
	v_pk_fma_f32 v[146:147], v[82:83], v[146:147], v[182:183]
	v_pk_fma_f32 v[178:179], v[80:81], v[144:145], v[180:181]
	v_pk_fma_f32 v[180:181], v[78:79], v[142:143], v[184:185]
	v_cvt_pk_bf16_f32 v142, v146, v147
	v_cvt_pk_bf16_f32 v143, v148, v149
	v_pk_mul_f32 v[182:183], v[198:199], v[178:179]
	v_cvt_pk_bf16_f32 v144, v180, v181
	v_cvt_pk_bf16_f32 v145, v178, v179
	global_store_dwordx4 v240, v[142:145], s[24:25]
	v_pk_mul_f32 v[184:185], v[202:203], v[180:181]
	s_nop 0
	v_pk_mul_f32 v[142:143], v[204:205], v[146:147]
	v_pk_mul_f32 v[144:145], v[200:201], v[148:149]
	v_cvt_pk_bf16_f32 v142, v142, v143
	s_nop 0
	v_cvt_pk_bf16_f32 v143, v144, v145
	v_cvt_pk_bf16_f32 v144, v184, v185
	v_cvt_pk_bf16_f32 v145, v182, v183
	global_store_dwordx4 v231, v[142:145], s[26:27]
	s_nop 1
	v_mul_f32_e32 v142, v147, v147
	v_mul_f32_e32 v143, v149, v149
	v_fmac_f32_e32 v142, v146, v146
	v_fmac_f32_e32 v143, v148, v148
	v_add_f32_e32 v142, v142, v143
	v_mul_f32_e32 v143, v181, v181
	v_fmac_f32_e32 v143, v180, v180
	v_add_f32_e32 v142, v143, v142
	v_mul_f32_e32 v143, v179, v179
	v_fmac_f32_e32 v143, v178, v178
	v_add_f32_e32 v178, v143, v142
	s_waitcnt vmcnt(4)
	v_lshlrev_b32_e32 v142, 16, v158
	v_and_b32_e32 v143, 0xffff0000, v158
	v_lshlrev_b32_e32 v144, 16, v159
	v_and_b32_e32 v145, 0xffff0000, v159
	v_lshlrev_b32_e32 v146, 16, v160
	v_and_b32_e32 v147, 0xffff0000, v160
	v_lshlrev_b32_e32 v148, 16, v161
	v_and_b32_e32 v149, 0xffff0000, v161
	v_pk_fma_f32 v[140:141], v[140:141], v[76:77], v[144:145]
	v_pk_fma_f32 v[138:139], v[138:139], v[74:75], v[142:143]
	v_pk_fma_f32 v[142:143], v[136:137], v[72:73], v[148:149]
	v_pk_fma_f32 v[144:145], v[134:135], v[70:71], v[146:147]
	v_cvt_pk_bf16_f32 v134, v138, v139
	v_cvt_pk_bf16_f32 v135, v140, v141
	v_pk_mul_f32 v[146:147], v[176:177], v[142:143]
	v_cvt_pk_bf16_f32 v136, v144, v145
	v_cvt_pk_bf16_f32 v137, v142, v143
	global_store_dwordx4 v240, v[134:137], s[24:25] offset:1024
	v_pk_mul_f32 v[148:149], v[194:195], v[144:145]
	v_mul_f32_e32 v0, v143, v143
	v_pk_mul_f32 v[136:137], v[196:197], v[140:141]
	v_pk_mul_f32 v[134:135], v[174:175], v[138:139]
	v_fmac_f32_e32 v0, v142, v142
	v_cvt_pk_bf16_f32 v134, v134, v135
	v_cvt_pk_bf16_f32 v135, v136, v137
	v_cvt_pk_bf16_f32 v136, v148, v149
	v_cvt_pk_bf16_f32 v137, v146, v147
	global_store_dwordx4 v231, v[134:137], s[26:27] offset:256
	s_nop 1
	v_mul_f32_e32 v135, v139, v139
	v_mul_f32_e32 v136, v141, v141
	v_mul_f32_e32 v134, v145, v145
	v_fmac_f32_e32 v135, v138, v138
	v_fmac_f32_e32 v136, v140, v140
	v_fmac_f32_e32 v134, v144, v144
	v_add_f32_e32 v135, v135, v136
	v_add_f32_e32 v134, v134, v135
	v_add_f32_e32 v0, v0, v134
	v_add_f32_e32 v0, v178, v0
	ds_bpermute_b32 v134, v229, v0
	s_waitcnt lgkmcnt(0)
	v_add_f32_e32 v0, v0, v134
	ds_bpermute_b32 v136, v228, v0
	v_lshl_add_u64 v[134:135], v[216:217], 3, s[28:29]
	s_and_saveexec_b64 s[2:3], s[8:9]
	s_cbranch_execz .LBB0_1089
	s_waitcnt lgkmcnt(0)
	v_add_f32_e32 v0, v0, v136
	v_mul_f32_e32 v0, 0x4b800000, v0
	v_trunc_f32_e32 v0, v0
	v_mul_f32_e32 v136, 0x2f800000, v0
	v_floor_f32_e32 v137, v136
	v_fmac_f32_e32 v0, 0xcf800000, v137
	v_cvt_u32_f32_e32 v136, v0
	v_cvt_u32_f32_e32 v137, v137
	flat_atomic_add_x2 v[134:135], v[136:137]
.LBB0_1089:
	s_or_b64 exec, exec, s[2:3]
	v_ffbh_u32_e32 v0, v219
	v_min_u32_e32 v0, 32, v0
	s_waitcnt lgkmcnt(0)
	v_lshlrev_b64 v[136:137], v0, v[218:219]
	v_min_u32_e32 v136, 1, v136
	v_or_b32_e32 v136, v137, v136
	v_cvt_f32_u32_e32 v136, v136
	v_sub_u32_e32 v0, 32, v0
	s_waitcnt vmcnt(0)
	v_and_b32_e32 v141, 0xffff0000, v155
	v_lshlrev_b32_e32 v142, 16, v156
	v_ldexp_f32 v0, v136, v0
	v_mul_f32_e32 v0, 0x33800000, v0
	v_fmamk_f32 v0, v0, 0x3b800000, v226
	v_mul_f32_e32 v136, 0x4f800000, v0
	v_cmp_gt_f32_e32 vcc, s71, v0
	v_and_b32_e32 v143, 0xffff0000, v156
	v_lshlrev_b32_e32 v144, 16, v157
	v_cndmask_b32_e32 v0, v0, v136, vcc
	v_sqrt_f32_e32 v136, v0
	v_and_b32_e32 v145, 0xffff0000, v157
	v_add_u32_e32 v137, -1, v136
	v_add_u32_e32 v138, 1, v136
	v_fma_f32 v139, -v137, v136, v0
	v_fma_f32 v140, -v138, v136, v0
	v_cmp_ge_f32_e64 s[10:11], 0, v139
	s_nop 1
	v_cndmask_b32_e64 v136, v136, v137, s[10:11]
	v_cmp_lt_f32_e64 s[10:11], 0, v140
	s_nop 1
	v_cndmask_b32_e64 v136, v136, v138, s[10:11]
	v_mul_f32_e32 v137, 0x37800000, v136
	v_cndmask_b32_e32 v136, v136, v137, vcc
	v_cmp_class_f32_e32 vcc, v0, v223
	s_nop 1
	v_cndmask_b32_e32 v0, v136, v0, vcc
	v_div_scale_f32 v136, s[2:3], v0, v0, 1.0
	v_rcp_f32_e32 v137, v136
	s_mov_b32 s2, 0x8000
	v_fma_f32 v138, -v136, v137, 1.0
	v_fmac_f32_e32 v137, v138, v137
	v_div_scale_f32 v138, vcc, 1.0, v0, 1.0
	v_mul_f32_e32 v139, v138, v137
	v_fma_f32 v140, -v136, v139, v138
	v_fmac_f32_e32 v139, v140, v137
	v_fma_f32 v136, -v136, v139, v138
	v_div_fmas_f32 v136, v136, v137, v139
	v_div_fixup_f32 v0, v136, v0, 1.0
	v_lshlrev_b32_e32 v136, 11, v216
	v_lshlrev_b32_e32 v138, 16, v154
	v_and_b32_e32 v139, 0xffff0000, v154
	v_lshlrev_b32_e32 v140, 16, v155
	v_pk_mul_f32 v[130:131], v[130:131], v[0:1] op_sel_hi:[1,0]
	v_pk_mul_f32 v[132:133], v[132:133], v[0:1] op_sel_hi:[1,0]
	v_pk_mul_f32 v[126:127], v[126:127], v[0:1] op_sel_hi:[1,0]
	v_add3_u32 v137, v230, v136, s2
	v_add_u32_e32 v241, s2, v240
	v_pk_mul_f32 v[128:129], v[128:129], v[0:1] op_sel_hi:[1,0]
	v_pk_fma_f32 v[132:133], v[84:85], v[132:133], v[140:141]
; __device__ __forceinline__ unsigned cvt_pk_bf16(float lo, float hi) { unsigned r; asm volatile("v_cvt_pk_bf16_f32 %0, %1, %2" : "=v"(r) : "v"(lo), "v"(hi)); return r; }
; #define PG8_GPTR(p) ((__attribute__((address_space(1))) char*)(p))
;     __device__ __forceinline__ void operator()(const f32x4 (&acc)[2][2][4][2], const Unit& u, int wr, int wc, int fr, int fq) const {
;     ...
; #pragma unroll
;             for (int mm = 0; mm < 2; ++mm) {
;                 const int m = mp + mm;
;                 const int row = u.pm * BM + ai * HALF + wr * 64 + m * 16 + fr; float q = 0.f;
; #pragma unroll
;                 for (int bj = 0; bj < 2; ++bj) {
;                     const unsigned offb = (unsigned)(row * DM + col0 + bj * HALF) * 2u;
;                     const u32x4 bw = bv[mm][bj];
;                     const f32x4 b0 = (f32x4){__uint_as_float(bw.x << 16), __uint_as_float(bw.x & 0xffff0000u), __uint_as_float(bw.y << 16), __uint_as_float(bw.y & 0xffff0000u)};
;                     const f32x4 b1 = (f32x4){__uint_as_float(bw.z << 16), __uint_as_float(bw.z & 0xffff0000u), __uint_as_float(bw.w << 16), __uint_as_float(bw.w & 0xffff0000u)};
;                     f32x4 a0 = acc[ai][bj][m][0], a1 = acc[ai][bj][m][1]; if constexpr (GN) { a0 *= rc[ai * 4 + m]; a1 *= rc[ai * 4 + m]; }
;                     const f32x4 o0 = b0 + g[bj][0] * a0, o1 = b1 + g[bj][1] * a1;
;                     u32x4 wo; wo.x = cvt_pk_bf16(o0[0], o0[1]); wo.y = cvt_pk_bf16(o0[2], o0[3]); wo.z = cvt_pk_bf16(o1[0], o1[1]); wo.w = cvt_pk_bf16(o1[2], o1[3]);
;                     *(gs_u32x4*)(PG8_GPTR(out) + offb) = wo;
;                     if (xg) {
;                         const f32x4 h0 = o0 * cf[bj][0], h1 = o1 * cf[bj][1];
;                         u32x4 w; w.x = cvt_pk_bf16(h0[0], h0[1]); w.y = cvt_pk_bf16(h0[2], h0[3]); w.z = cvt_pk_bf16(h1[0], h1[1]); w.w = cvt_pk_bf16(h1[2], h1[3]);
;                         *(gs_u32x4*)(PG8_GPTR(xg) + offb) = w;
;                         q += (o0[0] * o0[0] + o0[1] * o0[1]) + (o0[2] * o0[2] + o0[3] * o0[3]) + (o1[0] * o1[0] + o1[1] * o1[1]) + (o1[2] * o1[2] + o1[3] * o1[3]);
;                     }
;                 }
;                 if (xg) ssq_put(ssq, row, q, fr, fq);
	v_pk_fma_f32 v[130:131], v[82:83], v[130:131], v[138:139]
	v_pk_fma_f32 v[140:141], v[78:79], v[126:127], v[142:143]
	v_cvt_pk_bf16_f32 v126, v130, v131
	v_cvt_pk_bf16_f32 v127, v132, v133
	v_pk_fma_f32 v[138:139], v[80:81], v[128:129], v[144:145]
	v_cvt_pk_bf16_f32 v128, v140, v141
	v_pk_mul_f32 v[144:145], v[202:203], v[140:141]
	v_cvt_pk_bf16_f32 v129, v138, v139
	global_store_dwordx4 v241, v[126:129], s[24:25]
	v_pk_mul_f32 v[142:143], v[198:199], v[138:139]
	v_pk_mul_f32 v[122:123], v[122:123], v[0:1] op_sel_hi:[1,0]
	v_pk_mul_f32 v[126:127], v[204:205], v[130:131]
	v_pk_mul_f32 v[128:129], v[200:201], v[132:133]
	v_cvt_pk_bf16_f32 v126, v126, v127
	v_pk_mul_f32 v[124:125], v[124:125], v[0:1] op_sel_hi:[1,0]
	v_cvt_pk_bf16_f32 v127, v128, v129
	v_cvt_pk_bf16_f32 v128, v144, v145
	v_cvt_pk_bf16_f32 v129, v142, v143
	global_store_dwordx4 v137, v[126:129], s[26:27]
	v_pk_mul_f32 v[118:119], v[118:119], v[0:1] op_sel_hi:[1,0]
	v_pk_mul_f32 v[120:121], v[120:121], v[0:1] op_sel_hi:[1,0]
	v_mul_f32_e32 v126, v131, v131
	v_mul_f32_e32 v127, v133, v133
	v_fmac_f32_e32 v126, v130, v130
	v_fmac_f32_e32 v127, v132, v132
	v_add_f32_e32 v126, v126, v127
	v_mul_f32_e32 v127, v141, v141
	v_fmac_f32_e32 v127, v140, v140
	v_add_f32_e32 v126, v127, v126
	v_mul_f32_e32 v127, v139, v139
	v_fmac_f32_e32 v127, v138, v138
	v_add_f32_e32 v138, v127, v126
	v_lshlrev_b32_e32 v126, 16, v150
	v_and_b32_e32 v127, 0xffff0000, v150
	v_lshlrev_b32_e32 v128, 16, v151
	v_and_b32_e32 v129, 0xffff0000, v151
	v_lshlrev_b32_e32 v130, 16, v152
	v_and_b32_e32 v131, 0xffff0000, v152
	v_lshlrev_b32_e32 v132, 16, v153
	v_and_b32_e32 v133, 0xffff0000, v153
	v_pk_fma_f32 v[124:125], v[124:125], v[76:77], v[128:129]
	v_pk_fma_f32 v[122:123], v[122:123], v[74:75], v[126:127]
	v_pk_fma_f32 v[126:127], v[120:121], v[72:73], v[132:133]
	v_pk_fma_f32 v[128:129], v[118:119], v[70:71], v[130:131]
	v_cvt_pk_bf16_f32 v118, v122, v123
	v_cvt_pk_bf16_f32 v119, v124, v125
	v_mul_f32_e32 v0, v127, v127
	v_cvt_pk_bf16_f32 v120, v128, v129
	v_cvt_pk_bf16_f32 v121, v126, v127
	global_store_dwordx4 v241, v[118:121], s[24:25] offset:1024
	v_fmac_f32_e32 v0, v126, v126
	v_pk_mul_f32 v[130:131], v[196:197], v[124:125]
	v_mul_f32_e32 v119, v123, v123
	v_mul_f32_e32 v120, v125, v125
	v_mul_f32_e32 v118, v129, v129
	v_fmac_f32_e32 v119, v122, v122
	v_fmac_f32_e32 v120, v124, v124
	v_fmac_f32_e32 v118, v128, v128
	v_add_f32_e32 v119, v119, v120
	v_add_f32_e32 v118, v118, v119
	v_add_f32_e32 v0, v0, v118
	v_add_f32_e32 v0, v138, v0
	ds_bpermute_b32 v121, v229, v0
	v_pk_mul_f32 v[118:119], v[174:175], v[122:123]
	v_pk_mul_f32 v[122:123], v[194:195], v[128:129]
	v_cvt_pk_bf16_f32 v120, v118, v119
	v_pk_mul_f32 v[124:125], v[176:177], v[126:127]
	s_waitcnt lgkmcnt(0)
	v_add_f32_e32 v0, v0, v121
	ds_bpermute_b32 v118, v228, v0
	v_cvt_pk_bf16_f32 v121, v130, v131
	v_cvt_pk_bf16_f32 v122, v122, v123
	v_cvt_pk_bf16_f32 v123, v124, v125
	global_store_dwordx4 v137, v[120:123], s[26:27] offset:256
	s_and_saveexec_b64 s[2:3], s[8:9]
	s_cbranch_execz .LBB0_1091
	s_waitcnt lgkmcnt(0)
	v_add_f32_e32 v0, v0, v118
	v_mul_f32_e32 v0, 0x4b800000, v0
	v_trunc_f32_e32 v0, v0
	v_mul_f32_e32 v118, 0x2f800000, v0
	v_floor_f32_e32 v119, v118
	v_fmac_f32_e32 v0, 0xcf800000, v119
	v_cvt_u32_f32_e32 v118, v0
	v_cvt_u32_f32_e32 v119, v119
	flat_atomic_add_x2 v[134:135], v[118:119] offset:128
.LBB0_1091:
	s_or_b64 exec, exec, s[2:3]
	v_ffbh_u32_e32 v0, v215
	v_min_u32_e32 v0, 32, v0
	s_waitcnt lgkmcnt(0)
	v_lshlrev_b64 v[118:119], v0, v[214:215]
	v_min_u32_e32 v118, 1, v118
	v_or_b32_e32 v118, v119, v118
	v_cvt_f32_u32_e32 v118, v118
	v_sub_u32_e32 v0, 32, v0
	v_ldexp_f32 v0, v118, v0
	v_mul_f32_e32 v0, 0x33800000, v0
	v_fmamk_f32 v0, v0, 0x3b800000, v226
	v_cmp_gt_f32_e32 vcc, s71, v0
	v_mul_f32_e32 v118, 0x4f800000, v0
	s_nop 0
	v_cndmask_b32_e32 v0, v0, v118, vcc
	v_sqrt_f32_e32 v118, v0
	s_nop 0
	v_add_u32_e32 v119, -1, v118
	v_fma_f32 v120, -v119, v118, v0
	v_cmp_ge_f32_e64 s[10:11], 0, v120
	v_add_u32_e32 v120, 1, v118
	s_nop 0
	v_cndmask_b32_e64 v119, v118, v119, s[10:11]
	v_fma_f32 v118, -v120, v118, v0
	v_cmp_lt_f32_e64 s[10:11], 0, v118
	s_nop 1
	v_cndmask_b32_e64 v118, v119, v120, s[10:11]
	v_mul_f32_e32 v119, 0x37800000, v118
	v_cndmask_b32_e32 v118, v118, v119, vcc
	v_cmp_class_f32_e32 vcc, v0, v223
	s_nop 1
	v_cndmask_b32_e32 v0, v118, v0, vcc
	v_div_scale_f32 v118, s[2:3], v0, v0, 1.0
	v_rcp_f32_e32 v119, v118
	s_mov_b32 s2, 0x10000
	v_add3_u32 v137, v230, v136, s2
	v_add_u32_e32 v241, s2, v240
	v_fma_f32 v120, -v118, v119, 1.0
	v_fmac_f32_e32 v119, v120, v119
	v_div_scale_f32 v120, vcc, 1.0, v0, 1.0
	v_mul_f32_e32 v121, v120, v119
	v_fma_f32 v122, -v118, v121, v120
	v_fmac_f32_e32 v121, v122, v119
	v_fma_f32 v118, -v118, v121, v120
	v_div_fmas_f32 v118, v118, v119, v121
	v_div_fixup_f32 v0, v118, v0, 1.0
	v_add_u32_e32 v118, 0x10000, v240
	global_load_dwordx4 v[130:133], v118, s[22:23]
	global_load_dwordx4 v[126:129], v118, s[22:23] offset:1024
	v_add_u32_e32 v118, 0x18000, v240
	global_load_dwordx4 v[122:125], v118, s[22:23]
	s_nop 0
	global_load_dwordx4 v[118:121], v118, s[22:23] offset:1024
	v_pk_mul_f32 v[114:115], v[114:115], v[0:1] op_sel_hi:[1,0]
	v_pk_mul_f32 v[116:117], v[116:117], v[0:1] op_sel_hi:[1,0]
	v_pk_mul_f32 v[110:111], v[110:111], v[0:1] op_sel_hi:[1,0]
	v_pk_mul_f32 v[112:113], v[112:113], v[0:1] op_sel_hi:[1,0]
	v_pk_mul_f32 v[106:107], v[106:107], v[0:1] op_sel_hi:[1,0]
	v_pk_mul_f32 v[108:109], v[108:109], v[0:1] op_sel_hi:[1,0]
	v_pk_mul_f32 v[102:103], v[102:103], v[0:1] op_sel_hi:[1,0]
	v_pk_mul_f32 v[104:105], v[104:105], v[0:1] op_sel_hi:[1,0]
	s_waitcnt vmcnt(0)
; __device__ __forceinline__ unsigned cvt_pk_bf16(float lo, float hi) { unsigned r; asm volatile("v_cvt_pk_bf16_f32 %0, %1, %2" : "=v"(r) : "v"(lo), "v"(hi)); return r; }
; #define PG8_GPTR(p) ((__attribute__((address_space(1))) char*)(p))
;     __device__ __forceinline__ void operator()(const f32x4 (&acc)[2][2][4][2], const Unit& u, int wr, int wc, int fr, int fq) const {
;     ...
; #pragma unroll
;             for (int mm = 0; mm < 2; ++mm) {
;                 const int m = mp + mm;
;                 const int row = u.pm * BM + ai * HALF + wr * 64 + m * 16 + fr; float q = 0.f;
; #pragma unroll
;                 for (int bj = 0; bj < 2; ++bj) {
;                     const unsigned offb = (unsigned)(row * DM + col0 + bj * HALF) * 2u;
;                     const u32x4 bw = bv[mm][bj];
;                     const f32x4 b0 = (f32x4){__uint_as_float(bw.x << 16), __uint_as_float(bw.x & 0xffff0000u), __uint_as_float(bw.y << 16), __uint_as_float(bw.y & 0xffff0000u)};
;                     const f32x4 b1 = (f32x4){__uint_as_float(bw.z << 16), __uint_as_float(bw.z & 0xffff0000u), __uint_as_float(bw.w << 16), __uint_as_float(bw.w & 0xffff0000u)};
;                     f32x4 a0 = acc[ai][bj][m][0], a1 = acc[ai][bj][m][1]; if constexpr (GN) { a0 *= rc[ai * 4 + m]; a1 *= rc[ai * 4 + m]; }
;                     const f32x4 o0 = b0 + g[bj][0] * a0, o1 = b1 + g[bj][1] * a1;
;                     u32x4 wo; wo.x = cvt_pk_bf16(o0[0], o0[1]); wo.y = cvt_pk_bf16(o0[2], o0[3]); wo.z = cvt_pk_bf16(o1[0], o1[1]); wo.w = cvt_pk_bf16(o1[2], o1[3]);
;                     *(gs_u32x4*)(PG8_GPTR(out) + offb) = wo;
;                     if (xg) {
;                         const f32x4 h0 = o0 * cf[bj][0], h1 = o1 * cf[bj][1];
;                         u32x4 w; w.x = cvt_pk_bf16(h0[0], h0[1]); w.y = cvt_pk_bf16(h0[2], h0[3]); w.z = cvt_pk_bf16(h1[0], h1[1]); w.w = cvt_pk_bf16(h1[2], h1[3]);
;                         *(gs_u32x4*)(PG8_GPTR(xg) + offb) = w;
;                         q += (o0[0] * o0[0] + o0[1] * o0[1]) + (o0[2] * o0[2] + o0[3] * o0[3]) + (o1[0] * o1[0] + o1[1] * o1[1]) + (o1[2] * o1[2] + o1[3] * o1[3]);
;                     }
;                 }
;                 if (xg) ssq_put(ssq, row, q, fr, fq);
	v_lshlrev_b32_e32 v138, 16, v130
	v_and_b32_e32 v139, 0xffff0000, v130
	v_lshlrev_b32_e32 v130, 16, v131
	v_and_b32_e32 v131, 0xffff0000, v131
	v_lshlrev_b32_e32 v140, 16, v132
	v_and_b32_e32 v141, 0xffff0000, v132
	v_lshlrev_b32_e32 v132, 16, v133
	v_and_b32_e32 v133, 0xffff0000, v133
	v_pk_fma_f32 v[116:117], v[84:85], v[116:117], v[130:131]
	v_pk_fma_f32 v[114:115], v[82:83], v[114:115], v[138:139]
	v_pk_fma_f32 v[130:131], v[80:81], v[112:113], v[132:133]
	v_pk_fma_f32 v[132:133], v[78:79], v[110:111], v[140:141]
	v_cvt_pk_bf16_f32 v110, v114, v115
	v_cvt_pk_bf16_f32 v111, v116, v117
	v_pk_mul_f32 v[138:139], v[198:199], v[130:131]
	v_cvt_pk_bf16_f32 v112, v132, v133
	v_cvt_pk_bf16_f32 v113, v130, v131
	global_store_dwordx4 v241, v[110:113], s[24:25]
	v_pk_mul_f32 v[140:141], v[202:203], v[132:133]
	s_nop 0
	v_pk_mul_f32 v[110:111], v[204:205], v[114:115]
	v_pk_mul_f32 v[112:113], v[200:201], v[116:117]
	v_cvt_pk_bf16_f32 v110, v110, v111
	s_nop 0
	v_cvt_pk_bf16_f32 v111, v112, v113
	v_cvt_pk_bf16_f32 v112, v140, v141
	v_cvt_pk_bf16_f32 v113, v138, v139
	global_store_dwordx4 v137, v[110:113], s[26:27]
	s_nop 1
	v_mul_f32_e32 v110, v115, v115
	v_mul_f32_e32 v111, v117, v117
	v_fmac_f32_e32 v110, v114, v114
	v_fmac_f32_e32 v111, v116, v116
	v_add_f32_e32 v110, v110, v111
	v_mul_f32_e32 v111, v133, v133
	v_fmac_f32_e32 v111, v132, v132
	v_add_f32_e32 v110, v111, v110
	v_mul_f32_e32 v111, v131, v131
	v_fmac_f32_e32 v111, v130, v130
	v_add_f32_e32 v130, v111, v110
	v_lshlrev_b32_e32 v110, 16, v126
	v_and_b32_e32 v111, 0xffff0000, v126
	v_lshlrev_b32_e32 v112, 16, v127
	v_and_b32_e32 v113, 0xffff0000, v127
	v_lshlrev_b32_e32 v114, 16, v128
	v_and_b32_e32 v115, 0xffff0000, v128
	v_lshlrev_b32_e32 v116, 16, v129
	v_and_b32_e32 v117, 0xffff0000, v129
	v_pk_fma_f32 v[108:109], v[108:109], v[76:77], v[112:113]
	v_pk_fma_f32 v[106:107], v[106:107], v[74:75], v[110:111]
	v_pk_fma_f32 v[110:111], v[104:105], v[72:73], v[116:117]
	v_pk_fma_f32 v[112:113], v[102:103], v[70:71], v[114:115]
	v_cvt_pk_bf16_f32 v102, v106, v107
	v_cvt_pk_bf16_f32 v103, v108, v109
	v_pk_mul_f32 v[114:115], v[176:177], v[110:111]
	v_cvt_pk_bf16_f32 v104, v112, v113
	v_cvt_pk_bf16_f32 v105, v110, v111
	global_store_dwordx4 v241, v[102:105], s[24:25] offset:1024
	v_pk_mul_f32 v[116:117], v[194:195], v[112:113]
	v_mul_f32_e32 v0, v111, v111
	v_pk_mul_f32 v[104:105], v[196:197], v[108:109]
	v_pk_mul_f32 v[102:103], v[174:175], v[106:107]
	v_fmac_f32_e32 v0, v110, v110
	v_cvt_pk_bf16_f32 v102, v102, v103
	v_cvt_pk_bf16_f32 v103, v104, v105
	v_cvt_pk_bf16_f32 v104, v116, v117
	v_cvt_pk_bf16_f32 v105, v114, v115
	global_store_dwordx4 v137, v[102:105], s[26:27] offset:256
	s_nop 1
	v_mul_f32_e32 v103, v107, v107
	v_mul_f32_e32 v104, v109, v109
	v_mul_f32_e32 v102, v113, v113
	v_fmac_f32_e32 v103, v106, v106
	v_fmac_f32_e32 v104, v108, v108
	v_fmac_f32_e32 v102, v112, v112
	v_add_f32_e32 v103, v103, v104
	v_add_f32_e32 v102, v102, v103
	v_add_f32_e32 v0, v0, v102
	v_add_f32_e32 v0, v130, v0
	ds_bpermute_b32 v102, v229, v0
	s_waitcnt lgkmcnt(0)
	v_add_f32_e32 v0, v0, v102
	ds_bpermute_b32 v102, v228, v0
	s_and_saveexec_b64 s[2:3], s[8:9]
	s_cbranch_execz .LBB0_1093
	s_waitcnt lgkmcnt(0)
	v_add_f32_e32 v0, v0, v102
	v_mul_f32_e32 v0, 0x4b800000, v0
	v_trunc_f32_e32 v0, v0
	v_mul_f32_e32 v102, 0x2f800000, v0
	v_floor_f32_e32 v103, v102
	v_fmac_f32_e32 v0, 0xcf800000, v103
	v_cvt_u32_f32_e32 v102, v0
	v_cvt_u32_f32_e32 v103, v103
	flat_atomic_add_x2 v[134:135], v[102:103] offset:256
.LBB0_1093:
	s_or_b64 exec, exec, s[2:3]
	v_ffbh_u32_e32 v0, v213
	v_min_u32_e32 v0, 32, v0
	s_waitcnt lgkmcnt(0)
	v_lshlrev_b64 v[102:103], v0, v[212:213]
	v_min_u32_e32 v102, 1, v102
	v_or_b32_e32 v102, v103, v102
	v_cvt_f32_u32_e32 v102, v102
	v_sub_u32_e32 v0, 32, v0
	v_and_b32_e32 v107, 0xffff0000, v124
	v_lshlrev_b32_e32 v108, 16, v125
	v_ldexp_f32 v0, v102, v0
	v_mul_f32_e32 v0, 0x33800000, v0
	v_fmamk_f32 v0, v0, 0x3b800000, v226
	v_mul_f32_e32 v102, 0x4f800000, v0
	v_cmp_gt_f32_e32 vcc, s71, v0
	v_and_b32_e32 v109, 0xffff0000, v125
	s_nop 0
	v_cndmask_b32_e32 v0, v0, v102, vcc
	v_sqrt_f32_e32 v102, v0
	s_nop 0
	v_add_u32_e32 v103, -1, v102
	v_add_u32_e32 v104, 1, v102
	v_fma_f32 v105, -v103, v102, v0
	v_fma_f32 v106, -v104, v102, v0
	v_cmp_ge_f32_e64 s[10:11], 0, v105
	s_nop 1
	v_cndmask_b32_e64 v102, v102, v103, s[10:11]
	v_cmp_lt_f32_e64 s[10:11], 0, v106
	s_nop 1
	v_cndmask_b32_e64 v102, v102, v104, s[10:11]
	v_mul_f32_e32 v103, 0x37800000, v102
	v_cndmask_b32_e32 v102, v102, v103, vcc
	v_cmp_class_f32_e32 vcc, v0, v223
	s_nop 1
	v_cndmask_b32_e32 v0, v102, v0, vcc
	v_div_scale_f32 v102, s[2:3], v0, v0, 1.0
	v_rcp_f32_e32 v103, v102
	s_mov_b32 s2, 0x18000
	v_add3_u32 v110, v230, v136, s2
	v_add_u32_e32 v241, s2, v240
	v_fma_f32 v104, -v102, v103, 1.0
	v_fmac_f32_e32 v103, v104, v103
	v_div_scale_f32 v104, vcc, 1.0, v0, 1.0
	v_mul_f32_e32 v105, v104, v103
	v_fma_f32 v106, -v102, v105, v104
	v_fmac_f32_e32 v105, v106, v103
	v_fma_f32 v102, -v102, v105, v104
	v_div_fmas_f32 v102, v102, v103, v105
	v_div_fixup_f32 v0, v102, v0, 1.0
	v_lshlrev_b32_e32 v102, 16, v122
	v_and_b32_e32 v103, 0xffff0000, v122
	v_lshlrev_b32_e32 v104, 16, v123
	v_and_b32_e32 v105, 0xffff0000, v123
	v_lshlrev_b32_e32 v106, 16, v124
	v_pk_mul_f32 v[98:99], v[98:99], v[0:1] op_sel_hi:[1,0]
	v_pk_mul_f32 v[100:101], v[100:101], v[0:1] op_sel_hi:[1,0]
	v_pk_mul_f32 v[94:95], v[94:95], v[0:1] op_sel_hi:[1,0]
	v_pk_mul_f32 v[96:97], v[96:97], v[0:1] op_sel_hi:[1,0]
	v_pk_fma_f32 v[100:101], v[84:85], v[100:101], v[104:105]
	v_pk_fma_f32 v[98:99], v[82:83], v[98:99], v[102:103]
	v_pk_fma_f32 v[104:105], v[78:79], v[94:95], v[106:107]
; __device__ __forceinline__ unsigned cvt_pk_bf16(float lo, float hi) { unsigned r; asm volatile("v_cvt_pk_bf16_f32 %0, %1, %2" : "=v"(r) : "v"(lo), "v"(hi)); return r; }
; #define PG8_GPTR(p) ((__attribute__((address_space(1))) char*)(p))
;     __device__ __forceinline__ void operator()(const f32x4 (&acc)[2][2][4][2], const Unit& u, int wr, int wc, int fr, int fq) const {
;     ...
; #pragma unroll
;             for (int mm = 0; mm < 2; ++mm) {
;                 const int m = mp + mm;
;                 const int row = u.pm * BM + ai * HALF + wr * 64 + m * 16 + fr; float q = 0.f;
; #pragma unroll
;                 for (int bj = 0; bj < 2; ++bj) {
;                     const unsigned offb = (unsigned)(row * DM + col0 + bj * HALF) * 2u;
;                     const u32x4 bw = bv[mm][bj];
;                     const f32x4 b0 = (f32x4){__uint_as_float(bw.x << 16), __uint_as_float(bw.x & 0xffff0000u), __uint_as_float(bw.y << 16), __uint_as_float(bw.y & 0xffff0000u)};
;                     const f32x4 b1 = (f32x4){__uint_as_float(bw.z << 16), __uint_as_float(bw.z & 0xffff0000u), __uint_as_float(bw.w << 16), __uint_as_float(bw.w & 0xffff0000u)};
;                     f32x4 a0 = acc[ai][bj][m][0], a1 = acc[ai][bj][m][1]; if constexpr (GN) { a0 *= rc[ai * 4 + m]; a1 *= rc[ai * 4 + m]; }
;                     const f32x4 o0 = b0 + g[bj][0] * a0, o1 = b1 + g[bj][1] * a1;
;                     u32x4 wo; wo.x = cvt_pk_bf16(o0[0], o0[1]); wo.y = cvt_pk_bf16(o0[2], o0[3]); wo.z = cvt_pk_bf16(o1[0], o1[1]); wo.w = cvt_pk_bf16(o1[2], o1[3]);
;                     *(gs_u32x4*)(PG8_GPTR(out) + offb) = wo;
;                     if (xg) {
;                         const f32x4 h0 = o0 * cf[bj][0], h1 = o1 * cf[bj][1];
;                         u32x4 w; w.x = cvt_pk_bf16(h0[0], h0[1]); w.y = cvt_pk_bf16(h0[2], h0[3]); w.z = cvt_pk_bf16(h1[0], h1[1]); w.w = cvt_pk_bf16(h1[2], h1[3]);
;                         *(gs_u32x4*)(PG8_GPTR(xg) + offb) = w;
;                         q += (o0[0] * o0[0] + o0[1] * o0[1]) + (o0[2] * o0[2] + o0[3] * o0[3]) + (o1[0] * o1[0] + o1[1] * o1[1]) + (o1[2] * o1[2] + o1[3] * o1[3]);
;                     }
;                 }
;                 if (xg) ssq_put(ssq, row, q, fr, fq);
	v_cvt_pk_bf16_f32 v94, v98, v99
	v_cvt_pk_bf16_f32 v95, v100, v101
	v_pk_fma_f32 v[102:103], v[80:81], v[96:97], v[108:109]
	v_cvt_pk_bf16_f32 v96, v104, v105
	v_pk_mul_f32 v[108:109], v[202:203], v[104:105]
	v_cvt_pk_bf16_f32 v97, v102, v103
	global_store_dwordx4 v241, v[94:97], s[24:25]
	v_pk_mul_f32 v[106:107], v[198:199], v[102:103]
	v_pk_mul_f32 v[90:91], v[90:91], v[0:1] op_sel_hi:[1,0]
	v_pk_mul_f32 v[94:95], v[204:205], v[98:99]
	v_pk_mul_f32 v[96:97], v[200:201], v[100:101]
	v_cvt_pk_bf16_f32 v94, v94, v95
	v_pk_mul_f32 v[92:93], v[92:93], v[0:1] op_sel_hi:[1,0]
	v_cvt_pk_bf16_f32 v95, v96, v97
	v_cvt_pk_bf16_f32 v96, v108, v109
	v_cvt_pk_bf16_f32 v97, v106, v107
	global_store_dwordx4 v110, v[94:97], s[26:27]
	v_pk_mul_f32 v[86:87], v[86:87], v[0:1] op_sel_hi:[1,0]
	v_pk_mul_f32 v[88:89], v[88:89], v[0:1] op_sel_hi:[1,0]
	v_mul_f32_e32 v94, v99, v99
	v_mul_f32_e32 v95, v101, v101
	v_fmac_f32_e32 v94, v98, v98
	v_fmac_f32_e32 v95, v100, v100
	v_add_f32_e32 v94, v94, v95
	v_mul_f32_e32 v95, v105, v105
	v_fmac_f32_e32 v95, v104, v104
	v_add_f32_e32 v94, v95, v94
	v_mul_f32_e32 v95, v103, v103
	v_fmac_f32_e32 v95, v102, v102
	v_add_f32_e32 v102, v95, v94
	v_lshlrev_b32_e32 v94, 16, v118
	v_and_b32_e32 v95, 0xffff0000, v118
	v_lshlrev_b32_e32 v96, 16, v119
	v_and_b32_e32 v97, 0xffff0000, v119
	v_lshlrev_b32_e32 v98, 16, v120
	v_and_b32_e32 v99, 0xffff0000, v120
	v_lshlrev_b32_e32 v100, 16, v121
	v_and_b32_e32 v101, 0xffff0000, v121
	v_pk_fma_f32 v[92:93], v[92:93], v[76:77], v[96:97]
	v_pk_fma_f32 v[90:91], v[90:91], v[74:75], v[94:95]
	v_pk_fma_f32 v[94:95], v[88:89], v[72:73], v[100:101]
	v_pk_fma_f32 v[96:97], v[86:87], v[70:71], v[98:99]
	v_cvt_pk_bf16_f32 v86, v90, v91
	v_cvt_pk_bf16_f32 v87, v92, v93
	v_mul_f32_e32 v0, v95, v95
	v_cvt_pk_bf16_f32 v88, v96, v97
	v_cvt_pk_bf16_f32 v89, v94, v95
	global_store_dwordx4 v241, v[86:89], s[24:25] offset:1024
	v_fmac_f32_e32 v0, v94, v94
	v_pk_mul_f32 v[98:99], v[196:197], v[92:93]
	v_mul_f32_e32 v87, v91, v91
	v_mul_f32_e32 v88, v93, v93
	v_mul_f32_e32 v86, v97, v97
	v_fmac_f32_e32 v87, v90, v90
	v_fmac_f32_e32 v88, v92, v92
	v_fmac_f32_e32 v86, v96, v96
	v_add_f32_e32 v87, v87, v88
	v_add_f32_e32 v86, v86, v87
	v_add_f32_e32 v0, v0, v86
	v_add_f32_e32 v0, v102, v0
	ds_bpermute_b32 v89, v229, v0
	v_pk_mul_f32 v[86:87], v[174:175], v[90:91]
	v_pk_mul_f32 v[90:91], v[194:195], v[96:97]
	v_cvt_pk_bf16_f32 v88, v86, v87
	v_pk_mul_f32 v[92:93], v[176:177], v[94:95]
	s_waitcnt lgkmcnt(0)
	v_add_f32_e32 v0, v0, v89
	ds_bpermute_b32 v86, v228, v0
	v_cvt_pk_bf16_f32 v89, v98, v99
	v_cvt_pk_bf16_f32 v90, v90, v91
	v_cvt_pk_bf16_f32 v91, v92, v93
	global_store_dwordx4 v110, v[88:91], s[26:27] offset:256
	s_and_saveexec_b64 s[2:3], s[8:9]
	s_cbranch_execz .LBB0_1095
	s_waitcnt lgkmcnt(0)
	v_add_f32_e32 v0, v0, v86
	v_mul_f32_e32 v0, 0x4b800000, v0
	v_trunc_f32_e32 v0, v0
	v_mul_f32_e32 v86, 0x2f800000, v0
	v_floor_f32_e32 v87, v86
	v_fmac_f32_e32 v0, 0xcf800000, v87
	v_cvt_u32_f32_e32 v86, v0
	v_cvt_u32_f32_e32 v87, v87
	flat_atomic_add_x2 v[134:135], v[86:87] offset:384
.LBB0_1095:
	s_or_b64 exec, exec, s[2:3]
	v_ffbh_u32_e32 v0, v211
	v_min_u32_e32 v0, 32, v0
	s_waitcnt lgkmcnt(0)
	v_lshlrev_b64 v[86:87], v0, v[210:211]
	v_min_u32_e32 v86, 1, v86
	v_or_b32_e32 v86, v87, v86
	v_cvt_f32_u32_e32 v86, v86
	v_sub_u32_e32 v0, 32, v0
	v_ldexp_f32 v0, v86, v0
	v_mul_f32_e32 v0, 0x33800000, v0
	v_fmamk_f32 v0, v0, 0x3b800000, v226
	v_cmp_gt_f32_e32 vcc, s71, v0
	v_mul_f32_e32 v86, 0x4f800000, v0
	s_nop 0
	v_cndmask_b32_e32 v0, v0, v86, vcc
	v_sqrt_f32_e32 v86, v0
	s_nop 0
	v_add_u32_e32 v87, -1, v86
	v_fma_f32 v88, -v87, v86, v0
	v_cmp_ge_f32_e64 s[10:11], 0, v88
	v_add_u32_e32 v88, 1, v86
	s_nop 0
	v_cndmask_b32_e64 v87, v86, v87, s[10:11]
	v_fma_f32 v86, -v88, v86, v0
	v_cmp_lt_f32_e64 s[10:11], 0, v86
	s_nop 1
	v_cndmask_b32_e64 v86, v87, v88, s[10:11]
	v_mul_f32_e32 v87, 0x37800000, v86
	v_cndmask_b32_e32 v86, v86, v87, vcc
	v_cmp_class_f32_e32 vcc, v0, v223
	s_nop 1
	v_cndmask_b32_e32 v0, v86, v0, vcc
	v_div_scale_f32 v86, s[2:3], v0, v0, 1.0
	v_rcp_f32_e32 v87, v86
	s_mov_b32 s2, 0x40000
	v_add3_u32 v106, v232, v230, s2
	v_add_u32_e32 v241, s2, v240
	v_fma_f32 v88, -v86, v87, 1.0
	v_fmac_f32_e32 v87, v88, v87
	v_div_scale_f32 v88, vcc, 1.0, v0, 1.0
	v_mul_f32_e32 v89, v88, v87
	v_fma_f32 v90, -v86, v89, v88
	v_fmac_f32_e32 v89, v90, v87
	v_fma_f32 v86, -v86, v89, v88
	v_div_fmas_f32 v86, v86, v87, v89
	v_div_fixup_f32 v0, v86, v0, 1.0
	v_add_u32_e32 v86, 0x40000, v240
	global_load_dwordx4 v[98:101], v86, s[22:23]
	global_load_dwordx4 v[94:97], v86, s[22:23] offset:1024
	v_add_u32_e32 v86, 0x48000, v240
	global_load_dwordx4 v[90:93], v86, s[22:23]
	s_nop 0
	global_load_dwordx4 v[86:89], v86, s[22:23] offset:1024
	v_pk_mul_f32 v[66:67], v[66:67], v[0:1] op_sel_hi:[1,0]
	v_pk_mul_f32 v[68:69], v[68:69], v[0:1] op_sel_hi:[1,0]
	v_pk_mul_f32 v[62:63], v[62:63], v[0:1] op_sel_hi:[1,0]
	v_pk_mul_f32 v[64:65], v[64:65], v[0:1] op_sel_hi:[1,0]
	v_pk_mul_f32 v[58:59], v[58:59], v[0:1] op_sel_hi:[1,0]
	v_pk_mul_f32 v[60:61], v[60:61], v[0:1] op_sel_hi:[1,0]
	v_pk_mul_f32 v[54:55], v[54:55], v[0:1] op_sel_hi:[1,0]
	v_pk_mul_f32 v[56:57], v[56:57], v[0:1] op_sel_hi:[1,0]
	s_waitcnt vmcnt(0)
; __device__ __forceinline__ unsigned cvt_pk_bf16(float lo, float hi) { unsigned r; asm volatile("v_cvt_pk_bf16_f32 %0, %1, %2" : "=v"(r) : "v"(lo), "v"(hi)); return r; }
; #define PG8_GPTR(p) ((__attribute__((address_space(1))) char*)(p))
;     __device__ __forceinline__ void operator()(const f32x4 (&acc)[2][2][4][2], const Unit& u, int wr, int wc, int fr, int fq) const {
;     ...
; #pragma unroll
;             for (int mm = 0; mm < 2; ++mm) {
;                 const int m = mp + mm;
;                 const int row = u.pm * BM + ai * HALF + wr * 64 + m * 16 + fr; float q = 0.f;
; #pragma unroll
;                 for (int bj = 0; bj < 2; ++bj) {
;                     const unsigned offb = (unsigned)(row * DM + col0 + bj * HALF) * 2u;
;                     const u32x4 bw = bv[mm][bj];
;                     const f32x4 b0 = (f32x4){__uint_as_float(bw.x << 16), __uint_as_float(bw.x & 0xffff0000u), __uint_as_float(bw.y << 16), __uint_as_float(bw.y & 0xffff0000u)};
;                     const f32x4 b1 = (f32x4){__uint_as_float(bw.z << 16), __uint_as_float(bw.z & 0xffff0000u), __uint_as_float(bw.w << 16), __uint_as_float(bw.w & 0xffff0000u)};
;                     f32x4 a0 = acc[ai][bj][m][0], a1 = acc[ai][bj][m][1]; if constexpr (GN) { a0 *= rc[ai * 4 + m]; a1 *= rc[ai * 4 + m]; }
;                     const f32x4 o0 = b0 + g[bj][0] * a0, o1 = b1 + g[bj][1] * a1;
;                     u32x4 wo; wo.x = cvt_pk_bf16(o0[0], o0[1]); wo.y = cvt_pk_bf16(o0[2], o0[3]); wo.z = cvt_pk_bf16(o1[0], o1[1]); wo.w = cvt_pk_bf16(o1[2], o1[3]);
;                     *(gs_u32x4*)(PG8_GPTR(out) + offb) = wo;
;                     if (xg) {
;                         const f32x4 h0 = o0 * cf[bj][0], h1 = o1 * cf[bj][1];
;                         u32x4 w; w.x = cvt_pk_bf16(h0[0], h0[1]); w.y = cvt_pk_bf16(h0[2], h0[3]); w.z = cvt_pk_bf16(h1[0], h1[1]); w.w = cvt_pk_bf16(h1[2], h1[3]);
;                         *(gs_u32x4*)(PG8_GPTR(xg) + offb) = w;
;                         q += (o0[0] * o0[0] + o0[1] * o0[1]) + (o0[2] * o0[2] + o0[3] * o0[3]) + (o1[0] * o1[0] + o1[1] * o1[1]) + (o1[2] * o1[2] + o1[3] * o1[3]);
;                     }
;                 }
;                 if (xg) ssq_put(ssq, row, q, fr, fq);
	v_lshlrev_b32_e32 v102, 16, v98
	v_and_b32_e32 v103, 0xffff0000, v98
	v_lshlrev_b32_e32 v98, 16, v99
	v_and_b32_e32 v99, 0xffff0000, v99
	v_lshlrev_b32_e32 v104, 16, v100
	v_and_b32_e32 v105, 0xffff0000, v100
	v_lshlrev_b32_e32 v100, 16, v101
	v_and_b32_e32 v101, 0xffff0000, v101
	v_pk_fma_f32 v[68:69], v[84:85], v[68:69], v[98:99]
	v_pk_fma_f32 v[66:67], v[82:83], v[66:67], v[102:103]
	v_pk_fma_f32 v[98:99], v[80:81], v[64:65], v[100:101]
	v_pk_fma_f32 v[100:101], v[78:79], v[62:63], v[104:105]
	v_cvt_pk_bf16_f32 v62, v66, v67
	v_cvt_pk_bf16_f32 v63, v68, v69
	v_pk_mul_f32 v[102:103], v[198:199], v[98:99]
	v_cvt_pk_bf16_f32 v64, v100, v101
	v_cvt_pk_bf16_f32 v65, v98, v99
	global_store_dwordx4 v241, v[62:65], s[24:25]
	v_pk_mul_f32 v[104:105], v[202:203], v[100:101]
	s_nop 0
	v_pk_mul_f32 v[62:63], v[204:205], v[66:67]
	v_pk_mul_f32 v[64:65], v[200:201], v[68:69]
	v_cvt_pk_bf16_f32 v62, v62, v63
	s_nop 0
	v_cvt_pk_bf16_f32 v63, v64, v65
	v_cvt_pk_bf16_f32 v64, v104, v105
	v_cvt_pk_bf16_f32 v65, v102, v103
	global_store_dwordx4 v106, v[62:65], s[26:27]
	s_nop 1
	v_mul_f32_e32 v62, v67, v67
	v_mul_f32_e32 v63, v69, v69
	v_fmac_f32_e32 v62, v66, v66
	v_fmac_f32_e32 v63, v68, v68
	v_add_f32_e32 v62, v62, v63
	v_mul_f32_e32 v63, v101, v101
	v_fmac_f32_e32 v63, v100, v100
	v_add_f32_e32 v62, v63, v62
	v_mul_f32_e32 v63, v99, v99
	v_fmac_f32_e32 v63, v98, v98
	v_add_f32_e32 v98, v63, v62
	v_lshlrev_b32_e32 v62, 16, v94
	v_and_b32_e32 v63, 0xffff0000, v94
	v_lshlrev_b32_e32 v64, 16, v95
	v_and_b32_e32 v65, 0xffff0000, v95
	v_lshlrev_b32_e32 v66, 16, v96
	v_and_b32_e32 v67, 0xffff0000, v96
	v_lshlrev_b32_e32 v68, 16, v97
	v_and_b32_e32 v69, 0xffff0000, v97
	v_pk_fma_f32 v[60:61], v[60:61], v[76:77], v[64:65]
	v_pk_fma_f32 v[58:59], v[58:59], v[74:75], v[62:63]
	v_pk_fma_f32 v[62:63], v[56:57], v[72:73], v[68:69]
	v_pk_fma_f32 v[64:65], v[54:55], v[70:71], v[66:67]
	v_cvt_pk_bf16_f32 v54, v58, v59
	v_cvt_pk_bf16_f32 v55, v60, v61
	v_pk_mul_f32 v[66:67], v[176:177], v[62:63]
	v_cvt_pk_bf16_f32 v56, v64, v65
	v_cvt_pk_bf16_f32 v57, v62, v63
	global_store_dwordx4 v241, v[54:57], s[24:25] offset:1024
	v_pk_mul_f32 v[68:69], v[194:195], v[64:65]
	v_mul_f32_e32 v0, v63, v63
	v_pk_mul_f32 v[56:57], v[196:197], v[60:61]
	v_pk_mul_f32 v[54:55], v[174:175], v[58:59]
	v_fmac_f32_e32 v0, v62, v62
	v_cvt_pk_bf16_f32 v54, v54, v55
	v_cvt_pk_bf16_f32 v55, v56, v57
	v_cvt_pk_bf16_f32 v56, v68, v69
	v_cvt_pk_bf16_f32 v57, v66, v67
	global_store_dwordx4 v106, v[54:57], s[26:27] offset:256
	s_nop 1
	v_mul_f32_e32 v55, v59, v59
	v_mul_f32_e32 v56, v61, v61
	v_mul_f32_e32 v54, v65, v65
	v_fmac_f32_e32 v55, v58, v58
	v_fmac_f32_e32 v56, v60, v60
	v_fmac_f32_e32 v54, v64, v64
	v_add_f32_e32 v55, v55, v56
	v_add_f32_e32 v54, v54, v55
	v_add_f32_e32 v0, v0, v54
	v_add_f32_e32 v0, v98, v0
	ds_bpermute_b32 v54, v229, v0
	s_waitcnt lgkmcnt(0)
	v_add_f32_e32 v0, v0, v54
	ds_bpermute_b32 v54, v228, v0
	s_and_saveexec_b64 s[2:3], s[8:9]
	s_cbranch_execz .LBB0_1097
	s_waitcnt lgkmcnt(0)
	v_add_f32_e32 v0, v0, v54
	v_mul_f32_e32 v0, 0x4b800000, v0
	v_trunc_f32_e32 v0, v0
	v_mul_f32_e32 v54, 0x2f800000, v0
	v_floor_f32_e32 v55, v54
	v_fmac_f32_e32 v0, 0xcf800000, v55
	v_cvt_u32_f32_e32 v54, v0
	v_cvt_u32_f32_e32 v55, v55
	flat_atomic_add_x2 v[134:135], v[54:55] offset:1024
.LBB0_1097:
	s_or_b64 exec, exec, s[2:3]
	v_ffbh_u32_e32 v0, v209
	v_min_u32_e32 v0, 32, v0
	s_waitcnt lgkmcnt(0)
	v_lshlrev_b64 v[54:55], v0, v[208:209]
	v_min_u32_e32 v54, 1, v54
	v_or_b32_e32 v54, v55, v54
	v_cvt_f32_u32_e32 v54, v54
	v_sub_u32_e32 v0, 32, v0
	v_and_b32_e32 v59, 0xffff0000, v92
	v_lshlrev_b32_e32 v60, 16, v93
	v_ldexp_f32 v0, v54, v0
	v_mul_f32_e32 v0, 0x33800000, v0
	v_fmamk_f32 v0, v0, 0x3b800000, v226
	v_mul_f32_e32 v54, 0x4f800000, v0
	v_cmp_gt_f32_e32 vcc, s71, v0
	v_and_b32_e32 v61, 0xffff0000, v93
	s_nop 0
	v_cndmask_b32_e32 v0, v0, v54, vcc
	v_sqrt_f32_e32 v54, v0
	s_nop 0
	v_add_u32_e32 v55, -1, v54
	v_add_u32_e32 v56, 1, v54
	v_fma_f32 v57, -v55, v54, v0
	v_fma_f32 v58, -v56, v54, v0
	v_cmp_ge_f32_e64 s[10:11], 0, v57
	s_nop 1
	v_cndmask_b32_e64 v54, v54, v55, s[10:11]
	v_cmp_lt_f32_e64 s[10:11], 0, v58
	s_nop 1
	v_cndmask_b32_e64 v54, v54, v56, s[10:11]
	v_mul_f32_e32 v55, 0x37800000, v54
	v_cndmask_b32_e32 v54, v54, v55, vcc
	v_cmp_class_f32_e32 vcc, v0, v223
	s_nop 1
	v_cndmask_b32_e32 v0, v54, v0, vcc
	v_div_scale_f32 v54, s[2:3], v0, v0, 1.0
	v_rcp_f32_e32 v55, v54
	s_mov_b32 s2, 0x48000
	v_add3_u32 v62, v136, v230, s2
	v_add_u32_e32 v241, s2, v240
	v_fma_f32 v56, -v54, v55, 1.0
	v_fmac_f32_e32 v55, v56, v55
	v_div_scale_f32 v56, vcc, 1.0, v0, 1.0
	v_mul_f32_e32 v57, v56, v55
	v_fma_f32 v58, -v54, v57, v56
	v_fmac_f32_e32 v57, v58, v55
	v_fma_f32 v54, -v54, v57, v56
	v_div_fmas_f32 v54, v54, v55, v57
	v_div_fixup_f32 v0, v54, v0, 1.0
	v_lshlrev_b32_e32 v54, 16, v90
	v_and_b32_e32 v55, 0xffff0000, v90
	v_lshlrev_b32_e32 v56, 16, v91
	v_and_b32_e32 v57, 0xffff0000, v91
	v_lshlrev_b32_e32 v58, 16, v92
	v_pk_mul_f32 v[50:51], v[50:51], v[0:1] op_sel_hi:[1,0]
	v_pk_mul_f32 v[52:53], v[52:53], v[0:1] op_sel_hi:[1,0]
	v_pk_mul_f32 v[46:47], v[46:47], v[0:1] op_sel_hi:[1,0]
	v_pk_mul_f32 v[48:49], v[48:49], v[0:1] op_sel_hi:[1,0]
	v_pk_fma_f32 v[52:53], v[84:85], v[52:53], v[56:57]
	v_pk_fma_f32 v[50:51], v[82:83], v[50:51], v[54:55]
	v_pk_fma_f32 v[56:57], v[78:79], v[46:47], v[58:59]
	v_cvt_pk_bf16_f32 v46, v50, v51
	v_cvt_pk_bf16_f32 v47, v52, v53
	v_pk_fma_f32 v[54:55], v[80:81], v[48:49], v[60:61]
	v_cvt_pk_bf16_f32 v48, v56, v57
	v_pk_mul_f32 v[60:61], v[202:203], v[56:57]
	v_cvt_pk_bf16_f32 v49, v54, v55
	global_store_dwordx4 v241, v[46:49], s[24:25]
	v_pk_mul_f32 v[58:59], v[198:199], v[54:55]
; __device__ __forceinline__ unsigned cvt_pk_bf16(float lo, float hi) { unsigned r; asm volatile("v_cvt_pk_bf16_f32 %0, %1, %2" : "=v"(r) : "v"(lo), "v"(hi)); return r; }
; #define PG8_GPTR(p) ((__attribute__((address_space(1))) char*)(p))
;     __device__ __forceinline__ void operator()(const f32x4 (&acc)[2][2][4][2], const Unit& u, int wr, int wc, int fr, int fq) const {
;     ...
; #pragma unroll
;             for (int mm = 0; mm < 2; ++mm) {
;                 const int m = mp + mm;
;                 const int row = u.pm * BM + ai * HALF + wr * 64 + m * 16 + fr; float q = 0.f;
; #pragma unroll
;                 for (int bj = 0; bj < 2; ++bj) {
;                     const unsigned offb = (unsigned)(row * DM + col0 + bj * HALF) * 2u;
;                     const u32x4 bw = bv[mm][bj];
;                     const f32x4 b0 = (f32x4){__uint_as_float(bw.x << 16), __uint_as_float(bw.x & 0xffff0000u), __uint_as_float(bw.y << 16), __uint_as_float(bw.y & 0xffff0000u)};
;                     const f32x4 b1 = (f32x4){__uint_as_float(bw.z << 16), __uint_as_float(bw.z & 0xffff0000u), __uint_as_float(bw.w << 16), __uint_as_float(bw.w & 0xffff0000u)};
;                     f32x4 a0 = acc[ai][bj][m][0], a1 = acc[ai][bj][m][1]; if constexpr (GN) { a0 *= rc[ai * 4 + m]; a1 *= rc[ai * 4 + m]; }
;                     const f32x4 o0 = b0 + g[bj][0] * a0, o1 = b1 + g[bj][1] * a1;
;                     u32x4 wo; wo.x = cvt_pk_bf16(o0[0], o0[1]); wo.y = cvt_pk_bf16(o0[2], o0[3]); wo.z = cvt_pk_bf16(o1[0], o1[1]); wo.w = cvt_pk_bf16(o1[2], o1[3]);
;                     *(gs_u32x4*)(PG8_GPTR(out) + offb) = wo;
;                     if (xg) {
;                         const f32x4 h0 = o0 * cf[bj][0], h1 = o1 * cf[bj][1];
;                         u32x4 w; w.x = cvt_pk_bf16(h0[0], h0[1]); w.y = cvt_pk_bf16(h0[2], h0[3]); w.z = cvt_pk_bf16(h1[0], h1[1]); w.w = cvt_pk_bf16(h1[2], h1[3]);
;                         *(gs_u32x4*)(PG8_GPTR(xg) + offb) = w;
;                         q += (o0[0] * o0[0] + o0[1] * o0[1]) + (o0[2] * o0[2] + o0[3] * o0[3]) + (o1[0] * o1[0] + o1[1] * o1[1]) + (o1[2] * o1[2] + o1[3] * o1[3]);
;                     }
;                 }
;                 if (xg) ssq_put(ssq, row, q, fr, fq);
	v_pk_mul_f32 v[42:43], v[42:43], v[0:1] op_sel_hi:[1,0]
	v_pk_mul_f32 v[46:47], v[204:205], v[50:51]
	v_pk_mul_f32 v[48:49], v[200:201], v[52:53]
	v_cvt_pk_bf16_f32 v46, v46, v47
	v_pk_mul_f32 v[44:45], v[44:45], v[0:1] op_sel_hi:[1,0]
	v_cvt_pk_bf16_f32 v47, v48, v49
	v_cvt_pk_bf16_f32 v48, v60, v61
	v_cvt_pk_bf16_f32 v49, v58, v59
	global_store_dwordx4 v62, v[46:49], s[26:27]
	v_pk_mul_f32 v[38:39], v[38:39], v[0:1] op_sel_hi:[1,0]
	v_pk_mul_f32 v[40:41], v[40:41], v[0:1] op_sel_hi:[1,0]
	v_mul_f32_e32 v46, v51, v51
	v_mul_f32_e32 v47, v53, v53
	v_fmac_f32_e32 v46, v50, v50
	v_fmac_f32_e32 v47, v52, v52
	v_add_f32_e32 v46, v46, v47
	v_mul_f32_e32 v47, v57, v57
	v_fmac_f32_e32 v47, v56, v56
	v_add_f32_e32 v46, v47, v46
	v_mul_f32_e32 v47, v55, v55
	v_fmac_f32_e32 v47, v54, v54
	v_add_f32_e32 v54, v47, v46
	v_lshlrev_b32_e32 v46, 16, v86
	v_and_b32_e32 v47, 0xffff0000, v86
	v_lshlrev_b32_e32 v48, 16, v87
	v_and_b32_e32 v49, 0xffff0000, v87
	v_lshlrev_b32_e32 v50, 16, v88
	v_and_b32_e32 v51, 0xffff0000, v88
	v_lshlrev_b32_e32 v52, 16, v89
	v_and_b32_e32 v53, 0xffff0000, v89
	v_pk_fma_f32 v[44:45], v[76:77], v[44:45], v[48:49]
	v_pk_fma_f32 v[42:43], v[74:75], v[42:43], v[46:47]
	v_pk_fma_f32 v[46:47], v[40:41], v[72:73], v[52:53]
	v_pk_fma_f32 v[48:49], v[38:39], v[70:71], v[50:51]
	v_cvt_pk_bf16_f32 v38, v42, v43
	v_cvt_pk_bf16_f32 v39, v44, v45
	v_mul_f32_e32 v0, v47, v47
	v_cvt_pk_bf16_f32 v40, v48, v49
	v_cvt_pk_bf16_f32 v41, v46, v47
	global_store_dwordx4 v241, v[38:41], s[24:25] offset:1024
	v_fmac_f32_e32 v0, v46, v46
	v_pk_mul_f32 v[50:51], v[196:197], v[44:45]
	v_mul_f32_e32 v39, v43, v43
	v_mul_f32_e32 v40, v45, v45
	v_mul_f32_e32 v38, v49, v49
	v_fmac_f32_e32 v39, v42, v42
	v_fmac_f32_e32 v40, v44, v44
	v_fmac_f32_e32 v38, v48, v48
	v_add_f32_e32 v39, v39, v40
	v_add_f32_e32 v38, v38, v39
	v_add_f32_e32 v0, v0, v38
	v_add_f32_e32 v0, v54, v0
	ds_bpermute_b32 v41, v229, v0
	v_pk_mul_f32 v[38:39], v[174:175], v[42:43]
	v_pk_mul_f32 v[42:43], v[194:195], v[48:49]
	v_cvt_pk_bf16_f32 v40, v38, v39
	v_pk_mul_f32 v[44:45], v[176:177], v[46:47]
	s_waitcnt lgkmcnt(0)
	v_add_f32_e32 v0, v0, v41
	ds_bpermute_b32 v38, v228, v0
	v_cvt_pk_bf16_f32 v41, v50, v51
	v_cvt_pk_bf16_f32 v42, v42, v43
	v_cvt_pk_bf16_f32 v43, v44, v45
	global_store_dwordx4 v62, v[40:43], s[26:27] offset:256
	s_and_saveexec_b64 s[2:3], s[8:9]
	s_cbranch_execz .LBB0_1099
	s_waitcnt lgkmcnt(0)
	v_add_f32_e32 v0, v0, v38
	v_mul_f32_e32 v0, 0x4b800000, v0
	v_trunc_f32_e32 v0, v0
	v_mul_f32_e32 v38, 0x2f800000, v0
	v_floor_f32_e32 v39, v38
	v_fmac_f32_e32 v0, 0xcf800000, v39
	v_cvt_u32_f32_e32 v38, v0
	v_cvt_u32_f32_e32 v39, v39
	flat_atomic_add_x2 v[134:135], v[38:39] offset:1152
.LBB0_1099:
	s_or_b64 exec, exec, s[2:3]
	v_ffbh_u32_e32 v0, v207
	v_min_u32_e32 v0, 32, v0
	s_waitcnt lgkmcnt(0)
	v_lshlrev_b64 v[38:39], v0, v[206:207]
	v_min_u32_e32 v38, 1, v38
	v_or_b32_e32 v38, v39, v38
	v_cvt_f32_u32_e32 v38, v38
	v_sub_u32_e32 v0, 32, v0
	v_ldexp_f32 v0, v38, v0
	v_mul_f32_e32 v0, 0x33800000, v0
	v_fmamk_f32 v0, v0, 0x3b800000, v226
	v_cmp_gt_f32_e32 vcc, s71, v0
	v_mul_f32_e32 v38, 0x4f800000, v0
	s_nop 0
	v_cndmask_b32_e32 v0, v0, v38, vcc
	v_sqrt_f32_e32 v38, v0
	s_nop 0
	v_add_u32_e32 v39, -1, v38
	v_fma_f32 v40, -v39, v38, v0
	v_cmp_ge_f32_e64 s[10:11], 0, v40
	v_add_u32_e32 v40, 1, v38
	s_nop 0
	v_cndmask_b32_e64 v39, v38, v39, s[10:11]
	v_fma_f32 v38, -v40, v38, v0
	v_cmp_lt_f32_e64 s[10:11], 0, v38
	s_nop 1
	v_cndmask_b32_e64 v38, v39, v40, s[10:11]
	v_mul_f32_e32 v39, 0x37800000, v38
	v_cndmask_b32_e32 v38, v38, v39, vcc
	v_cmp_class_f32_e32 vcc, v0, v223
	s_nop 1
	v_cndmask_b32_e32 v0, v38, v0, vcc
	v_div_scale_f32 v38, s[2:3], v0, v0, 1.0
	v_rcp_f32_e32 v39, v38
	s_mov_b32 s2, 0x50000
	v_add3_u32 v58, v136, v230, s2
	v_add_u32_e32 v241, s2, v240
	v_fma_f32 v40, -v38, v39, 1.0
	v_fmac_f32_e32 v39, v40, v39
	v_div_scale_f32 v40, vcc, 1.0, v0, 1.0
	v_mul_f32_e32 v41, v40, v39
	v_fma_f32 v42, -v38, v41, v40
	v_fmac_f32_e32 v41, v42, v39
	v_fma_f32 v38, -v38, v41, v40
	v_div_fmas_f32 v38, v38, v39, v41
	v_div_fixup_f32 v0, v38, v0, 1.0
	v_add_u32_e32 v38, 0x50000, v240
	global_load_dwordx4 v[50:53], v38, s[22:23]
	global_load_dwordx4 v[46:49], v38, s[22:23] offset:1024
	v_add_u32_e32 v38, 0x58000, v240
	global_load_dwordx4 v[42:45], v38, s[22:23]
	s_nop 0
	global_load_dwordx4 v[38:41], v38, s[22:23] offset:1024
	v_pk_mul_f32 v[34:35], v[34:35], v[0:1] op_sel_hi:[1,0]
	v_pk_mul_f32 v[36:37], v[36:37], v[0:1] op_sel_hi:[1,0]
	v_pk_mul_f32 v[30:31], v[30:31], v[0:1] op_sel_hi:[1,0]
	v_pk_mul_f32 v[32:33], v[32:33], v[0:1] op_sel_hi:[1,0]
	v_pk_mul_f32 v[26:27], v[26:27], v[0:1] op_sel_hi:[1,0]
	v_pk_mul_f32 v[28:29], v[28:29], v[0:1] op_sel_hi:[1,0]
	v_pk_mul_f32 v[22:23], v[22:23], v[0:1] op_sel_hi:[1,0]
	v_pk_mul_f32 v[24:25], v[24:25], v[0:1] op_sel_hi:[1,0]
	s_waitcnt vmcnt(0)
; __device__ __forceinline__ unsigned cvt_pk_bf16(float lo, float hi) { unsigned r; asm volatile("v_cvt_pk_bf16_f32 %0, %1, %2" : "=v"(r) : "v"(lo), "v"(hi)); return r; }
; #define PG8_GPTR(p) ((__attribute__((address_space(1))) char*)(p))
;     __device__ __forceinline__ void operator()(const f32x4 (&acc)[2][2][4][2], const Unit& u, int wr, int wc, int fr, int fq) const {
;     ...
; #pragma unroll
;             for (int mm = 0; mm < 2; ++mm) {
;                 const int m = mp + mm;
;                 const int row = u.pm * BM + ai * HALF + wr * 64 + m * 16 + fr; float q = 0.f;
; #pragma unroll
;                 for (int bj = 0; bj < 2; ++bj) {
;                     const unsigned offb = (unsigned)(row * DM + col0 + bj * HALF) * 2u;
;                     const u32x4 bw = bv[mm][bj];
;                     const f32x4 b0 = (f32x4){__uint_as_float(bw.x << 16), __uint_as_float(bw.x & 0xffff0000u), __uint_as_float(bw.y << 16), __uint_as_float(bw.y & 0xffff0000u)};
;                     const f32x4 b1 = (f32x4){__uint_as_float(bw.z << 16), __uint_as_float(bw.z & 0xffff0000u), __uint_as_float(bw.w << 16), __uint_as_float(bw.w & 0xffff0000u)};
;                     f32x4 a0 = acc[ai][bj][m][0], a1 = acc[ai][bj][m][1]; if constexpr (GN) { a0 *= rc[ai * 4 + m]; a1 *= rc[ai * 4 + m]; }
;                     const f32x4 o0 = b0 + g[bj][0] * a0, o1 = b1 + g[bj][1] * a1;
;                     u32x4 wo; wo.x = cvt_pk_bf16(o0[0], o0[1]); wo.y = cvt_pk_bf16(o0[2], o0[3]); wo.z = cvt_pk_bf16(o1[0], o1[1]); wo.w = cvt_pk_bf16(o1[2], o1[3]);
;                     *(gs_u32x4*)(PG8_GPTR(out) + offb) = wo;
;                     if (xg) {
;                         const f32x4 h0 = o0 * cf[bj][0], h1 = o1 * cf[bj][1];
;                         u32x4 w; w.x = cvt_pk_bf16(h0[0], h0[1]); w.y = cvt_pk_bf16(h0[2], h0[3]); w.z = cvt_pk_bf16(h1[0], h1[1]); w.w = cvt_pk_bf16(h1[2], h1[3]);
;                         *(gs_u32x4*)(PG8_GPTR(xg) + offb) = w;
;                         q += (o0[0] * o0[0] + o0[1] * o0[1]) + (o0[2] * o0[2] + o0[3] * o0[3]) + (o1[0] * o1[0] + o1[1] * o1[1]) + (o1[2] * o1[2] + o1[3] * o1[3]);
;                     }
;                 }
;                 if (xg) ssq_put(ssq, row, q, fr, fq);
	v_lshlrev_b32_e32 v54, 16, v50
	v_and_b32_e32 v55, 0xffff0000, v50
	v_lshlrev_b32_e32 v50, 16, v51
	v_and_b32_e32 v51, 0xffff0000, v51
	v_lshlrev_b32_e32 v56, 16, v52
	v_and_b32_e32 v57, 0xffff0000, v52
	v_lshlrev_b32_e32 v52, 16, v53
	v_and_b32_e32 v53, 0xffff0000, v53
	v_pk_fma_f32 v[36:37], v[84:85], v[36:37], v[50:51]
	v_pk_fma_f32 v[34:35], v[82:83], v[34:35], v[54:55]
	v_pk_fma_f32 v[50:51], v[80:81], v[32:33], v[52:53]
	v_pk_fma_f32 v[52:53], v[78:79], v[30:31], v[56:57]
	v_cvt_pk_bf16_f32 v30, v34, v35
	v_cvt_pk_bf16_f32 v31, v36, v37
	v_pk_mul_f32 v[54:55], v[198:199], v[50:51]
	v_cvt_pk_bf16_f32 v32, v52, v53
	v_cvt_pk_bf16_f32 v33, v50, v51
	global_store_dwordx4 v241, v[30:33], s[24:25]
	v_pk_mul_f32 v[56:57], v[202:203], v[52:53]
	s_nop 0
	v_pk_mul_f32 v[30:31], v[204:205], v[34:35]
	v_pk_mul_f32 v[32:33], v[200:201], v[36:37]
	v_cvt_pk_bf16_f32 v30, v30, v31
	s_nop 0
	v_cvt_pk_bf16_f32 v31, v32, v33
	v_cvt_pk_bf16_f32 v32, v56, v57
	v_cvt_pk_bf16_f32 v33, v54, v55
	global_store_dwordx4 v58, v[30:33], s[26:27]
	s_nop 1
	v_mul_f32_e32 v30, v35, v35
	v_mul_f32_e32 v31, v37, v37
	v_fmac_f32_e32 v30, v34, v34
	v_fmac_f32_e32 v31, v36, v36
	v_add_f32_e32 v30, v30, v31
	v_mul_f32_e32 v31, v53, v53
	v_fmac_f32_e32 v31, v52, v52
	v_add_f32_e32 v30, v31, v30
	v_mul_f32_e32 v31, v51, v51
	v_fmac_f32_e32 v31, v50, v50
	v_add_f32_e32 v50, v31, v30
	v_lshlrev_b32_e32 v30, 16, v46
	v_and_b32_e32 v31, 0xffff0000, v46
	v_lshlrev_b32_e32 v32, 16, v47
	v_and_b32_e32 v33, 0xffff0000, v47
	v_lshlrev_b32_e32 v34, 16, v48
	v_and_b32_e32 v35, 0xffff0000, v48
	v_lshlrev_b32_e32 v36, 16, v49
	v_and_b32_e32 v37, 0xffff0000, v49
	v_pk_fma_f32 v[28:29], v[76:77], v[28:29], v[32:33]
	v_pk_fma_f32 v[26:27], v[74:75], v[26:27], v[30:31]
	v_pk_fma_f32 v[30:31], v[72:73], v[24:25], v[36:37]
	v_pk_fma_f32 v[32:33], v[70:71], v[22:23], v[34:35]
	v_cvt_pk_bf16_f32 v22, v26, v27
	v_cvt_pk_bf16_f32 v23, v28, v29
	v_pk_mul_f32 v[34:35], v[176:177], v[30:31]
	v_cvt_pk_bf16_f32 v24, v32, v33
	v_cvt_pk_bf16_f32 v25, v30, v31
	global_store_dwordx4 v241, v[22:25], s[24:25] offset:1024
	v_pk_mul_f32 v[36:37], v[194:195], v[32:33]
	v_mul_f32_e32 v0, v31, v31
	v_pk_mul_f32 v[24:25], v[196:197], v[28:29]
	v_pk_mul_f32 v[22:23], v[174:175], v[26:27]
	v_fmac_f32_e32 v0, v30, v30
	v_cvt_pk_bf16_f32 v22, v22, v23
	v_cvt_pk_bf16_f32 v23, v24, v25
	v_cvt_pk_bf16_f32 v24, v36, v37
	v_cvt_pk_bf16_f32 v25, v34, v35
	global_store_dwordx4 v58, v[22:25], s[26:27] offset:256
	s_nop 1
	v_mul_f32_e32 v23, v27, v27
	v_mul_f32_e32 v24, v29, v29
	v_mul_f32_e32 v22, v33, v33
	v_fmac_f32_e32 v23, v26, v26
	v_fmac_f32_e32 v24, v28, v28
	v_fmac_f32_e32 v22, v32, v32
	v_add_f32_e32 v23, v23, v24
	v_add_f32_e32 v22, v22, v23
	v_add_f32_e32 v0, v0, v22
	v_add_f32_e32 v0, v50, v0
	ds_bpermute_b32 v22, v229, v0
	s_waitcnt lgkmcnt(0)
	v_add_f32_e32 v0, v0, v22
	ds_bpermute_b32 v22, v228, v0
	s_and_saveexec_b64 s[2:3], s[8:9]
	s_cbranch_execz .LBB0_1101
	s_waitcnt lgkmcnt(0)
	v_add_f32_e32 v0, v0, v22
	v_mul_f32_e32 v0, 0x4b800000, v0
	v_trunc_f32_e32 v0, v0
	v_mul_f32_e32 v22, 0x2f800000, v0
	v_floor_f32_e32 v23, v22
	v_fmac_f32_e32 v0, 0xcf800000, v23
	v_cvt_u32_f32_e32 v22, v0
	v_cvt_u32_f32_e32 v23, v23
	flat_atomic_add_x2 v[134:135], v[22:23] offset:1280
; __device__ __forceinline__ unsigned cvt_pk_bf16(float lo, float hi) { unsigned r; asm volatile("v_cvt_pk_bf16_f32 %0, %1, %2" : "=v"(r) : "v"(lo), "v"(hi)); return r; }
; #define PG8_GPTR(p) ((__attribute__((address_space(1))) char*)(p))
;     __device__ __forceinline__ void operator()(const f32x4 (&acc)[2][2][4][2], const Unit& u, int wr, int wc, int fr, int fq) const {
;     ...
; #pragma unroll
;             for (int mm = 0; mm < 2; ++mm) {
;                 const int m = mp + mm;
;                 const int row = u.pm * BM + ai * HALF + wr * 64 + m * 16 + fr; float q = 0.f;
; #pragma unroll
;                 for (int bj = 0; bj < 2; ++bj) {
;                     const unsigned offb = (unsigned)(row * DM + col0 + bj * HALF) * 2u;
;                     const u32x4 bw = bv[mm][bj];
;                     const f32x4 b0 = (f32x4){__uint_as_float(bw.x << 16), __uint_as_float(bw.x & 0xffff0000u), __uint_as_float(bw.y << 16), __uint_as_float(bw.y & 0xffff0000u)};
;                     const f32x4 b1 = (f32x4){__uint_as_float(bw.z << 16), __uint_as_float(bw.z & 0xffff0000u), __uint_as_float(bw.w << 16), __uint_as_float(bw.w & 0xffff0000u)};
;                     f32x4 a0 = acc[ai][bj][m][0], a1 = acc[ai][bj][m][1]; if constexpr (GN) { a0 *= rc[ai * 4 + m]; a1 *= rc[ai * 4 + m]; }
;                     const f32x4 o0 = b0 + g[bj][0] * a0, o1 = b1 + g[bj][1] * a1;
;                     u32x4 wo; wo.x = cvt_pk_bf16(o0[0], o0[1]); wo.y = cvt_pk_bf16(o0[2], o0[3]); wo.z = cvt_pk_bf16(o1[0], o1[1]); wo.w = cvt_pk_bf16(o1[2], o1[3]);
;                     *(gs_u32x4*)(PG8_GPTR(out) + offb) = wo;
;                     if (xg) {
;                         const f32x4 h0 = o0 * cf[bj][0], h1 = o1 * cf[bj][1];
;                         u32x4 w; w.x = cvt_pk_bf16(h0[0], h0[1]); w.y = cvt_pk_bf16(h0[2], h0[3]); w.z = cvt_pk_bf16(h1[0], h1[1]); w.w = cvt_pk_bf16(h1[2], h1[3]);
;                         *(gs_u32x4*)(PG8_GPTR(xg) + offb) = w;
;                         q += (o0[0] * o0[0] + o0[1] * o0[1]) + (o0[2] * o0[2] + o0[3] * o0[3]) + (o1[0] * o1[0] + o1[1] * o1[1]) + (o1[2] * o1[2] + o1[3] * o1[3]);
;                     }
;                 }
;                 if (xg) ssq_put(ssq, row, q, fr, fq);
.LBB0_1101:
	s_or_b64 exec, exec, s[2:3]
	v_ffbh_u32_e32 v0, v3
	v_min_u32_e32 v0, 32, v0
	v_lshlrev_b64 v[2:3], v0, v[2:3]
	v_min_u32_e32 v2, 1, v2
	v_or_b32_e32 v2, v3, v2
	v_cvt_f32_u32_e32 v2, v2
	v_sub_u32_e32 v0, 32, v0
	v_and_b32_e32 v25, 0xffff0000, v44
	v_lshlrev_b32_e32 v26, 16, v45
	v_ldexp_f32 v0, v2, v0
	v_mul_f32_e32 v0, 0x33800000, v0
	v_fmamk_f32 v0, v0, 0x3b800000, v226
	v_mul_f32_e32 v2, 0x4f800000, v0
	v_cmp_gt_f32_e32 vcc, s71, v0
	v_and_b32_e32 v27, 0xffff0000, v45
	s_nop 0
	v_cndmask_b32_e32 v0, v0, v2, vcc
	v_sqrt_f32_e32 v2, v0
	s_nop 0
	v_add_u32_e32 v3, -1, v2
	s_waitcnt lgkmcnt(0)
	v_add_u32_e32 v22, 1, v2
	v_fma_f32 v23, -v3, v2, v0
	v_fma_f32 v24, -v22, v2, v0
	v_cmp_ge_f32_e64 s[10:11], 0, v23
	s_nop 1
	v_cndmask_b32_e64 v2, v2, v3, s[10:11]
	v_cmp_lt_f32_e64 s[10:11], 0, v24
	s_nop 1
	v_cndmask_b32_e64 v2, v2, v22, s[10:11]
	v_mul_f32_e32 v3, 0x37800000, v2
	v_cndmask_b32_e32 v2, v2, v3, vcc
	v_cmp_class_f32_e32 vcc, v0, v223
	s_nop 1
	v_cndmask_b32_e32 v0, v2, v0, vcc
	v_div_scale_f32 v2, s[2:3], v0, v0, 1.0
	v_rcp_f32_e32 v3, v2
	s_mov_b32 s2, 0x58000
	v_add3_u32 v28, v136, v230, s2
	v_add_u32_e32 v241, s2, v240
	v_fma_f32 v22, -v2, v3, 1.0
	v_fmac_f32_e32 v3, v22, v3
	v_div_scale_f32 v22, vcc, 1.0, v0, 1.0
	v_mul_f32_e32 v23, v22, v3
	v_fma_f32 v24, -v2, v23, v22
	v_fmac_f32_e32 v23, v24, v3
	v_fma_f32 v2, -v2, v23, v22
	v_div_fmas_f32 v2, v2, v3, v23
	v_div_fixup_f32 v0, v2, v0, 1.0
	v_lshlrev_b32_e32 v2, 16, v42
	v_and_b32_e32 v3, 0xffff0000, v42
	v_lshlrev_b32_e32 v22, 16, v43
	v_and_b32_e32 v23, 0xffff0000, v43
	v_lshlrev_b32_e32 v24, 16, v44
	v_pk_mul_f32 v[18:19], v[18:19], v[0:1] op_sel_hi:[1,0]
	v_pk_mul_f32 v[20:21], v[20:21], v[0:1] op_sel_hi:[1,0]
	v_pk_mul_f32 v[12:13], v[12:13], v[0:1] op_sel_hi:[1,0]
	v_pk_mul_f32 v[14:15], v[14:15], v[0:1] op_sel_hi:[1,0]
	v_pk_fma_f32 v[20:21], v[84:85], v[20:21], v[22:23]
	v_pk_fma_f32 v[2:3], v[82:83], v[18:19], v[2:3]
	v_pk_fma_f32 v[22:23], v[78:79], v[12:13], v[24:25]
	v_cvt_pk_bf16_f32 v12, v2, v3
	v_cvt_pk_bf16_f32 v13, v20, v21
	v_pk_fma_f32 v[18:19], v[80:81], v[14:15], v[26:27]
	v_cvt_pk_bf16_f32 v14, v22, v23
	v_pk_mul_f32 v[26:27], v[202:203], v[22:23]
	v_cvt_pk_bf16_f32 v15, v18, v19
	global_store_dwordx4 v241, v[12:15], s[24:25]
	v_pk_mul_f32 v[24:25], v[198:199], v[18:19]
	v_pk_mul_f32 v[8:9], v[8:9], v[0:1] op_sel_hi:[1,0]
	v_pk_mul_f32 v[12:13], v[204:205], v[2:3]
	v_mul_f32_e32 v3, v3, v3
	v_fmac_f32_e32 v3, v2, v2
	v_mul_f32_e32 v2, v21, v21
	v_fmac_f32_e32 v2, v20, v20
	v_add_f32_e32 v2, v3, v2
	v_mul_f32_e32 v3, v23, v23
	v_fmac_f32_e32 v3, v22, v22
	v_pk_mul_f32 v[14:15], v[200:201], v[20:21]
	v_add_f32_e32 v2, v3, v2
	v_mul_f32_e32 v3, v19, v19
	v_cvt_pk_bf16_f32 v12, v12, v13
	v_cvt_pk_bf16_f32 v13, v14, v15
	v_cvt_pk_bf16_f32 v14, v26, v27
	v_cvt_pk_bf16_f32 v15, v24, v25
	v_fmac_f32_e32 v3, v18, v18
	global_store_dwordx4 v28, v[12:15], s[26:27]
	v_add_f32_e32 v20, v3, v2
	v_lshlrev_b32_e32 v2, 16, v38
	v_and_b32_e32 v3, 0xffff0000, v38
	v_lshlrev_b32_e32 v12, 16, v39
	v_and_b32_e32 v13, 0xffff0000, v39
	v_lshlrev_b32_e32 v14, 16, v40
	v_and_b32_e32 v15, 0xffff0000, v40
	v_pk_mul_f32 v[10:11], v[10:11], v[0:1] op_sel_hi:[1,0]
	v_pk_mul_f32 v[4:5], v[4:5], v[0:1] op_sel_hi:[1,0]
	v_lshlrev_b32_e32 v18, 16, v41
	v_and_b32_e32 v19, 0xffff0000, v41
	v_pk_mul_f32 v[6:7], v[6:7], v[0:1] op_sel_hi:[1,0]
	v_pk_fma_f32 v[10:11], v[76:77], v[10:11], v[12:13]
	v_pk_fma_f32 v[8:9], v[74:75], v[8:9], v[2:3]
	v_pk_fma_f32 v[12:13], v[70:71], v[4:5], v[14:15]
	v_cvt_pk_bf16_f32 v2, v8, v9
	v_cvt_pk_bf16_f32 v3, v10, v11
	v_pk_fma_f32 v[6:7], v[72:73], v[6:7], v[18:19]
	v_cvt_pk_bf16_f32 v4, v12, v13
	v_pk_mul_f32 v[14:15], v[196:197], v[10:11]
	v_cvt_pk_bf16_f32 v5, v6, v7
	global_store_dwordx4 v241, v[2:5], s[24:25] offset:1024
	v_mul_f32_e32 v0, v7, v7
	v_fmac_f32_e32 v0, v6, v6
	v_mul_f32_e32 v3, v9, v9
	v_mul_f32_e32 v4, v11, v11
	v_mul_f32_e32 v2, v13, v13
	v_fmac_f32_e32 v3, v8, v8
	v_fmac_f32_e32 v4, v10, v10
	v_fmac_f32_e32 v2, v12, v12
	v_add_f32_e32 v3, v3, v4
	v_add_f32_e32 v2, v2, v3
	v_add_f32_e32 v0, v0, v2
	v_add_f32_e32 v0, v20, v0
	ds_bpermute_b32 v5, v229, v0
	v_pk_mul_f32 v[2:3], v[174:175], v[8:9]
	v_pk_mul_f32 v[8:9], v[176:177], v[6:7]
	v_cvt_pk_bf16_f32 v4, v2, v3
	v_pk_mul_f32 v[6:7], v[194:195], v[12:13]
	s_waitcnt lgkmcnt(0)
	v_add_f32_e32 v0, v0, v5
	ds_bpermute_b32 v2, v228, v0
	v_cvt_pk_bf16_f32 v5, v14, v15
	v_cvt_pk_bf16_f32 v6, v6, v7
	v_cvt_pk_bf16_f32 v7, v8, v9
	global_store_dwordx4 v28, v[4:7], s[26:27] offset:256
	s_and_saveexec_b64 s[2:3], s[8:9]
	s_cbranch_execz .LBB0_1103
	s_waitcnt lgkmcnt(0)
	v_add_f32_e32 v0, v0, v2
	v_mul_f32_e32 v0, 0x4b800000, v0
	v_trunc_f32_e32 v0, v0
	v_mul_f32_e32 v2, 0x2f800000, v0
	v_floor_f32_e32 v3, v2
	v_fmac_f32_e32 v0, 0xcf800000, v3
	v_cvt_u32_f32_e32 v2, v0
	v_cvt_u32_f32_e32 v3, v3
	flat_atomic_add_x2 v[134:135], v[2:3] offset:1408

; __device__ __forceinline__ int opaque_tid(int wave_s) { int l; asm volatile("v_mbcnt_lo_u32_b32 %0, -1, 0\n\tv_mbcnt_hi_u32_b32 %0, -1, %0" : "=v"(l)); return (wave_s << 6) | l; }
; #define PG8_STAGE(bufoff, gbase, voff) do { _Pragma("unroll") for (int _i = 0; _i < 2; ++_i) \
;         __builtin_amdgcn_global_load_lds((const unsigned*)((const char*)(gbase) + (voff)[_i]), (PG8_LAS unsigned*)(lds + (bufoff) + ldsw + _i * 8192), 16, 0, 0); } while (0)
; #define PG8_LDA(dst, b, h) do { _Pragma("unroll") for (int m = 0; m < 4; ++m) _Pragma("unroll") for (int k = 0; k < 2; ++k) dst[m][k] = *(const PG8_LAS bf16x8*)(lds + PG8_SA(b, h) + aoff + m * 2048 + k * 1024); } while (0)
; #define PG8_LDB(dst, b, h) do { _Pragma("unroll") for (int n = 0; n < 2; ++n) _Pragma("unroll") for (int k = 0; k < 2; ++k) dst[n][k] = *(const PG8_LAS bf16x8*)(lds + PG8_SB(b, h) + boff + n * 2048 + k * 1024); } while (0)
; #define PG8_BAR __builtin_amdgcn_s_barrier()
; template <class Epi, class Sched, bool ALIGN_EPI = false, bool SP2 = false>
; __device__ __forceinline__ void gemm_phase(PG8_LAS unsigned char* lds, const Gemm g, const Sched& S, const Epi& E, const int wave_s) {
;     ...
;     for (;;) {
;         const bool has_next = S.next(ui + 1, nxt);
;         const char* nA = has_next ? (const char*)g.A + (size_t)nxt.pm * tstepA : cA; const char* nB = has_next ? (const char*)g.Bt + (size_t)nxt.pn * tstepB : cB;
;         for (int t = 0; t < nt; t += 2) {
;             if constexpr (Epi::KHOOK) { if (t == 6 || t == 12) { const int l3_ = opaque_tid(wave_s) & 63; E.khook(acc, t, wr, l3_ & 15, ui & 1, lds); } }
;             const bool last = (t == nt - 2);
;             const char* a1 = cA + (size_t)(t + 1) * kstep;
;             const char* a2 = last ? nA : cA + (size_t)(t + 2) * kstep; const char* b2 = last ? nB : cB + (size_t)(t + 2) * kstep;
;             const char* a3 = a2 + kstep; const char* b3 = b2 + kstep;
;             if (last && has_next) S.a_ready(nxt);
;             if constexpr (SP2) {
;             PG8_LDB(B0, 0, 0); PG8_LDB(B1, 0, 1); PG8_SCHED; PG8_LDA(At, 0, 0); PG8_STAGE(PG8_SA(1, 1), a1 + hstepA, voffA);
;             PG8_WAIT_V(8); PG8_WAIT_L(0); PG8_BAR; PG8_MMA(0, 0, At, B0); PG8_MMA(0, 1, At, B1); PG8_BAR; PG8_SCHED;
;             PG8_LDA(At, 0, 1); PG8_STAGE(PG8_SB(0, 0), b2, voffB); PG8_STAGE(PG8_SB(0, 1), b2 + hstepB, voffB); PG8_STAGE(PG8_SA(0, 0), a2, voffA);
.LBB0_1164:
	s_ashr_i32 s19, s18, 31
	s_lshl_b64 s[2:3], s[18:19], 19
	s_add_u32 s22, s40, s2
	s_addc_u32 s23, s41, s3
	s_and_b64 s[2:3], s[8:9], exec
	s_cselect_b32 s2, s23, s31
	s_cselect_b32 s3, s22, s30
	s_ashr_i32 s21, s20, 31
	s_lshl_b64 s[4:5], s[20:21], 19
	s_add_u32 s24, s42, s4
	s_addc_u32 s25, s43, s5
	s_and_b64 s[4:5], s[8:9], exec
	s_cselect_b32 s19, s25, s7
	s_cselect_b32 s21, s24, s6
	s_add_u32 s54, s6, 0x100
	s_addc_u32 s55, s7, 0
	s_add_u32 s6, s30, 0x40080
	v_mov_b32_e32 v2, 0
	s_addc_u32 s7, s31, 0
	s_mov_b32 s56, -2
	v_mov_b32_e32 v3, v2
	v_mov_b32_e32 v4, v2
	v_mov_b32_e32 v5, v2
	v_mov_b32_e32 v6, v2
	v_mov_b32_e32 v7, v2
	v_mov_b32_e32 v8, v2
	v_mov_b32_e32 v9, v2
	v_mov_b32_e32 v22, v2
	v_mov_b32_e32 v23, v2
	v_mov_b32_e32 v24, v2
	v_mov_b32_e32 v25, v2
	v_mov_b32_e32 v26, v2
	v_mov_b32_e32 v27, v2
	v_mov_b32_e32 v28, v2
	v_mov_b32_e32 v29, v2
	v_mov_b32_e32 v38, v2
	v_mov_b32_e32 v39, v2
	v_mov_b32_e32 v40, v2
	v_mov_b32_e32 v41, v2
	v_mov_b32_e32 v42, v2
	v_mov_b32_e32 v43, v2
	v_mov_b32_e32 v44, v2
	v_mov_b32_e32 v45, v2
	v_mov_b32_e32 v54, v2
	v_mov_b32_e32 v55, v2
	v_mov_b32_e32 v56, v2
	v_mov_b32_e32 v57, v2
	v_mov_b32_e32 v58, v2
	v_mov_b32_e32 v59, v2
	v_mov_b32_e32 v60, v2
	v_mov_b32_e32 v61, v2
	v_mov_b32_e32 v10, v2
	v_mov_b32_e32 v11, v2
	v_mov_b32_e32 v12, v2
	v_mov_b32_e32 v13, v2
	v_mov_b32_e32 v18, v2
	v_mov_b32_e32 v19, v2
	v_mov_b32_e32 v20, v2
	v_mov_b32_e32 v21, v2
	v_mov_b32_e32 v30, v2
	v_mov_b32_e32 v31, v2
	v_mov_b32_e32 v32, v2
	v_mov_b32_e32 v33, v2
	v_mov_b32_e32 v34, v2
	v_mov_b32_e32 v35, v2
	v_mov_b32_e32 v36, v2
	v_mov_b32_e32 v37, v2
	v_mov_b32_e32 v46, v2
	v_mov_b32_e32 v47, v2
	v_mov_b32_e32 v48, v2
	v_mov_b32_e32 v49, v2
	v_mov_b32_e32 v50, v2
	v_mov_b32_e32 v51, v2
	v_mov_b32_e32 v52, v2
	v_mov_b32_e32 v53, v2
	v_mov_b32_e32 v62, v2
	v_mov_b32_e32 v63, v2
	v_mov_b32_e32 v64, v2
	v_mov_b32_e32 v65, v2
	v_mov_b32_e32 v66, v2
	v_mov_b32_e32 v67, v2
	v_mov_b32_e32 v68, v2
	v_mov_b32_e32 v69, v2
	v_mov_b32_e32 v70, v2
	v_mov_b32_e32 v71, v2
	v_mov_b32_e32 v72, v2
	v_mov_b32_e32 v73, v2
	v_mov_b32_e32 v74, v2
	v_mov_b32_e32 v75, v2
	v_mov_b32_e32 v76, v2
	v_mov_b32_e32 v77, v2
	v_mov_b32_e32 v86, v2
	v_mov_b32_e32 v87, v2
	v_mov_b32_e32 v88, v2
	v_mov_b32_e32 v89, v2
	v_mov_b32_e32 v94, v2
	v_mov_b32_e32 v95, v2
	v_mov_b32_e32 v96, v2
	v_mov_b32_e32 v97, v2
	v_mov_b32_e32 v118, v2
	v_mov_b32_e32 v119, v2
	v_mov_b32_e32 v120, v2
	v_mov_b32_e32 v121, v2
	v_mov_b32_e32 v122, v2
	v_mov_b32_e32 v123, v2
	v_mov_b32_e32 v124, v2
	v_mov_b32_e32 v125, v2
	v_mov_b32_e32 v134, v2
	v_mov_b32_e32 v135, v2
	v_mov_b32_e32 v136, v2
	v_mov_b32_e32 v137, v2
	v_mov_b32_e32 v138, v2
	v_mov_b32_e32 v139, v2
	v_mov_b32_e32 v140, v2
	v_mov_b32_e32 v141, v2
	v_mov_b32_e32 v78, v2
	v_mov_b32_e32 v79, v2
	v_mov_b32_e32 v80, v2
	v_mov_b32_e32 v81, v2
	v_mov_b32_e32 v82, v2
	v_mov_b32_e32 v83, v2
	v_mov_b32_e32 v84, v2
	v_mov_b32_e32 v85, v2
	v_mov_b32_e32 v110, v2
	v_mov_b32_e32 v111, v2
	v_mov_b32_e32 v112, v2
	v_mov_b32_e32 v113, v2
	v_mov_b32_e32 v114, v2
	v_mov_b32_e32 v115, v2
	v_mov_b32_e32 v116, v2
	v_mov_b32_e32 v117, v2
	v_mov_b32_e32 v126, v2
	v_mov_b32_e32 v127, v2
	v_mov_b32_e32 v128, v2
	v_mov_b32_e32 v129, v2
	v_mov_b32_e32 v130, v2
	v_mov_b32_e32 v131, v2
	v_mov_b32_e32 v132, v2
	v_mov_b32_e32 v133, v2
	v_mov_b32_e32 v142, v2
	v_mov_b32_e32 v143, v2
	v_mov_b32_e32 v144, v2
	v_mov_b32_e32 v145, v2
	v_mov_b32_e32 v146, v2
	v_mov_b32_e32 v147, v2
	v_mov_b32_e32 v148, v2
	v_mov_b32_e32 v149, v2
.LBB0_1165:
	s_add_u32 s4, s6, 0xfffc0080
	s_addc_u32 s5, s7, -1
	s_add_i32 s57, 0, 0x10000
	s_cmp_eq_u32 s56, 12
	s_cselect_b32 s31, s2, s5
	s_cselect_b32 s30, s3, s4
	v_add_u32_e32 v0, s57, v17
	s_cselect_b32 s5, s19, s55
	s_cselect_b32 s4, s21, s54
	s_add_i32 s73, 0, 0x14000
	ds_read_b128 v[90:93], v0
	ds_read_b128 v[98:101], v0 offset:1024
	ds_read_b128 v[102:105], v0 offset:2048
	ds_read_b128 v[106:109], v0 offset:3072
	v_add_u32_e32 v0, s73, v17
	ds_read_b128 v[160:163], v0
	ds_read_b128 v[168:171], v0 offset:1024
	ds_read_b128 v[172:175], v0 offset:2048
	ds_read_b128 v[176:179], v0 offset:3072
	v_lshl_add_u64 v[164:165], s[6:7], 0, v[158:159]
	s_add_i32 m0, s27, 0xc000
	ds_read_b128 v[180:183], v166
	ds_read_b128 v[184:187], v166 offset:1024
	ds_read_b128 v[188:191], v166 offset:2048
	ds_read_b128 v[192:195], v166 offset:3072
	ds_read_b128 v[196:199], v166 offset:4096
	ds_read_b128 v[200:203], v166 offset:5120
	ds_read_b128 v[204:207], v166 offset:6144
	ds_read_b128 v[208:211], v166 offset:7168
	global_load_lds_dwordx4 v[164:165], off
	v_lshl_add_u64 v[164:165], s[6:7], 0, v[156:157]
	s_add_i32 m0, s27, 0xe000
	s_nop 0
	global_load_lds_dwordx4 v[164:165], off
	s_waitcnt vmcnt(8)
	s_waitcnt lgkmcnt(0)
	s_barrier
; #define PG8_STAGE(bufoff, gbase, voff) do { _Pragma("unroll") for (int _i = 0; _i < 2; ++_i) \
;         __builtin_amdgcn_global_load_lds((const unsigned*)((const char*)(gbase) + (voff)[_i]), (PG8_LAS unsigned*)(lds + (bufoff) + ldsw + _i * 8192), 16, 0, 0); } while (0)
; #define PG8_LDA(dst, b, h) do { _Pragma("unroll") for (int m = 0; m < 4; ++m) _Pragma("unroll") for (int k = 0; k < 2; ++k) dst[m][k] = *(const PG8_LAS bf16x8*)(lds + PG8_SA(b, h) + aoff + m * 2048 + k * 1024); } while (0)
; #define PG8_LDB(dst, b, h) do { _Pragma("unroll") for (int n = 0; n < 2; ++n) _Pragma("unroll") for (int k = 0; k < 2; ++k) dst[n][k] = *(const PG8_LAS bf16x8*)(lds + PG8_SB(b, h) + boff + n * 2048 + k * 1024); } while (0)
; #define PG8_MMA(ai, bj, At, Bt) do { __builtin_amdgcn_s_setprio(1); _Pragma("unroll") for (int m = 0; m < 4; ++m) _Pragma("unroll") for (int n = 0; n < 2; ++n) _Pragma("unroll") for (int k = 0; k < 2; ++k) \
;         acc[ai][bj][m][n] = __builtin_amdgcn_mfma_f32_16x16x32_bf16(Bt[n][k], At[m][k], acc[ai][bj][m][n], 0, 0, 0); __builtin_amdgcn_s_setprio(0); } while (0)
; #define PG8_WAIT_V(n) asm volatile("s_waitcnt vmcnt(" #n ")" ::: "memory")
; #define PG8_WAIT_L(n) asm volatile("s_waitcnt lgkmcnt(" #n ")" ::: "memory")
; #define PG8_BAR __builtin_amdgcn_s_barrier()
; #define PG8_SCHED __builtin_amdgcn_sched_barrier(0)
; template <class Epi, class Sched, bool ALIGN_EPI = false, bool SP2 = false>
; __device__ __forceinline__ void gemm_phase(PG8_LAS unsigned char* lds, const Gemm g, const Sched& S, const Epi& E, const int wave_s) {
;     ...
;             PG8_LDB(B0, 0, 0); PG8_LDB(B1, 0, 1); PG8_SCHED; PG8_LDA(At, 0, 0); PG8_STAGE(PG8_SA(1, 1), a1 + hstepA, voffA);
;             PG8_WAIT_V(8); PG8_WAIT_L(0); PG8_BAR; PG8_MMA(0, 0, At, B0); PG8_MMA(0, 1, At, B1); PG8_BAR; PG8_SCHED;
;             PG8_LDA(At, 0, 1); PG8_STAGE(PG8_SB(0, 0), b2, voffB); PG8_STAGE(PG8_SB(0, 1), b2 + hstepB, voffB); PG8_STAGE(PG8_SA(0, 0), a2, voffA);
;             PG8_WAIT_V(8); PG8_WAIT_L(0); PG8_BAR; PG8_MMA(1, 0, At, B0); PG8_MMA(1, 1, At, B1); PG8_BAR; PG8_SCHED;
;             PG8_LDB(B0, 1, 0); PG8_LDB(B1, 1, 1); PG8_SCHED; PG8_LDA(At, 1, 0); PG8_STAGE(PG8_SA(0, 1), a2 + hstepA, voffA);
;             PG8_WAIT_V(8); PG8_WAIT_L(0); PG8_BAR; PG8_MMA(0, 0, At, B0); PG8_MMA(0, 1, At, B1); PG8_BAR; PG8_SCHED;
	s_setprio 1
	s_waitcnt lgkmcnt(0)
	v_mfma_f32_16x16x32_bf16 v[146:149], v[90:93], v[180:183], v[146:149]
	v_mfma_f32_16x16x32_bf16 v[142:145], v[102:105], v[180:183], v[142:145]
	v_mfma_f32_16x16x32_bf16 v[130:133], v[90:93], v[188:191], v[130:133]
	v_mfma_f32_16x16x32_bf16 v[126:129], v[102:105], v[188:191], v[126:129]
	v_mfma_f32_16x16x32_bf16 v[114:117], v[90:93], v[196:199], v[114:117]
	v_mfma_f32_16x16x32_bf16 v[110:113], v[102:105], v[196:199], v[110:113]
	v_mfma_f32_16x16x32_bf16 v[82:85], v[90:93], v[204:207], v[82:85]
	v_mfma_f32_16x16x32_bf16 v[78:81], v[102:105], v[204:207], v[78:81]
	v_mfma_f32_16x16x32_bf16 v[146:149], v[98:101], v[184:187], v[146:149]
	v_mfma_f32_16x16x32_bf16 v[142:145], v[106:109], v[184:187], v[142:145]
	v_mfma_f32_16x16x32_bf16 v[130:133], v[98:101], v[192:195], v[130:133]
	v_mfma_f32_16x16x32_bf16 v[126:129], v[106:109], v[192:195], v[126:129]
	v_mfma_f32_16x16x32_bf16 v[114:117], v[98:101], v[200:203], v[114:117]
	v_mfma_f32_16x16x32_bf16 v[110:113], v[106:109], v[200:203], v[110:113]
	v_mfma_f32_16x16x32_bf16 v[82:85], v[98:101], v[208:211], v[82:85]
	v_mfma_f32_16x16x32_bf16 v[78:81], v[106:109], v[208:211], v[78:81]
	s_setprio 0
	s_setprio 1
	v_mfma_f32_16x16x32_bf16 v[138:141], v[160:163], v[180:183], v[138:141]
	v_mfma_f32_16x16x32_bf16 v[134:137], v[172:175], v[180:183], v[134:137]
	v_mfma_f32_16x16x32_bf16 v[122:125], v[160:163], v[188:191], v[122:125]
	v_mfma_f32_16x16x32_bf16 v[118:121], v[172:175], v[188:191], v[118:121]
	v_mfma_f32_16x16x32_bf16 v[94:97], v[160:163], v[196:199], v[94:97]
	v_mfma_f32_16x16x32_bf16 v[86:89], v[172:175], v[196:199], v[86:89]
	v_mfma_f32_16x16x32_bf16 v[74:77], v[160:163], v[204:207], v[74:77]
	v_mfma_f32_16x16x32_bf16 v[70:73], v[172:175], v[204:207], v[70:73]
	v_mfma_f32_16x16x32_bf16 v[138:141], v[168:171], v[184:187], v[138:141]
	v_mfma_f32_16x16x32_bf16 v[134:137], v[176:179], v[184:187], v[134:137]
	v_mfma_f32_16x16x32_bf16 v[122:125], v[168:171], v[192:195], v[122:125]
	v_mfma_f32_16x16x32_bf16 v[118:121], v[176:179], v[192:195], v[118:121]
	v_mfma_f32_16x16x32_bf16 v[94:97], v[168:171], v[200:203], v[94:97]
	v_mfma_f32_16x16x32_bf16 v[86:89], v[176:179], v[200:203], v[86:89]
	v_mfma_f32_16x16x32_bf16 v[74:77], v[168:171], v[208:211], v[74:77]
	v_mfma_f32_16x16x32_bf16 v[70:73], v[176:179], v[208:211], v[70:73]
	s_setprio 0
	s_barrier
	s_add_i32 s57, s57, s44
	v_lshl_add_u64 v[164:165], s[4:5], 0, v[150:151]
	s_mov_b32 m0, s57
	ds_read_b128 v[180:183], v166 offset:16384
	ds_read_b128 v[184:187], v166 offset:17408
	ds_read_b128 v[188:191], v166 offset:18432
	ds_read_b128 v[192:195], v166 offset:19456
	ds_read_b128 v[196:199], v166 offset:20480
	ds_read_b128 v[200:203], v166 offset:21504
	ds_read_b128 v[204:207], v166 offset:22528
	ds_read_b128 v[208:211], v166 offset:23552
	global_load_lds_dwordx4 v[164:165], off
	s_add_i32 m0, s57, 0x2000
	s_add_u32 s66, s4, 0x40000
	v_lshl_add_u64 v[212:213], s[4:5], 0, v[154:155]
	s_addc_u32 s67, s5, 0
	s_add_i32 s57, s73, s44
	global_load_lds_dwordx4 v[212:213], off
	v_lshl_add_u64 v[214:215], s[66:67], 0, v[150:151]
	s_mov_b32 m0, s57
	v_lshl_add_u64 v[216:217], s[30:31], 0, v[152:153]
	global_load_lds_dwordx4 v[214:215], off
	v_lshl_add_u64 v[214:215], s[66:67], 0, v[154:155]
	s_add_i32 m0, s57, 0x2000
	s_nop 0
	global_load_lds_dwordx4 v[214:215], off
	v_lshl_add_u64 v[214:215], s[30:31], 0, v[14:15]
	s_mov_b32 m0, s27
	s_nop 0
	global_load_lds_dwordx4 v[214:215], off
	s_mov_b32 m0, s29
	s_nop 0
	global_load_lds_dwordx4 v[216:217], off
	s_waitcnt vmcnt(8)
	s_waitcnt lgkmcnt(0)
	s_barrier
	s_setprio 1
	s_waitcnt lgkmcnt(0)
	v_mfma_f32_16x16x32_bf16 v[66:69], v[90:93], v[180:183], v[66:69]
	v_mfma_f32_16x16x32_bf16 v[62:65], v[102:105], v[180:183], v[62:65]
	v_mfma_f32_16x16x32_bf16 v[50:53], v[90:93], v[188:191], v[50:53]
	v_mfma_f32_16x16x32_bf16 v[46:49], v[102:105], v[188:191], v[46:49]
	v_mfma_f32_16x16x32_bf16 v[34:37], v[90:93], v[196:199], v[34:37]
	v_mfma_f32_16x16x32_bf16 v[30:33], v[102:105], v[196:199], v[30:33]
	v_mfma_f32_16x16x32_bf16 v[18:21], v[90:93], v[204:207], v[18:21]
	v_mfma_f32_16x16x32_bf16 v[10:13], v[102:105], v[204:207], v[10:13]
	v_mfma_f32_16x16x32_bf16 v[66:69], v[98:101], v[184:187], v[66:69]
	v_mfma_f32_16x16x32_bf16 v[62:65], v[106:109], v[184:187], v[62:65]
	v_mfma_f32_16x16x32_bf16 v[50:53], v[98:101], v[192:195], v[50:53]
	v_mfma_f32_16x16x32_bf16 v[46:49], v[106:109], v[192:195], v[46:49]
	v_mfma_f32_16x16x32_bf16 v[34:37], v[98:101], v[200:203], v[34:37]
	v_mfma_f32_16x16x32_bf16 v[30:33], v[106:109], v[200:203], v[30:33]
	v_mfma_f32_16x16x32_bf16 v[18:21], v[98:101], v[208:211], v[18:21]
	v_mfma_f32_16x16x32_bf16 v[10:13], v[106:109], v[208:211], v[10:13]
	s_setprio 0
	s_setprio 1
	v_mfma_f32_16x16x32_bf16 v[58:61], v[160:163], v[180:183], v[58:61]
	v_mfma_f32_16x16x32_bf16 v[54:57], v[172:175], v[180:183], v[54:57]
	v_mfma_f32_16x16x32_bf16 v[42:45], v[160:163], v[188:191], v[42:45]
	v_mfma_f32_16x16x32_bf16 v[38:41], v[172:175], v[188:191], v[38:41]
	v_mfma_f32_16x16x32_bf16 v[26:29], v[160:163], v[196:199], v[26:29]
	v_mfma_f32_16x16x32_bf16 v[22:25], v[172:175], v[196:199], v[22:25]
	v_mfma_f32_16x16x32_bf16 v[6:9], v[160:163], v[204:207], v[6:9]
	v_mfma_f32_16x16x32_bf16 v[2:5], v[172:175], v[204:207], v[2:5]
	v_mfma_f32_16x16x32_bf16 v[58:61], v[168:171], v[184:187], v[58:61]
	v_mfma_f32_16x16x32_bf16 v[54:57], v[176:179], v[184:187], v[54:57]
	v_mfma_f32_16x16x32_bf16 v[42:45], v[168:171], v[192:195], v[42:45]
	v_mfma_f32_16x16x32_bf16 v[38:41], v[176:179], v[192:195], v[38:41]
	v_mfma_f32_16x16x32_bf16 v[26:29], v[168:171], v[200:203], v[26:29]
	v_mfma_f32_16x16x32_bf16 v[22:25], v[176:179], v[200:203], v[22:25]
	v_mfma_f32_16x16x32_bf16 v[6:9], v[168:171], v[208:211], v[6:9]
	v_mfma_f32_16x16x32_bf16 v[2:5], v[176:179], v[208:211], v[2:5]
	s_setprio 0
	s_barrier
; #define PG8_STAGE(bufoff, gbase, voff) do { _Pragma("unroll") for (int _i = 0; _i < 2; ++_i) \
;         __builtin_amdgcn_global_load_lds((const unsigned*)((const char*)(gbase) + (voff)[_i]), (PG8_LAS unsigned*)(lds + (bufoff) + ldsw + _i * 8192), 16, 0, 0); } while (0)
; #define PG8_LDA(dst, b, h) do { _Pragma("unroll") for (int m = 0; m < 4; ++m) _Pragma("unroll") for (int k = 0; k < 2; ++k) dst[m][k] = *(const PG8_LAS bf16x8*)(lds + PG8_SA(b, h) + aoff + m * 2048 + k * 1024); } while (0)
; #define PG8_LDB(dst, b, h) do { _Pragma("unroll") for (int n = 0; n < 2; ++n) _Pragma("unroll") for (int k = 0; k < 2; ++k) dst[n][k] = *(const PG8_LAS bf16x8*)(lds + PG8_SB(b, h) + boff + n * 2048 + k * 1024); } while (0)
; #define PG8_MMA(ai, bj, At, Bt) do { __builtin_amdgcn_s_setprio(1); _Pragma("unroll") for (int m = 0; m < 4; ++m) _Pragma("unroll") for (int n = 0; n < 2; ++n) _Pragma("unroll") for (int k = 0; k < 2; ++k) \
;         acc[ai][bj][m][n] = __builtin_amdgcn_mfma_f32_16x16x32_bf16(Bt[n][k], At[m][k], acc[ai][bj][m][n], 0, 0, 0); __builtin_amdgcn_s_setprio(0); } while (0)
; #define PG8_WAIT_V(n) asm volatile("s_waitcnt vmcnt(" #n ")" ::: "memory")
; #define PG8_WAIT_L(n) asm volatile("s_waitcnt lgkmcnt(" #n ")" ::: "memory")
; #define PG8_BAR __builtin_amdgcn_s_barrier()
; #define PG8_SCHED __builtin_amdgcn_sched_barrier(0)
; template <class Epi, class Sched, bool ALIGN_EPI = false, bool SP2 = false>
; __device__ __forceinline__ void gemm_phase(PG8_LAS unsigned char* lds, const Gemm g, const Sched& S, const Epi& E, const int wave_s) {
;     ...
;             PG8_LDB(B0, 1, 0); PG8_LDB(B1, 1, 1); PG8_SCHED; PG8_LDA(At, 1, 0); PG8_STAGE(PG8_SA(0, 1), a2 + hstepA, voffA);
;             PG8_WAIT_V(8); PG8_WAIT_L(0); PG8_BAR; PG8_MMA(0, 0, At, B0); PG8_MMA(0, 1, At, B1); PG8_BAR; PG8_SCHED;
;             PG8_LDA(At, 1, 1); PG8_STAGE(PG8_SB(1, 0), b3, voffB); PG8_STAGE(PG8_SB(1, 1), b3 + hstepB, voffB); PG8_STAGE(PG8_SA(1, 0), a3, voffA);
;             PG8_WAIT_V(8); PG8_WAIT_L(0); PG8_BAR; PG8_MMA(1, 0, At, B0); PG8_MMA(1, 1, At, B1); PG8_BAR; PG8_SCHED;
	s_add_i32 s57, 0, 0x18000
	v_add_u32_e32 v0, s57, v17
	s_add_i32 s66, 0, 0x1c000
	ds_read_b128 v[90:93], v0
	ds_read_b128 v[98:101], v0 offset:1024
	ds_read_b128 v[102:105], v0 offset:2048
	ds_read_b128 v[106:109], v0 offset:3072
	v_add_u32_e32 v0, s66, v17
	ds_read_b128 v[160:163], v0
	ds_read_b128 v[168:171], v0 offset:1024
	ds_read_b128 v[172:175], v0 offset:2048
	ds_read_b128 v[176:179], v0 offset:3072
	s_add_u32 s30, s30, 0x40000
	s_addc_u32 s31, s31, 0
	s_mov_b32 m0, s45
	v_lshl_add_u64 v[218:219], s[30:31], 0, v[14:15]
	ds_read_b128 v[180:183], v166 offset:32768
	ds_read_b128 v[184:187], v166 offset:33792
	ds_read_b128 v[188:191], v166 offset:34816
	ds_read_b128 v[192:195], v166 offset:35840
	ds_read_b128 v[196:199], v166 offset:36864
	ds_read_b128 v[200:203], v166 offset:37888
	ds_read_b128 v[204:207], v166 offset:38912
	ds_read_b128 v[208:211], v166 offset:39936
	global_load_lds_dwordx4 v[218:219], off
	v_lshl_add_u64 v[218:219], s[30:31], 0, v[152:153]
	s_mov_b32 m0, s46
	s_nop 0
	global_load_lds_dwordx4 v[218:219], off
	s_waitcnt vmcnt(8)
	s_waitcnt lgkmcnt(0)
	s_barrier
	s_setprio 1
	s_waitcnt lgkmcnt(0)
	v_mfma_f32_16x16x32_bf16 v[146:149], v[90:93], v[180:183], v[146:149]
	v_mfma_f32_16x16x32_bf16 v[142:145], v[102:105], v[180:183], v[142:145]
	v_mfma_f32_16x16x32_bf16 v[130:133], v[90:93], v[188:191], v[130:133]
	v_mfma_f32_16x16x32_bf16 v[126:129], v[102:105], v[188:191], v[126:129]
	v_mfma_f32_16x16x32_bf16 v[114:117], v[90:93], v[196:199], v[114:117]
	v_mfma_f32_16x16x32_bf16 v[110:113], v[102:105], v[196:199], v[110:113]
	v_mfma_f32_16x16x32_bf16 v[82:85], v[90:93], v[204:207], v[82:85]
	v_mfma_f32_16x16x32_bf16 v[78:81], v[102:105], v[204:207], v[78:81]
	v_mfma_f32_16x16x32_bf16 v[146:149], v[98:101], v[184:187], v[146:149]
	v_mfma_f32_16x16x32_bf16 v[142:145], v[106:109], v[184:187], v[142:145]
	v_mfma_f32_16x16x32_bf16 v[130:133], v[98:101], v[192:195], v[130:133]
	v_mfma_f32_16x16x32_bf16 v[126:129], v[106:109], v[192:195], v[126:129]
	v_mfma_f32_16x16x32_bf16 v[114:117], v[98:101], v[200:203], v[114:117]
	v_mfma_f32_16x16x32_bf16 v[110:113], v[106:109], v[200:203], v[110:113]
	v_mfma_f32_16x16x32_bf16 v[82:85], v[98:101], v[208:211], v[82:85]
	v_mfma_f32_16x16x32_bf16 v[78:81], v[106:109], v[208:211], v[78:81]
	s_setprio 0
	s_setprio 1
	v_mfma_f32_16x16x32_bf16 v[138:141], v[160:163], v[180:183], v[138:141]
	v_mfma_f32_16x16x32_bf16 v[134:137], v[172:175], v[180:183], v[134:137]
	v_mfma_f32_16x16x32_bf16 v[122:125], v[160:163], v[188:191], v[122:125]
	v_mfma_f32_16x16x32_bf16 v[118:121], v[172:175], v[188:191], v[118:121]
	v_mfma_f32_16x16x32_bf16 v[94:97], v[160:163], v[196:199], v[94:97]
	v_mfma_f32_16x16x32_bf16 v[86:89], v[172:175], v[196:199], v[86:89]
	v_mfma_f32_16x16x32_bf16 v[74:77], v[160:163], v[204:207], v[74:77]
	v_mfma_f32_16x16x32_bf16 v[70:73], v[172:175], v[204:207], v[70:73]
	v_mfma_f32_16x16x32_bf16 v[138:141], v[168:171], v[184:187], v[138:141]
	v_mfma_f32_16x16x32_bf16 v[134:137], v[176:179], v[184:187], v[134:137]
	v_mfma_f32_16x16x32_bf16 v[122:125], v[168:171], v[192:195], v[122:125]
	v_mfma_f32_16x16x32_bf16 v[118:121], v[176:179], v[192:195], v[118:121]
	v_mfma_f32_16x16x32_bf16 v[94:97], v[168:171], v[200:203], v[94:97]
	v_mfma_f32_16x16x32_bf16 v[86:89], v[176:179], v[200:203], v[86:89]
	v_mfma_f32_16x16x32_bf16 v[74:77], v[168:171], v[208:211], v[74:77]
	v_mfma_f32_16x16x32_bf16 v[70:73], v[176:179], v[208:211], v[70:73]
	s_setprio 0
	s_barrier
	s_add_i32 s30, s57, s44
	v_lshl_add_u64 v[164:165], v[164:165], 0, s[58:59]
	s_mov_b32 m0, s30
	ds_read_b128 v[180:183], v166 offset:49152
	ds_read_b128 v[184:187], v166 offset:50176
	ds_read_b128 v[188:191], v166 offset:51200
	ds_read_b128 v[192:195], v166 offset:52224
	ds_read_b128 v[196:199], v166 offset:53248
	ds_read_b128 v[200:203], v166 offset:54272
	ds_read_b128 v[204:207], v166 offset:55296
	ds_read_b128 v[208:211], v166 offset:56320
	global_load_lds_dwordx4 v[164:165], off
	s_add_i32 m0, s30, 0x2000
	s_add_u32 s4, s4, 0x40080
	v_lshl_add_u64 v[164:165], v[212:213], 0, s[58:59]
	s_addc_u32 s5, s5, 0
	s_add_i32 s30, s66, s44
	global_load_lds_dwordx4 v[164:165], off
	v_lshl_add_u64 v[164:165], s[4:5], 0, v[150:151]
	s_mov_b32 m0, s30
	s_nop 0
	global_load_lds_dwordx4 v[164:165], off
	v_lshl_add_u64 v[164:165], s[4:5], 0, v[154:155]
	s_add_i32 m0, s30, 0x2000
	s_nop 0
	global_load_lds_dwordx4 v[164:165], off
	v_lshl_add_u64 v[164:165], v[214:215], 0, s[58:59]
	s_mov_b32 m0, s49
	s_nop 0
	global_load_lds_dwordx4 v[164:165], off
	v_lshl_add_u64 v[164:165], v[216:217], 0, s[58:59]
	s_mov_b32 m0, s50
	s_nop 0
	global_load_lds_dwordx4 v[164:165], off
	s_waitcnt vmcnt(8)
	s_waitcnt lgkmcnt(0)
	s_barrier
; __device__ __forceinline__ int opaque_tid(int wave_s) { int l; asm volatile("v_mbcnt_lo_u32_b32 %0, -1, 0\n\tv_mbcnt_hi_u32_b32 %0, -1, %0" : "=v"(l)); return (wave_s << 6) | l; }
; template <class Epi, class Sched, bool ALIGN_EPI = false, bool SP2 = false>
; __device__ __forceinline__ void gemm_phase(PG8_LAS unsigned char* lds, const Gemm g, const Sched& S, const Epi& E, const int wave_s) {
;     ...
;             PG8_WAIT_V(8); PG8_WAIT_L(0); PG8_BAR; PG8_MMA(1, 0, At, B0); PG8_MMA(1, 1, At, B1); PG8_BAR; PG8_SCHED;
;             } else {
;             PG8_LDB(B0, 0, 0); PG8_SCHED; PG8_LDA(At, 0, 0); PG8_STAGE(PG8_SA(1, 1), a1 + hstepA, voffA);
;             PG8_WAIT_L(8); PG8_BAR; PG8_WAIT_L(0); PG8_MMA(0, 0, At, B0); PG8_BAR; PG8_SCHED;
;             PG8_LDB(B1, 0, 1); PG8_STAGE(PG8_SB(0, 0), b2, voffB);
;             PG8_BAR; PG8_WAIT_L(0); PG8_MMA(0, 1, At, B1); PG8_BAR;
;             PG8_LDA(At, 0, 1); PG8_STAGE(PG8_SA(0, 0), a2, voffA);
;             PG8_BAR; PG8_WAIT_L(0); PG8_MMA(1, 0, At, B0); PG8_BAR; PG8_SCHED;
;             PG8_STAGE(PG8_SB(0, 1), b2 + hstepB, voffB);
;             PG8_WAIT_V(6); PG8_BAR; PG8_MMA(1, 1, At, B1); PG8_BAR;
;             PG8_LDB(B0, 1, 0); PG8_SCHED; PG8_LDA(At, 1, 0); PG8_STAGE(PG8_SA(0, 1), a2 + hstepA, voffA);
;             PG8_WAIT_L(8); PG8_BAR; PG8_WAIT_L(0); PG8_MMA(0, 0, At, B0); PG8_BAR; PG8_SCHED;
;             PG8_LDB(B1, 1, 1); PG8_STAGE(PG8_SB(1, 0), b3, voffB);
;             PG8_BAR; PG8_WAIT_L(0); PG8_MMA(0, 1, At, B1); PG8_BAR;
;             PG8_LDA(At, 1, 1); PG8_STAGE(PG8_SA(1, 0), a3, voffA);
;             PG8_BAR; PG8_WAIT_L(0); PG8_MMA(1, 0, At, B0); PG8_BAR; PG8_SCHED;
;             PG8_STAGE(PG8_SB(1, 1), b3 + hstepB, voffB);
;             PG8_WAIT_V(6); PG8_BAR; PG8_MMA(1, 1, At, B1); PG8_BAR;
;             }
;         }
;         if constexpr (ALIGN_EPI) { if (wr == 0) PG8_BAR; }
;         if constexpr (Epi::KHOOK || Epi::PREF) { if (has_next) E.prefetch(nxt, (ui + 1) & 1, lds, opaque_tid(wave_s)); }
;     __device__ __forceinline__ void prefetch(const Unit& u, int par, PG8_LAS unsigned char* lds, int tid) const {
;         PG8_LAS float* rp = (PG8_LAS float*)(lds + STAGE_BYTES + 5120) + par * 512;
;         if (tid < BM) rp[tid] = 1.0f / sqrtf(ssq_val(ssqx[u.pm * BM + tid]) * (1.0f / DM) + EPS);
;         else rp[tid] = shw[(size_t)((u.pm * BM) >> 12) * 7680 + u.pn * BM + (tid - BM)];
;     }
	s_setprio 1
	s_waitcnt lgkmcnt(0)
	v_mfma_f32_16x16x32_bf16 v[66:69], v[90:93], v[180:183], v[66:69]
	v_mfma_f32_16x16x32_bf16 v[62:65], v[102:105], v[180:183], v[62:65]
	v_mfma_f32_16x16x32_bf16 v[50:53], v[90:93], v[188:191], v[50:53]
	v_mfma_f32_16x16x32_bf16 v[46:49], v[102:105], v[188:191], v[46:49]
	v_mfma_f32_16x16x32_bf16 v[34:37], v[90:93], v[196:199], v[34:37]
	v_mfma_f32_16x16x32_bf16 v[30:33], v[102:105], v[196:199], v[30:33]
	v_mfma_f32_16x16x32_bf16 v[18:21], v[90:93], v[204:207], v[18:21]
	v_mfma_f32_16x16x32_bf16 v[10:13], v[102:105], v[204:207], v[10:13]
	v_mfma_f32_16x16x32_bf16 v[66:69], v[98:101], v[184:187], v[66:69]
	v_mfma_f32_16x16x32_bf16 v[62:65], v[106:109], v[184:187], v[62:65]
	v_mfma_f32_16x16x32_bf16 v[50:53], v[98:101], v[192:195], v[50:53]
	v_mfma_f32_16x16x32_bf16 v[46:49], v[106:109], v[192:195], v[46:49]
	v_mfma_f32_16x16x32_bf16 v[34:37], v[98:101], v[200:203], v[34:37]
	v_mfma_f32_16x16x32_bf16 v[30:33], v[106:109], v[200:203], v[30:33]
	v_mfma_f32_16x16x32_bf16 v[18:21], v[98:101], v[208:211], v[18:21]
	v_mfma_f32_16x16x32_bf16 v[10:13], v[106:109], v[208:211], v[10:13]
	s_setprio 0
	s_setprio 1
	v_mfma_f32_16x16x32_bf16 v[58:61], v[160:163], v[180:183], v[58:61]
	v_mfma_f32_16x16x32_bf16 v[54:57], v[172:175], v[180:183], v[54:57]
	v_mfma_f32_16x16x32_bf16 v[42:45], v[160:163], v[188:191], v[42:45]
	v_mfma_f32_16x16x32_bf16 v[38:41], v[172:175], v[188:191], v[38:41]
	v_mfma_f32_16x16x32_bf16 v[26:29], v[160:163], v[196:199], v[26:29]
	v_mfma_f32_16x16x32_bf16 v[22:25], v[172:175], v[196:199], v[22:25]
	v_mfma_f32_16x16x32_bf16 v[6:9], v[160:163], v[204:207], v[6:9]
	v_mfma_f32_16x16x32_bf16 v[2:5], v[172:175], v[204:207], v[2:5]
	v_mfma_f32_16x16x32_bf16 v[58:61], v[168:171], v[184:187], v[58:61]
	v_mfma_f32_16x16x32_bf16 v[54:57], v[176:179], v[184:187], v[54:57]
	v_mfma_f32_16x16x32_bf16 v[42:45], v[168:171], v[192:195], v[42:45]
	v_mfma_f32_16x16x32_bf16 v[38:41], v[176:179], v[192:195], v[38:41]
	v_mfma_f32_16x16x32_bf16 v[26:29], v[168:171], v[200:203], v[26:29]
	v_mfma_f32_16x16x32_bf16 v[22:25], v[176:179], v[200:203], v[22:25]
	v_mfma_f32_16x16x32_bf16 v[6:9], v[168:171], v[208:211], v[6:9]
	v_mfma_f32_16x16x32_bf16 v[2:5], v[176:179], v[208:211], v[2:5]
	s_setprio 0
	s_barrier
	s_add_i32 s56, s56, 2
	s_add_u32 s54, s54, 0x100
	s_addc_u32 s55, s55, 0
	s_add_u32 s6, s6, 0x100
	s_addc_u32 s7, s7, 0
	s_cmp_gt_u32 s56, 13
	s_cbranch_scc0 .LBB0_1165
	s_and_b64 vcc, exec, s[16:17]
	s_cbranch_vccz .LBB0_1168
	s_barrier
.LBB0_1168:
	v_cndmask_b32_e64 v0, 0, 1, s[8:9]
	v_cmp_ne_u32_e64 s[6:7], 1, v0
	s_andn2_b64 vcc, exec, s[8:9]
	s_cbranch_vccnz .LBB0_1174
	v_mbcnt_lo_u32_b32 v0, -1, 0
	v_mbcnt_hi_u32_b32 v0, -1, v0
	s_nop 0
	v_or_b32_e32 v0, s63, v0
	v_cmp_lt_i32_e32 vcc, s96, v0
	s_and_saveexec_b64 s[2:3], vcc
	s_xor_b64 s[2:3], exec, s[2:3]
	s_cbranch_execz .LBB0_1171
	s_ashr_i32 s8, s18, 4
	s_lshl_b32 s4, s20, 8
	s_ashr_i32 s5, s4, 31
	s_mul_hi_i32 s9, s8, 0x7800
	s_mulk_i32 s8, 0x7800
	s_add_u32 s8, s35, s8
	s_addc_u32 s9, s36, s9
	s_lshl_b64 s[4:5], s[4:5], 2
	s_add_u32 s4, s8, s4
	s_addc_u32 s5, s9, s5
	v_lshl_add_u64 v[90:91], v[0:1], 2, s[4:5]
	v_add_co_u32_e32 v90, vcc, 0xfffffc00, v90
	s_nop 1
	v_addc_co_u32_e32 v91, vcc, -1, v91, vcc
	flat_load_dword v90, v[90:91]
.LBB0_1171:
	s_andn2_saveexec_b64 s[4:5], s[2:3]
	s_cbranch_execz .LBB0_1173
	s_waitcnt vmcnt(0) lgkmcnt(0)
	v_lshl_add_u32 v90, s18, 8, v0
	v_ashrrev_i32_e32 v91, 31, v90
	v_lshl_add_u64 v[90:91], v[90:91], 3, s[10:11]
	flat_load_dwordx2 v[90:91], v[90:91]
	s_waitcnt vmcnt(0) lgkmcnt(0)
	v_ffbh_u32_e32 v92, v91
	v_min_u32_e32 v92, 32, v92
	v_lshlrev_b64 v[90:91], v92, v[90:91]
	v_min_u32_e32 v90, 1, v90
	v_or_b32_e32 v90, v91, v90
	v_cvt_f32_u32_e32 v90, v90
	v_sub_u32_e32 v91, 32, v92
	v_ldexp_f32 v90, v90, v91
	v_mul_f32_e32 v90, 0x33800000, v90
	v_fmamk_f32 v90, v90, 0x3a800000, v226
	v_mul_f32_e32 v91, 0x4f800000, v90
	v_cmp_gt_f32_e32 vcc, s71, v90
	s_nop 1
	v_cndmask_b32_e32 v90, v90, v91, vcc
	v_sqrt_f32_e32 v91, v90
	s_nop 0
	v_add_u32_e32 v92, -1, v91
	v_add_u32_e32 v93, 1, v91
	v_fma_f32 v98, -v92, v91, v90
	v_fma_f32 v99, -v93, v91, v90
	v_cmp_ge_f32_e64 s[8:9], 0, v98
	s_nop 1
	v_cndmask_b32_e64 v91, v91, v92, s[8:9]
	v_cmp_lt_f32_e64 s[8:9], 0, v99
	s_nop 1
	v_cndmask_b32_e64 v91, v91, v93, s[8:9]
	v_mul_f32_e32 v92, 0x37800000, v91
	v_cndmask_b32_e32 v91, v91, v92, vcc
	v_cmp_class_f32_e32 vcc, v90, v223
	s_nop 1
	v_cndmask_b32_e32 v90, v91, v90, vcc
	v_div_scale_f32 v91, s[2:3], v90, v90, 1.0
	v_rcp_f32_e32 v92, v91
	v_div_scale_f32 v93, vcc, 1.0, v90, 1.0
	v_fma_f32 v98, -v91, v92, 1.0
	v_fmac_f32_e32 v92, v98, v92
	v_mul_f32_e32 v98, v93, v92
	v_fma_f32 v99, -v91, v98, v93
	v_fmac_f32_e32 v98, v99, v92
	v_fma_f32 v91, -v91, v98, v93
	v_div_fmas_f32 v91, v91, v92, v98
	v_div_fixup_f32 v90, v91, v90, 1.0
.LBB0_1173:
	s_or_b64 exec, exec, s[4:5]
	s_lshl_b32 s2, s51, 11
	s_and_b32 s2, s2, 0x800
	s_add_i32 s2, s2, 0
	v_lshl_add_u32 v0, v0, 2, s2
	v_add_u32_e32 v0, 0x21400, v0
	s_waitcnt vmcnt(0) lgkmcnt(0)
	ds_write_b32 v0, v90
; #define PG8_LAS __attribute__((address_space(3)))
;     __device__ __forceinline__ void operator()(const f32x4 (&acc)[2][2][4][2], const Unit& u, int wr, int wc, int fr, int fq, int par, PG8_LAS unsigned char* lds) const {
;         const int row0 = u.pm * BM + wr * 64 + fr, col0 = u.pn * HALF + wc * 32 + 8 * fq;
;         const PG8_LAS float* rp = (const PG8_LAS float*)(lds + STAGE_BYTES + 5120) + par * 512;
;         const PG8_LAS float* sp = rp + 256 + wc * 32 + 8 * fq;
;         const f32x4 sg0 = *(const PG8_LAS f32x4*)sp, sg1 = *(const PG8_LAS f32x4*)(sp + 4), su0 = *(const PG8_LAS f32x4*)(sp + HALF), su1 = *(const PG8_LAS f32x4*)(sp + HALF + 4);
;         float rsv[8];
; #pragma unroll
;         for (int i = 0; i < 8; ++i) rsv[i] = rp[(i >> 2) * HALF + wr * 64 + (i & 3) * 16 + fr];
; #pragma unroll
;         for (int ai = 0; ai < 2; ++ai)
; #pragma unroll
;             for (int m = 0; m < 4; ++m) {
;                 const int row = row0 + ai * HALF + m * 16;
;                 const float rs = rsv[ai * 4 + m];
;                 const f32x4 g0 = acc[ai][0][m][0] * rs + sg0, g1 = acc[ai][0][m][1] * rs + sg1, u0 = acc[ai][1][m][0] * rs + su0, u1 = acc[ai][1][m][1] * rs + su1;
;                 f32x4 h0, h1;
;                 { const f32x2 a = swiglu_pk((f32x2){g0[0], g0[1]}, (f32x2){u0[0], u0[1]}), b2 = swiglu_pk((f32x2){g0[2], g0[3]}, (f32x2){u0[2], u0[3]});
;                   const f32x2 c = swiglu_pk((f32x2){g1[0], g1[1]}, (f32x2){u1[0], u1[1]}), d = swiglu_pk((f32x2){g1[2], g1[3]}, (f32x2){u1[2], u1[3]});
;                   h0 = (f32x4){a.x, a.y, b2.x, b2.y}; h1 = (f32x4){c.x, c.y, d.x, d.y}; }
.LBB0_1174:
	s_lshl_b32 s2, s28, 8
	v_mbcnt_lo_u32_b32 v0, -1, 0
	v_mbcnt_hi_u32_b32 v0, -1, v0
	s_add_i32 s2, s2, s47
	v_and_b32_e32 v160, 15, v0
	v_or_b32_e32 v167, s2, v160
	s_lshl_b32 s2, s52, 11
	s_and_b32 s2, s2, 0x800
	s_add_i32 s2, s2, 0
	v_lshrrev_b32_e32 v0, 1, v0
	s_add_i32 s2, s2, 0x21400
	s_lshl_b32 s3, s48, 2
	v_and_b32_e32 v0, 24, v0
	s_add_i32 s3, s2, s3
	v_lshl_add_u32 v90, v0, 2, s3
	s_lshl_b32 s3, s47, 2
	s_add_i32 s2, s2, s3
	v_lshl_add_u32 v160, v160, 2, s2
	ds_read_b128 v[106:109], v90 offset:1024
	ds_read_b128 v[102:105], v90 offset:1040
	ds_read_b128 v[98:101], v90 offset:1536
	ds_read_b128 v[90:93], v90 offset:1552
	ds_read2_b32 v[168:169], v160 offset1:16
	ds_read2_b32 v[164:165], v160 offset0:32 offset1:48
	ds_read2_b32 v[162:163], v160 offset0:128 offset1:144
	ds_read2_b32 v[160:161], v160 offset0:160 offset1:176
	s_lshl_b32 s2, s26, 7
	s_waitcnt lgkmcnt(0)
	v_pk_fma_f32 v[146:147], v[146:147], v[168:169], v[106:107] op_sel_hi:[1,0,1]
	v_pk_fma_f32 v[148:149], v[148:149], v[168:169], v[108:109] op_sel_hi:[1,0,1]
	v_pk_mul_f32 v[170:171], v[146:147], s[84:85] op_sel_hi:[1,0]
	v_pk_fma_f32 v[138:139], v[138:139], v[168:169], v[98:99] op_sel_hi:[1,0,1]
	v_exp_f32_e32 v170, v170
	v_exp_f32_e32 v171, v171
	v_pk_fma_f32 v[142:143], v[142:143], v[168:169], v[102:103] op_sel_hi:[1,0,1]
	v_pk_fma_f32 v[140:141], v[140:141], v[168:169], v[100:101] op_sel_hi:[1,0,1]
	v_pk_fma_f32 v[144:145], v[144:145], v[168:169], v[104:105] op_sel_hi:[1,0,1]
	v_pk_add_f32 v[170:171], v[170:171], 1.0 op_sel_hi:[1,0]
	v_pk_fma_f32 v[134:135], v[134:135], v[168:169], v[90:91] op_sel_hi:[1,0,1]
	v_rcp_f32_e32 v170, v170
	v_rcp_f32_e32 v171, v171
	s_or_b32 s2, s2, s48
	v_or_b32_e32 v0, s2, v0
	v_pk_fma_f32 v[136:137], v[136:137], v[168:169], v[92:93] op_sel_hi:[1,0,1]
	v_pk_mul_f32 v[146:147], v[146:147], v[170:171]
	s_movk_i32 s2, 0xb00
	v_pk_mul_f32 v[138:139], v[138:139], v[146:147]
	v_pk_mul_f32 v[146:147], v[148:149], s[84:85] op_sel_hi:[1,0]
	v_pk_fma_f32 v[114:115], v[114:115], v[164:165], v[106:107] op_sel_hi:[1,0,1]
	v_exp_f32_e32 v146, v146
	v_exp_f32_e32 v147, v147
	v_pk_fma_f32 v[116:117], v[116:117], v[164:165], v[108:109] op_sel_hi:[1,0,1]
	v_pk_fma_f32 v[94:95], v[94:95], v[164:165], v[98:99] op_sel_hi:[1,0,1]
	v_pk_fma_f32 v[110:111], v[110:111], v[164:165], v[102:103] op_sel_hi:[1,0,1]
	v_pk_add_f32 v[146:147], v[146:147], 1.0 op_sel_hi:[1,0]
	v_pk_fma_f32 v[96:97], v[96:97], v[164:165], v[100:101] op_sel_hi:[1,0,1]
	v_rcp_f32_e32 v146, v146
	v_rcp_f32_e32 v147, v147
	v_pk_fma_f32 v[112:113], v[112:113], v[164:165], v[104:105] op_sel_hi:[1,0,1]
	v_pk_fma_f32 v[86:87], v[86:87], v[164:165], v[90:91] op_sel_hi:[1,0,1]
	v_pk_fma_f32 v[88:89], v[88:89], v[164:165], v[92:93] op_sel_hi:[1,0,1]
	v_pk_mul_f32 v[146:147], v[148:149], v[146:147]
	v_pk_fma_f32 v[66:67], v[66:67], v[162:163], v[106:107] op_sel_hi:[1,0,1]
	v_pk_mul_f32 v[140:141], v[140:141], v[146:147]
	v_pk_mul_f32 v[146:147], v[142:143], s[84:85] op_sel_hi:[1,0]
	v_pk_fma_f32 v[68:69], v[68:69], v[162:163], v[108:109] op_sel_hi:[1,0,1]
	v_exp_f32_e32 v146, v146
	v_exp_f32_e32 v147, v147
	v_pk_fma_f32 v[58:59], v[58:59], v[162:163], v[98:99] op_sel_hi:[1,0,1]
	v_pk_fma_f32 v[62:63], v[62:63], v[162:163], v[102:103] op_sel_hi:[1,0,1]
	v_pk_fma_f32 v[60:61], v[60:61], v[162:163], v[100:101] op_sel_hi:[1,0,1]
	v_pk_add_f32 v[146:147], v[146:147], 1.0 op_sel_hi:[1,0]
	v_pk_fma_f32 v[64:65], v[64:65], v[162:163], v[104:105] op_sel_hi:[1,0,1]
	v_rcp_f32_e32 v146, v146
	v_rcp_f32_e32 v147, v147
	v_pk_fma_f32 v[54:55], v[54:55], v[162:163], v[90:91] op_sel_hi:[1,0,1]
	v_pk_fma_f32 v[56:57], v[56:57], v[162:163], v[92:93] op_sel_hi:[1,0,1]
	v_pk_fma_f32 v[34:35], v[34:35], v[160:161], v[106:107] op_sel_hi:[1,0,1]
	v_pk_mul_f32 v[142:143], v[142:143], v[146:147]
	v_pk_fma_f32 v[36:37], v[36:37], v[160:161], v[108:109] op_sel_hi:[1,0,1]
	v_pk_mul_f32 v[142:143], v[134:135], v[142:143]
	v_pk_mul_f32 v[134:135], v[144:145], s[84:85] op_sel_hi:[1,0]
	v_pk_fma_f32 v[26:27], v[26:27], v[160:161], v[98:99] op_sel_hi:[1,0,1]
	v_exp_f32_e32 v134, v134
	v_exp_f32_e32 v135, v135
	v_pk_fma_f32 v[30:31], v[30:31], v[160:161], v[102:103] op_sel_hi:[1,0,1]
	v_pk_fma_f32 v[28:29], v[28:29], v[160:161], v[100:101] op_sel_hi:[1,0,1]
	v_pk_fma_f32 v[32:33], v[32:33], v[160:161], v[104:105] op_sel_hi:[1,0,1]
	v_pk_add_f32 v[134:135], v[134:135], 1.0 op_sel_hi:[1,0]
	v_pk_fma_f32 v[22:23], v[22:23], v[160:161], v[90:91] op_sel_hi:[1,0,1]
	v_rcp_f32_e32 v134, v134
	v_rcp_f32_e32 v135, v135
	v_pk_fma_f32 v[24:25], v[24:25], v[160:161], v[92:93] op_sel_hi:[1,0,1]
	s_and_b64 vcc, exec, s[6:7]
	v_pk_mul_f32 v[134:135], v[144:145], v[134:135]
	s_nop 0
	v_pk_mul_f32 v[144:145], v[136:137], v[134:135]
	v_cvt_pk_bf16_f32 v134, v138, v139
	v_mul_lo_u32 v138, v167, s2
	v_add_lshl_u32 v0, v0, v138, 1
	v_cvt_pk_bf16_f32 v135, v140, v141
	v_cvt_pk_bf16_f32 v136, v142, v143
	v_cvt_pk_bf16_f32 v137, v144, v145
	global_store_dwordx4 v0, v[134:137], s[14:15]
	s_mov_b64 s[2:3], -1
	s_nop 0
	v_mov_b32_e32 v134, v169
	v_pk_fma_f32 v[130:131], v[130:131], v[134:135], v[106:107] op_sel_hi:[1,0,1]
	v_pk_fma_f32 v[132:133], v[132:133], v[134:135], v[108:109] op_sel_hi:[1,0,1]
	v_pk_fma_f32 v[128:129], v[128:129], v[134:135], v[104:105] op_sel_hi:[1,0,1]
	v_pk_fma_f32 v[126:127], v[126:127], v[134:135], v[102:103] op_sel_hi:[1,0,1]
	v_pk_fma_f32 v[124:125], v[124:125], v[134:135], v[100:101] op_sel_hi:[1,0,1]
	v_pk_fma_f32 v[122:123], v[122:123], v[134:135], v[98:99] op_sel_hi:[1,0,1]
	v_pk_fma_f32 v[120:121], v[120:121], v[134:135], v[92:93] op_sel_hi:[1,0,1]
	v_pk_fma_f32 v[118:119], v[118:119], v[134:135], v[90:91] op_sel_hi:[1,0,1]
; __device__ __forceinline__ unsigned cvt_pk_bf16(float lo, float hi) { unsigned r; asm volatile("v_cvt_pk_bf16_f32 %0, %1, %2" : "=v"(r) : "v"(lo), "v"(hi)); return r; }
; #define PG8_GPTR(p) ((__attribute__((address_space(1))) char*)(p))
;     __device__ __forceinline__ void operator()(const f32x4 (&acc)[2][2][4][2], const Unit& u, int wr, int wc, int fr, int fq, int par, PG8_LAS unsigned char* lds) const {
;     ...
; #pragma unroll
;         for (int ai = 0; ai < 2; ++ai)
; #pragma unroll
;             for (int m = 0; m < 4; ++m) {
;                 const int row = row0 + ai * HALF + m * 16;
;                 const float rs = rsv[ai * 4 + m];
;                 const f32x4 g0 = acc[ai][0][m][0] * rs + sg0, g1 = acc[ai][0][m][1] * rs + sg1, u0 = acc[ai][1][m][0] * rs + su0, u1 = acc[ai][1][m][1] * rs + su1;
;                 f32x4 h0, h1;
;                 { const f32x2 a = swiglu_pk((f32x2){g0[0], g0[1]}, (f32x2){u0[0], u0[1]}), b2 = swiglu_pk((f32x2){g0[2], g0[3]}, (f32x2){u0[2], u0[3]});
;                   const f32x2 c = swiglu_pk((f32x2){g1[0], g1[1]}, (f32x2){u1[0], u1[1]}), d = swiglu_pk((f32x2){g1[2], g1[3]}, (f32x2){u1[2], u1[3]});
;                   h0 = (f32x4){a.x, a.y, b2.x, b2.y}; h1 = (f32x4){c.x, c.y, d.x, d.y}; }
;                 u32x4 w; w.x = cvt_pk_bf16(h0[0], h0[1]); w.y = cvt_pk_bf16(h0[2], h0[3]); w.z = cvt_pk_bf16(h1[0], h1[1]); w.w = cvt_pk_bf16(h1[2], h1[3]);
;                 *(gs_u32x4*)(PG8_GPTR(O) + (unsigned)(row * FFN + col0) * 2u) = w;
;             }
	v_pk_mul_f32 v[134:135], v[130:131], s[84:85] op_sel_hi:[1,0]
	s_nop 0
	v_exp_f32_e32 v134, v134
	v_exp_f32_e32 v135, v135
	s_nop 0
	v_pk_add_f32 v[134:135], v[134:135], 1.0 op_sel_hi:[1,0]
	s_nop 0
	v_rcp_f32_e32 v134, v134
	v_rcp_f32_e32 v135, v135
	s_nop 0
	v_pk_mul_f32 v[130:131], v[130:131], v[134:135]
	s_nop 0
	v_pk_mul_f32 v[122:123], v[122:123], v[130:131]
	v_pk_mul_f32 v[130:131], v[132:133], s[84:85] op_sel_hi:[1,0]
	s_nop 0
	v_exp_f32_e32 v130, v130
	v_exp_f32_e32 v131, v131
	s_nop 0
	v_pk_add_f32 v[130:131], v[130:131], 1.0 op_sel_hi:[1,0]
	s_nop 0
	v_rcp_f32_e32 v130, v130
	v_rcp_f32_e32 v131, v131
	s_nop 0
	v_pk_mul_f32 v[130:131], v[132:133], v[130:131]
	s_nop 0
	v_pk_mul_f32 v[124:125], v[124:125], v[130:131]
	v_pk_mul_f32 v[130:131], v[126:127], s[84:85] op_sel_hi:[1,0]
	s_nop 0
	v_exp_f32_e32 v130, v130
	v_exp_f32_e32 v131, v131
	s_nop 0
	v_pk_add_f32 v[130:131], v[130:131], 1.0 op_sel_hi:[1,0]
	s_nop 0
	v_rcp_f32_e32 v130, v130
	v_rcp_f32_e32 v131, v131
	s_nop 0
	v_pk_mul_f32 v[126:127], v[126:127], v[130:131]
	s_nop 0
	v_pk_mul_f32 v[126:127], v[118:119], v[126:127]
	v_pk_mul_f32 v[118:119], v[128:129], s[84:85] op_sel_hi:[1,0]
	s_nop 0
	v_exp_f32_e32 v118, v118
	v_exp_f32_e32 v119, v119
	s_nop 0
	v_pk_add_f32 v[118:119], v[118:119], 1.0 op_sel_hi:[1,0]
	s_nop 0
	v_rcp_f32_e32 v118, v118
	v_rcp_f32_e32 v119, v119
	s_nop 0
	v_pk_mul_f32 v[118:119], v[128:129], v[118:119]
	s_nop 0
	v_pk_mul_f32 v[128:129], v[120:121], v[118:119]
	v_cvt_pk_bf16_f32 v118, v122, v123
	v_cvt_pk_bf16_f32 v119, v124, v125
	v_add_u32_e32 v122, 0x16000, v0
	v_cvt_pk_bf16_f32 v120, v126, v127
	v_cvt_pk_bf16_f32 v121, v128, v129
	global_store_dwordx4 v122, v[118:121], s[14:15]
	s_nop 1
	v_pk_mul_f32 v[118:119], v[114:115], s[84:85] op_sel_hi:[1,0]
	s_nop 0
	v_exp_f32_e32 v118, v118
	v_exp_f32_e32 v119, v119
	s_nop 0
	v_pk_add_f32 v[118:119], v[118:119], 1.0 op_sel_hi:[1,0]
	s_nop 0
	v_rcp_f32_e32 v118, v118
	v_rcp_f32_e32 v119, v119
	s_nop 0
	v_pk_mul_f32 v[114:115], v[114:115], v[118:119]
	s_nop 0
	v_pk_mul_f32 v[94:95], v[94:95], v[114:115]
	v_pk_mul_f32 v[114:115], v[116:117], s[84:85] op_sel_hi:[1,0]
	s_nop 0
	v_exp_f32_e32 v114, v114
	v_exp_f32_e32 v115, v115
	s_nop 0
	v_pk_add_f32 v[114:115], v[114:115], 1.0 op_sel_hi:[1,0]
	s_nop 0
	v_rcp_f32_e32 v114, v114
	v_rcp_f32_e32 v115, v115
	s_nop 0
	v_pk_mul_f32 v[114:115], v[116:117], v[114:115]
	s_nop 0
	v_pk_mul_f32 v[96:97], v[96:97], v[114:115]
	v_pk_mul_f32 v[114:115], v[110:111], s[84:85] op_sel_hi:[1,0]
	s_nop 0
	v_exp_f32_e32 v114, v114
	v_exp_f32_e32 v115, v115
	s_nop 0
	v_pk_add_f32 v[114:115], v[114:115], 1.0 op_sel_hi:[1,0]
	s_nop 0
	v_rcp_f32_e32 v114, v114
	v_rcp_f32_e32 v115, v115
	s_nop 0
	v_pk_mul_f32 v[110:111], v[110:111], v[114:115]
	s_nop 0
	v_pk_mul_f32 v[110:111], v[86:87], v[110:111]
	v_pk_mul_f32 v[86:87], v[112:113], s[84:85] op_sel_hi:[1,0]
	s_nop 0
	v_exp_f32_e32 v86, v86
	v_exp_f32_e32 v87, v87
	s_nop 0
	v_pk_add_f32 v[86:87], v[86:87], 1.0 op_sel_hi:[1,0]
	s_nop 0
	v_rcp_f32_e32 v86, v86
	v_rcp_f32_e32 v87, v87
	s_nop 0
	v_pk_mul_f32 v[86:87], v[112:113], v[86:87]
	s_nop 0
	v_pk_mul_f32 v[112:113], v[88:89], v[86:87]
	v_cvt_pk_bf16_f32 v86, v94, v95
	v_add_u32_e32 v94, 0x2c000, v0
	v_cvt_pk_bf16_f32 v87, v96, v97
	v_cvt_pk_bf16_f32 v88, v110, v111
	v_cvt_pk_bf16_f32 v89, v112, v113
	global_store_dwordx4 v94, v[86:89], s[14:15]
	s_nop 1
	v_mov_b32_e32 v86, v165
	v_pk_fma_f32 v[82:83], v[82:83], v[86:87], v[106:107] op_sel_hi:[1,0,1]
	v_pk_fma_f32 v[84:85], v[84:85], v[86:87], v[108:109] op_sel_hi:[1,0,1]
	v_pk_fma_f32 v[80:81], v[80:81], v[86:87], v[104:105] op_sel_hi:[1,0,1]
	v_pk_fma_f32 v[78:79], v[78:79], v[86:87], v[102:103] op_sel_hi:[1,0,1]
	v_pk_fma_f32 v[76:77], v[76:77], v[86:87], v[100:101] op_sel_hi:[1,0,1]
	v_pk_fma_f32 v[74:75], v[74:75], v[86:87], v[98:99] op_sel_hi:[1,0,1]
	v_pk_fma_f32 v[72:73], v[72:73], v[86:87], v[92:93] op_sel_hi:[1,0,1]
	v_pk_fma_f32 v[70:71], v[70:71], v[86:87], v[90:91] op_sel_hi:[1,0,1]
	v_pk_mul_f32 v[86:87], v[82:83], s[84:85] op_sel_hi:[1,0]
	s_nop 0
	v_exp_f32_e32 v86, v86
	v_exp_f32_e32 v87, v87
	s_nop 0
	v_pk_add_f32 v[86:87], v[86:87], 1.0 op_sel_hi:[1,0]
	s_nop 0
	v_rcp_f32_e32 v86, v86
	v_rcp_f32_e32 v87, v87
	s_nop 0
	v_pk_mul_f32 v[82:83], v[82:83], v[86:87]
	s_nop 0
	v_pk_mul_f32 v[74:75], v[74:75], v[82:83]
	v_pk_mul_f32 v[82:83], v[84:85], s[84:85] op_sel_hi:[1,0]
	s_nop 0
	v_exp_f32_e32 v82, v82
	v_exp_f32_e32 v83, v83
	s_nop 0
	v_pk_add_f32 v[82:83], v[82:83], 1.0 op_sel_hi:[1,0]
	s_nop 0
	v_rcp_f32_e32 v82, v82
	v_rcp_f32_e32 v83, v83
	s_nop 0
	v_pk_mul_f32 v[82:83], v[84:85], v[82:83]
	s_nop 0
	v_pk_mul_f32 v[76:77], v[76:77], v[82:83]
	v_pk_mul_f32 v[82:83], v[78:79], s[84:85] op_sel_hi:[1,0]
	s_nop 0
	v_exp_f32_e32 v82, v82
	v_exp_f32_e32 v83, v83
	s_nop 0
	v_pk_add_f32 v[82:83], v[82:83], 1.0 op_sel_hi:[1,0]
	s_nop 0
	v_rcp_f32_e32 v82, v82
	v_rcp_f32_e32 v83, v83
	s_nop 0
	v_pk_mul_f32 v[78:79], v[78:79], v[82:83]
	s_nop 0
	v_pk_mul_f32 v[78:79], v[70:71], v[78:79]
	v_pk_mul_f32 v[70:71], v[80:81], s[84:85] op_sel_hi:[1,0]
	s_nop 0
	v_exp_f32_e32 v70, v70
	v_exp_f32_e32 v71, v71
	s_nop 0
	v_pk_add_f32 v[70:71], v[70:71], 1.0 op_sel_hi:[1,0]
	s_nop 0
	v_rcp_f32_e32 v70, v70
	v_rcp_f32_e32 v71, v71
	s_nop 0
	v_pk_mul_f32 v[70:71], v[80:81], v[70:71]
	s_nop 0
	v_pk_mul_f32 v[80:81], v[72:73], v[70:71]
	v_cvt_pk_bf16_f32 v70, v74, v75
	v_cvt_pk_bf16_f32 v71, v76, v77
	v_add_u32_e32 v74, 0x42000, v0
	v_cvt_pk_bf16_f32 v72, v78, v79
	v_cvt_pk_bf16_f32 v73, v80, v81
	global_store_dwordx4 v74, v[70:73], s[14:15]
	s_nop 1
	v_pk_mul_f32 v[70:71], v[66:67], s[84:85] op_sel_hi:[1,0]
	s_nop 0
	v_exp_f32_e32 v70, v70
; __device__ __forceinline__ unsigned cvt_pk_bf16(float lo, float hi) { unsigned r; asm volatile("v_cvt_pk_bf16_f32 %0, %1, %2" : "=v"(r) : "v"(lo), "v"(hi)); return r; }
; #define PG8_GPTR(p) ((__attribute__((address_space(1))) char*)(p))
;     __device__ __forceinline__ void operator()(const f32x4 (&acc)[2][2][4][2], const Unit& u, int wr, int wc, int fr, int fq, int par, PG8_LAS unsigned char* lds) const {
;     ...
; #pragma unroll
;         for (int ai = 0; ai < 2; ++ai)
; #pragma unroll
;             for (int m = 0; m < 4; ++m) {
;                 const int row = row0 + ai * HALF + m * 16;
;                 const float rs = rsv[ai * 4 + m];
;                 const f32x4 g0 = acc[ai][0][m][0] * rs + sg0, g1 = acc[ai][0][m][1] * rs + sg1, u0 = acc[ai][1][m][0] * rs + su0, u1 = acc[ai][1][m][1] * rs + su1;
;                 f32x4 h0, h1;
;                 { const f32x2 a = swiglu_pk((f32x2){g0[0], g0[1]}, (f32x2){u0[0], u0[1]}), b2 = swiglu_pk((f32x2){g0[2], g0[3]}, (f32x2){u0[2], u0[3]});
;                   const f32x2 c = swiglu_pk((f32x2){g1[0], g1[1]}, (f32x2){u1[0], u1[1]}), d = swiglu_pk((f32x2){g1[2], g1[3]}, (f32x2){u1[2], u1[3]});
;                   h0 = (f32x4){a.x, a.y, b2.x, b2.y}; h1 = (f32x4){c.x, c.y, d.x, d.y}; }
;                 u32x4 w; w.x = cvt_pk_bf16(h0[0], h0[1]); w.y = cvt_pk_bf16(h0[2], h0[3]); w.z = cvt_pk_bf16(h1[0], h1[1]); w.w = cvt_pk_bf16(h1[2], h1[3]);
;                 *(gs_u32x4*)(PG8_GPTR(O) + (unsigned)(row * FFN + col0) * 2u) = w;
;             }
	v_exp_f32_e32 v71, v71
	s_nop 0
	v_pk_add_f32 v[70:71], v[70:71], 1.0 op_sel_hi:[1,0]
	s_nop 0
	v_rcp_f32_e32 v70, v70
	v_rcp_f32_e32 v71, v71
	s_nop 0
	v_pk_mul_f32 v[66:67], v[66:67], v[70:71]
	s_nop 0
	v_pk_mul_f32 v[58:59], v[58:59], v[66:67]
	v_pk_mul_f32 v[66:67], v[68:69], s[84:85] op_sel_hi:[1,0]
	s_nop 0
	v_exp_f32_e32 v66, v66
	v_exp_f32_e32 v67, v67
	s_nop 0
	v_pk_add_f32 v[66:67], v[66:67], 1.0 op_sel_hi:[1,0]
	s_nop 0
	v_rcp_f32_e32 v66, v66
	v_rcp_f32_e32 v67, v67
	s_nop 0
	v_pk_mul_f32 v[66:67], v[68:69], v[66:67]
	s_nop 0
	v_pk_mul_f32 v[60:61], v[60:61], v[66:67]
	v_pk_mul_f32 v[66:67], v[62:63], s[84:85] op_sel_hi:[1,0]
	s_nop 0
	v_exp_f32_e32 v66, v66
	v_exp_f32_e32 v67, v67
	s_nop 0
	v_pk_add_f32 v[66:67], v[66:67], 1.0 op_sel_hi:[1,0]
	s_nop 0
	v_rcp_f32_e32 v66, v66
	v_rcp_f32_e32 v67, v67
	s_nop 0
	v_pk_mul_f32 v[62:63], v[62:63], v[66:67]
	s_nop 0
	v_pk_mul_f32 v[62:63], v[54:55], v[62:63]
	v_pk_mul_f32 v[54:55], v[64:65], s[84:85] op_sel_hi:[1,0]
	s_nop 0
	v_exp_f32_e32 v54, v54
	v_exp_f32_e32 v55, v55
	s_nop 0
	v_pk_add_f32 v[54:55], v[54:55], 1.0 op_sel_hi:[1,0]
	s_nop 0
	v_rcp_f32_e32 v54, v54
	v_rcp_f32_e32 v55, v55
	s_nop 0
	v_pk_mul_f32 v[54:55], v[64:65], v[54:55]
	s_nop 0
	v_pk_mul_f32 v[64:65], v[56:57], v[54:55]
	v_cvt_pk_bf16_f32 v54, v58, v59
	v_add_u32_e32 v58, 0xb0000, v0
	v_cvt_pk_bf16_f32 v55, v60, v61
	v_cvt_pk_bf16_f32 v56, v62, v63
	v_cvt_pk_bf16_f32 v57, v64, v65
	global_store_dwordx4 v58, v[54:57], s[14:15]
	s_nop 1
	v_mov_b32_e32 v54, v163
	v_pk_fma_f32 v[50:51], v[50:51], v[54:55], v[106:107] op_sel_hi:[1,0,1]
	v_pk_fma_f32 v[52:53], v[52:53], v[54:55], v[108:109] op_sel_hi:[1,0,1]
	v_pk_fma_f32 v[48:49], v[48:49], v[54:55], v[104:105] op_sel_hi:[1,0,1]
	v_pk_fma_f32 v[46:47], v[46:47], v[54:55], v[102:103] op_sel_hi:[1,0,1]
	v_pk_fma_f32 v[44:45], v[44:45], v[54:55], v[100:101] op_sel_hi:[1,0,1]
	v_pk_fma_f32 v[42:43], v[42:43], v[54:55], v[98:99] op_sel_hi:[1,0,1]
	v_pk_fma_f32 v[40:41], v[40:41], v[54:55], v[92:93] op_sel_hi:[1,0,1]
	v_pk_fma_f32 v[38:39], v[38:39], v[54:55], v[90:91] op_sel_hi:[1,0,1]
	v_pk_mul_f32 v[54:55], v[50:51], s[84:85] op_sel_hi:[1,0]
	s_nop 0
	v_exp_f32_e32 v54, v54
	v_exp_f32_e32 v55, v55
	s_nop 0
	v_pk_add_f32 v[54:55], v[54:55], 1.0 op_sel_hi:[1,0]
	s_nop 0
	v_rcp_f32_e32 v54, v54
	v_rcp_f32_e32 v55, v55
	s_nop 0
	v_pk_mul_f32 v[50:51], v[50:51], v[54:55]
	s_nop 0
	v_pk_mul_f32 v[42:43], v[42:43], v[50:51]
	v_pk_mul_f32 v[50:51], v[52:53], s[84:85] op_sel_hi:[1,0]
	s_nop 0
	v_exp_f32_e32 v50, v50
	v_exp_f32_e32 v51, v51
	s_nop 0
	v_pk_add_f32 v[50:51], v[50:51], 1.0 op_sel_hi:[1,0]
	s_nop 0
	v_rcp_f32_e32 v50, v50
	v_rcp_f32_e32 v51, v51
	s_nop 0
	v_pk_mul_f32 v[50:51], v[52:53], v[50:51]
	s_nop 0
	v_pk_mul_f32 v[44:45], v[44:45], v[50:51]
	v_pk_mul_f32 v[50:51], v[46:47], s[84:85] op_sel_hi:[1,0]
	s_nop 0
	v_exp_f32_e32 v50, v50
	v_exp_f32_e32 v51, v51
	s_nop 0
	v_pk_add_f32 v[50:51], v[50:51], 1.0 op_sel_hi:[1,0]
	s_nop 0
	v_rcp_f32_e32 v50, v50
	v_rcp_f32_e32 v51, v51
	s_nop 0
	v_pk_mul_f32 v[46:47], v[46:47], v[50:51]
	s_nop 0
	v_pk_mul_f32 v[46:47], v[38:39], v[46:47]
	v_pk_mul_f32 v[38:39], v[48:49], s[84:85] op_sel_hi:[1,0]
	s_nop 0
	v_exp_f32_e32 v38, v38
	v_exp_f32_e32 v39, v39
	s_nop 0
	v_pk_add_f32 v[38:39], v[38:39], 1.0 op_sel_hi:[1,0]
	s_nop 0
	v_rcp_f32_e32 v38, v38
	v_rcp_f32_e32 v39, v39
	s_nop 0
	v_pk_mul_f32 v[38:39], v[48:49], v[38:39]
	s_nop 0
	v_pk_mul_f32 v[48:49], v[40:41], v[38:39]
	v_cvt_pk_bf16_f32 v38, v42, v43
	v_cvt_pk_bf16_f32 v39, v44, v45
	v_add_u32_e32 v42, 0xc6000, v0
	v_cvt_pk_bf16_f32 v40, v46, v47
	v_cvt_pk_bf16_f32 v41, v48, v49
	global_store_dwordx4 v42, v[38:41], s[14:15]
	s_nop 1
	v_pk_mul_f32 v[38:39], v[34:35], s[84:85] op_sel_hi:[1,0]
	s_nop 0
; __device__ __forceinline__ unsigned cvt_pk_bf16(float lo, float hi) { unsigned r; asm volatile("v_cvt_pk_bf16_f32 %0, %1, %2" : "=v"(r) : "v"(lo), "v"(hi)); return r; }
; #define PG8_BAR __builtin_amdgcn_s_barrier()
; #define PG8_GPTR(p) ((__attribute__((address_space(1))) char*)(p))
; template <class Epi, class Sched, bool ALIGN_EPI = false, bool SP2 = false>
; __device__ __forceinline__ void gemm_phase(PG8_LAS unsigned char* lds, const Gemm g, const Sched& S, const Epi& E, const int wave_s) {
;     ...
;         if (!has_next) break;
; #pragma unroll
;         for (int a = 0; a < 2; ++a)
; #pragma unroll
;             for (int b = 0; b < 2; ++b)
; #pragma unroll
;                 for (int m = 0; m < 4; ++m)
; #pragma unroll
;                     for (int n = 0; n < 2; ++n) acc[a][b][m][n] = (f32x4){0.f, 0.f, 0.f, 0.f};
;         cur = nxt; cA = nA; cB = nB; ++ui;
;         if constexpr (ALIGN_EPI) { if (wr == 1) PG8_BAR; }
;     }
;     __device__ __forceinline__ void operator()(const f32x4 (&acc)[2][2][4][2], const Unit& u, int wr, int wc, int fr, int fq, int par, PG8_LAS unsigned char* lds) const {
;     ...
; #pragma unroll
;         for (int ai = 0; ai < 2; ++ai)
; #pragma unroll
;             for (int m = 0; m < 4; ++m) {
;                 const int row = row0 + ai * HALF + m * 16;
;                 const float rs = rsv[ai * 4 + m];
;                 const f32x4 g0 = acc[ai][0][m][0] * rs + sg0, g1 = acc[ai][0][m][1] * rs + sg1, u0 = acc[ai][1][m][0] * rs + su0, u1 = acc[ai][1][m][1] * rs + su1;
;                 f32x4 h0, h1;
;                 { const f32x2 a = swiglu_pk((f32x2){g0[0], g0[1]}, (f32x2){u0[0], u0[1]}), b2 = swiglu_pk((f32x2){g0[2], g0[3]}, (f32x2){u0[2], u0[3]});
;                   const f32x2 c = swiglu_pk((f32x2){g1[0], g1[1]}, (f32x2){u1[0], u1[1]}), d = swiglu_pk((f32x2){g1[2], g1[3]}, (f32x2){u1[2], u1[3]});
;                   h0 = (f32x4){a.x, a.y, b2.x, b2.y}; h1 = (f32x4){c.x, c.y, d.x, d.y}; }
;                 u32x4 w; w.x = cvt_pk_bf16(h0[0], h0[1]); w.y = cvt_pk_bf16(h0[2], h0[3]); w.z = cvt_pk_bf16(h1[0], h1[1]); w.w = cvt_pk_bf16(h1[2], h1[3]);
;                 *(gs_u32x4*)(PG8_GPTR(O) + (unsigned)(row * FFN + col0) * 2u) = w;
;             }
	v_exp_f32_e32 v38, v38
	v_exp_f32_e32 v39, v39
	s_nop 0
	v_pk_add_f32 v[38:39], v[38:39], 1.0 op_sel_hi:[1,0]
	s_nop 0
	v_rcp_f32_e32 v38, v38
	v_rcp_f32_e32 v39, v39
	s_nop 0
	v_pk_mul_f32 v[34:35], v[34:35], v[38:39]
	s_nop 0
	v_pk_mul_f32 v[26:27], v[26:27], v[34:35]
	v_pk_mul_f32 v[34:35], v[36:37], s[84:85] op_sel_hi:[1,0]
	s_nop 0
	v_exp_f32_e32 v34, v34
	v_exp_f32_e32 v35, v35
	s_nop 0
	v_pk_add_f32 v[34:35], v[34:35], 1.0 op_sel_hi:[1,0]
	s_nop 0
	v_rcp_f32_e32 v34, v34
	v_rcp_f32_e32 v35, v35
	s_nop 0
	v_pk_mul_f32 v[34:35], v[36:37], v[34:35]
	s_nop 0
	v_pk_mul_f32 v[28:29], v[28:29], v[34:35]
	v_pk_mul_f32 v[34:35], v[30:31], s[84:85] op_sel_hi:[1,0]
	s_nop 0
	v_exp_f32_e32 v34, v34
	v_exp_f32_e32 v35, v35
	s_nop 0
	v_pk_add_f32 v[34:35], v[34:35], 1.0 op_sel_hi:[1,0]
	s_nop 0
	v_rcp_f32_e32 v34, v34
	v_rcp_f32_e32 v35, v35
	s_nop 0
	v_pk_mul_f32 v[30:31], v[30:31], v[34:35]
	s_nop 0
	v_pk_mul_f32 v[30:31], v[22:23], v[30:31]
	v_pk_mul_f32 v[22:23], v[32:33], s[84:85] op_sel_hi:[1,0]
	s_nop 0
	v_exp_f32_e32 v22, v22
	v_exp_f32_e32 v23, v23
	s_nop 0
	v_pk_add_f32 v[22:23], v[22:23], 1.0 op_sel_hi:[1,0]
	s_nop 0
	v_rcp_f32_e32 v22, v22
	v_rcp_f32_e32 v23, v23
	s_nop 0
	v_pk_mul_f32 v[22:23], v[32:33], v[22:23]
	s_nop 0
	v_pk_mul_f32 v[32:33], v[24:25], v[22:23]
	v_cvt_pk_bf16_f32 v22, v26, v27
	v_add_u32_e32 v26, 0xdc000, v0
	v_cvt_pk_bf16_f32 v23, v28, v29
	v_cvt_pk_bf16_f32 v24, v30, v31
	v_cvt_pk_bf16_f32 v25, v32, v33
	global_store_dwordx4 v26, v[22:25], s[14:15]
	v_add_u32_e32 v0, 0xf2000, v0
	s_nop 0
	v_mov_b32_e32 v22, v161
	v_pk_fma_f32 v[18:19], v[18:19], v[22:23], v[106:107] op_sel_hi:[1,0,1]
	v_pk_fma_f32 v[20:21], v[20:21], v[22:23], v[108:109] op_sel_hi:[1,0,1]
	v_pk_fma_f32 v[12:13], v[12:13], v[22:23], v[104:105] op_sel_hi:[1,0,1]
	v_pk_fma_f32 v[10:11], v[10:11], v[22:23], v[102:103] op_sel_hi:[1,0,1]
	v_pk_fma_f32 v[8:9], v[8:9], v[22:23], v[100:101] op_sel_hi:[1,0,1]
	v_pk_fma_f32 v[6:7], v[6:7], v[22:23], v[98:99] op_sel_hi:[1,0,1]
	v_pk_fma_f32 v[4:5], v[4:5], v[22:23], v[92:93] op_sel_hi:[1,0,1]
	v_pk_fma_f32 v[2:3], v[2:3], v[22:23], v[90:91] op_sel_hi:[1,0,1]
	v_pk_mul_f32 v[22:23], v[18:19], s[84:85] op_sel_hi:[1,0]
	s_nop 0
	v_exp_f32_e32 v22, v22
	v_exp_f32_e32 v23, v23
	s_nop 0
	v_pk_add_f32 v[22:23], v[22:23], 1.0 op_sel_hi:[1,0]
	s_nop 0
	v_rcp_f32_e32 v22, v22
	v_rcp_f32_e32 v23, v23
	s_nop 0
	v_pk_mul_f32 v[18:19], v[18:19], v[22:23]
	s_nop 0
	v_pk_mul_f32 v[6:7], v[6:7], v[18:19]
	v_pk_mul_f32 v[18:19], v[20:21], s[84:85] op_sel_hi:[1,0]
	s_nop 0
	v_exp_f32_e32 v18, v18
	v_exp_f32_e32 v19, v19
	s_nop 0
	v_pk_add_f32 v[18:19], v[18:19], 1.0 op_sel_hi:[1,0]
	s_nop 0
	v_rcp_f32_e32 v18, v18
	v_rcp_f32_e32 v19, v19
	s_nop 0
	v_pk_mul_f32 v[18:19], v[20:21], v[18:19]
	s_nop 0
	v_pk_mul_f32 v[8:9], v[8:9], v[18:19]
	v_pk_mul_f32 v[18:19], v[10:11], s[84:85] op_sel_hi:[1,0]
	s_nop 0
	v_exp_f32_e32 v18, v18
	v_exp_f32_e32 v19, v19
	s_nop 0
	v_pk_add_f32 v[18:19], v[18:19], 1.0 op_sel_hi:[1,0]
	s_nop 0
	v_rcp_f32_e32 v18, v18
	v_rcp_f32_e32 v19, v19
	s_nop 0
	v_pk_mul_f32 v[10:11], v[10:11], v[18:19]
	s_nop 0
	v_pk_mul_f32 v[10:11], v[2:3], v[10:11]
	v_pk_mul_f32 v[2:3], v[12:13], s[84:85] op_sel_hi:[1,0]
	s_nop 0
	v_exp_f32_e32 v2, v2
	v_exp_f32_e32 v3, v3
	s_nop 0
	v_pk_add_f32 v[2:3], v[2:3], 1.0 op_sel_hi:[1,0]
	s_nop 0
	v_rcp_f32_e32 v2, v2
	v_rcp_f32_e32 v3, v3
	s_nop 0
	v_pk_mul_f32 v[2:3], v[12:13], v[2:3]
	s_nop 0
	v_pk_mul_f32 v[12:13], v[4:5], v[2:3]
	v_cvt_pk_bf16_f32 v2, v6, v7
	v_cvt_pk_bf16_f32 v3, v8, v9
	v_cvt_pk_bf16_f32 v4, v10, v11
	s_nop 0
	v_cvt_pk_bf16_f32 v5, v12, v13
	global_store_dwordx4 v0, v[2:5], s[14:15]
	s_cbranch_vccnz .LBB0_1161
	s_andn2_b64 vcc, exec, s[12:13]
	s_cbranch_vccnz .LBB0_1160
	s_barrier
	s_branch .LBB0_1160

; #define PG8_GCPTR(p) ((__attribute__((address_space(1))) const char*)(p))
;     __device__ __forceinline__ void operator()(const f32x4 (&acc)[2][2][4][2], const Unit& u, int wr, int wc, int fr, int fq) const {
;     ...
;         const int col0 = u.pn * BM + wc * 32 + 8 * fq; const int b = (u.pm * BM) >> 12;
;         const float* gp = gate + (size_t)b * NMOD + col0; const float* sp = sc + (size_t)b * NMOD + col0;
;         f32x4 g[2][2], cf[2][2];
; #pragma unroll
;         for (int bj = 0; bj < 2; ++bj) {
;             g[bj][0] = *(const f32x4*)(gp + bj * HALF); g[bj][1] = *(const f32x4*)(gp + bj * HALF + 4);
;             const f32x4 n0 = *(const f32x4*)(nw + col0 + bj * HALF), n1 = *(const f32x4*)(nw + col0 + bj * HALF + 4);
;             const f32x4 c0 = *(const f32x4*)(sp + bj * HALF), c1 = *(const f32x4*)(sp + bj * HALF + 4);
;             cf[bj][0] = n0 * (c0 + 1.0f); cf[bj][1] = n1 * (c1 + 1.0f);
;         }
; #pragma unroll
;         for (int ai = 0; ai < 2; ++ai)
; #pragma unroll
;         for (int mp = 0; mp < 4; mp += 2) {
;             u32x4 bv[2][2];
; #pragma unroll
;             for (int mm = 0; mm < 2; ++mm)
; #pragma unroll
;                 for (int bj = 0; bj < 2; ++bj)
;                     bv[mm][bj] = *(gl_u32x4*)(PG8_GCPTR(base) + (unsigned)((u.pm * BM + ai * HALF + wr * 64 + (mp + mm) * 16 + fr) * DM + col0 + bj * HALF) * 2u);
; #pragma unroll
;             for (int mm = 0; mm < 2; ++mm) {
;                 const int m = mp + mm;
;                 const int row = u.pm * BM + ai * HALF + wr * 64 + m * 16 + fr; float q = 0.f;
; #pragma unroll
;                 for (int bj = 0; bj < 2; ++bj) {
;                     const unsigned offb = (unsigned)(row * DM + col0 + bj * HALF) * 2u;
;                     const u32x4 bw = bv[mm][bj];
;                     const f32x4 b0 = (f32x4){__uint_as_float(bw.x << 16), __uint_as_float(bw.x & 0xffff0000u), __uint_as_float(bw.y << 16), __uint_as_float(bw.y & 0xffff0000u)};
;                     const f32x4 b1 = (f32x4){__uint_as_float(bw.z << 16), __uint_as_float(bw.z & 0xffff0000u), __uint_as_float(bw.w << 16), __uint_as_float(bw.w & 0xffff0000u)};
;                     f32x4 a0 = acc[ai][bj][m][0], a1 = acc[ai][bj][m][1]; if constexpr (GN) { a0 *= rc[ai * 4 + m]; a1 *= rc[ai * 4 + m]; }
;                     const f32x4 o0 = b0 + g[bj][0] * a0, o1 = b1 + g[bj][1] * a1;
.LBB0_1246:
	v_mbcnt_lo_u32_b32 v0, -1, 0
	v_mbcnt_hi_u32_b32 v0, -1, v0
	s_lshl_b32 s2, s88, 8
	v_bfe_u32 v205, v0, 4, 2
	v_and_b32_e32 v219, 15, v0
	v_lshl_or_b32 v0, v205, 3, s2
	s_ashr_i32 s2, s87, 4
	v_or_b32_e32 v174, s51, v0
	s_mul_i32 s5, s2, 0x6000
	s_mul_hi_i32 s4, s2, 0x6000
	s_add_u32 s2, s67, s5
	v_ashrrev_i32_e32 v175, 31, v174
	s_addc_u32 s3, s73, s4
	v_lshlrev_b64 v[62:63], 2, v[174:175]
	v_lshl_add_u64 v[158:159], s[2:3], 0, v[62:63]
	s_add_u32 s2, s48, s5
	s_addc_u32 s3, s49, s4
	v_lshl_add_u64 v[162:163], s[2:3], 0, v[62:63]
	v_lshl_add_u64 v[164:165], s[18:19], 0, v[62:63]
	flat_load_dwordx4 v[74:77], v[158:159]
	flat_load_dwordx4 v[70:73], v[158:159] offset:16
	global_load_dwordx4 v[62:65], v[164:165], off offset:16
	global_load_dwordx4 v[66:69], v[164:165], off
	flat_load_dwordx4 v[150:153], v[162:163]
	flat_load_dwordx4 v[154:157], v[162:163] offset:16
	s_lshl_b32 s2, s87, 8
	s_add_i32 s2, s2, s50
	v_or_b32_e32 v204, s2, v219
	v_lshlrev_b32_e32 v217, 1, v174
	v_lshlrev_b32_e32 v218, 11, v204
	v_add_u32_e32 v0, v217, v218
	v_and_b32_e32 v240, 0xffff8000, v0
	v_bfe_u32 v241, v0, 11, 4
	v_lshl_or_b32 v240, v241, 6, v240
	v_bfe_u32 v241, v0, 9, 2
	v_lshl_or_b32 v240, v241, 13, v240
	v_bfe_u32 v241, v0, 6, 2
	v_lshl_or_b32 v240, v241, 11, v240
	v_and_b32_e32 v241, 48, v0
	v_or_b32_e32 v240, v240, v241
	s_andn2_b64 vcc, exec, s[26:27]
	v_lshl_add_u64 v[214:215], s[12:13], 0, v[0:1]
	s_waitcnt vmcnt(0) lgkmcnt(0)
	v_pk_add_f32 v[152:153], v[152:153], 1.0 op_sel_hi:[1,0]
	v_pk_add_f32 v[150:151], v[150:151], 1.0 op_sel_hi:[1,0]
	v_pk_mul_f32 v[210:211], v[68:69], v[152:153]
	v_pk_mul_f32 v[212:213], v[66:67], v[150:151]
	v_pk_add_f32 v[66:67], v[156:157], 1.0 op_sel_hi:[1,0]
	v_pk_add_f32 v[68:69], v[154:155], 1.0 op_sel_hi:[1,0]
	v_pk_mul_f32 v[206:207], v[64:65], v[66:67]
	v_pk_mul_f32 v[208:209], v[62:63], v[68:69]
	flat_load_dwordx4 v[66:69], v[158:159] offset:512
	flat_load_dwordx4 v[62:65], v[158:159] offset:528
	s_nop 0
	global_load_dwordx4 v[158:161], v[164:165], off offset:528
	global_load_dwordx4 v[166:169], v[164:165], off offset:512
	flat_load_dwordx4 v[170:173], v[162:163] offset:512
	s_nop 0
	flat_load_dwordx4 v[162:165], v[162:163] offset:528
	s_nop 0
	global_load_dwordx4 v[178:181], v240, s[20:21]
	global_load_dwordx4 v[174:177], v240, s[20:21] offset:1024
	v_add_u32_e32 v150, 0x8000, v240
	global_load_dwordx4 v[154:157], v150, s[20:21]
	s_nop 0
	global_load_dwordx4 v[150:153], v150, s[20:21] offset:1024
	s_waitcnt vmcnt(0)
	v_lshlrev_b32_e32 v182, 16, v178
	v_and_b32_e32 v183, 0xffff0000, v178
	v_lshlrev_b32_e32 v178, 16, v179
	v_and_b32_e32 v179, 0xffff0000, v179
	v_lshlrev_b32_e32 v184, 16, v180
	v_and_b32_e32 v185, 0xffff0000, v180
	v_lshlrev_b32_e32 v180, 16, v181
	v_and_b32_e32 v181, 0xffff0000, v181
	v_pk_fma_f32 v[148:149], v[148:149], v[76:77], v[178:179]
	v_pk_fma_f32 v[146:147], v[146:147], v[74:75], v[182:183]
	v_pk_fma_f32 v[144:145], v[144:145], v[72:73], v[180:181]
	v_cvt_pk_bf16_f32 v178, v146, v147
	v_pk_fma_f32 v[142:143], v[142:143], v[70:71], v[184:185]
	v_cvt_pk_bf16_f32 v179, v148, v149
	s_nop 0
	v_cvt_pk_bf16_f32 v180, v142, v143
	v_cvt_pk_bf16_f32 v181, v144, v145
	global_store_dwordx4 v240, v[178:181], s[22:23]
	s_nop 1
	v_cndmask_b32_e64 v178, 0, 1, s[26:27]
	v_cmp_ne_u32_e64 s[8:9], 1, v178
	s_cbranch_vccnz .LBB0_1248
	v_pk_mul_f32 v[178:179], v[212:213], v[146:147]
	v_pk_mul_f32 v[180:181], v[210:211], v[148:149]
	v_cvt_pk_bf16_f32 v178, v178, v179
	v_pk_mul_f32 v[148:149], v[148:149], v[148:149]
	v_cvt_pk_bf16_f32 v179, v180, v181
	v_pk_mul_f32 v[146:147], v[146:147], v[146:147]
	v_pk_mul_f32 v[182:183], v[206:207], v[144:145]
	v_pk_mul_f32 v[184:185], v[208:209], v[142:143]
	v_pk_mul_f32 v[144:145], v[144:145], v[144:145]
	v_cvt_pk_bf16_f32 v180, v184, v185
	v_cvt_pk_bf16_f32 v181, v182, v183
	global_store_dwordx4 v[214:215], v[178:181], off
	v_pk_mul_f32 v[142:143], v[142:143], v[142:143]
	s_nop 0
	v_mov_b32_e32 v178, v146
	v_mov_b32_e32 v179, v149
	v_pk_mov_b32 v[146:147], v[146:147], v[148:149] op_sel:[1,0]
	v_mov_b32_e32 v148, v144
	v_pk_add_f32 v[146:147], v[146:147], v[178:179]
	v_mov_b32_e32 v149, v142
	v_mov_b32_e32 v142, v145
	v_pk_add_f32 v[142:143], v[148:149], v[142:143]
	v_add_f32_e32 v144, v146, v147
	v_add_f32_e32 v143, v143, v144
	v_add_f32_e32 v227, v142, v143
	s_branch .LBB0_1249

; __device__ __forceinline__ unsigned cvt_pk_bf16(float lo, float hi) { unsigned r; asm volatile("v_cvt_pk_bf16_f32 %0, %1, %2" : "=v"(r) : "v"(lo), "v"(hi)); return r; }
; #define PG8_GPTR(p) ((__attribute__((address_space(1))) char*)(p))
;     __device__ __forceinline__ void operator()(const f32x4 (&acc)[2][2][4][2], const Unit& u, int wr, int wc, int fr, int fq) const {
;     ...
; #pragma unroll
;             for (int mm = 0; mm < 2; ++mm) {
;                 const int m = mp + mm;
;                 const int row = u.pm * BM + ai * HALF + wr * 64 + m * 16 + fr; float q = 0.f;
; #pragma unroll
;                 for (int bj = 0; bj < 2; ++bj) {
;                     const unsigned offb = (unsigned)(row * DM + col0 + bj * HALF) * 2u;
;                     const u32x4 bw = bv[mm][bj];
;                     const f32x4 b0 = (f32x4){__uint_as_float(bw.x << 16), __uint_as_float(bw.x & 0xffff0000u), __uint_as_float(bw.y << 16), __uint_as_float(bw.y & 0xffff0000u)};
;                     const f32x4 b1 = (f32x4){__uint_as_float(bw.z << 16), __uint_as_float(bw.z & 0xffff0000u), __uint_as_float(bw.w << 16), __uint_as_float(bw.w & 0xffff0000u)};
;                     f32x4 a0 = acc[ai][bj][m][0], a1 = acc[ai][bj][m][1]; if constexpr (GN) { a0 *= rc[ai * 4 + m]; a1 *= rc[ai * 4 + m]; }
;                     const f32x4 o0 = b0 + g[bj][0] * a0, o1 = b1 + g[bj][1] * a1;
;                     u32x4 wo; wo.x = cvt_pk_bf16(o0[0], o0[1]); wo.y = cvt_pk_bf16(o0[2], o0[3]); wo.z = cvt_pk_bf16(o1[0], o1[1]); wo.w = cvt_pk_bf16(o1[2], o1[3]);
;                     *(gs_u32x4*)(PG8_GPTR(out) + offb) = wo;
;                     if (xg) {
;                         const f32x4 h0 = o0 * cf[bj][0], h1 = o1 * cf[bj][1];
;                         u32x4 w; w.x = cvt_pk_bf16(h0[0], h0[1]); w.y = cvt_pk_bf16(h0[2], h0[3]); w.z = cvt_pk_bf16(h1[0], h1[1]); w.w = cvt_pk_bf16(h1[2], h1[3]);
;                         *(gs_u32x4*)(PG8_GPTR(xg) + offb) = w;
;                         q += (o0[0] * o0[0] + o0[1] * o0[1]) + (o0[2] * o0[2] + o0[3] * o0[3]) + (o1[0] * o1[0] + o1[1] * o1[1]) + (o1[2] * o1[2] + o1[3] * o1[3]);
;                     }
;                 }
;                 if (xg) ssq_put(ssq, row, q, fr, fq);
.LBB0_1249:
	s_waitcnt lgkmcnt(0)
	v_pk_add_f32 v[142:143], v[172:173], 1.0 op_sel_hi:[1,0]
	v_pk_add_f32 v[144:145], v[170:171], 1.0 op_sel_hi:[1,0]
	v_pk_mul_f32 v[148:149], v[168:169], v[142:143]
	v_pk_mul_f32 v[142:143], v[166:167], v[144:145]
	v_pk_add_f32 v[144:145], v[164:165], 1.0 op_sel_hi:[1,0]
	v_pk_add_f32 v[146:147], v[162:163], 1.0 op_sel_hi:[1,0]
	v_pk_mul_f32 v[144:145], v[160:161], v[144:145]
	v_pk_mul_f32 v[146:147], v[158:159], v[146:147]
	v_lshlrev_b32_e32 v158, 6, v205
	v_lshlrev_b32_e32 v160, 2, v219
	s_movk_i32 s2, 0x80
	v_bitop3_b32 v159, v158, 64, v160 bitop3:0x36
	v_bitop3_b32 v158, v158, s2, v160 bitop3:0x36
	v_lshlrev_b32_e32 v160, 16, v174
	v_and_b32_e32 v161, 0xffff0000, v174
	v_lshlrev_b32_e32 v162, 16, v175
	v_and_b32_e32 v163, 0xffff0000, v175
	v_lshlrev_b32_e32 v164, 16, v176
	v_and_b32_e32 v165, 0xffff0000, v176
	v_lshlrev_b32_e32 v166, 16, v177
	v_and_b32_e32 v167, 0xffff0000, v177
	v_lshl_add_u64 v[178:179], s[22:23], 0, v[0:1]
	v_cmp_eq_u32_e64 s[10:11], 0, v205
	v_pk_fma_f32 v[140:141], v[140:141], v[68:69], v[162:163]
	v_pk_fma_f32 v[138:139], v[138:139], v[66:67], v[160:161]
	v_pk_fma_f32 v[136:137], v[136:137], v[64:65], v[166:167]
	v_pk_fma_f32 v[134:135], v[134:135], v[62:63], v[164:165]
	s_and_b64 vcc, exec, s[8:9]
	v_cvt_pk_bf16_f32 v160, v138, v139
	v_cvt_pk_bf16_f32 v161, v140, v141
	v_cvt_pk_bf16_f32 v162, v134, v135
	v_cvt_pk_bf16_f32 v163, v136, v137
	global_store_dwordx4 v240, v[160:163], s[22:23] offset:1024
	s_cbranch_vccnz .LBB0_1253
	s_nop 0
	v_pk_mul_f32 v[160:161], v[148:149], v[140:141]
	v_mul_f32_e32 v164, v139, v139
	v_mul_f32_e32 v141, v141, v141
	v_mul_f32_e32 v163, v135, v135
	v_fmac_f32_e32 v164, v138, v138
	v_fmac_f32_e32 v141, v140, v140
	v_mul_f32_e32 v162, v137, v137
	v_fmac_f32_e32 v163, v134, v134
	v_add_f32_e32 v140, v164, v141
	v_fmac_f32_e32 v162, v136, v136
	v_add_f32_e32 v140, v163, v140
	v_add_f32_e32 v140, v162, v140
	v_add_f32_e32 v164, v140, v227
	ds_bpermute_b32 v165, v159, v164
	v_pk_mul_f32 v[162:163], v[146:147], v[134:135]
	v_pk_mul_f32 v[138:139], v[142:143], v[138:139]
	v_pk_mul_f32 v[140:141], v[144:145], v[136:137]
	v_cvt_pk_bf16_f32 v136, v138, v139
	s_waitcnt lgkmcnt(0)
	v_add_f32_e32 v134, v164, v165
	ds_bpermute_b32 v135, v158, v134
	v_cvt_pk_bf16_f32 v137, v160, v161
	v_cvt_pk_bf16_f32 v138, v162, v163
	v_cvt_pk_bf16_f32 v139, v140, v141
	global_store_dwordx4 v[214:215], v[136:139], off offset:256
	s_and_saveexec_b64 s[2:3], s[10:11]
	s_cbranch_execz .LBB0_1252
	s_waitcnt lgkmcnt(0)
	v_add_f32_e32 v134, v134, v135
	v_mul_f32_e32 v134, 0x4b800000, v134
	v_trunc_f32_e32 v134, v134
	v_mul_f32_e32 v135, 0x2f800000, v134
	v_floor_f32_e32 v135, v135
	v_fmac_f32_e32 v134, 0xcf800000, v135
	v_cvt_u32_f32_e32 v134, v134
	v_cvt_u32_f32_e32 v135, v135
	v_ashrrev_i32_e32 v205, 31, v204
	v_lshl_add_u64 v[136:137], v[204:205], 3, s[16:17]
	flat_atomic_add_x2 v[136:137], v[134:135]

; __device__ __forceinline__ unsigned cvt_pk_bf16(float lo, float hi) { unsigned r; asm volatile("v_cvt_pk_bf16_f32 %0, %1, %2" : "=v"(r) : "v"(lo), "v"(hi)); return r; }
; #define PG8_GPTR(p) ((__attribute__((address_space(1))) char*)(p))
;     __device__ __forceinline__ void operator()(const f32x4 (&acc)[2][2][4][2], const Unit& u, int wr, int wc, int fr, int fq) const {
;     ...
; #pragma unroll
;             for (int mm = 0; mm < 2; ++mm) {
;                 const int m = mp + mm;
;                 const int row = u.pm * BM + ai * HALF + wr * 64 + m * 16 + fr; float q = 0.f;
; #pragma unroll
;                 for (int bj = 0; bj < 2; ++bj) {
;                     const unsigned offb = (unsigned)(row * DM + col0 + bj * HALF) * 2u;
;                     const u32x4 bw = bv[mm][bj];
;                     const f32x4 b0 = (f32x4){__uint_as_float(bw.x << 16), __uint_as_float(bw.x & 0xffff0000u), __uint_as_float(bw.y << 16), __uint_as_float(bw.y & 0xffff0000u)};
;                     const f32x4 b1 = (f32x4){__uint_as_float(bw.z << 16), __uint_as_float(bw.z & 0xffff0000u), __uint_as_float(bw.w << 16), __uint_as_float(bw.w & 0xffff0000u)};
;                     f32x4 a0 = acc[ai][bj][m][0], a1 = acc[ai][bj][m][1]; if constexpr (GN) { a0 *= rc[ai * 4 + m]; a1 *= rc[ai * 4 + m]; }
;                     const f32x4 o0 = b0 + g[bj][0] * a0, o1 = b1 + g[bj][1] * a1;
;                     u32x4 wo; wo.x = cvt_pk_bf16(o0[0], o0[1]); wo.y = cvt_pk_bf16(o0[2], o0[3]); wo.z = cvt_pk_bf16(o1[0], o1[1]); wo.w = cvt_pk_bf16(o1[2], o1[3]);
;                     *(gs_u32x4*)(PG8_GPTR(out) + offb) = wo;
;                     if (xg) {
;                         const f32x4 h0 = o0 * cf[bj][0], h1 = o1 * cf[bj][1];
;                         u32x4 w; w.x = cvt_pk_bf16(h0[0], h0[1]); w.y = cvt_pk_bf16(h0[2], h0[3]); w.z = cvt_pk_bf16(h1[0], h1[1]); w.w = cvt_pk_bf16(h1[2], h1[3]);
;                         *(gs_u32x4*)(PG8_GPTR(xg) + offb) = w;
;                         q += (o0[0] * o0[0] + o0[1] * o0[1]) + (o0[2] * o0[2] + o0[3] * o0[3]) + (o1[0] * o1[0] + o1[1] * o1[1]) + (o1[2] * o1[2] + o1[3] * o1[3]);
;                     }
;                 }
;                 if (xg) ssq_put(ssq, row, q, fr, fq);
.LBB0_1253:
	s_mov_b32 s2, 0x8000
	v_add3_u32 v134, v217, v218, s2
	v_add_u32_e32 v241, s2, v240
	v_lshlrev_b32_e32 v136, 16, v154
	v_and_b32_e32 v137, 0xffff0000, v154
	v_lshlrev_b32_e32 v138, 16, v155
	v_and_b32_e32 v139, 0xffff0000, v155
	v_lshlrev_b32_e32 v140, 16, v156
	v_and_b32_e32 v141, 0xffff0000, v156
	v_lshlrev_b32_e32 v154, 16, v157
	v_and_b32_e32 v155, 0xffff0000, v157
	s_waitcnt lgkmcnt(0)
	v_mov_b32_e32 v135, v1
	v_pk_fma_f32 v[132:133], v[132:133], v[76:77], v[138:139]
	v_pk_fma_f32 v[130:131], v[130:131], v[74:75], v[136:137]
	v_pk_fma_f32 v[128:129], v[128:129], v[72:73], v[154:155]
	v_pk_fma_f32 v[136:137], v[126:127], v[70:71], v[140:141]
	s_and_b64 vcc, exec, s[8:9]
	v_lshl_add_u64 v[126:127], s[12:13], 0, v[134:135]
	v_cvt_pk_bf16_f32 v138, v130, v131
	v_cvt_pk_bf16_f32 v139, v132, v133
	v_cvt_pk_bf16_f32 v140, v136, v137
	v_cvt_pk_bf16_f32 v141, v128, v129
	global_store_dwordx4 v241, v[138:141], s[22:23]
	s_cbranch_vccnz .LBB0_1255
	s_nop 0
	v_pk_mul_f32 v[138:139], v[212:213], v[130:131]
	v_pk_mul_f32 v[140:141], v[210:211], v[132:133]
	v_cvt_pk_bf16_f32 v138, v138, v139
	v_pk_mul_f32 v[132:133], v[132:133], v[132:133]
	v_cvt_pk_bf16_f32 v139, v140, v141
	v_pk_mul_f32 v[130:131], v[130:131], v[130:131]
	v_pk_mul_f32 v[154:155], v[206:207], v[128:129]
	v_pk_mul_f32 v[156:157], v[208:209], v[136:137]
	v_pk_mul_f32 v[128:129], v[128:129], v[128:129]
	v_cvt_pk_bf16_f32 v140, v156, v157
	v_cvt_pk_bf16_f32 v141, v154, v155
	global_store_dwordx4 v[126:127], v[138:141], off
	s_nop 1
	v_mov_b32_e32 v138, v130
	v_mov_b32_e32 v139, v133
	v_pk_mov_b32 v[130:131], v[130:131], v[132:133] op_sel:[1,0]
	v_pk_mul_f32 v[132:133], v[136:137], v[136:137]
	v_pk_add_f32 v[130:131], v[130:131], v[138:139]
	v_mov_b32_e32 v136, v128
	v_mov_b32_e32 v137, v132
	v_mov_b32_e32 v132, v129
	v_pk_add_f32 v[128:129], v[136:137], v[132:133]
	v_add_f32_e32 v130, v130, v131
	v_add_f32_e32 v129, v129, v130
	v_add_f32_e32 v128, v128, v129
	s_branch .LBB0_1256

; __device__ __forceinline__ unsigned cvt_pk_bf16(float lo, float hi) { unsigned r; asm volatile("v_cvt_pk_bf16_f32 %0, %1, %2" : "=v"(r) : "v"(lo), "v"(hi)); return r; }
; #define PG8_GPTR(p) ((__attribute__((address_space(1))) char*)(p))
;     __device__ __forceinline__ void operator()(const f32x4 (&acc)[2][2][4][2], const Unit& u, int wr, int wc, int fr, int fq) const {
;     ...
; #pragma unroll
;             for (int mm = 0; mm < 2; ++mm) {
;                 const int m = mp + mm;
;                 const int row = u.pm * BM + ai * HALF + wr * 64 + m * 16 + fr; float q = 0.f;
; #pragma unroll
;                 for (int bj = 0; bj < 2; ++bj) {
;                     const unsigned offb = (unsigned)(row * DM + col0 + bj * HALF) * 2u;
;                     const u32x4 bw = bv[mm][bj];
;                     const f32x4 b0 = (f32x4){__uint_as_float(bw.x << 16), __uint_as_float(bw.x & 0xffff0000u), __uint_as_float(bw.y << 16), __uint_as_float(bw.y & 0xffff0000u)};
;                     const f32x4 b1 = (f32x4){__uint_as_float(bw.z << 16), __uint_as_float(bw.z & 0xffff0000u), __uint_as_float(bw.w << 16), __uint_as_float(bw.w & 0xffff0000u)};
;                     f32x4 a0 = acc[ai][bj][m][0], a1 = acc[ai][bj][m][1]; if constexpr (GN) { a0 *= rc[ai * 4 + m]; a1 *= rc[ai * 4 + m]; }
;                     const f32x4 o0 = b0 + g[bj][0] * a0, o1 = b1 + g[bj][1] * a1;
;                     u32x4 wo; wo.x = cvt_pk_bf16(o0[0], o0[1]); wo.y = cvt_pk_bf16(o0[2], o0[3]); wo.z = cvt_pk_bf16(o1[0], o1[1]); wo.w = cvt_pk_bf16(o1[2], o1[3]);
;                     *(gs_u32x4*)(PG8_GPTR(out) + offb) = wo;
;                     if (xg) {
;                         const f32x4 h0 = o0 * cf[bj][0], h1 = o1 * cf[bj][1];
;                         u32x4 w; w.x = cvt_pk_bf16(h0[0], h0[1]); w.y = cvt_pk_bf16(h0[2], h0[3]); w.z = cvt_pk_bf16(h1[0], h1[1]); w.w = cvt_pk_bf16(h1[2], h1[3]);
;                         *(gs_u32x4*)(PG8_GPTR(xg) + offb) = w;
;                         q += (o0[0] * o0[0] + o0[1] * o0[1]) + (o0[2] * o0[2] + o0[3] * o0[3]) + (o1[0] * o1[0] + o1[1] * o1[1]) + (o1[2] * o1[2] + o1[3] * o1[3]);
;                     }
;                 }
;                 if (xg) ssq_put(ssq, row, q, fr, fq);
.LBB0_1256:
	v_lshlrev_b32_e32 v130, 16, v150
	v_and_b32_e32 v131, 0xffff0000, v150
	v_lshlrev_b32_e32 v132, 16, v151
	v_and_b32_e32 v133, 0xffff0000, v151
	v_lshlrev_b32_e32 v136, 16, v152
	v_and_b32_e32 v137, 0xffff0000, v152
	v_lshlrev_b32_e32 v138, 16, v153
	v_and_b32_e32 v139, 0xffff0000, v153
	v_lshl_add_u64 v[134:135], s[22:23], 0, v[134:135]
	v_pk_fma_f32 v[124:125], v[124:125], v[68:69], v[132:133]
	v_pk_fma_f32 v[122:123], v[122:123], v[66:67], v[130:131]
	v_pk_fma_f32 v[120:121], v[120:121], v[64:65], v[138:139]
	v_pk_fma_f32 v[118:119], v[118:119], v[62:63], v[136:137]
	s_and_b64 vcc, exec, s[8:9]
	v_cvt_pk_bf16_f32 v130, v122, v123
	v_cvt_pk_bf16_f32 v131, v124, v125
	v_cvt_pk_bf16_f32 v132, v118, v119
	v_cvt_pk_bf16_f32 v133, v120, v121
	global_store_dwordx4 v241, v[130:133], s[22:23] offset:1024
	s_cbranch_vccnz .LBB0_1260
	s_nop 0
	v_pk_mul_f32 v[130:131], v[148:149], v[124:125]
	v_mul_f32_e32 v133, v123, v123
	v_mul_f32_e32 v125, v125, v125
	v_mul_f32_e32 v132, v119, v119
	v_fmac_f32_e32 v133, v122, v122
	v_fmac_f32_e32 v125, v124, v124
	v_mul_f32_e32 v129, v121, v121
	v_fmac_f32_e32 v132, v118, v118
	v_add_f32_e32 v124, v133, v125
	v_fmac_f32_e32 v129, v120, v120
	v_add_f32_e32 v124, v132, v124
	v_add_f32_e32 v124, v129, v124
	v_add_f32_e32 v132, v124, v128
	ds_bpermute_b32 v133, v159, v132
	v_pk_mul_f32 v[128:129], v[146:147], v[118:119]
	v_pk_mul_f32 v[122:123], v[142:143], v[122:123]
	v_pk_mul_f32 v[124:125], v[144:145], v[120:121]
	v_cvt_pk_bf16_f32 v120, v122, v123
	s_waitcnt lgkmcnt(0)
	v_add_f32_e32 v118, v132, v133
	ds_bpermute_b32 v119, v158, v118
	v_cvt_pk_bf16_f32 v121, v130, v131
	v_cvt_pk_bf16_f32 v122, v128, v129
	v_cvt_pk_bf16_f32 v123, v124, v125
	global_store_dwordx4 v[126:127], v[120:123], off offset:256
	s_and_saveexec_b64 s[2:3], s[10:11]
	s_cbranch_execz .LBB0_1259
	s_waitcnt lgkmcnt(0)
	v_add_f32_e32 v118, v118, v119
	v_mul_f32_e32 v118, 0x4b800000, v118
	v_trunc_f32_e32 v118, v118
	v_mul_f32_e32 v119, 0x2f800000, v118
	v_floor_f32_e32 v119, v119
	v_fmac_f32_e32 v118, 0xcf800000, v119
	v_cvt_u32_f32_e32 v118, v118
	v_cvt_u32_f32_e32 v119, v119
	v_ashrrev_i32_e32 v205, 31, v204
	v_lshl_add_u64 v[120:121], v[204:205], 3, s[16:17]
	flat_atomic_add_x2 v[120:121], v[118:119] offset:128

; __device__ __forceinline__ unsigned cvt_pk_bf16(float lo, float hi) { unsigned r; asm volatile("v_cvt_pk_bf16_f32 %0, %1, %2" : "=v"(r) : "v"(lo), "v"(hi)); return r; }
; #define PG8_GPTR(p) ((__attribute__((address_space(1))) char*)(p))
;     __device__ __forceinline__ void operator()(const f32x4 (&acc)[2][2][4][2], const Unit& u, int wr, int wc, int fr, int fq) const {
;     ...
; #pragma unroll
;             for (int mm = 0; mm < 2; ++mm) {
;                 const int m = mp + mm;
;                 const int row = u.pm * BM + ai * HALF + wr * 64 + m * 16 + fr; float q = 0.f;
; #pragma unroll
;                 for (int bj = 0; bj < 2; ++bj) {
;                     const unsigned offb = (unsigned)(row * DM + col0 + bj * HALF) * 2u;
;                     const u32x4 bw = bv[mm][bj];
;                     const f32x4 b0 = (f32x4){__uint_as_float(bw.x << 16), __uint_as_float(bw.x & 0xffff0000u), __uint_as_float(bw.y << 16), __uint_as_float(bw.y & 0xffff0000u)};
;                     const f32x4 b1 = (f32x4){__uint_as_float(bw.z << 16), __uint_as_float(bw.z & 0xffff0000u), __uint_as_float(bw.w << 16), __uint_as_float(bw.w & 0xffff0000u)};
;                     f32x4 a0 = acc[ai][bj][m][0], a1 = acc[ai][bj][m][1]; if constexpr (GN) { a0 *= rc[ai * 4 + m]; a1 *= rc[ai * 4 + m]; }
;                     const f32x4 o0 = b0 + g[bj][0] * a0, o1 = b1 + g[bj][1] * a1;
;                     u32x4 wo; wo.x = cvt_pk_bf16(o0[0], o0[1]); wo.y = cvt_pk_bf16(o0[2], o0[3]); wo.z = cvt_pk_bf16(o1[0], o1[1]); wo.w = cvt_pk_bf16(o1[2], o1[3]);
;                     *(gs_u32x4*)(PG8_GPTR(out) + offb) = wo;
;                     if (xg) {
;                         const f32x4 h0 = o0 * cf[bj][0], h1 = o1 * cf[bj][1];
;                         u32x4 w; w.x = cvt_pk_bf16(h0[0], h0[1]); w.y = cvt_pk_bf16(h0[2], h0[3]); w.z = cvt_pk_bf16(h1[0], h1[1]); w.w = cvt_pk_bf16(h1[2], h1[3]);
;                         *(gs_u32x4*)(PG8_GPTR(xg) + offb) = w;
;                         q += (o0[0] * o0[0] + o0[1] * o0[1]) + (o0[2] * o0[2] + o0[3] * o0[3]) + (o1[0] * o1[0] + o1[1] * o1[1]) + (o1[2] * o1[2] + o1[3] * o1[3]);
;                     }
;                 }
;                 if (xg) ssq_put(ssq, row, q, fr, fq);
.LBB0_1260:
	v_add_u32_e32 v118, 0x10000, v240
	global_load_dwordx4 v[132:135], v118, s[20:21]
	global_load_dwordx4 v[126:129], v118, s[20:21] offset:1024
	v_add_u32_e32 v118, 0x18000, v240
	global_load_dwordx4 v[122:125], v118, s[20:21]
	s_waitcnt lgkmcnt(0)
	global_load_dwordx4 v[118:121], v118, s[20:21] offset:1024
	s_mov_b32 s2, 0x10000
	v_add3_u32 v130, v217, v218, s2
	v_add_u32_e32 v241, s2, v240
	v_mov_b32_e32 v131, v1
	s_and_b64 vcc, exec, s[8:9]
	s_waitcnt vmcnt(0)
	v_lshlrev_b32_e32 v136, 16, v132
	v_and_b32_e32 v137, 0xffff0000, v132
	v_lshlrev_b32_e32 v132, 16, v133
	v_and_b32_e32 v133, 0xffff0000, v133
	v_lshlrev_b32_e32 v138, 16, v134
	v_and_b32_e32 v139, 0xffff0000, v134
	v_lshlrev_b32_e32 v134, 16, v135
	v_and_b32_e32 v135, 0xffff0000, v135
	v_pk_fma_f32 v[116:117], v[116:117], v[76:77], v[132:133]
	v_pk_fma_f32 v[114:115], v[114:115], v[74:75], v[136:137]
	v_pk_fma_f32 v[112:113], v[112:113], v[72:73], v[134:135]
	v_cvt_pk_bf16_f32 v132, v114, v115
	v_cvt_pk_bf16_f32 v133, v116, v117
	v_pk_fma_f32 v[110:111], v[110:111], v[70:71], v[138:139]
	s_nop 0
	v_cvt_pk_bf16_f32 v134, v110, v111
	v_cvt_pk_bf16_f32 v135, v112, v113
	global_store_dwordx4 v241, v[132:135], s[22:23]
	s_nop 1
	v_lshl_add_u64 v[132:133], s[12:13], 0, v[130:131]
	s_cbranch_vccnz .LBB0_1262
	v_pk_mul_f32 v[134:135], v[212:213], v[114:115]
	v_pk_mul_f32 v[136:137], v[210:211], v[116:117]
	v_cvt_pk_bf16_f32 v134, v134, v135
	v_pk_mul_f32 v[116:117], v[116:117], v[116:117]
	v_cvt_pk_bf16_f32 v135, v136, v137
	v_pk_mul_f32 v[114:115], v[114:115], v[114:115]
	v_pk_mul_f32 v[138:139], v[206:207], v[112:113]
	v_pk_mul_f32 v[140:141], v[208:209], v[110:111]
	v_pk_mul_f32 v[112:113], v[112:113], v[112:113]
	v_cvt_pk_bf16_f32 v136, v140, v141
	v_cvt_pk_bf16_f32 v137, v138, v139
	global_store_dwordx4 v[132:133], v[134:137], off
	v_pk_mul_f32 v[110:111], v[110:111], v[110:111]
	s_nop 0
	v_mov_b32_e32 v134, v114
	v_mov_b32_e32 v135, v117
	v_pk_mov_b32 v[114:115], v[114:115], v[116:117] op_sel:[1,0]
	v_mov_b32_e32 v116, v112
	v_pk_add_f32 v[114:115], v[114:115], v[134:135]
	v_mov_b32_e32 v117, v110
	v_mov_b32_e32 v110, v113
	v_pk_add_f32 v[110:111], v[116:117], v[110:111]
	v_add_f32_e32 v112, v114, v115
	v_add_f32_e32 v111, v111, v112
	v_add_f32_e32 v110, v110, v111
	s_branch .LBB0_1263

; __device__ __forceinline__ unsigned cvt_pk_bf16(float lo, float hi) { unsigned r; asm volatile("v_cvt_pk_bf16_f32 %0, %1, %2" : "=v"(r) : "v"(lo), "v"(hi)); return r; }
; #define PG8_GPTR(p) ((__attribute__((address_space(1))) char*)(p))
;     __device__ __forceinline__ void operator()(const f32x4 (&acc)[2][2][4][2], const Unit& u, int wr, int wc, int fr, int fq) const {
;     ...
; #pragma unroll
;             for (int mm = 0; mm < 2; ++mm) {
;                 const int m = mp + mm;
;                 const int row = u.pm * BM + ai * HALF + wr * 64 + m * 16 + fr; float q = 0.f;
; #pragma unroll
;                 for (int bj = 0; bj < 2; ++bj) {
;                     const unsigned offb = (unsigned)(row * DM + col0 + bj * HALF) * 2u;
;                     const u32x4 bw = bv[mm][bj];
;                     const f32x4 b0 = (f32x4){__uint_as_float(bw.x << 16), __uint_as_float(bw.x & 0xffff0000u), __uint_as_float(bw.y << 16), __uint_as_float(bw.y & 0xffff0000u)};
;                     const f32x4 b1 = (f32x4){__uint_as_float(bw.z << 16), __uint_as_float(bw.z & 0xffff0000u), __uint_as_float(bw.w << 16), __uint_as_float(bw.w & 0xffff0000u)};
;                     f32x4 a0 = acc[ai][bj][m][0], a1 = acc[ai][bj][m][1]; if constexpr (GN) { a0 *= rc[ai * 4 + m]; a1 *= rc[ai * 4 + m]; }
;                     const f32x4 o0 = b0 + g[bj][0] * a0, o1 = b1 + g[bj][1] * a1;
;                     u32x4 wo; wo.x = cvt_pk_bf16(o0[0], o0[1]); wo.y = cvt_pk_bf16(o0[2], o0[3]); wo.z = cvt_pk_bf16(o1[0], o1[1]); wo.w = cvt_pk_bf16(o1[2], o1[3]);
;                     *(gs_u32x4*)(PG8_GPTR(out) + offb) = wo;
;                     if (xg) {
;                         const f32x4 h0 = o0 * cf[bj][0], h1 = o1 * cf[bj][1];
;                         u32x4 w; w.x = cvt_pk_bf16(h0[0], h0[1]); w.y = cvt_pk_bf16(h0[2], h0[3]); w.z = cvt_pk_bf16(h1[0], h1[1]); w.w = cvt_pk_bf16(h1[2], h1[3]);
;                         *(gs_u32x4*)(PG8_GPTR(xg) + offb) = w;
;                         q += (o0[0] * o0[0] + o0[1] * o0[1]) + (o0[2] * o0[2] + o0[3] * o0[3]) + (o1[0] * o1[0] + o1[1] * o1[1]) + (o1[2] * o1[2] + o1[3] * o1[3]);
;                     }
;                 }
;                 if (xg) ssq_put(ssq, row, q, fr, fq);
.LBB0_1263:
	v_lshlrev_b32_e32 v112, 16, v126
	v_and_b32_e32 v113, 0xffff0000, v126
	v_lshlrev_b32_e32 v114, 16, v127
	v_and_b32_e32 v115, 0xffff0000, v127
	v_lshlrev_b32_e32 v126, 16, v128
	v_and_b32_e32 v127, 0xffff0000, v128
	v_lshlrev_b32_e32 v128, 16, v129
	v_and_b32_e32 v129, 0xffff0000, v129
	v_lshl_add_u64 v[116:117], s[22:23], 0, v[130:131]
	v_pk_fma_f32 v[108:109], v[108:109], v[68:69], v[114:115]
	v_pk_fma_f32 v[106:107], v[106:107], v[66:67], v[112:113]
	v_pk_fma_f32 v[104:105], v[104:105], v[64:65], v[128:129]
	v_pk_fma_f32 v[102:103], v[102:103], v[62:63], v[126:127]
	s_and_b64 vcc, exec, s[8:9]
	v_cvt_pk_bf16_f32 v112, v106, v107
	v_cvt_pk_bf16_f32 v113, v108, v109
	v_cvt_pk_bf16_f32 v114, v102, v103
	v_cvt_pk_bf16_f32 v115, v104, v105
	global_store_dwordx4 v241, v[112:115], s[22:23] offset:1024
	s_cbranch_vccnz .LBB0_1267
	s_nop 0
	v_pk_mul_f32 v[112:113], v[148:149], v[108:109]
	v_mul_f32_e32 v115, v107, v107
	v_mul_f32_e32 v109, v109, v109
	v_mul_f32_e32 v114, v103, v103
	v_fmac_f32_e32 v115, v106, v106
	v_fmac_f32_e32 v109, v108, v108
	v_mul_f32_e32 v111, v105, v105
	v_fmac_f32_e32 v114, v102, v102
	v_add_f32_e32 v108, v115, v109
	v_fmac_f32_e32 v111, v104, v104
	v_add_f32_e32 v108, v114, v108
	v_add_f32_e32 v108, v111, v108
	v_add_f32_e32 v114, v108, v110
	ds_bpermute_b32 v115, v159, v114
	v_pk_mul_f32 v[110:111], v[146:147], v[102:103]
	v_pk_mul_f32 v[106:107], v[142:143], v[106:107]
	v_pk_mul_f32 v[108:109], v[144:145], v[104:105]
	v_cvt_pk_bf16_f32 v104, v106, v107
	s_waitcnt lgkmcnt(0)
	v_add_f32_e32 v102, v114, v115
	ds_bpermute_b32 v103, v158, v102
	v_cvt_pk_bf16_f32 v105, v112, v113
	v_cvt_pk_bf16_f32 v106, v110, v111
	v_cvt_pk_bf16_f32 v107, v108, v109
	global_store_dwordx4 v[132:133], v[104:107], off offset:256
	s_and_saveexec_b64 s[2:3], s[10:11]
	s_cbranch_execz .LBB0_1266
	s_waitcnt lgkmcnt(0)
	v_add_f32_e32 v102, v102, v103
	v_mul_f32_e32 v102, 0x4b800000, v102
	v_trunc_f32_e32 v102, v102
	v_mul_f32_e32 v103, 0x2f800000, v102
	v_floor_f32_e32 v103, v103
	v_fmac_f32_e32 v102, 0xcf800000, v103
	v_cvt_u32_f32_e32 v102, v102
	v_cvt_u32_f32_e32 v103, v103
	v_ashrrev_i32_e32 v205, 31, v204
	v_lshl_add_u64 v[104:105], v[204:205], 3, s[16:17]
	flat_atomic_add_x2 v[104:105], v[102:103] offset:256

; __device__ __forceinline__ unsigned cvt_pk_bf16(float lo, float hi) { unsigned r; asm volatile("v_cvt_pk_bf16_f32 %0, %1, %2" : "=v"(r) : "v"(lo), "v"(hi)); return r; }
; #define PG8_GPTR(p) ((__attribute__((address_space(1))) char*)(p))
;     __device__ __forceinline__ void operator()(const f32x4 (&acc)[2][2][4][2], const Unit& u, int wr, int wc, int fr, int fq) const {
;     ...
; #pragma unroll
;             for (int mm = 0; mm < 2; ++mm) {
;                 const int m = mp + mm;
;                 const int row = u.pm * BM + ai * HALF + wr * 64 + m * 16 + fr; float q = 0.f;
; #pragma unroll
;                 for (int bj = 0; bj < 2; ++bj) {
;                     const unsigned offb = (unsigned)(row * DM + col0 + bj * HALF) * 2u;
;                     const u32x4 bw = bv[mm][bj];
;                     const f32x4 b0 = (f32x4){__uint_as_float(bw.x << 16), __uint_as_float(bw.x & 0xffff0000u), __uint_as_float(bw.y << 16), __uint_as_float(bw.y & 0xffff0000u)};
;                     const f32x4 b1 = (f32x4){__uint_as_float(bw.z << 16), __uint_as_float(bw.z & 0xffff0000u), __uint_as_float(bw.w << 16), __uint_as_float(bw.w & 0xffff0000u)};
;                     f32x4 a0 = acc[ai][bj][m][0], a1 = acc[ai][bj][m][1]; if constexpr (GN) { a0 *= rc[ai * 4 + m]; a1 *= rc[ai * 4 + m]; }
;                     const f32x4 o0 = b0 + g[bj][0] * a0, o1 = b1 + g[bj][1] * a1;
;                     u32x4 wo; wo.x = cvt_pk_bf16(o0[0], o0[1]); wo.y = cvt_pk_bf16(o0[2], o0[3]); wo.z = cvt_pk_bf16(o1[0], o1[1]); wo.w = cvt_pk_bf16(o1[2], o1[3]);
;                     *(gs_u32x4*)(PG8_GPTR(out) + offb) = wo;
;                     if (xg) {
;                         const f32x4 h0 = o0 * cf[bj][0], h1 = o1 * cf[bj][1];
;                         u32x4 w; w.x = cvt_pk_bf16(h0[0], h0[1]); w.y = cvt_pk_bf16(h0[2], h0[3]); w.z = cvt_pk_bf16(h1[0], h1[1]); w.w = cvt_pk_bf16(h1[2], h1[3]);
;                         *(gs_u32x4*)(PG8_GPTR(xg) + offb) = w;
;                         q += (o0[0] * o0[0] + o0[1] * o0[1]) + (o0[2] * o0[2] + o0[3] * o0[3]) + (o1[0] * o1[0] + o1[1] * o1[1]) + (o1[2] * o1[2] + o1[3] * o1[3]);
;                     }
;                 }
;                 if (xg) ssq_put(ssq, row, q, fr, fq);
.LBB0_1267:
	s_mov_b32 s2, 0x18000
	v_add3_u32 v102, v217, v218, s2
	v_add_u32_e32 v241, s2, v240
	v_lshlrev_b32_e32 v104, 16, v122
	v_and_b32_e32 v105, 0xffff0000, v122
	v_lshlrev_b32_e32 v106, 16, v123
	v_and_b32_e32 v107, 0xffff0000, v123
	v_lshlrev_b32_e32 v108, 16, v124
	v_and_b32_e32 v109, 0xffff0000, v124
	v_lshlrev_b32_e32 v110, 16, v125
	v_and_b32_e32 v111, 0xffff0000, v125
	s_waitcnt lgkmcnt(0)
	v_mov_b32_e32 v103, v1
	v_pk_fma_f32 v[100:101], v[100:101], v[76:77], v[106:107]
	v_pk_fma_f32 v[98:99], v[98:99], v[74:75], v[104:105]
	v_pk_fma_f32 v[96:97], v[96:97], v[72:73], v[110:111]
	v_pk_fma_f32 v[104:105], v[94:95], v[70:71], v[108:109]
	s_and_b64 vcc, exec, s[8:9]
	v_lshl_add_u64 v[94:95], s[12:13], 0, v[102:103]
	v_cvt_pk_bf16_f32 v106, v98, v99
	v_cvt_pk_bf16_f32 v107, v100, v101
	v_cvt_pk_bf16_f32 v108, v104, v105
	v_cvt_pk_bf16_f32 v109, v96, v97
	global_store_dwordx4 v241, v[106:109], s[22:23]
	s_cbranch_vccnz .LBB0_1269
	s_nop 0
	v_pk_mul_f32 v[106:107], v[212:213], v[98:99]
	v_pk_mul_f32 v[108:109], v[210:211], v[100:101]
	v_cvt_pk_bf16_f32 v106, v106, v107
	v_pk_mul_f32 v[100:101], v[100:101], v[100:101]
	v_cvt_pk_bf16_f32 v107, v108, v109
	v_pk_mul_f32 v[98:99], v[98:99], v[98:99]
	v_pk_mul_f32 v[110:111], v[206:207], v[96:97]
	v_pk_mul_f32 v[112:113], v[208:209], v[104:105]
	v_pk_mul_f32 v[96:97], v[96:97], v[96:97]
	v_cvt_pk_bf16_f32 v108, v112, v113
	v_cvt_pk_bf16_f32 v109, v110, v111
	global_store_dwordx4 v[94:95], v[106:109], off
	s_nop 1
	v_mov_b32_e32 v106, v98
	v_mov_b32_e32 v107, v101
	v_pk_mov_b32 v[98:99], v[98:99], v[100:101] op_sel:[1,0]
	v_pk_mul_f32 v[100:101], v[104:105], v[104:105]
	v_pk_add_f32 v[98:99], v[98:99], v[106:107]
	v_mov_b32_e32 v104, v96
	v_mov_b32_e32 v105, v100
	v_mov_b32_e32 v100, v97
	v_pk_add_f32 v[96:97], v[104:105], v[100:101]
	v_add_f32_e32 v98, v98, v99
	v_add_f32_e32 v97, v97, v98
	v_add_f32_e32 v96, v96, v97
	s_branch .LBB0_1270

; __device__ __forceinline__ unsigned cvt_pk_bf16(float lo, float hi) { unsigned r; asm volatile("v_cvt_pk_bf16_f32 %0, %1, %2" : "=v"(r) : "v"(lo), "v"(hi)); return r; }
; #define PG8_GPTR(p) ((__attribute__((address_space(1))) char*)(p))
;     __device__ __forceinline__ void operator()(const f32x4 (&acc)[2][2][4][2], const Unit& u, int wr, int wc, int fr, int fq) const {
;     ...
; #pragma unroll
;             for (int mm = 0; mm < 2; ++mm) {
;                 const int m = mp + mm;
;                 const int row = u.pm * BM + ai * HALF + wr * 64 + m * 16 + fr; float q = 0.f;
; #pragma unroll
;                 for (int bj = 0; bj < 2; ++bj) {
;                     const unsigned offb = (unsigned)(row * DM + col0 + bj * HALF) * 2u;
;                     const u32x4 bw = bv[mm][bj];
;                     const f32x4 b0 = (f32x4){__uint_as_float(bw.x << 16), __uint_as_float(bw.x & 0xffff0000u), __uint_as_float(bw.y << 16), __uint_as_float(bw.y & 0xffff0000u)};
;                     const f32x4 b1 = (f32x4){__uint_as_float(bw.z << 16), __uint_as_float(bw.z & 0xffff0000u), __uint_as_float(bw.w << 16), __uint_as_float(bw.w & 0xffff0000u)};
;                     f32x4 a0 = acc[ai][bj][m][0], a1 = acc[ai][bj][m][1]; if constexpr (GN) { a0 *= rc[ai * 4 + m]; a1 *= rc[ai * 4 + m]; }
;                     const f32x4 o0 = b0 + g[bj][0] * a0, o1 = b1 + g[bj][1] * a1;
;                     u32x4 wo; wo.x = cvt_pk_bf16(o0[0], o0[1]); wo.y = cvt_pk_bf16(o0[2], o0[3]); wo.z = cvt_pk_bf16(o1[0], o1[1]); wo.w = cvt_pk_bf16(o1[2], o1[3]);
;                     *(gs_u32x4*)(PG8_GPTR(out) + offb) = wo;
;                     if (xg) {
;                         const f32x4 h0 = o0 * cf[bj][0], h1 = o1 * cf[bj][1];
;                         u32x4 w; w.x = cvt_pk_bf16(h0[0], h0[1]); w.y = cvt_pk_bf16(h0[2], h0[3]); w.z = cvt_pk_bf16(h1[0], h1[1]); w.w = cvt_pk_bf16(h1[2], h1[3]);
;                         *(gs_u32x4*)(PG8_GPTR(xg) + offb) = w;
;                         q += (o0[0] * o0[0] + o0[1] * o0[1]) + (o0[2] * o0[2] + o0[3] * o0[3]) + (o1[0] * o1[0] + o1[1] * o1[1]) + (o1[2] * o1[2] + o1[3] * o1[3]);
;                     }
;                 }
;                 if (xg) ssq_put(ssq, row, q, fr, fq);
.LBB0_1270:
	v_lshlrev_b32_e32 v98, 16, v118
	v_and_b32_e32 v99, 0xffff0000, v118
	v_lshlrev_b32_e32 v100, 16, v119
	v_and_b32_e32 v101, 0xffff0000, v119
	v_lshlrev_b32_e32 v104, 16, v120
	v_and_b32_e32 v105, 0xffff0000, v120
	v_lshlrev_b32_e32 v106, 16, v121
	v_and_b32_e32 v107, 0xffff0000, v121
	v_lshl_add_u64 v[102:103], s[22:23], 0, v[102:103]
	v_pk_fma_f32 v[92:93], v[92:93], v[68:69], v[100:101]
	v_pk_fma_f32 v[90:91], v[90:91], v[66:67], v[98:99]
	v_pk_fma_f32 v[88:89], v[88:89], v[64:65], v[106:107]
	v_pk_fma_f32 v[86:87], v[86:87], v[62:63], v[104:105]
	s_and_b64 vcc, exec, s[8:9]
	v_cvt_pk_bf16_f32 v98, v90, v91
	v_cvt_pk_bf16_f32 v99, v92, v93
	v_cvt_pk_bf16_f32 v100, v86, v87
	v_cvt_pk_bf16_f32 v101, v88, v89
	global_store_dwordx4 v241, v[98:101], s[22:23] offset:1024
	s_cbranch_vccnz .LBB0_1274
	s_nop 0
	v_pk_mul_f32 v[98:99], v[148:149], v[92:93]
	v_mul_f32_e32 v101, v91, v91
	v_mul_f32_e32 v93, v93, v93
	v_mul_f32_e32 v100, v87, v87
	v_fmac_f32_e32 v101, v90, v90
	v_fmac_f32_e32 v93, v92, v92
	v_mul_f32_e32 v97, v89, v89
	v_fmac_f32_e32 v100, v86, v86
	v_add_f32_e32 v92, v101, v93
	v_fmac_f32_e32 v97, v88, v88
	v_add_f32_e32 v92, v100, v92
	v_add_f32_e32 v92, v97, v92
	v_add_f32_e32 v100, v92, v96
	ds_bpermute_b32 v101, v159, v100
	v_pk_mul_f32 v[96:97], v[146:147], v[86:87]
	v_pk_mul_f32 v[90:91], v[142:143], v[90:91]
	v_pk_mul_f32 v[92:93], v[144:145], v[88:89]
	v_cvt_pk_bf16_f32 v88, v90, v91
	s_waitcnt lgkmcnt(0)
	v_add_f32_e32 v86, v100, v101
	ds_bpermute_b32 v87, v158, v86
	v_cvt_pk_bf16_f32 v89, v98, v99
	v_cvt_pk_bf16_f32 v90, v96, v97
	v_cvt_pk_bf16_f32 v91, v92, v93
	global_store_dwordx4 v[94:95], v[88:91], off offset:256
	s_and_saveexec_b64 s[2:3], s[10:11]
	s_cbranch_execz .LBB0_1273
	s_waitcnt lgkmcnt(0)
	v_add_f32_e32 v86, v86, v87
	v_mul_f32_e32 v86, 0x4b800000, v86
	v_trunc_f32_e32 v86, v86
	v_mul_f32_e32 v87, 0x2f800000, v86
	v_floor_f32_e32 v87, v87
	v_fmac_f32_e32 v86, 0xcf800000, v87
	v_cvt_u32_f32_e32 v86, v86
	v_cvt_u32_f32_e32 v87, v87
	v_ashrrev_i32_e32 v205, 31, v204
	v_lshl_add_u64 v[88:89], v[204:205], 3, s[16:17]
	flat_atomic_add_x2 v[88:89], v[86:87] offset:384

; __device__ __forceinline__ unsigned cvt_pk_bf16(float lo, float hi) { unsigned r; asm volatile("v_cvt_pk_bf16_f32 %0, %1, %2" : "=v"(r) : "v"(lo), "v"(hi)); return r; }
; #define PG8_GPTR(p) ((__attribute__((address_space(1))) char*)(p))
;     __device__ __forceinline__ void operator()(const f32x4 (&acc)[2][2][4][2], const Unit& u, int wr, int wc, int fr, int fq) const {
;     ...
; #pragma unroll
;             for (int mm = 0; mm < 2; ++mm) {
;                 const int m = mp + mm;
;                 const int row = u.pm * BM + ai * HALF + wr * 64 + m * 16 + fr; float q = 0.f;
; #pragma unroll
;                 for (int bj = 0; bj < 2; ++bj) {
;                     const unsigned offb = (unsigned)(row * DM + col0 + bj * HALF) * 2u;
;                     const u32x4 bw = bv[mm][bj];
;                     const f32x4 b0 = (f32x4){__uint_as_float(bw.x << 16), __uint_as_float(bw.x & 0xffff0000u), __uint_as_float(bw.y << 16), __uint_as_float(bw.y & 0xffff0000u)};
;                     const f32x4 b1 = (f32x4){__uint_as_float(bw.z << 16), __uint_as_float(bw.z & 0xffff0000u), __uint_as_float(bw.w << 16), __uint_as_float(bw.w & 0xffff0000u)};
;                     f32x4 a0 = acc[ai][bj][m][0], a1 = acc[ai][bj][m][1]; if constexpr (GN) { a0 *= rc[ai * 4 + m]; a1 *= rc[ai * 4 + m]; }
;                     const f32x4 o0 = b0 + g[bj][0] * a0, o1 = b1 + g[bj][1] * a1;
;                     u32x4 wo; wo.x = cvt_pk_bf16(o0[0], o0[1]); wo.y = cvt_pk_bf16(o0[2], o0[3]); wo.z = cvt_pk_bf16(o1[0], o1[1]); wo.w = cvt_pk_bf16(o1[2], o1[3]);
;                     *(gs_u32x4*)(PG8_GPTR(out) + offb) = wo;
;                     if (xg) {
;                         const f32x4 h0 = o0 * cf[bj][0], h1 = o1 * cf[bj][1];
;                         u32x4 w; w.x = cvt_pk_bf16(h0[0], h0[1]); w.y = cvt_pk_bf16(h0[2], h0[3]); w.z = cvt_pk_bf16(h1[0], h1[1]); w.w = cvt_pk_bf16(h1[2], h1[3]);
;                         *(gs_u32x4*)(PG8_GPTR(xg) + offb) = w;
;                         q += (o0[0] * o0[0] + o0[1] * o0[1]) + (o0[2] * o0[2] + o0[3] * o0[3]) + (o1[0] * o1[0] + o1[1] * o1[1]) + (o1[2] * o1[2] + o1[3] * o1[3]);
;                     }
;                 }
;                 if (xg) ssq_put(ssq, row, q, fr, fq);
.LBB0_1274:
	v_add_u32_e32 v86, 0x40000, v240
	global_load_dwordx4 v[100:103], v86, s[20:21]
	global_load_dwordx4 v[94:97], v86, s[20:21] offset:1024
	v_add_u32_e32 v86, 0x48000, v240
	global_load_dwordx4 v[90:93], v86, s[20:21]
	s_waitcnt lgkmcnt(0)
	global_load_dwordx4 v[86:89], v86, s[20:21] offset:1024
	s_mov_b32 s2, 0x40000
	v_add3_u32 v98, v218, v217, s2
	v_add_u32_e32 v241, s2, v240
	v_mov_b32_e32 v99, v1
	s_and_b64 vcc, exec, s[8:9]
	s_waitcnt vmcnt(0)
	v_lshlrev_b32_e32 v104, 16, v100
	v_and_b32_e32 v105, 0xffff0000, v100
	v_lshlrev_b32_e32 v100, 16, v101
	v_and_b32_e32 v101, 0xffff0000, v101
	v_lshlrev_b32_e32 v106, 16, v102
	v_and_b32_e32 v107, 0xffff0000, v102
	v_lshlrev_b32_e32 v102, 16, v103
	v_and_b32_e32 v103, 0xffff0000, v103
	v_pk_fma_f32 v[84:85], v[84:85], v[76:77], v[100:101]
	v_pk_fma_f32 v[82:83], v[82:83], v[74:75], v[104:105]
	v_pk_fma_f32 v[80:81], v[80:81], v[72:73], v[102:103]
	v_cvt_pk_bf16_f32 v100, v82, v83
	v_cvt_pk_bf16_f32 v101, v84, v85
	v_pk_fma_f32 v[78:79], v[78:79], v[70:71], v[106:107]
	s_nop 0
	v_cvt_pk_bf16_f32 v102, v78, v79
	v_cvt_pk_bf16_f32 v103, v80, v81
	global_store_dwordx4 v241, v[100:103], s[22:23]
	s_nop 1
	v_lshl_add_u64 v[100:101], s[12:13], 0, v[98:99]
	s_cbranch_vccnz .LBB0_1276
	v_pk_mul_f32 v[102:103], v[212:213], v[82:83]
	v_pk_mul_f32 v[104:105], v[210:211], v[84:85]
	v_cvt_pk_bf16_f32 v102, v102, v103
	v_pk_mul_f32 v[84:85], v[84:85], v[84:85]
	v_cvt_pk_bf16_f32 v103, v104, v105
	v_pk_mul_f32 v[82:83], v[82:83], v[82:83]
	v_pk_mul_f32 v[106:107], v[206:207], v[80:81]
	v_pk_mul_f32 v[108:109], v[208:209], v[78:79]
	v_pk_mul_f32 v[80:81], v[80:81], v[80:81]
	v_cvt_pk_bf16_f32 v104, v108, v109
	v_cvt_pk_bf16_f32 v105, v106, v107
	global_store_dwordx4 v[100:101], v[102:105], off
	v_pk_mul_f32 v[78:79], v[78:79], v[78:79]
	s_nop 0
	v_mov_b32_e32 v102, v82
	v_mov_b32_e32 v103, v85
	v_pk_mov_b32 v[82:83], v[82:83], v[84:85] op_sel:[1,0]
	v_mov_b32_e32 v84, v80
	v_pk_add_f32 v[82:83], v[82:83], v[102:103]
	v_mov_b32_e32 v85, v78
	v_mov_b32_e32 v78, v81
	v_pk_add_f32 v[78:79], v[84:85], v[78:79]
	v_add_f32_e32 v80, v82, v83
	v_add_f32_e32 v79, v79, v80
	v_add_f32_e32 v78, v78, v79
	s_branch .LBB0_1277

; __device__ __forceinline__ unsigned cvt_pk_bf16(float lo, float hi) { unsigned r; asm volatile("v_cvt_pk_bf16_f32 %0, %1, %2" : "=v"(r) : "v"(lo), "v"(hi)); return r; }
; #define PG8_GPTR(p) ((__attribute__((address_space(1))) char*)(p))
;     __device__ __forceinline__ void operator()(const f32x4 (&acc)[2][2][4][2], const Unit& u, int wr, int wc, int fr, int fq) const {
;     ...
; #pragma unroll
;             for (int mm = 0; mm < 2; ++mm) {
;                 const int m = mp + mm;
;                 const int row = u.pm * BM + ai * HALF + wr * 64 + m * 16 + fr; float q = 0.f;
; #pragma unroll
;                 for (int bj = 0; bj < 2; ++bj) {
;                     const unsigned offb = (unsigned)(row * DM + col0 + bj * HALF) * 2u;
;                     const u32x4 bw = bv[mm][bj];
;                     const f32x4 b0 = (f32x4){__uint_as_float(bw.x << 16), __uint_as_float(bw.x & 0xffff0000u), __uint_as_float(bw.y << 16), __uint_as_float(bw.y & 0xffff0000u)};
;                     const f32x4 b1 = (f32x4){__uint_as_float(bw.z << 16), __uint_as_float(bw.z & 0xffff0000u), __uint_as_float(bw.w << 16), __uint_as_float(bw.w & 0xffff0000u)};
;                     f32x4 a0 = acc[ai][bj][m][0], a1 = acc[ai][bj][m][1]; if constexpr (GN) { a0 *= rc[ai * 4 + m]; a1 *= rc[ai * 4 + m]; }
;                     const f32x4 o0 = b0 + g[bj][0] * a0, o1 = b1 + g[bj][1] * a1;
;                     u32x4 wo; wo.x = cvt_pk_bf16(o0[0], o0[1]); wo.y = cvt_pk_bf16(o0[2], o0[3]); wo.z = cvt_pk_bf16(o1[0], o1[1]); wo.w = cvt_pk_bf16(o1[2], o1[3]);
;                     *(gs_u32x4*)(PG8_GPTR(out) + offb) = wo;
;                     if (xg) {
;                         const f32x4 h0 = o0 * cf[bj][0], h1 = o1 * cf[bj][1];
;                         u32x4 w; w.x = cvt_pk_bf16(h0[0], h0[1]); w.y = cvt_pk_bf16(h0[2], h0[3]); w.z = cvt_pk_bf16(h1[0], h1[1]); w.w = cvt_pk_bf16(h1[2], h1[3]);
;                         *(gs_u32x4*)(PG8_GPTR(xg) + offb) = w;
;                         q += (o0[0] * o0[0] + o0[1] * o0[1]) + (o0[2] * o0[2] + o0[3] * o0[3]) + (o1[0] * o1[0] + o1[1] * o1[1]) + (o1[2] * o1[2] + o1[3] * o1[3]);
;                     }
;                 }
;                 if (xg) ssq_put(ssq, row, q, fr, fq);
.LBB0_1277:
	v_lshlrev_b32_e32 v80, 16, v94
	v_and_b32_e32 v81, 0xffff0000, v94
	v_lshlrev_b32_e32 v82, 16, v95
	v_and_b32_e32 v83, 0xffff0000, v95
	v_lshlrev_b32_e32 v94, 16, v96
	v_and_b32_e32 v95, 0xffff0000, v96
	v_lshlrev_b32_e32 v96, 16, v97
	v_and_b32_e32 v97, 0xffff0000, v97
	v_lshl_add_u64 v[84:85], s[22:23], 0, v[98:99]
	v_pk_fma_f32 v[60:61], v[60:61], v[68:69], v[82:83]
	v_pk_fma_f32 v[58:59], v[58:59], v[66:67], v[80:81]
	v_pk_fma_f32 v[56:57], v[56:57], v[64:65], v[96:97]
	v_pk_fma_f32 v[54:55], v[54:55], v[62:63], v[94:95]
	s_and_b64 vcc, exec, s[8:9]
	v_cvt_pk_bf16_f32 v80, v58, v59
	v_cvt_pk_bf16_f32 v81, v60, v61
	v_cvt_pk_bf16_f32 v82, v54, v55
	v_cvt_pk_bf16_f32 v83, v56, v57
	global_store_dwordx4 v241, v[80:83], s[22:23] offset:1024
	s_cbranch_vccnz .LBB0_1281
	s_nop 0
	v_pk_mul_f32 v[80:81], v[148:149], v[60:61]
	v_mul_f32_e32 v83, v59, v59
	v_mul_f32_e32 v61, v61, v61
	v_mul_f32_e32 v82, v55, v55
	v_fmac_f32_e32 v83, v58, v58
	v_fmac_f32_e32 v61, v60, v60
	v_mul_f32_e32 v79, v57, v57
	v_fmac_f32_e32 v82, v54, v54
	v_add_f32_e32 v60, v83, v61
	v_fmac_f32_e32 v79, v56, v56
	v_add_f32_e32 v60, v82, v60
	v_add_f32_e32 v60, v79, v60
	v_add_f32_e32 v82, v60, v78
	ds_bpermute_b32 v83, v159, v82
	v_pk_mul_f32 v[78:79], v[146:147], v[54:55]
	v_pk_mul_f32 v[58:59], v[142:143], v[58:59]
	v_pk_mul_f32 v[60:61], v[144:145], v[56:57]
	v_cvt_pk_bf16_f32 v56, v58, v59
	s_waitcnt lgkmcnt(0)
	v_add_f32_e32 v54, v82, v83
	ds_bpermute_b32 v55, v158, v54
	v_cvt_pk_bf16_f32 v57, v80, v81
	v_cvt_pk_bf16_f32 v58, v78, v79
	v_cvt_pk_bf16_f32 v59, v60, v61
	global_store_dwordx4 v[100:101], v[56:59], off offset:256
	s_and_saveexec_b64 s[2:3], s[10:11]
	s_cbranch_execz .LBB0_1280
	s_waitcnt lgkmcnt(0)
	v_add_f32_e32 v54, v54, v55
	v_mul_f32_e32 v54, 0x4b800000, v54
	v_trunc_f32_e32 v54, v54
	v_mul_f32_e32 v55, 0x2f800000, v54
	v_floor_f32_e32 v55, v55
	v_fmac_f32_e32 v54, 0xcf800000, v55
	v_cvt_u32_f32_e32 v54, v54
	v_cvt_u32_f32_e32 v55, v55
	v_ashrrev_i32_e32 v205, 31, v204
	v_lshl_add_u64 v[56:57], v[204:205], 3, s[16:17]
	flat_atomic_add_x2 v[56:57], v[54:55] offset:1024

; __device__ __forceinline__ unsigned cvt_pk_bf16(float lo, float hi) { unsigned r; asm volatile("v_cvt_pk_bf16_f32 %0, %1, %2" : "=v"(r) : "v"(lo), "v"(hi)); return r; }
; #define PG8_GPTR(p) ((__attribute__((address_space(1))) char*)(p))
;     __device__ __forceinline__ void operator()(const f32x4 (&acc)[2][2][4][2], const Unit& u, int wr, int wc, int fr, int fq) const {
;     ...
; #pragma unroll
;             for (int mm = 0; mm < 2; ++mm) {
;                 const int m = mp + mm;
;                 const int row = u.pm * BM + ai * HALF + wr * 64 + m * 16 + fr; float q = 0.f;
; #pragma unroll
;                 for (int bj = 0; bj < 2; ++bj) {
;                     const unsigned offb = (unsigned)(row * DM + col0 + bj * HALF) * 2u;
;                     const u32x4 bw = bv[mm][bj];
;                     const f32x4 b0 = (f32x4){__uint_as_float(bw.x << 16), __uint_as_float(bw.x & 0xffff0000u), __uint_as_float(bw.y << 16), __uint_as_float(bw.y & 0xffff0000u)};
;                     const f32x4 b1 = (f32x4){__uint_as_float(bw.z << 16), __uint_as_float(bw.z & 0xffff0000u), __uint_as_float(bw.w << 16), __uint_as_float(bw.w & 0xffff0000u)};
;                     f32x4 a0 = acc[ai][bj][m][0], a1 = acc[ai][bj][m][1]; if constexpr (GN) { a0 *= rc[ai * 4 + m]; a1 *= rc[ai * 4 + m]; }
;                     const f32x4 o0 = b0 + g[bj][0] * a0, o1 = b1 + g[bj][1] * a1;
;                     u32x4 wo; wo.x = cvt_pk_bf16(o0[0], o0[1]); wo.y = cvt_pk_bf16(o0[2], o0[3]); wo.z = cvt_pk_bf16(o1[0], o1[1]); wo.w = cvt_pk_bf16(o1[2], o1[3]);
;                     *(gs_u32x4*)(PG8_GPTR(out) + offb) = wo;
;                     if (xg) {
;                         const f32x4 h0 = o0 * cf[bj][0], h1 = o1 * cf[bj][1];
;                         u32x4 w; w.x = cvt_pk_bf16(h0[0], h0[1]); w.y = cvt_pk_bf16(h0[2], h0[3]); w.z = cvt_pk_bf16(h1[0], h1[1]); w.w = cvt_pk_bf16(h1[2], h1[3]);
;                         *(gs_u32x4*)(PG8_GPTR(xg) + offb) = w;
;                         q += (o0[0] * o0[0] + o0[1] * o0[1]) + (o0[2] * o0[2] + o0[3] * o0[3]) + (o1[0] * o1[0] + o1[1] * o1[1]) + (o1[2] * o1[2] + o1[3] * o1[3]);
;                     }
;                 }
;                 if (xg) ssq_put(ssq, row, q, fr, fq);
.LBB0_1281:
	s_mov_b32 s2, 0x48000
	v_add3_u32 v54, v218, v217, s2
	v_add_u32_e32 v241, s2, v240
	v_lshlrev_b32_e32 v56, 16, v90
	v_and_b32_e32 v57, 0xffff0000, v90
	v_lshlrev_b32_e32 v58, 16, v91
	v_and_b32_e32 v59, 0xffff0000, v91
	v_lshlrev_b32_e32 v60, 16, v92
	v_and_b32_e32 v61, 0xffff0000, v92
	v_lshlrev_b32_e32 v78, 16, v93
	v_and_b32_e32 v79, 0xffff0000, v93
	s_waitcnt lgkmcnt(0)
	v_mov_b32_e32 v55, v1
	v_pk_fma_f32 v[52:53], v[52:53], v[76:77], v[58:59]
	v_pk_fma_f32 v[50:51], v[50:51], v[74:75], v[56:57]
	v_pk_fma_f32 v[48:49], v[48:49], v[72:73], v[78:79]
	v_pk_fma_f32 v[56:57], v[46:47], v[70:71], v[60:61]
	s_and_b64 vcc, exec, s[8:9]
	v_lshl_add_u64 v[46:47], s[12:13], 0, v[54:55]
	v_cvt_pk_bf16_f32 v58, v50, v51
	v_cvt_pk_bf16_f32 v59, v52, v53
	v_cvt_pk_bf16_f32 v60, v56, v57
	v_cvt_pk_bf16_f32 v61, v48, v49
	global_store_dwordx4 v241, v[58:61], s[22:23]
	s_cbranch_vccnz .LBB0_1283
	s_nop 0
	v_pk_mul_f32 v[58:59], v[212:213], v[50:51]
	v_pk_mul_f32 v[60:61], v[210:211], v[52:53]
	v_cvt_pk_bf16_f32 v58, v58, v59
	v_pk_mul_f32 v[52:53], v[52:53], v[52:53]
	v_cvt_pk_bf16_f32 v59, v60, v61
	v_pk_mul_f32 v[50:51], v[50:51], v[50:51]
	v_pk_mul_f32 v[78:79], v[206:207], v[48:49]
	v_pk_mul_f32 v[80:81], v[208:209], v[56:57]
	v_pk_mul_f32 v[48:49], v[48:49], v[48:49]
	v_cvt_pk_bf16_f32 v60, v80, v81
	v_cvt_pk_bf16_f32 v61, v78, v79
	global_store_dwordx4 v[46:47], v[58:61], off
	s_nop 1
	v_mov_b32_e32 v58, v50
	v_mov_b32_e32 v59, v53
	v_pk_mov_b32 v[50:51], v[50:51], v[52:53] op_sel:[1,0]
	v_pk_mul_f32 v[52:53], v[56:57], v[56:57]
	v_pk_add_f32 v[50:51], v[50:51], v[58:59]
	v_mov_b32_e32 v56, v48
	v_mov_b32_e32 v57, v52
	v_mov_b32_e32 v52, v49
	v_pk_add_f32 v[48:49], v[56:57], v[52:53]
	v_add_f32_e32 v50, v50, v51
	v_add_f32_e32 v49, v49, v50
	v_add_f32_e32 v48, v48, v49
	s_branch .LBB0_1284

; __device__ __forceinline__ unsigned cvt_pk_bf16(float lo, float hi) { unsigned r; asm volatile("v_cvt_pk_bf16_f32 %0, %1, %2" : "=v"(r) : "v"(lo), "v"(hi)); return r; }
; #define PG8_GPTR(p) ((__attribute__((address_space(1))) char*)(p))
;     __device__ __forceinline__ void operator()(const f32x4 (&acc)[2][2][4][2], const Unit& u, int wr, int wc, int fr, int fq) const {
;     ...
; #pragma unroll
;             for (int mm = 0; mm < 2; ++mm) {
;                 const int m = mp + mm;
;                 const int row = u.pm * BM + ai * HALF + wr * 64 + m * 16 + fr; float q = 0.f;
; #pragma unroll
;                 for (int bj = 0; bj < 2; ++bj) {
;                     const unsigned offb = (unsigned)(row * DM + col0 + bj * HALF) * 2u;
;                     const u32x4 bw = bv[mm][bj];
;                     const f32x4 b0 = (f32x4){__uint_as_float(bw.x << 16), __uint_as_float(bw.x & 0xffff0000u), __uint_as_float(bw.y << 16), __uint_as_float(bw.y & 0xffff0000u)};
;                     const f32x4 b1 = (f32x4){__uint_as_float(bw.z << 16), __uint_as_float(bw.z & 0xffff0000u), __uint_as_float(bw.w << 16), __uint_as_float(bw.w & 0xffff0000u)};
;                     f32x4 a0 = acc[ai][bj][m][0], a1 = acc[ai][bj][m][1]; if constexpr (GN) { a0 *= rc[ai * 4 + m]; a1 *= rc[ai * 4 + m]; }
;                     const f32x4 o0 = b0 + g[bj][0] * a0, o1 = b1 + g[bj][1] * a1;
;                     u32x4 wo; wo.x = cvt_pk_bf16(o0[0], o0[1]); wo.y = cvt_pk_bf16(o0[2], o0[3]); wo.z = cvt_pk_bf16(o1[0], o1[1]); wo.w = cvt_pk_bf16(o1[2], o1[3]);
;                     *(gs_u32x4*)(PG8_GPTR(out) + offb) = wo;
;                     if (xg) {
;                         const f32x4 h0 = o0 * cf[bj][0], h1 = o1 * cf[bj][1];
;                         u32x4 w; w.x = cvt_pk_bf16(h0[0], h0[1]); w.y = cvt_pk_bf16(h0[2], h0[3]); w.z = cvt_pk_bf16(h1[0], h1[1]); w.w = cvt_pk_bf16(h1[2], h1[3]);
;                         *(gs_u32x4*)(PG8_GPTR(xg) + offb) = w;
;                         q += (o0[0] * o0[0] + o0[1] * o0[1]) + (o0[2] * o0[2] + o0[3] * o0[3]) + (o1[0] * o1[0] + o1[1] * o1[1]) + (o1[2] * o1[2] + o1[3] * o1[3]);
;                     }
;                 }
;                 if (xg) ssq_put(ssq, row, q, fr, fq);
.LBB0_1284:
	v_lshlrev_b32_e32 v50, 16, v86
	v_and_b32_e32 v51, 0xffff0000, v86
	v_lshlrev_b32_e32 v52, 16, v87
	v_and_b32_e32 v53, 0xffff0000, v87
	v_lshlrev_b32_e32 v56, 16, v88
	v_and_b32_e32 v57, 0xffff0000, v88
	v_lshlrev_b32_e32 v58, 16, v89
	v_and_b32_e32 v59, 0xffff0000, v89
	v_lshl_add_u64 v[54:55], s[22:23], 0, v[54:55]
	v_pk_fma_f32 v[44:45], v[44:45], v[68:69], v[52:53]
	v_pk_fma_f32 v[42:43], v[42:43], v[66:67], v[50:51]
	v_pk_fma_f32 v[40:41], v[40:41], v[64:65], v[58:59]
	v_pk_fma_f32 v[38:39], v[38:39], v[62:63], v[56:57]
	s_and_b64 vcc, exec, s[8:9]
	v_cvt_pk_bf16_f32 v50, v42, v43
	v_cvt_pk_bf16_f32 v51, v44, v45
	v_cvt_pk_bf16_f32 v52, v38, v39
	v_cvt_pk_bf16_f32 v53, v40, v41
	global_store_dwordx4 v241, v[50:53], s[22:23] offset:1024
	s_cbranch_vccnz .LBB0_1288
	s_nop 0
	v_pk_mul_f32 v[50:51], v[148:149], v[44:45]
	v_mul_f32_e32 v53, v43, v43
	v_mul_f32_e32 v45, v45, v45
	v_mul_f32_e32 v52, v39, v39
	v_fmac_f32_e32 v53, v42, v42
	v_fmac_f32_e32 v45, v44, v44
	v_mul_f32_e32 v49, v41, v41
	v_fmac_f32_e32 v52, v38, v38
	v_add_f32_e32 v44, v53, v45
	v_fmac_f32_e32 v49, v40, v40
	v_add_f32_e32 v44, v52, v44
	v_add_f32_e32 v44, v49, v44
	v_add_f32_e32 v52, v44, v48
	ds_bpermute_b32 v53, v159, v52
	v_pk_mul_f32 v[48:49], v[146:147], v[38:39]
	v_pk_mul_f32 v[42:43], v[142:143], v[42:43]
	v_pk_mul_f32 v[44:45], v[144:145], v[40:41]
	v_cvt_pk_bf16_f32 v40, v42, v43
	s_waitcnt lgkmcnt(0)
	v_add_f32_e32 v38, v52, v53
	ds_bpermute_b32 v39, v158, v38
	v_cvt_pk_bf16_f32 v41, v50, v51
	v_cvt_pk_bf16_f32 v42, v48, v49
	v_cvt_pk_bf16_f32 v43, v44, v45
	global_store_dwordx4 v[46:47], v[40:43], off offset:256
	s_and_saveexec_b64 s[2:3], s[10:11]
	s_cbranch_execz .LBB0_1287
	s_waitcnt lgkmcnt(0)
	v_add_f32_e32 v38, v38, v39
	v_mul_f32_e32 v38, 0x4b800000, v38
	v_trunc_f32_e32 v38, v38
	v_mul_f32_e32 v39, 0x2f800000, v38
	v_floor_f32_e32 v39, v39
	v_fmac_f32_e32 v38, 0xcf800000, v39
	v_cvt_u32_f32_e32 v38, v38
	v_cvt_u32_f32_e32 v39, v39
	v_ashrrev_i32_e32 v205, 31, v204
	v_lshl_add_u64 v[40:41], v[204:205], 3, s[16:17]
	flat_atomic_add_x2 v[40:41], v[38:39] offset:1152

; __device__ __forceinline__ unsigned cvt_pk_bf16(float lo, float hi) { unsigned r; asm volatile("v_cvt_pk_bf16_f32 %0, %1, %2" : "=v"(r) : "v"(lo), "v"(hi)); return r; }
; #define PG8_GPTR(p) ((__attribute__((address_space(1))) char*)(p))
; #define PG8_GCPTR(p) ((__attribute__((address_space(1))) const char*)(p))
;     __device__ __forceinline__ void operator()(const f32x4 (&acc)[2][2][4][2], const Unit& u, int wr, int wc, int fr, int fq) const {
;     ...
;                     bv[mm][bj] = *(gl_u32x4*)(PG8_GCPTR(base) + (unsigned)((u.pm * BM + ai * HALF + wr * 64 + (mp + mm) * 16 + fr) * DM + col0 + bj * HALF) * 2u);
; #pragma unroll
;             for (int mm = 0; mm < 2; ++mm) {
;                 const int m = mp + mm;
;                 const int row = u.pm * BM + ai * HALF + wr * 64 + m * 16 + fr; float q = 0.f;
; #pragma unroll
;                 for (int bj = 0; bj < 2; ++bj) {
;                     const unsigned offb = (unsigned)(row * DM + col0 + bj * HALF) * 2u;
;                     const u32x4 bw = bv[mm][bj];
;                     const f32x4 b0 = (f32x4){__uint_as_float(bw.x << 16), __uint_as_float(bw.x & 0xffff0000u), __uint_as_float(bw.y << 16), __uint_as_float(bw.y & 0xffff0000u)};
;                     const f32x4 b1 = (f32x4){__uint_as_float(bw.z << 16), __uint_as_float(bw.z & 0xffff0000u), __uint_as_float(bw.w << 16), __uint_as_float(bw.w & 0xffff0000u)};
;                     f32x4 a0 = acc[ai][bj][m][0], a1 = acc[ai][bj][m][1]; if constexpr (GN) { a0 *= rc[ai * 4 + m]; a1 *= rc[ai * 4 + m]; }
;                     const f32x4 o0 = b0 + g[bj][0] * a0, o1 = b1 + g[bj][1] * a1;
;                     u32x4 wo; wo.x = cvt_pk_bf16(o0[0], o0[1]); wo.y = cvt_pk_bf16(o0[2], o0[3]); wo.z = cvt_pk_bf16(o1[0], o1[1]); wo.w = cvt_pk_bf16(o1[2], o1[3]);
;                     *(gs_u32x4*)(PG8_GPTR(out) + offb) = wo;
;                     if (xg) {
;                         const f32x4 h0 = o0 * cf[bj][0], h1 = o1 * cf[bj][1];
;                         u32x4 w; w.x = cvt_pk_bf16(h0[0], h0[1]); w.y = cvt_pk_bf16(h0[2], h0[3]); w.z = cvt_pk_bf16(h1[0], h1[1]); w.w = cvt_pk_bf16(h1[2], h1[3]);
;                         *(gs_u32x4*)(PG8_GPTR(xg) + offb) = w;
;                         q += (o0[0] * o0[0] + o0[1] * o0[1]) + (o0[2] * o0[2] + o0[3] * o0[3]) + (o1[0] * o1[0] + o1[1] * o1[1]) + (o1[2] * o1[2] + o1[3] * o1[3]);
;                     }
.LBB0_1288:
	v_add_u32_e32 v38, 0x50000, v240
	global_load_dwordx4 v[50:53], v38, s[20:21]
	v_add_u32_e32 v0, 0x58000, v240
	global_load_dwordx4 v[46:49], v38, s[20:21] offset:1024
	global_load_dwordx4 v[42:45], v0, s[20:21]
	s_waitcnt lgkmcnt(0)
	global_load_dwordx4 v[38:41], v0, s[20:21] offset:1024
	s_mov_b32 s2, 0x50000
	v_add3_u32 v0, v218, v217, s2
	v_add_u32_e32 v241, s2, v240
	s_and_b64 vcc, exec, s[8:9]
	s_waitcnt vmcnt(0)
	v_lshlrev_b32_e32 v54, 16, v50
	v_and_b32_e32 v55, 0xffff0000, v50
	v_lshlrev_b32_e32 v50, 16, v51
	v_and_b32_e32 v51, 0xffff0000, v51
	v_lshlrev_b32_e32 v56, 16, v52
	v_and_b32_e32 v57, 0xffff0000, v52
	v_lshlrev_b32_e32 v52, 16, v53
	v_and_b32_e32 v53, 0xffff0000, v53
	v_pk_fma_f32 v[36:37], v[36:37], v[76:77], v[50:51]
	v_pk_fma_f32 v[50:51], v[34:35], v[74:75], v[54:55]
	v_pk_fma_f32 v[32:33], v[32:33], v[72:73], v[52:53]
	v_pk_fma_f32 v[34:35], v[30:31], v[70:71], v[56:57]
	v_lshl_add_u64 v[30:31], s[12:13], 0, v[0:1]
	v_cvt_pk_bf16_f32 v52, v50, v51
	v_cvt_pk_bf16_f32 v53, v36, v37
	v_cvt_pk_bf16_f32 v54, v34, v35
	v_cvt_pk_bf16_f32 v55, v32, v33
	global_store_dwordx4 v241, v[52:55], s[22:23]
	s_cbranch_vccnz .LBB0_1290
	s_nop 0
	v_pk_mul_f32 v[52:53], v[212:213], v[50:51]
	v_pk_mul_f32 v[54:55], v[210:211], v[36:37]
	v_cvt_pk_bf16_f32 v52, v52, v53
	v_pk_mul_f32 v[36:37], v[36:37], v[36:37]
	v_cvt_pk_bf16_f32 v53, v54, v55
	v_pk_mul_f32 v[50:51], v[50:51], v[50:51]
	v_pk_mul_f32 v[56:57], v[206:207], v[32:33]
	v_pk_mul_f32 v[58:59], v[208:209], v[34:35]
	v_pk_mul_f32 v[32:33], v[32:33], v[32:33]
	v_cvt_pk_bf16_f32 v54, v58, v59
	v_cvt_pk_bf16_f32 v55, v56, v57
	global_store_dwordx4 v[30:31], v[52:55], off
	v_pk_mul_f32 v[34:35], v[34:35], v[34:35]
	s_nop 0
	v_mov_b32_e32 v52, v50
	v_mov_b32_e32 v53, v37
	v_pk_mov_b32 v[36:37], v[50:51], v[36:37] op_sel:[1,0]
	v_mov_b32_e32 v50, v32
	v_pk_add_f32 v[36:37], v[36:37], v[52:53]
	v_mov_b32_e32 v51, v34
	v_mov_b32_e32 v34, v33
	v_pk_add_f32 v[32:33], v[50:51], v[34:35]
	v_add_f32_e32 v34, v36, v37
	v_add_f32_e32 v33, v33, v34
	v_add_f32_e32 v32, v32, v33
	s_branch .LBB0_1291

; __device__ __forceinline__ float shfl_x(float v, int m, int lane) { return __builtin_bit_cast(float, __builtin_amdgcn_ds_bpermute((lane ^ m) << 2, __builtin_bit_cast(int, v))); }
; #define PG8_GPTR(p) ((__attribute__((address_space(1))) char*)(p))
; __device__ __forceinline__ void ssq_put(ssq_t* p, int row, float q, int fr, int fq) {
;     const int lane = fr + 16 * fq;
;     q += shfl_x(q, 16, lane); q += shfl_x(q, 32, lane);
;     if (fq == 0) __hip_atomic_fetch_add(p + row, (ssq_t)(q * SSQ_FX), __ATOMIC_RELAXED, __HIP_MEMORY_SCOPE_AGENT);
; }
;     __device__ __forceinline__ void operator()(const f32x4 (&acc)[2][2][4][2], const Unit& u, int wr, int wc, int fr, int fq) const {
;     ...
;                 for (int bj = 0; bj < 2; ++bj) {
;                     const unsigned offb = (unsigned)(row * DM + col0 + bj * HALF) * 2u;
;                     const u32x4 bw = bv[mm][bj];
;                     const f32x4 b0 = (f32x4){__uint_as_float(bw.x << 16), __uint_as_float(bw.x & 0xffff0000u), __uint_as_float(bw.y << 16), __uint_as_float(bw.y & 0xffff0000u)};
;                     const f32x4 b1 = (f32x4){__uint_as_float(bw.z << 16), __uint_as_float(bw.z & 0xffff0000u), __uint_as_float(bw.w << 16), __uint_as_float(bw.w & 0xffff0000u)};
;                     f32x4 a0 = acc[ai][bj][m][0], a1 = acc[ai][bj][m][1]; if constexpr (GN) { a0 *= rc[ai * 4 + m]; a1 *= rc[ai * 4 + m]; }
;                     const f32x4 o0 = b0 + g[bj][0] * a0, o1 = b1 + g[bj][1] * a1;
;                     u32x4 wo; wo.x = cvt_pk_bf16(o0[0], o0[1]); wo.y = cvt_pk_bf16(o0[2], o0[3]); wo.z = cvt_pk_bf16(o1[0], o1[1]); wo.w = cvt_pk_bf16(o1[2], o1[3]);
;                     *(gs_u32x4*)(PG8_GPTR(out) + offb) = wo;
;                     if (xg) {
;                         const f32x4 h0 = o0 * cf[bj][0], h1 = o1 * cf[bj][1];
;                         u32x4 w; w.x = cvt_pk_bf16(h0[0], h0[1]); w.y = cvt_pk_bf16(h0[2], h0[3]); w.z = cvt_pk_bf16(h1[0], h1[1]); w.w = cvt_pk_bf16(h1[2], h1[3]);
;                         *(gs_u32x4*)(PG8_GPTR(xg) + offb) = w;
;                         q += (o0[0] * o0[0] + o0[1] * o0[1]) + (o0[2] * o0[2] + o0[3] * o0[3]) + (o1[0] * o1[0] + o1[1] * o1[1]) + (o1[2] * o1[2] + o1[3] * o1[3]);
;                     }
;                 }
;                 if (xg) ssq_put(ssq, row, q, fr, fq);
.LBB0_1291:
	v_lshlrev_b32_e32 v34, 16, v46
	v_and_b32_e32 v35, 0xffff0000, v46
	v_lshlrev_b32_e32 v36, 16, v47
	v_and_b32_e32 v37, 0xffff0000, v47
	v_lshlrev_b32_e32 v46, 16, v48
	v_and_b32_e32 v47, 0xffff0000, v48
	v_lshlrev_b32_e32 v48, 16, v49
	v_and_b32_e32 v49, 0xffff0000, v49
	v_lshl_add_u64 v[50:51], s[22:23], 0, v[0:1]
	v_pk_fma_f32 v[28:29], v[28:29], v[68:69], v[36:37]
	v_pk_fma_f32 v[26:27], v[26:27], v[66:67], v[34:35]
	v_pk_fma_f32 v[24:25], v[24:25], v[64:65], v[48:49]
	v_pk_fma_f32 v[22:23], v[22:23], v[62:63], v[46:47]
	s_and_b64 vcc, exec, s[8:9]
	v_cvt_pk_bf16_f32 v34, v26, v27
	v_cvt_pk_bf16_f32 v35, v28, v29
	v_cvt_pk_bf16_f32 v36, v22, v23
	v_cvt_pk_bf16_f32 v37, v24, v25
	global_store_dwordx4 v241, v[34:37], s[22:23] offset:1024
	s_cbranch_vccnz .LBB0_1295
	s_nop 0
	v_pk_mul_f32 v[34:35], v[148:149], v[28:29]
	v_mul_f32_e32 v36, v27, v27
	v_mul_f32_e32 v29, v29, v29
	v_mul_f32_e32 v33, v23, v23
	v_fmac_f32_e32 v36, v26, v26
	v_fmac_f32_e32 v29, v28, v28
	v_mul_f32_e32 v0, v25, v25
	v_fmac_f32_e32 v33, v22, v22
	v_add_f32_e32 v28, v36, v29
	v_fmac_f32_e32 v0, v24, v24
	v_add_f32_e32 v28, v33, v28
	v_add_f32_e32 v0, v0, v28
	v_add_f32_e32 v0, v0, v32
	ds_bpermute_b32 v36, v159, v0
	v_pk_mul_f32 v[32:33], v[146:147], v[22:23]
	v_pk_mul_f32 v[26:27], v[142:143], v[26:27]
	v_pk_mul_f32 v[28:29], v[144:145], v[24:25]
	v_cvt_pk_bf16_f32 v24, v26, v27
	s_waitcnt lgkmcnt(0)
	v_add_f32_e32 v0, v0, v36
	ds_bpermute_b32 v22, v158, v0
	v_cvt_pk_bf16_f32 v25, v34, v35
	v_cvt_pk_bf16_f32 v26, v32, v33
	v_cvt_pk_bf16_f32 v27, v28, v29
	global_store_dwordx4 v[30:31], v[24:27], off offset:256
	s_and_saveexec_b64 s[2:3], s[10:11]
	s_cbranch_execz .LBB0_1294
	s_waitcnt lgkmcnt(0)
	v_add_f32_e32 v0, v0, v22
	v_mul_f32_e32 v0, 0x4b800000, v0
	v_trunc_f32_e32 v0, v0
	v_mul_f32_e32 v22, 0x2f800000, v0
	v_floor_f32_e32 v23, v22
	v_fmac_f32_e32 v0, 0xcf800000, v23
	v_cvt_u32_f32_e32 v22, v0
	v_cvt_u32_f32_e32 v23, v23
	v_ashrrev_i32_e32 v205, 31, v204
	v_lshl_add_u64 v[24:25], v[204:205], 3, s[16:17]
	flat_atomic_add_x2 v[24:25], v[22:23] offset:1280

; __device__ __forceinline__ unsigned cvt_pk_bf16(float lo, float hi) { unsigned r; asm volatile("v_cvt_pk_bf16_f32 %0, %1, %2" : "=v"(r) : "v"(lo), "v"(hi)); return r; }
; #define PG8_GPTR(p) ((__attribute__((address_space(1))) char*)(p))
; #define PG8_GCPTR(p) ((__attribute__((address_space(1))) const char*)(p))
;     __device__ __forceinline__ void operator()(const f32x4 (&acc)[2][2][4][2], const Unit& u, int wr, int wc, int fr, int fq) const {
;     ...
;                     bv[mm][bj] = *(gl_u32x4*)(PG8_GCPTR(base) + (unsigned)((u.pm * BM + ai * HALF + wr * 64 + (mp + mm) * 16 + fr) * DM + col0 + bj * HALF) * 2u);
; #pragma unroll
;             for (int mm = 0; mm < 2; ++mm) {
;                 const int m = mp + mm;
;                 const int row = u.pm * BM + ai * HALF + wr * 64 + m * 16 + fr; float q = 0.f;
; #pragma unroll
;                 for (int bj = 0; bj < 2; ++bj) {
;                     const unsigned offb = (unsigned)(row * DM + col0 + bj * HALF) * 2u;
;                     const u32x4 bw = bv[mm][bj];
;                     const f32x4 b0 = (f32x4){__uint_as_float(bw.x << 16), __uint_as_float(bw.x & 0xffff0000u), __uint_as_float(bw.y << 16), __uint_as_float(bw.y & 0xffff0000u)};
;                     const f32x4 b1 = (f32x4){__uint_as_float(bw.z << 16), __uint_as_float(bw.z & 0xffff0000u), __uint_as_float(bw.w << 16), __uint_as_float(bw.w & 0xffff0000u)};
;                     f32x4 a0 = acc[ai][bj][m][0], a1 = acc[ai][bj][m][1]; if constexpr (GN) { a0 *= rc[ai * 4 + m]; a1 *= rc[ai * 4 + m]; }
;                     const f32x4 o0 = b0 + g[bj][0] * a0, o1 = b1 + g[bj][1] * a1;
;                     u32x4 wo; wo.x = cvt_pk_bf16(o0[0], o0[1]); wo.y = cvt_pk_bf16(o0[2], o0[3]); wo.z = cvt_pk_bf16(o1[0], o1[1]); wo.w = cvt_pk_bf16(o1[2], o1[3]);
;                     *(gs_u32x4*)(PG8_GPTR(out) + offb) = wo;
;                     if (xg) {
;                         const f32x4 h0 = o0 * cf[bj][0], h1 = o1 * cf[bj][1];
;                         u32x4 w; w.x = cvt_pk_bf16(h0[0], h0[1]); w.y = cvt_pk_bf16(h0[2], h0[3]); w.z = cvt_pk_bf16(h1[0], h1[1]); w.w = cvt_pk_bf16(h1[2], h1[3]);
;                         *(gs_u32x4*)(PG8_GPTR(xg) + offb) = w;
;                         q += (o0[0] * o0[0] + o0[1] * o0[1]) + (o0[2] * o0[2] + o0[3] * o0[3]) + (o1[0] * o1[0] + o1[1] * o1[1]) + (o1[2] * o1[2] + o1[3] * o1[3]);
;                     }
.LBB0_1295:
	s_mov_b32 s2, 0x58000
	v_add3_u32 v0, v218, v217, s2
	v_add_u32_e32 v241, s2, v240
	s_waitcnt lgkmcnt(0)
	v_lshlrev_b32_e32 v22, 16, v42
	v_and_b32_e32 v23, 0xffff0000, v42
	v_lshlrev_b32_e32 v24, 16, v43
	v_and_b32_e32 v25, 0xffff0000, v43
	v_lshlrev_b32_e32 v26, 16, v44
	v_and_b32_e32 v27, 0xffff0000, v44
	v_lshlrev_b32_e32 v28, 16, v45
	v_and_b32_e32 v29, 0xffff0000, v45
	v_pk_fma_f32 v[20:21], v[20:21], v[76:77], v[24:25]
	v_pk_fma_f32 v[18:19], v[18:19], v[74:75], v[22:23]
	v_pk_fma_f32 v[12:13], v[12:13], v[72:73], v[28:29]
	v_pk_fma_f32 v[22:23], v[10:11], v[70:71], v[26:27]
	s_and_b64 vcc, exec, s[8:9]
	v_lshl_add_u64 v[10:11], s[12:13], 0, v[0:1]
	v_cvt_pk_bf16_f32 v24, v18, v19
	v_cvt_pk_bf16_f32 v25, v20, v21
	v_cvt_pk_bf16_f32 v26, v22, v23
	v_cvt_pk_bf16_f32 v27, v12, v13
	global_store_dwordx4 v241, v[24:27], s[22:23]
	s_cbranch_vccnz .LBB0_1297
	s_nop 0
	v_pk_mul_f32 v[24:25], v[212:213], v[18:19]
	v_pk_mul_f32 v[26:27], v[210:211], v[20:21]
	v_cvt_pk_bf16_f32 v24, v24, v25
	v_pk_mul_f32 v[20:21], v[20:21], v[20:21]
	v_cvt_pk_bf16_f32 v25, v26, v27
	v_pk_mul_f32 v[18:19], v[18:19], v[18:19]
	v_pk_mul_f32 v[28:29], v[206:207], v[12:13]
	v_pk_mul_f32 v[30:31], v[208:209], v[22:23]
	v_pk_mul_f32 v[12:13], v[12:13], v[12:13]
	v_cvt_pk_bf16_f32 v26, v30, v31
	v_cvt_pk_bf16_f32 v27, v28, v29
	global_store_dwordx4 v[10:11], v[24:27], off
	s_nop 1
	v_mov_b32_e32 v24, v18
	v_mov_b32_e32 v25, v21
	v_pk_mov_b32 v[18:19], v[18:19], v[20:21] op_sel:[1,0]
	v_pk_mul_f32 v[20:21], v[22:23], v[22:23]
	v_pk_add_f32 v[18:19], v[18:19], v[24:25]
	v_mov_b32_e32 v22, v12
	v_mov_b32_e32 v23, v20
	v_mov_b32_e32 v20, v13
	v_pk_add_f32 v[12:13], v[22:23], v[20:21]
	v_add_f32_e32 v18, v18, v19
	v_add_f32_e32 v13, v13, v18
	v_add_f32_e32 v12, v12, v13
	s_branch .LBB0_1298

; __device__ __forceinline__ float shfl_x(float v, int m, int lane) { return __builtin_bit_cast(float, __builtin_amdgcn_ds_bpermute((lane ^ m) << 2, __builtin_bit_cast(int, v))); }
; #define PG8_GPTR(p) ((__attribute__((address_space(1))) char*)(p))
; __device__ __forceinline__ void ssq_put(ssq_t* p, int row, float q, int fr, int fq) {
;     const int lane = fr + 16 * fq;
;     q += shfl_x(q, 16, lane); q += shfl_x(q, 32, lane);
;     if (fq == 0) __hip_atomic_fetch_add(p + row, (ssq_t)(q * SSQ_FX), __ATOMIC_RELAXED, __HIP_MEMORY_SCOPE_AGENT);
; }
;     __device__ __forceinline__ void operator()(const f32x4 (&acc)[2][2][4][2], const Unit& u, int wr, int wc, int fr, int fq) const {
;     ...
;                 for (int bj = 0; bj < 2; ++bj) {
;                     const unsigned offb = (unsigned)(row * DM + col0 + bj * HALF) * 2u;
;                     const u32x4 bw = bv[mm][bj];
;                     const f32x4 b0 = (f32x4){__uint_as_float(bw.x << 16), __uint_as_float(bw.x & 0xffff0000u), __uint_as_float(bw.y << 16), __uint_as_float(bw.y & 0xffff0000u)};
;                     const f32x4 b1 = (f32x4){__uint_as_float(bw.z << 16), __uint_as_float(bw.z & 0xffff0000u), __uint_as_float(bw.w << 16), __uint_as_float(bw.w & 0xffff0000u)};
;                     f32x4 a0 = acc[ai][bj][m][0], a1 = acc[ai][bj][m][1]; if constexpr (GN) { a0 *= rc[ai * 4 + m]; a1 *= rc[ai * 4 + m]; }
;                     const f32x4 o0 = b0 + g[bj][0] * a0, o1 = b1 + g[bj][1] * a1;
;                     u32x4 wo; wo.x = cvt_pk_bf16(o0[0], o0[1]); wo.y = cvt_pk_bf16(o0[2], o0[3]); wo.z = cvt_pk_bf16(o1[0], o1[1]); wo.w = cvt_pk_bf16(o1[2], o1[3]);
;                     *(gs_u32x4*)(PG8_GPTR(out) + offb) = wo;
;                     if (xg) {
;                         const f32x4 h0 = o0 * cf[bj][0], h1 = o1 * cf[bj][1];
;                         u32x4 w; w.x = cvt_pk_bf16(h0[0], h0[1]); w.y = cvt_pk_bf16(h0[2], h0[3]); w.z = cvt_pk_bf16(h1[0], h1[1]); w.w = cvt_pk_bf16(h1[2], h1[3]);
;                         *(gs_u32x4*)(PG8_GPTR(xg) + offb) = w;
;                         q += (o0[0] * o0[0] + o0[1] * o0[1]) + (o0[2] * o0[2] + o0[3] * o0[3]) + (o1[0] * o1[0] + o1[1] * o1[1]) + (o1[2] * o1[2] + o1[3] * o1[3]);
;                     }
;                 }
;                 if (xg) ssq_put(ssq, row, q, fr, fq);
.LBB0_1298:
	v_lshlrev_b32_e32 v18, 16, v38
	v_and_b32_e32 v19, 0xffff0000, v38
	v_lshlrev_b32_e32 v20, 16, v39
	v_and_b32_e32 v21, 0xffff0000, v39
	v_lshlrev_b32_e32 v24, 16, v40
	v_and_b32_e32 v25, 0xffff0000, v40
	v_lshlrev_b32_e32 v26, 16, v41
	v_and_b32_e32 v27, 0xffff0000, v41
	v_lshl_add_u64 v[22:23], s[22:23], 0, v[0:1]
	v_pk_fma_f32 v[8:9], v[8:9], v[68:69], v[20:21]
	v_pk_fma_f32 v[6:7], v[6:7], v[66:67], v[18:19]
	v_pk_fma_f32 v[4:5], v[4:5], v[64:65], v[26:27]
	v_pk_fma_f32 v[2:3], v[2:3], v[62:63], v[24:25]
	s_and_b64 vcc, exec, s[8:9]
	v_cvt_pk_bf16_f32 v18, v6, v7
	v_cvt_pk_bf16_f32 v19, v8, v9
	v_cvt_pk_bf16_f32 v20, v2, v3
	v_cvt_pk_bf16_f32 v21, v4, v5
	global_store_dwordx4 v241, v[18:21], s[22:23] offset:1024
	s_cbranch_vccnz .LBB0_1302
	s_nop 0
	v_pk_mul_f32 v[18:19], v[148:149], v[8:9]
	v_mul_f32_e32 v20, v7, v7
	v_mul_f32_e32 v9, v9, v9
	v_mul_f32_e32 v13, v3, v3
	v_fmac_f32_e32 v20, v6, v6
	v_fmac_f32_e32 v9, v8, v8
	v_mul_f32_e32 v0, v5, v5
	v_fmac_f32_e32 v13, v2, v2
	v_add_f32_e32 v8, v20, v9
	v_fmac_f32_e32 v0, v4, v4
	v_add_f32_e32 v8, v13, v8
	v_add_f32_e32 v0, v0, v8
	v_add_f32_e32 v0, v0, v12
	ds_bpermute_b32 v20, v159, v0
	v_pk_mul_f32 v[12:13], v[146:147], v[2:3]
	v_pk_mul_f32 v[6:7], v[142:143], v[6:7]
	v_pk_mul_f32 v[8:9], v[144:145], v[4:5]
	v_cvt_pk_bf16_f32 v4, v6, v7
	s_waitcnt lgkmcnt(0)
	v_add_f32_e32 v0, v0, v20
	ds_bpermute_b32 v2, v158, v0
	v_cvt_pk_bf16_f32 v5, v18, v19
	v_cvt_pk_bf16_f32 v6, v12, v13
	v_cvt_pk_bf16_f32 v7, v8, v9
	global_store_dwordx4 v[10:11], v[4:7], off offset:256
	s_and_saveexec_b64 s[2:3], s[10:11]
	s_cbranch_execz .LBB0_1301
	s_waitcnt lgkmcnt(0)
	v_add_f32_e32 v0, v0, v2
	v_mul_f32_e32 v0, 0x4b800000, v0
	v_trunc_f32_e32 v0, v0
	v_mul_f32_e32 v2, 0x2f800000, v0
	v_floor_f32_e32 v3, v2
	v_fmac_f32_e32 v0, 0xcf800000, v3
	v_cvt_u32_f32_e32 v2, v0
	v_cvt_u32_f32_e32 v3, v3
	v_ashrrev_i32_e32 v205, 31, v204
	v_lshl_add_u64 v[4:5], v[204:205], 3, s[16:17]
	flat_atomic_add_x2 v[4:5], v[2:3] offset:1408

; __device__ __forceinline__ int opaque_tid(int wave_s) { int l; asm volatile("v_mbcnt_lo_u32_b32 %0, -1, 0\n\tv_mbcnt_hi_u32_b32 %0, -1, %0" : "=v"(l)); return (wave_s << 6) | l; }
; __device__ __forceinline__ float bflo(unsigned w) { return __uint_as_float(w << 16); }
; __device__ __forceinline__ float bfhi(unsigned w) { return __uint_as_float(w & 0xffff0000u); }
; __device__ __forceinline__ void final_norm_pass(const bf16_t* x16, float* out, const float* nw, int vcu, int ngw, const int wave_s) {
;     const int tid_ = opaque_tid(wave_s), lane = tid_ & 63, gw = vcu * NWAVES + (tid_ >> 6);
;     f32x4 wv[4];
; #pragma unroll
;     for (int j = 0; j < 4; ++j) wv[j] = *(const f32x4*)(nw + 16 * lane + 4 * j);
;     for (int m0 = 4 * gw; m0 < MTOK; m0 += 4 * ngw) {
;         u32x4 a[4], b[4];
; #pragma unroll
;         for (int i = 0; i < 4; ++i) { const u32x4* xr = (const u32x4*)(x16 + (size_t)(m0 + i) * DM + 16 * lane); a[i] = xr[0]; b[i] = xr[1]; }
; #pragma unroll
;         for (int i = 0; i < 4; ++i) {
;             f32x4 v[4];
;             v[0] = (f32x4){bflo(a[i].x), bfhi(a[i].x), bflo(a[i].y), bfhi(a[i].y)}; v[1] = (f32x4){bflo(a[i].z), bfhi(a[i].z), bflo(a[i].w), bfhi(a[i].w)};
;             v[2] = (f32x4){bflo(b[i].x), bfhi(b[i].x), bflo(b[i].y), bfhi(b[i].y)}; v[3] = (f32x4){bflo(b[i].z), bfhi(b[i].z), bflo(b[i].w), bfhi(b[i].w)};
;             float s = 0.f;
; #pragma unroll
;             for (int j = 0; j < 4; ++j) s += (v[j].x * v[j].x + v[j].y * v[j].y) + (v[j].z * v[j].z + v[j].w * v[j].w);
;             const float rstd = 1.0f / sqrtf(wave_sum(s, lane) * (1.0f / DM) + EPS);
;             f32x4* orow = (f32x4*)(out + (size_t)(m0 + i) * DM + 16 * lane);
; #pragma unroll
;             for (int j = 0; j < 4; ++j) orow[j] = v[j] * rstd * wv[j];
;         }
.LBB0_1351:
	v_readlane_b32 s7, v255, 4
	v_mbcnt_lo_u32_b32 v0, -1, 0
	v_mbcnt_hi_u32_b32 v0, -1, v0
	s_nop 1
	v_or_b32_e32 v1, s7, v0
	v_ashrrev_i32_e32 v1, 4, v1
	v_and_b32_e32 v1, -4, v1
	v_lshl_add_u32 v16, s6, 5, v1
	s_mov_b32 s6, 0x10000
	v_cmp_gt_i32_e32 vcc, s6, v16
	s_and_saveexec_b64 s[6:7], vcc
	s_cbranch_execz .LBB0_1354
	v_and_b32_e32 v22, 63, v0
	v_lshlrev_b32_e32 v20, 6, v22
	s_waitcnt lgkmcnt(0)
	global_load_dwordx4 v[0:3], v20, s[0:1] offset:48
	global_load_dwordx4 v[4:7], v20, s[0:1] offset:32
	global_load_dwordx4 v[8:11], v20, s[0:1] offset:16
	global_load_dwordx4 v[12:15], v20, s[0:1]
	v_lshlrev_b32_e32 v17, 2, v22
	v_xor_b32_e32 v110, 4, v17
	v_xor_b32_e32 v111, 8, v17
	v_xor_b32_e32 v112, 16, v17
	v_xor_b32_e32 v113, 32, v17
	v_xor_b32_e32 v114, 64, v17
	v_xor_b32_e32 v115, 0x80, v17
	v_ashrrev_i32_e32 v17, 31, v16
	v_lshlrev_b64 v[18:19], 12, v[16:17]
	v_or_b32_e32 v18, v18, v20
	v_lshlrev_b64 v[20:21], 11, v[16:17]
	s_lshl_b32 s10, s38, 5
	v_lshl_add_u64 v[18:19], s[4:5], 0, v[18:19]
	s_mov_b64 s[0:1], 0x3030
	v_lshl_or_b32 v20, v22, 5, v20
	v_lshl_add_u64 v[18:19], v[18:19], 0, s[0:1]
	s_ashr_i32 s11, s10, 31
	v_lshl_add_u64 v[20:21], s[2:3], 0, v[20:21]
	s_mov_b64 s[0:1], 0x8001810
	s_lshl_b64 s[12:13], s[10:11], 12
	v_lshl_add_u64 v[20:21], v[20:21], 0, s[0:1]
	s_lshl_b64 s[14:15], s[10:11], 11
	s_mov_b64 s[16:17], 0
	s_movk_i32 s11, 0xeff0
	s_movk_i32 s18, 0xf000
	v_mov_b32_e32 v17, 0x358637bd
	s_mov_b32 s19, 0xf800000
	v_mov_b32_e32 v116, 0x260
	s_movk_i32 s20, 0xcfd0
	s_movk_i32 s21, 0xcfe0
	s_movk_i32 s22, 0xcff0
	s_movk_i32 s23, 0xd000
	s_movk_i32 s24, 0xdfd0
	s_movk_i32 s25, 0xdfe0
	s_movk_i32 s26, 0xdff0
	s_movk_i32 s27, 0xe000
	s_movk_i32 s28, 0xefd0
	s_movk_i32 s29, 0xefe0
	s_movk_i32 s30, 0xffd0
	s_movk_i32 s31, 0xffe0
	s_mov_b32 s33, 0xffff
	v_mbcnt_lo_u32_b32 v160, -1, 0
	v_mbcnt_hi_u32_b32 v160, -1, v160
	v_lshrrev_b32_e32 v161, 1, v160
	v_and_b32_e32 v162, 24, v161
	v_and_b32_e32 v163, 3, v161
	v_lshl_or_b32 v162, v163, 1, v162
	v_bfe_u32 v163, v161, 2, 1
	v_or_b32_e32 v162, v162, v163
	v_lshlrev_b32_e32 v162, 10, v162
	v_and_b32_e32 v163, 1, v160
	v_lshl_or_b32 v162, v163, 5, v162
	v_and_b32_e32 v163, 15, v16
	v_mul_u32_u24_e32 v163, 0x7c0, v163
	v_lshlrev_b32_e32 v161, 5, v160
	v_sub_u32_e32 v162, v162, v161
	v_sub_u32_e32 v162, v162, v163
	v_add_u32_e32 v162, 0xffffe7f0, v162
	v_ashrrev_i32_e32 v163, 31, v162
.LBB0_1353:
	v_lshl_add_u64 v[164:165], v[20:21], 0, v[162:163]
	v_add_co_u32_e32 v38, vcc, 0xffffe7f0, v20
	v_add_co_u32_e64 v40, s[0:1], -16, v20
	s_nop 0
	v_addc_co_u32_e32 v39, vcc, -1, v21, vcc
	v_addc_co_u32_e64 v41, s[0:1], -1, v21, s[0:1]
	flat_load_dwordx4 v[64:67], v[164:165] offset:208
	flat_load_dwordx4 v[58:61], v[164:165] offset:192
	v_add_co_u32_e32 v40, vcc, 0xffffe800, v20
	flat_load_dwordx4 v[70:73], v[164:165] offset:0
	s_nop 0
	v_addc_co_u32_e32 v41, vcc, -1, v21, vcc
	v_add_co_u32_e32 v38, vcc, 0xffffeff0, v20
	flat_load_dwordx4 v[78:81], v[164:165] offset:16
	s_nop 0
	v_addc_co_u32_e32 v39, vcc, -1, v21, vcc
	v_add_co_u32_e32 v40, vcc, 0xfffff000, v20
	flat_load_dwordx4 v[90:93], v[164:165] offset:64
	s_nop 0
	v_addc_co_u32_e32 v41, vcc, -1, v21, vcc
	v_add_co_u32_e32 v38, vcc, 0xfffff7f0, v20
	flat_load_dwordx4 v[96:99], v[164:165] offset:80
	s_nop 0
	v_addc_co_u32_e32 v39, vcc, -1, v21, vcc
	v_add_co_u32_e32 v40, vcc, 0xfffff800, v20
	v_add_co_u32_e64 v22, s[0:1], s20, v18
	s_nop 0
	v_addc_co_u32_e32 v41, vcc, -1, v21, vcc
	flat_load_dwordx4 v[100:103], v[164:165] offset:128
	flat_load_dwordx4 v[118:121], v[164:165] offset:144
	v_addc_co_u32_e64 v23, s[0:1], -1, v19, s[0:1]
	v_add_co_u32_e64 v24, s[0:1], s21, v18
	v_add_u32_e32 v16, s10, v16
	s_nop 0
	v_addc_co_u32_e64 v25, s[0:1], -1, v19, s[0:1]
	v_add_co_u32_e64 v26, s[0:1], s22, v18
	v_lshl_add_u64 v[20:21], v[20:21], 0, s[14:15]
	s_nop 0
	v_addc_co_u32_e64 v27, s[0:1], -1, v19, s[0:1]
	v_add_co_u32_e64 v28, s[0:1], s23, v18
	s_waitcnt vmcnt(0) lgkmcnt(0)
	v_lshlrev_b32_e32 v62, 16, v64
	v_lshlrev_b32_e32 v56, 16, v58
	v_and_b32_e32 v57, 0xffff0000, v58
	v_lshlrev_b32_e32 v58, 16, v59
	v_lshlrev_b32_e32 v68, 16, v70
	v_and_b32_e32 v69, 0xffff0000, v70
	v_lshlrev_b32_e32 v70, 16, v71
	v_lshlrev_b32_e32 v83, 16, v61
	v_lshlrev_b32_e32 v82, 16, v60
	v_and_b32_e32 v61, 0xffff0000, v61
	v_and_b32_e32 v60, 0xffff0000, v60
	v_and_b32_e32 v63, 0xffff0000, v64
	v_lshlrev_b32_e32 v64, 16, v65
	v_and_b32_e32 v71, 0xffff0000, v71
	v_lshlrev_b32_e32 v95, 16, v73
	v_lshlrev_b32_e32 v94, 16, v72
	v_and_b32_e32 v73, 0xffff0000, v73
	v_and_b32_e32 v72, 0xffff0000, v72
	v_lshlrev_b32_e32 v74, 16, v80
	v_and_b32_e32 v135, 0xffff0000, v80
	v_mul_f32_e32 v80, v68, v68
	v_mul_f32_e32 v128, v70, v70
	v_and_b32_e32 v59, 0xffff0000, v59
	v_and_b32_e32 v65, 0xffff0000, v65
	v_mul_f32_e32 v104, v56, v56
	v_mul_f32_e32 v106, v58, v58
	v_pk_mul_f32 v[108:109], v[60:61], v[60:61]
	v_mul_f32_e32 v122, v62, v62
	v_mul_f32_e32 v124, v64, v64
	v_pk_mul_f32 v[130:131], v[72:73], v[72:73]
	v_lshlrev_b32_e32 v84, 16, v78
	v_lshlrev_b32_e32 v86, 16, v79
	v_pk_fma_f32 v[132:133], v[68:69], v[68:69], v[80:81] op_sel_hi:[1,1,0]
	v_pk_fma_f32 v[128:129], v[70:71], v[70:71], v[128:129] op_sel_hi:[1,1,0]
	v_lshlrev_b32_e32 v38, 16, v66
	v_lshlrev_b32_e32 v40, 16, v67
	v_and_b32_e32 v41, 0xffff0000, v67
	v_and_b32_e32 v85, 0xffff0000, v78
	v_and_b32_e32 v87, 0xffff0000, v79
	v_mov_b32_e32 v88, v94
	v_mov_b32_e32 v89, v72
	v_mov_b32_e32 v72, v95
	v_pk_fma_f32 v[104:105], v[56:57], v[56:57], v[104:105] op_sel_hi:[1,1,0]
	v_pk_fma_f32 v[106:107], v[58:59], v[58:59], v[106:107] op_sel_hi:[1,1,0]
	v_pk_fma_f32 v[108:109], v[82:83], v[82:83], v[108:109]
; __device__ __forceinline__ float shfl_x(float v, int m, int lane) { return __builtin_bit_cast(float, __builtin_amdgcn_ds_bpermute((lane ^ m) << 2, __builtin_bit_cast(int, v))); }
; __device__ __forceinline__ float wave_sum(float v, int lane) {
; #pragma unroll
;     for (int o = 1; o < 64; o <<= 1) v += shfl_x(v, o, lane);
;     return v;
; __device__ __forceinline__ void final_norm_pass(const bf16_t* x16, float* out, const float* nw, int vcu, int ngw, const int wave_s) {
;     ...
;             float s = 0.f;
; #pragma unroll
;             for (int j = 0; j < 4; ++j) s += (v[j].x * v[j].x + v[j].y * v[j].y) + (v[j].z * v[j].z + v[j].w * v[j].w);
;             const float rstd = 1.0f / sqrtf(wave_sum(s, lane) * (1.0f / DM) + EPS);
	v_pk_fma_f32 v[122:123], v[62:63], v[62:63], v[122:123] op_sel_hi:[1,1,0]
	v_pk_fma_f32 v[124:125], v[64:65], v[64:65], v[124:125] op_sel_hi:[1,1,0]
	v_pk_fma_f32 v[94:95], v[94:95], v[94:95], v[130:131]
	v_mul_f32_e32 v130, v84, v84
	v_mul_f32_e32 v134, v86, v86
	v_lshlrev_b32_e32 v78, 16, v90
	v_lshlrev_b32_e32 v80, 16, v91
	v_mov_b32_e32 v137, v129
	v_pk_add_f32 v[128:129], v[132:133], v[128:129]
	v_mov_b32_e32 v126, v38
	v_lshlrev_b32_e32 v76, 16, v81
	v_and_b32_e32 v77, 0xffff0000, v81
	v_mov_b32_e32 v136, v74
	v_and_b32_e32 v79, 0xffff0000, v90
	v_and_b32_e32 v81, 0xffff0000, v91
	v_pk_add_f32 v[140:141], v[108:109], v[108:109] op_sel_hi:[0,1]
	v_mul_f32_e32 v122, v40, v40
	v_mul_f32_e32 v124, v41, v41
	v_mov_b32_e32 v39, v105
	v_mov_b32_e32 v127, v107
	v_pk_add_f32 v[90:91], v[104:105], v[106:107]
	v_pk_add_f32 v[142:143], v[94:95], v[94:95] op_sel_hi:[0,1]
	v_pk_fma_f32 v[106:107], v[84:85], v[84:85], v[130:131] op_sel_hi:[1,1,0]
	v_pk_fma_f32 v[108:109], v[86:87], v[86:87], v[134:135] op_sel_hi:[1,1,0]
	v_mov_b32_e32 v75, v133
	v_mul_f32_e32 v128, v78, v78
	v_mul_f32_e32 v130, v80, v80
	v_and_b32_e32 v117, 0xffff0000, v66
	v_mov_b32_e32 v66, v82
	v_mov_b32_e32 v67, v60
	v_mov_b32_e32 v60, v83
	v_and_b32_e32 v83, 0xffff0000, v93
	v_and_b32_e32 v82, 0xffff0000, v92
	v_lshlrev_b32_e32 v90, 16, v98
	v_and_b32_e32 v154, 0xffff0000, v98
	v_lshlrev_b32_e32 v94, 16, v96
	v_lshlrev_b32_e32 v98, 16, v97
	v_pk_mul_f32 v[126:127], v[38:39], v[126:127]
	v_pk_add_f32 v[122:123], v[122:123], v[124:125]
	v_mul_f32_e32 v142, v135, v135
	v_mul_f32_e32 v106, v76, v76
	v_mul_f32_e32 v108, v77, v77
	v_pk_mul_f32 v[124:125], v[74:75], v[136:137]
	v_mov_b32_e32 v75, v135
	v_pk_fma_f32 v[134:135], v[78:79], v[78:79], v[128:129] op_sel_hi:[1,1,0]
	v_pk_fma_f32 v[130:131], v[80:81], v[80:81], v[130:131] op_sel_hi:[1,1,0]
	v_lshlrev_b32_e32 v139, 16, v93
	v_lshlrev_b32_e32 v138, 16, v92
	v_lshlrev_b32_e32 v92, 16, v99
	v_and_b32_e32 v93, 0xffff0000, v99
	v_pk_mul_f32 v[132:133], v[82:83], v[82:83]
	v_and_b32_e32 v95, 0xffff0000, v96
	v_and_b32_e32 v99, 0xffff0000, v97
	v_mul_f32_e32 v140, v117, v117
	v_mul_f32_e32 v128, v94, v94
	v_mul_f32_e32 v136, v98, v98
	v_lshlrev_b32_e32 v96, 16, v100
	v_and_b32_e32 v97, 0xffff0000, v100
	v_lshlrev_b32_e32 v100, 16, v101
	v_lshlrev_b32_e32 v145, 16, v103
	v_lshlrev_b32_e32 v144, 16, v102
	v_and_b32_e32 v103, 0xffff0000, v103
	v_and_b32_e32 v102, 0xffff0000, v102
	v_mov_b32_e32 v127, v91
	v_pk_add_f32 v[146:147], v[106:107], v[108:109]
	v_pk_add_f32 v[106:107], v[134:135], v[130:131]
	v_mov_b32_e32 v104, v138
	v_mov_b32_e32 v105, v82
	v_mov_b32_e32 v82, v139
	v_mov_b32_e32 v39, v117
	v_pk_fma_f32 v[132:133], v[138:139], v[138:139], v[132:133]
	v_mov_b32_e32 v138, v90
	v_and_b32_e32 v101, 0xffff0000, v101
	v_mov_b32_e32 v125, v129
	v_pk_fma_f32 v[128:129], v[94:95], v[94:95], v[128:129] op_sel_hi:[1,1,0]
	v_pk_fma_f32 v[136:137], v[98:99], v[98:99], v[136:137] op_sel_hi:[1,1,0]
	v_mov_b32_e32 v91, v135
	v_mov_b32_e32 v139, v131
	v_lshlrev_b32_e32 v106, 16, v120
	v_and_b32_e32 v117, 0xffff0000, v120
	v_mul_f32_e32 v120, v96, v96
	v_mul_f32_e32 v130, v100, v100
	v_pk_mul_f32 v[134:135], v[102:103], v[102:103]
	v_lshlrev_b32_e32 v148, 16, v118
	v_and_b32_e32 v149, 0xffff0000, v118
	v_lshlrev_b32_e32 v150, 16, v119
	v_and_b32_e32 v151, 0xffff0000, v119
	v_pk_add_f32 v[118:119], v[126:127], v[140:141]
	v_pk_add_f32 v[132:133], v[132:133], v[132:133] op_sel_hi:[0,1]
	v_lshlrev_b32_e32 v108, 16, v121
	v_and_b32_e32 v109, 0xffff0000, v121
	v_pk_add_f32 v[124:125], v[124:125], v[142:143]
	v_mul_f32_e32 v128, v92, v92
	v_mul_f32_e32 v136, v93, v93
	v_pk_mul_f32 v[126:127], v[90:91], v[138:139]
	v_pk_fma_f32 v[120:121], v[96:97], v[96:97], v[120:121] op_sel_hi:[1,1,0]
	v_pk_fma_f32 v[130:131], v[100:101], v[100:101], v[130:131] op_sel_hi:[1,1,0]
	v_pk_fma_f32 v[134:135], v[144:145], v[144:145], v[134:135]
	v_pk_add_f32 v[118:119], v[118:119], v[122:123]
	v_mul_f32_e32 v132, v154, v154
	v_mul_f32_e32 v138, v148, v148
	v_mul_f32_e32 v140, v150, v150
	v_mov_b32_e32 v142, v106
	v_pk_add_f32 v[122:123], v[124:125], v[146:147]
	v_mov_b32_e32 v127, v107
	v_pk_add_f32 v[124:125], v[128:129], v[136:137]
	v_pk_add_f32 v[128:129], v[134:135], v[134:135] op_sel_hi:[0,1]
	v_mov_b32_e32 v107, v121
	v_mov_b32_e32 v143, v131
	v_pk_add_f32 v[120:121], v[120:121], v[130:131]
	v_add_f32_e32 v130, v118, v119
	v_pk_fma_f32 v[134:135], v[148:149], v[148:149], v[138:139] op_sel_hi:[1,1,0]
	v_pk_fma_f32 v[136:137], v[150:151], v[150:151], v[140:141] op_sel_hi:[1,1,0]
	v_add_f32_e32 v131, v122, v123
	v_pk_add_f32 v[118:119], v[126:127], v[132:133]
	v_mul_f32_e32 v128, v117, v117
	v_pk_mul_f32 v[122:123], v[106:107], v[142:143]
	v_mov_b32_e32 v107, v117
	ds_bpermute_b32 v117, v110, v130
	v_mul_f32_e32 v134, v108, v108
	v_mul_f32_e32 v136, v109, v109
	ds_bpermute_b32 v126, v110, v131
	v_pk_add_f32 v[118:119], v[118:119], v[124:125]
	v_mov_b32_e32 v123, v121
	v_pk_add_f32 v[120:121], v[134:135], v[136:137]
	v_add_f32_e32 v124, v118, v119
	v_pk_add_f32 v[118:119], v[122:123], v[128:129]
	ds_bpermute_b32 v122, v110, v124
	v_pk_add_f32 v[118:119], v[118:119], v[120:121]
	s_waitcnt lgkmcnt(2)
	v_add_f32_e32 v117, v130, v117
	v_add_f32_e32 v118, v118, v119
	ds_bpermute_b32 v119, v110, v118
	s_waitcnt lgkmcnt(2)
	v_add_f32_e32 v120, v131, v126
	ds_bpermute_b32 v121, v111, v117
	ds_bpermute_b32 v123, v111, v120
	s_waitcnt lgkmcnt(3)
	v_add_f32_e32 v122, v124, v122
	ds_bpermute_b32 v124, v111, v122
	s_waitcnt lgkmcnt(3)
	v_add_f32_e32 v118, v118, v119
	ds_bpermute_b32 v119, v111, v118
	s_waitcnt lgkmcnt(3)
	v_add_f32_e32 v117, v117, v121
	s_waitcnt lgkmcnt(2)
; __device__ __forceinline__ float shfl_x(float v, int m, int lane) { return __builtin_bit_cast(float, __builtin_amdgcn_ds_bpermute((lane ^ m) << 2, __builtin_bit_cast(int, v))); }
; __device__ __forceinline__ float wave_sum(float v, int lane) {
; #pragma unroll
;     for (int o = 1; o < 64; o <<= 1) v += shfl_x(v, o, lane);
;     return v;
; __device__ __forceinline__ void final_norm_pass(const bf16_t* x16, float* out, const float* nw, int vcu, int ngw, const int wave_s) {
;     ...
;             float s = 0.f;
; #pragma unroll
;             for (int j = 0; j < 4; ++j) s += (v[j].x * v[j].x + v[j].y * v[j].y) + (v[j].z * v[j].z + v[j].w * v[j].w);
;             const float rstd = 1.0f / sqrtf(wave_sum(s, lane) * (1.0f / DM) + EPS);
	v_add_f32_e32 v120, v120, v123
	ds_bpermute_b32 v121, v112, v117
	ds_bpermute_b32 v123, v112, v120
	v_addc_co_u32_e64 v29, s[0:1], -1, v19, s[0:1]
	s_waitcnt lgkmcnt(3)
	v_add_f32_e32 v122, v122, v124
	v_add_co_u32_e64 v30, s[0:1], s24, v18
	ds_bpermute_b32 v124, v112, v122
	s_nop 0
	v_addc_co_u32_e64 v31, s[0:1], -1, v19, s[0:1]
	s_waitcnt lgkmcnt(3)
	v_add_f32_e32 v118, v118, v119
	v_add_co_u32_e64 v32, s[0:1], s25, v18
	ds_bpermute_b32 v119, v112, v118
	s_waitcnt lgkmcnt(3)
	v_add_f32_e32 v117, v117, v121
	v_addc_co_u32_e64 v33, s[0:1], -1, v19, s[0:1]
	s_waitcnt lgkmcnt(2)
	v_add_f32_e32 v120, v120, v123
	ds_bpermute_b32 v121, v113, v117
	v_add_co_u32_e64 v34, s[0:1], s26, v18
	ds_bpermute_b32 v123, v113, v120
	s_nop 0
	v_addc_co_u32_e64 v35, s[0:1], -1, v19, s[0:1]
	s_waitcnt lgkmcnt(3)
	v_add_f32_e32 v122, v122, v124
	v_add_co_u32_e64 v36, s[0:1], s27, v18
	ds_bpermute_b32 v124, v113, v122
	s_nop 0
	v_addc_co_u32_e64 v37, s[0:1], -1, v19, s[0:1]
	s_waitcnt lgkmcnt(3)
	v_add_f32_e32 v118, v118, v119
	v_add_co_u32_e64 v42, s[0:1], s28, v18
	ds_bpermute_b32 v119, v113, v118
	s_waitcnt lgkmcnt(3)
	v_add_f32_e32 v117, v117, v121
	v_addc_co_u32_e64 v43, s[0:1], -1, v19, s[0:1]
	s_waitcnt lgkmcnt(2)
	v_add_f32_e32 v120, v120, v123
	ds_bpermute_b32 v121, v114, v117
	v_add_co_u32_e64 v44, s[0:1], s29, v18
	ds_bpermute_b32 v123, v114, v120
	s_nop 0
	v_addc_co_u32_e64 v45, s[0:1], -1, v19, s[0:1]
	s_waitcnt lgkmcnt(3)
	v_add_f32_e32 v122, v122, v124
	v_add_co_u32_e64 v46, s[0:1], s11, v18
	ds_bpermute_b32 v124, v114, v122
	s_nop 0
	v_addc_co_u32_e64 v47, s[0:1], -1, v19, s[0:1]
	s_waitcnt lgkmcnt(3)
	v_add_f32_e32 v118, v118, v119
	v_add_co_u32_e64 v48, s[0:1], s18, v18
	ds_bpermute_b32 v119, v114, v118
	s_waitcnt lgkmcnt(3)
	v_add_f32_e32 v117, v117, v121
	v_addc_co_u32_e64 v49, s[0:1], -1, v19, s[0:1]
	s_waitcnt lgkmcnt(2)
	v_add_f32_e32 v120, v120, v123
	ds_bpermute_b32 v121, v115, v117
	v_add_co_u32_e64 v50, s[0:1], s30, v18
	ds_bpermute_b32 v123, v115, v120
	s_nop 0
	v_addc_co_u32_e64 v51, s[0:1], -1, v19, s[0:1]
	s_waitcnt lgkmcnt(3)
	v_add_f32_e32 v122, v122, v124
	v_add_co_u32_e64 v52, s[0:1], s31, v18
	ds_bpermute_b32 v124, v115, v122
	s_nop 0
	v_addc_co_u32_e64 v53, s[0:1], -1, v19, s[0:1]
	s_waitcnt lgkmcnt(3)
	v_add_f32_e32 v118, v118, v119
	v_add_co_u32_e64 v54, s[0:1], -16, v18
	ds_bpermute_b32 v119, v115, v118
	s_waitcnt lgkmcnt(3)
	v_add_f32_e32 v117, v117, v121
	v_addc_co_u32_e64 v55, s[0:1], -1, v19, s[0:1]
	s_waitcnt lgkmcnt(2)
	v_add_f32_e32 v120, v120, v123
	v_fmamk_f32 v117, v117, 0x3a800000, v17
	v_cmp_lt_i32_e64 s[0:1], s33, v16
	v_fmamk_f32 v120, v120, 0x3a800000, v17
	v_mul_f32_e32 v121, 0x4f800000, v117
	v_cmp_gt_f32_e32 vcc, s19, v117
	s_or_b64 s[16:17], s[0:1], s[16:17]
	v_mul_f32_e32 v123, 0x4f800000, v120
	s_waitcnt lgkmcnt(1)
	v_add_f32_e32 v122, v122, v124
	v_cndmask_b32_e32 v117, v117, v121, vcc
	v_cmp_gt_f32_e64 s[0:1], s19, v120
	v_fmamk_f32 v121, v122, 0x3a800000, v17
	v_sqrt_f32_e32 v122, v117
	v_cndmask_b32_e64 v120, v120, v123, s[0:1]
	v_sqrt_f32_e32 v123, v120
	v_mul_f32_e32 v124, 0x4f800000, v121
	s_waitcnt lgkmcnt(0)
	v_add_f32_e32 v118, v118, v119
	v_cmp_gt_f32_e64 s[2:3], s19, v121
	v_fmamk_f32 v118, v118, 0x3a800000, v17
	v_cmp_gt_f32_e64 s[4:5], s19, v118
	v_cndmask_b32_e64 v119, v121, v124, s[2:3]
	v_sqrt_f32_e32 v121, v119
	v_mul_f32_e32 v124, 0x4f800000, v118
	v_cndmask_b32_e64 v118, v118, v124, s[4:5]
	v_add_u32_e32 v124, -1, v122
	v_add_u32_e32 v125, 1, v122
	v_add_u32_e32 v126, -1, v123
	v_fma_f32 v129, -v124, v122, v117
	v_add_u32_e32 v127, 1, v123
	v_sqrt_f32_e32 v128, v118
	v_fma_f32 v130, -v125, v122, v117
	v_fma_f32 v131, -v126, v123, v120
	v_cmp_ge_f32_e64 s[6:7], 0, v129
	v_fma_f32 v132, -v127, v123, v120
	v_cmp_ge_f32_e64 s[8:9], 0, v131
	v_cndmask_b32_e64 v122, v122, v124, s[6:7]
	v_cmp_lt_f32_e64 s[6:7], 0, v130
	v_add_u32_e32 v124, -1, v121
	v_cndmask_b32_e64 v123, v123, v126, s[8:9]
	v_add_u32_e32 v126, 1, v121
	v_cndmask_b32_e64 v122, v122, v125, s[6:7]
	v_cmp_lt_f32_e64 s[6:7], 0, v132
	v_fma_f32 v125, -v124, v121, v119
	v_mul_f32_e32 v129, 0x37800000, v122
	v_cndmask_b32_e64 v123, v123, v127, s[6:7]
	v_fma_f32 v127, -v126, v121, v119
	v_cmp_ge_f32_e64 s[6:7], 0, v125
	v_mul_f32_e32 v130, 0x37800000, v123
	v_cndmask_b32_e32 v122, v122, v129, vcc
	v_cndmask_b32_e64 v121, v121, v124, s[6:7]
	v_cmp_lt_f32_e64 s[6:7], 0, v127
	v_add_u32_e32 v124, -1, v128
	v_cmp_class_f32_e32 vcc, v117, v116
	v_add_u32_e32 v125, 1, v128
	v_cndmask_b32_e64 v123, v123, v130, s[0:1]
	v_cndmask_b32_e64 v121, v121, v126, s[6:7]
	v_fma_f32 v126, -v124, v128, v118
	v_cndmask_b32_e32 v117, v122, v117, vcc
	v_cmp_class_f32_e32 vcc, v120, v116
	v_fma_f32 v127, -v125, v128, v118
	v_mul_f32_e32 v122, 0x37800000, v121
	v_cndmask_b32_e32 v120, v123, v120, vcc
	v_cmp_ge_f32_e32 vcc, 0, v126
	v_cndmask_b32_e64 v121, v121, v122, s[2:3]
	v_cmp_class_f32_e64 s[2:3], v119, v116
	v_cndmask_b32_e32 v123, v128, v124, vcc
	v_cmp_lt_f32_e32 vcc, 0, v127
	v_div_scale_f32 v124, s[0:1], v117, v117, 1.0
	v_div_scale_f32 v127, s[6:7], v120, v120, 1.0
	v_cndmask_b32_e32 v122, v123, v125, vcc
	v_rcp_f32_e32 v125, v124
	v_rcp_f32_e32 v123, v127
	v_cndmask_b32_e64 v129, v121, v119, s[2:3]
	v_mul_f32_e32 v119, 0x37800000, v122
	v_div_scale_f32 v121, s[2:3], v129, v129, 1.0
	v_cndmask_b32_e64 v119, v122, v119, s[4:5]
	v_cmp_class_f32_e32 vcc, v118, v116
	v_rcp_f32_e32 v131, v121
	v_div_scale_f32 v126, s[0:1], 1.0, v117, 1.0
	v_cndmask_b32_e32 v132, v119, v118, vcc
; __device__ __forceinline__ void final_norm_pass(const bf16_t* x16, float* out, const float* nw, int vcu, int ngw, const int wave_s) {
;     ...
;             const float rstd = 1.0f / sqrtf(wave_sum(s, lane) * (1.0f / DM) + EPS);
;             f32x4* orow = (f32x4*)(out + (size_t)(m0 + i) * DM + 16 * lane);
; #pragma unroll
;             for (int j = 0; j < 4; ++j) orow[j] = v[j] * rstd * wv[j];
;         }
	v_div_scale_f32 v133, s[4:5], v132, v132, 1.0
	v_fma_f32 v118, -v124, v125, 1.0
	v_fma_f32 v119, -v127, v123, 1.0
	v_rcp_f32_e32 v135, v133
	v_div_scale_f32 v128, s[6:7], 1.0, v120, 1.0
	v_fmac_f32_e32 v125, v118, v125
	v_fmac_f32_e32 v123, v119, v123
	v_mul_f32_e32 v136, v126, v125
	v_mul_f32_e32 v118, v128, v123
	v_fma_f32 v119, -v121, v131, 1.0
	v_div_scale_f32 v130, s[2:3], 1.0, v129, 1.0
	v_fma_f32 v122, -v124, v136, v126
	v_fma_f32 v137, -v127, v118, v128
	v_fmac_f32_e32 v131, v119, v131
	v_fmac_f32_e32 v136, v122, v125
	v_fmac_f32_e32 v118, v137, v123
	v_mul_f32_e32 v119, v130, v131
	v_fma_f32 v122, -v133, v135, 1.0
	v_div_scale_f32 v134, s[4:5], 1.0, v132, 1.0
	v_fma_f32 v124, -v124, v136, v126
	v_fma_f32 v126, -v127, v118, v128
	v_fma_f32 v127, -v121, v119, v130
	v_fmac_f32_e32 v135, v122, v135
	s_mov_b64 vcc, s[6:7]
	v_div_fmas_f32 v118, v126, v123, v118
	v_fmac_f32_e32 v119, v127, v131
	v_mul_f32_e32 v126, v134, v135
	v_div_fixup_f32 v118, v118, v120, 1.0
	v_fma_f32 v120, -v121, v119, v130
	v_fma_f32 v121, -v133, v126, v134
	s_mov_b64 vcc, s[2:3]
	v_pk_mul_f32 v[68:69], v[118:119], v[68:69] op_sel_hi:[0,1]
	v_pk_mul_f32 v[70:71], v[118:119], v[70:71] op_sel_hi:[0,1]
	v_pk_mul_f32 v[88:89], v[118:119], v[88:89] op_sel_hi:[0,1]
	v_pk_mul_f32 v[72:73], v[118:119], v[72:73] op_sel_hi:[0,1]
	v_pk_mul_f32 v[76:77], v[76:77], v[118:119] op_sel_hi:[1,0]
	v_div_fmas_f32 v127, v120, v131, v119
	v_fmac_f32_e32 v126, v121, v135
	v_mov_b32_e32 v91, v154
	v_pk_mul_f32 v[84:85], v[118:119], v[84:85] op_sel_hi:[0,1]
	v_pk_mul_f32 v[86:87], v[118:119], v[86:87] op_sel_hi:[0,1]
	v_pk_mul_f32 v[122:123], v[74:75], v[118:119] op_sel_hi:[1,0]
	v_pk_mul_f32 v[70:71], v[14:15], v[70:71]
	v_pk_mul_f32 v[68:69], v[12:13], v[68:69]
	v_pk_mul_f32 v[74:75], v[10:11], v[72:73]
	v_pk_mul_f32 v[72:73], v[8:9], v[88:89]
	v_pk_mul_f32 v[120:121], v[2:3], v[76:77]
	v_div_fixup_f32 v76, v127, v129, 1.0
	v_fma_f32 v77, -v133, v126, v134
	s_mov_b64 vcc, s[4:5]
	v_pk_mul_f32 v[86:87], v[6:7], v[86:87]
	v_pk_mul_f32 v[84:85], v[4:5], v[84:85]
	v_pk_mul_f32 v[118:119], v[0:1], v[122:123]
	flat_store_dwordx4 v[22:23], v[68:71]
	flat_store_dwordx4 v[24:25], v[72:75]
	flat_store_dwordx4 v[26:27], v[84:87]
	flat_store_dwordx4 v[28:29], v[118:121]
	v_pk_mul_f32 v[22:23], v[76:77], v[78:79] op_sel_hi:[0,1]
	v_pk_mul_f32 v[24:25], v[76:77], v[80:81] op_sel_hi:[0,1]
	v_pk_mul_f32 v[26:27], v[76:77], v[104:105] op_sel_hi:[0,1]
	v_pk_mul_f32 v[28:29], v[76:77], v[82:83] op_sel_hi:[0,1]
	v_pk_mul_f32 v[68:69], v[76:77], v[94:95] op_sel_hi:[0,1]
	v_pk_mul_f32 v[70:71], v[76:77], v[98:99] op_sel_hi:[0,1]
	v_pk_mul_f32 v[72:73], v[90:91], v[76:77] op_sel_hi:[1,0]
	v_pk_mul_f32 v[74:75], v[92:93], v[76:77] op_sel_hi:[1,0]
	v_div_fmas_f32 v76, v77, v135, v126
	s_mov_b64 vcc, s[0:1]
	v_pk_mul_f32 v[24:25], v[14:15], v[24:25]
	v_pk_mul_f32 v[22:23], v[12:13], v[22:23]
	v_pk_mul_f32 v[68:69], v[4:5], v[68:69]
	v_div_fixup_f32 v76, v76, v132, 1.0
	v_div_fmas_f32 v77, v124, v125, v136
	v_mov_b32_e32 v152, v144
	v_mov_b32_e32 v153, v102
	v_mov_b32_e32 v102, v145
	v_pk_mul_f32 v[28:29], v[10:11], v[28:29]
	v_pk_mul_f32 v[26:27], v[8:9], v[26:27]
	v_pk_mul_f32 v[70:71], v[6:7], v[70:71]
	v_pk_mul_f32 v[74:75], v[2:3], v[74:75]
	v_pk_mul_f32 v[72:73], v[0:1], v[72:73]
	flat_store_dwordx4 v[30:31], v[22:25]
	flat_store_dwordx4 v[32:33], v[26:29]
	flat_store_dwordx4 v[34:35], v[68:71]
	flat_store_dwordx4 v[36:37], v[72:75]
	v_pk_mul_f32 v[22:23], v[76:77], v[96:97] op_sel_hi:[0,1]
	v_pk_mul_f32 v[24:25], v[76:77], v[100:101] op_sel_hi:[0,1]
	v_div_fixup_f32 v68, v77, v117, 1.0
	v_pk_mul_f32 v[26:27], v[76:77], v[152:153] op_sel_hi:[0,1]
	v_pk_mul_f32 v[28:29], v[76:77], v[102:103] op_sel_hi:[0,1]
	v_pk_mul_f32 v[30:31], v[76:77], v[148:149] op_sel_hi:[0,1]
	v_pk_mul_f32 v[32:33], v[76:77], v[150:151] op_sel_hi:[0,1]
	v_pk_mul_f32 v[34:35], v[106:107], v[76:77] op_sel_hi:[1,0]
	v_pk_mul_f32 v[36:37], v[108:109], v[76:77] op_sel_hi:[1,0]
	v_pk_mul_f32 v[24:25], v[14:15], v[24:25]
	v_pk_mul_f32 v[22:23], v[12:13], v[22:23]
	v_pk_mul_f32 v[56:57], v[68:69], v[56:57] op_sel_hi:[0,1]
	v_pk_mul_f32 v[58:59], v[68:69], v[58:59] op_sel_hi:[0,1]
	v_pk_mul_f32 v[28:29], v[10:11], v[28:29]
	v_pk_mul_f32 v[26:27], v[8:9], v[26:27]
	v_pk_mul_f32 v[32:33], v[6:7], v[32:33]
	v_pk_mul_f32 v[30:31], v[4:5], v[30:31]
	v_pk_mul_f32 v[36:37], v[2:3], v[36:37]
	v_pk_mul_f32 v[34:35], v[0:1], v[34:35]
	v_pk_mul_f32 v[66:67], v[68:69], v[66:67] op_sel_hi:[0,1]
	v_pk_mul_f32 v[60:61], v[68:69], v[60:61] op_sel_hi:[0,1]
	v_pk_mul_f32 v[62:63], v[68:69], v[62:63] op_sel_hi:[0,1]
	v_pk_mul_f32 v[64:65], v[68:69], v[64:65] op_sel_hi:[0,1]
	v_pk_mul_f32 v[38:39], v[38:39], v[68:69] op_sel_hi:[1,0]
	v_pk_mul_f32 v[40:41], v[40:41], v[68:69] op_sel_hi:[1,0]
	flat_store_dwordx4 v[42:43], v[22:25]
	flat_store_dwordx4 v[44:45], v[26:29]
	flat_store_dwordx4 v[46:47], v[30:33]
	flat_store_dwordx4 v[48:49], v[34:37]
	v_pk_mul_f32 v[24:25], v[14:15], v[58:59]
	v_pk_mul_f32 v[22:23], v[12:13], v[56:57]
	v_pk_mul_f32 v[28:29], v[10:11], v[60:61]
	v_pk_mul_f32 v[26:27], v[8:9], v[66:67]
	v_pk_mul_f32 v[32:33], v[6:7], v[64:65]
	v_pk_mul_f32 v[30:31], v[4:5], v[62:63]
	v_pk_mul_f32 v[36:37], v[2:3], v[40:41]
	v_pk_mul_f32 v[34:35], v[0:1], v[38:39]
	flat_store_dwordx4 v[50:51], v[22:25]
	flat_store_dwordx4 v[52:53], v[26:29]
	flat_store_dwordx4 v[54:55], v[30:33]
	flat_store_dwordx4 v[18:19], v[34:37]
	v_lshl_add_u64 v[18:19], v[18:19], 0, s[12:13]
	s_andn2_b64 exec, exec, s[16:17]
	s_cbranch_execnz .LBB0_1353
